# GEMM MMA blocks: mid-block s_setprio 0/1 toggle removed (64 sites)
# speedup vs baseline: 1.0000x; 1.0000x over previous
; #define PG8_STAGE(bufoff, gbase, voff) do { _Pragma("unroll") for (int _i = 0; _i < 2; ++_i) \
;         __builtin_amdgcn_global_load_lds((const unsigned*)((const char*)(gbase) + (voff)[_i]), (PG8_LAS unsigned*)(lds + (bufoff) + ldsw + _i * 8192), 16, 0, 0); } while (0)
; #define PG8_LDA(dst, b, h) do { _Pragma("unroll") for (int m = 0; m < 4; ++m) _Pragma("unroll") for (int k = 0; k < 2; ++k) dst[m][k] = *(const PG8_LAS bf16x8*)(lds + PG8_SA(b, h) + aoff + m * 2048 + k * 1024); } while (0)
; #define PG8_LDB(dst, b, h) do { _Pragma("unroll") for (int n = 0; n < 2; ++n) _Pragma("unroll") for (int k = 0; k < 2; ++k) dst[n][k] = *(const PG8_LAS bf16x8*)(lds + PG8_SB(b, h) + boff + n * 2048 + k * 1024); } while (0)
; #define PG8_MMA(ai, bj, At, Bt) do { __builtin_amdgcn_s_setprio(1); _Pragma("unroll") for (int m = 0; m < 4; ++m) _Pragma("unroll") for (int n = 0; n < 2; ++n) _Pragma("unroll") for (int k = 0; k < 2; ++k) \
;         acc[ai][bj][m][n] = __builtin_amdgcn_mfma_f32_16x16x32_bf16(Bt[n][k], At[m][k], acc[ai][bj][m][n], 0, 0, 0); __builtin_amdgcn_s_setprio(0); } while (0)
; #define PG8_WAIT_V(n) asm volatile("s_waitcnt vmcnt(" #n ")" ::: "memory")
; #define PG8_WAIT_L(n) asm volatile("s_waitcnt lgkmcnt(" #n ")" ::: "memory")
; #define PG8_BAR __builtin_amdgcn_s_barrier()
; #define PG8_SCHED __builtin_amdgcn_sched_barrier(0)
; template <class Epi, class Sched, bool ALIGN_EPI = false, bool SP2 = false>
; __device__ __forceinline__ void gemm_phase(PG8_LAS unsigned char* lds, const Gemm g, const Sched& S, const Epi& E) {
;     ...
;             PG8_LDB(B0, 0, 0); PG8_LDB(B1, 0, 1); PG8_SCHED; PG8_LDA(At, 0, 0); PG8_STAGE(PG8_SA(1, 1), a1 + hstep, voffA);
;             PG8_WAIT_V(8); PG8_WAIT_L(0); PG8_BAR; PG8_MMA(0, 0, At, B0); PG8_MMA(0, 1, At, B1); PG8_BAR; PG8_SCHED;
;             PG8_LDA(At, 0, 1); PG8_STAGE(PG8_SB(0, 0), b2, voffB); PG8_STAGE(PG8_SB(0, 1), b2 + hstep, voffB); PG8_STAGE(PG8_SA(0, 0), a2, voffA);
;             PG8_WAIT_V(8); PG8_WAIT_L(0); PG8_BAR; PG8_MMA(1, 0, At, B0); PG8_MMA(1, 1, At, B1); PG8_BAR; PG8_SCHED;
.LfwP2_0_e:
	s_waitcnt lgkmcnt(0)
	s_barrier
	s_setprio 1
	s_waitcnt lgkmcnt(0)
	v_mfma_f32_16x16x32_bf16 v[124:127], v[144:147], v[184:187], 0
	v_mfma_f32_16x16x32_bf16 v[120:123], v[160:163], v[184:187], 0
	v_mfma_f32_16x16x32_bf16 v[116:119], v[144:147], v[192:195], 0
	v_mfma_f32_16x16x32_bf16 v[108:111], v[160:163], v[192:195], 0
	v_mfma_f32_16x16x32_bf16 v[100:103], v[144:147], v[200:203], 0
	v_mfma_f32_16x16x32_bf16 v[92:95], v[160:163], v[200:203], 0
	v_mfma_f32_16x16x32_bf16 v[84:87], v[144:147], v[208:211], 0
	v_mfma_f32_16x16x32_bf16 v[76:79], v[160:163], v[208:211], 0
	v_mfma_f32_16x16x32_bf16 v[124:127], v[156:159], v[188:191], v[124:127]
	v_mfma_f32_16x16x32_bf16 v[120:123], v[164:167], v[188:191], v[120:123]
	v_mfma_f32_16x16x32_bf16 v[116:119], v[156:159], v[196:199], v[116:119]
	v_mfma_f32_16x16x32_bf16 v[108:111], v[164:167], v[196:199], v[108:111]
	v_mfma_f32_16x16x32_bf16 v[100:103], v[156:159], v[204:207], v[100:103]
	v_mfma_f32_16x16x32_bf16 v[92:95], v[164:167], v[204:207], v[92:95]
	v_mfma_f32_16x16x32_bf16 v[84:87], v[156:159], v[212:215], v[84:87]
	v_mfma_f32_16x16x32_bf16 v[76:79], v[164:167], v[212:215], v[76:79]
	v_mfma_f32_16x16x32_bf16 v[112:115], v[168:171], v[184:187], 0
	v_mfma_f32_16x16x32_bf16 v[104:107], v[176:179], v[184:187], 0
	v_mfma_f32_16x16x32_bf16 v[96:99], v[168:171], v[192:195], 0
	v_mfma_f32_16x16x32_bf16 v[88:91], v[176:179], v[192:195], 0
	v_mfma_f32_16x16x32_bf16 v[80:83], v[168:171], v[200:203], 0
	v_mfma_f32_16x16x32_bf16 v[72:75], v[176:179], v[200:203], 0
	v_mfma_f32_16x16x32_bf16 v[68:71], v[168:171], v[208:211], 0
	v_mfma_f32_16x16x32_bf16 v[64:67], v[176:179], v[208:211], 0
	v_mfma_f32_16x16x32_bf16 v[112:115], v[172:175], v[188:191], v[112:115]
	v_mfma_f32_16x16x32_bf16 v[104:107], v[180:183], v[188:191], v[104:107]
	v_mfma_f32_16x16x32_bf16 v[96:99], v[172:175], v[196:199], v[96:99]
	v_mfma_f32_16x16x32_bf16 v[88:91], v[180:183], v[196:199], v[88:91]
	v_mfma_f32_16x16x32_bf16 v[80:83], v[172:175], v[204:207], v[80:83]
	v_mfma_f32_16x16x32_bf16 v[72:75], v[180:183], v[204:207], v[72:75]
	v_mfma_f32_16x16x32_bf16 v[68:71], v[172:175], v[212:215], v[68:71]
	v_mfma_f32_16x16x32_bf16 v[64:67], v[180:183], v[212:215], v[64:67]
	s_setprio 0
	s_barrier
	s_add_i32 s33, s76, s54
	s_add_u32 s56, s44, s10
	s_addc_u32 s57, s45, s11
	s_mov_b32 m0, s33
	ds_read_b128 v[184:187], v154 offset:16384
	ds_read_b128 v[188:191], v154 offset:17408
	ds_read_b128 v[192:195], v154 offset:18432
	ds_read_b128 v[196:199], v154 offset:19456
	ds_read_b128 v[200:203], v154 offset:20480
	ds_read_b128 v[204:207], v154 offset:21504
	ds_read_b128 v[208:211], v154 offset:22528
	ds_read_b128 v[212:215], v154 offset:23552
	global_load_lds_dwordx4 v130, s[44:45]
	s_add_i32 m0, s33, 0x2000
	s_add_u32 s90, s44, 0x40000
	s_addc_u32 s91, s45, 0
	s_add_i32 s33, s77, s54
	global_load_lds_dwordx4 v134, s[44:45]
	s_mov_b32 m0, s33
	s_add_u32 s58, s46, s10
	s_addc_u32 s59, s47, s11
	global_load_lds_dwordx4 v130, s[90:91]
	s_add_i32 m0, s33, 0x2000
	s_nop 0
	global_load_lds_dwordx4 v134, s[90:91]
	s_mov_b32 m0, s41
	s_nop 0
	global_load_lds_dwordx4 v128, s[46:47]
	s_mov_b32 m0, s63
	s_nop 0
	global_load_lds_dwordx4 v132, s[46:47]
	s_cmp_eq_u32 s60, 0
	s_cbranch_scc1 .LfwP2_1_s
	s_waitcnt vmcnt(24)
	s_branch .LfwP2_1_e

; #define PG8_STAGE(bufoff, gbase, voff) do { _Pragma("unroll") for (int _i = 0; _i < 2; ++_i) \
;         __builtin_amdgcn_global_load_lds((const unsigned*)((const char*)(gbase) + (voff)[_i]), (PG8_LAS unsigned*)(lds + (bufoff) + ldsw + _i * 8192), 16, 0, 0); } while (0)
; #define PG8_LDA(dst, b, h) do { _Pragma("unroll") for (int m = 0; m < 4; ++m) _Pragma("unroll") for (int k = 0; k < 2; ++k) dst[m][k] = *(const PG8_LAS bf16x8*)(lds + PG8_SA(b, h) + aoff + m * 2048 + k * 1024); } while (0)
; #define PG8_LDB(dst, b, h) do { _Pragma("unroll") for (int n = 0; n < 2; ++n) _Pragma("unroll") for (int k = 0; k < 2; ++k) dst[n][k] = *(const PG8_LAS bf16x8*)(lds + PG8_SB(b, h) + boff + n * 2048 + k * 1024); } while (0)
; #define PG8_MMA(ai, bj, At, Bt) do { __builtin_amdgcn_s_setprio(1); _Pragma("unroll") for (int m = 0; m < 4; ++m) _Pragma("unroll") for (int n = 0; n < 2; ++n) _Pragma("unroll") for (int k = 0; k < 2; ++k) \
;         acc[ai][bj][m][n] = __builtin_amdgcn_mfma_f32_16x16x32_bf16(Bt[n][k], At[m][k], acc[ai][bj][m][n], 0, 0, 0); __builtin_amdgcn_s_setprio(0); } while (0)
; #define PG8_WAIT_V(n) asm volatile("s_waitcnt vmcnt(" #n ")" ::: "memory")
; #define PG8_WAIT_L(n) asm volatile("s_waitcnt lgkmcnt(" #n ")" ::: "memory")
; #define PG8_BAR __builtin_amdgcn_s_barrier()
; #define PG8_SCHED __builtin_amdgcn_sched_barrier(0)
; template <class Epi, class Sched, bool ALIGN_EPI = false, bool SP2 = false>
; __device__ __forceinline__ void gemm_phase(PG8_LAS unsigned char* lds, const Gemm g, const Sched& S, const Epi& E) {
;     ...
;             PG8_WAIT_V(8); PG8_WAIT_L(0); PG8_BAR; PG8_MMA(1, 0, At, B0); PG8_MMA(1, 1, At, B1); PG8_BAR; PG8_SCHED;
;             PG8_LDB(B0, 1, 0); PG8_LDB(B1, 1, 1); PG8_SCHED; PG8_LDA(At, 1, 0); PG8_STAGE(PG8_SA(0, 1), a2 + hstep, voffA);
;             PG8_WAIT_V(8); PG8_WAIT_L(0); PG8_BAR; PG8_MMA(0, 0, At, B0); PG8_MMA(0, 1, At, B1); PG8_BAR; PG8_SCHED;
.LfwP2_1_e:
	s_waitcnt lgkmcnt(0)
	s_barrier
	s_setprio 1
	s_waitcnt lgkmcnt(0)
	v_mfma_f32_16x16x32_bf16 v[60:63], v[144:147], v[184:187], 0
	v_mfma_f32_16x16x32_bf16 v[56:59], v[160:163], v[184:187], 0
	v_mfma_f32_16x16x32_bf16 v[52:55], v[144:147], v[192:195], 0
	v_mfma_f32_16x16x32_bf16 v[44:47], v[160:163], v[192:195], 0
	v_mfma_f32_16x16x32_bf16 v[36:39], v[144:147], v[200:203], 0
	v_mfma_f32_16x16x32_bf16 v[28:31], v[160:163], v[200:203], 0
	v_mfma_f32_16x16x32_bf16 v[20:23], v[144:147], v[208:211], 0
	v_mfma_f32_16x16x32_bf16 v[12:15], v[160:163], v[208:211], 0
	v_mfma_f32_16x16x32_bf16 v[60:63], v[156:159], v[188:191], v[60:63]
	v_mfma_f32_16x16x32_bf16 v[56:59], v[164:167], v[188:191], v[56:59]
	v_mfma_f32_16x16x32_bf16 v[52:55], v[156:159], v[196:199], v[52:55]
	v_mfma_f32_16x16x32_bf16 v[44:47], v[164:167], v[196:199], v[44:47]
	v_mfma_f32_16x16x32_bf16 v[36:39], v[156:159], v[204:207], v[36:39]
	v_mfma_f32_16x16x32_bf16 v[28:31], v[164:167], v[204:207], v[28:31]
	v_mfma_f32_16x16x32_bf16 v[20:23], v[156:159], v[212:215], v[20:23]
	v_mfma_f32_16x16x32_bf16 v[12:15], v[164:167], v[212:215], v[12:15]
	v_mfma_f32_16x16x32_bf16 v[48:51], v[168:171], v[184:187], 0
	v_mfma_f32_16x16x32_bf16 v[40:43], v[176:179], v[184:187], 0
	v_mfma_f32_16x16x32_bf16 v[32:35], v[168:171], v[192:195], 0
	v_mfma_f32_16x16x32_bf16 v[24:27], v[176:179], v[192:195], 0
	v_mfma_f32_16x16x32_bf16 v[16:19], v[168:171], v[200:203], 0
	v_mfma_f32_16x16x32_bf16 v[8:11], v[176:179], v[200:203], 0
	v_mfma_f32_16x16x32_bf16 v[4:7], v[168:171], v[208:211], 0
	v_mfma_f32_16x16x32_bf16 v[0:3], v[176:179], v[208:211], 0
	v_mfma_f32_16x16x32_bf16 v[48:51], v[172:175], v[188:191], v[48:51]
	v_mfma_f32_16x16x32_bf16 v[40:43], v[180:183], v[188:191], v[40:43]
	v_mfma_f32_16x16x32_bf16 v[32:35], v[172:175], v[196:199], v[32:35]
	v_mfma_f32_16x16x32_bf16 v[24:27], v[180:183], v[196:199], v[24:27]
	v_mfma_f32_16x16x32_bf16 v[16:19], v[172:175], v[204:207], v[16:19]
	v_mfma_f32_16x16x32_bf16 v[8:11], v[180:183], v[204:207], v[8:11]
	v_mfma_f32_16x16x32_bf16 v[4:7], v[172:175], v[212:215], v[4:7]
	v_mfma_f32_16x16x32_bf16 v[0:3], v[180:183], v[212:215], v[0:3]
	s_setprio 0
	s_barrier
	s_add_i32 s33, 0, 0x18000
	v_add_u32_e32 v155, s33, v149
	s_add_i32 s34, 0, 0x1c000
	ds_read_b128 v[144:147], v155
	ds_read_b128 v[156:159], v155 offset:1024
	ds_read_b128 v[160:163], v155 offset:2048
	ds_read_b128 v[164:167], v155 offset:3072
	v_add_u32_e32 v155, s34, v149
	ds_read_b128 v[168:171], v155
	ds_read_b128 v[172:175], v155 offset:1024
	ds_read_b128 v[176:179], v155 offset:2048
	ds_read_b128 v[180:183], v155 offset:3072
	s_add_u32 s46, s46, 0x40000
	s_addc_u32 s47, s47, 0
	s_mov_b32 m0, s70
	ds_read_b128 v[184:187], v154 offset:32768
	ds_read_b128 v[188:191], v154 offset:33792
	ds_read_b128 v[192:195], v154 offset:34816
	ds_read_b128 v[196:199], v154 offset:35840
	ds_read_b128 v[200:203], v154 offset:36864
	ds_read_b128 v[204:207], v154 offset:37888
	ds_read_b128 v[208:211], v154 offset:38912
	ds_read_b128 v[212:215], v154 offset:39936
	global_load_lds_dwordx4 v128, s[46:47]
	s_mov_b32 m0, s71
	s_nop 0
	global_load_lds_dwordx4 v132, s[46:47]
	s_waitcnt vmcnt(8)
	s_waitcnt lgkmcnt(0)
	s_barrier
	s_setprio 1
	s_waitcnt lgkmcnt(0)
	v_mfma_f32_16x16x32_bf16 v[124:127], v[144:147], v[184:187], v[124:127]
	v_mfma_f32_16x16x32_bf16 v[120:123], v[160:163], v[184:187], v[120:123]
	v_mfma_f32_16x16x32_bf16 v[116:119], v[144:147], v[192:195], v[116:119]
	v_mfma_f32_16x16x32_bf16 v[108:111], v[160:163], v[192:195], v[108:111]
	v_mfma_f32_16x16x32_bf16 v[100:103], v[144:147], v[200:203], v[100:103]
	v_mfma_f32_16x16x32_bf16 v[92:95], v[160:163], v[200:203], v[92:95]
	v_mfma_f32_16x16x32_bf16 v[84:87], v[144:147], v[208:211], v[84:87]
	v_mfma_f32_16x16x32_bf16 v[76:79], v[160:163], v[208:211], v[76:79]
	v_mfma_f32_16x16x32_bf16 v[124:127], v[156:159], v[188:191], v[124:127]
	v_mfma_f32_16x16x32_bf16 v[120:123], v[164:167], v[188:191], v[120:123]
	v_mfma_f32_16x16x32_bf16 v[116:119], v[156:159], v[196:199], v[116:119]
	v_mfma_f32_16x16x32_bf16 v[108:111], v[164:167], v[196:199], v[108:111]
	v_mfma_f32_16x16x32_bf16 v[100:103], v[156:159], v[204:207], v[100:103]
	v_mfma_f32_16x16x32_bf16 v[92:95], v[164:167], v[204:207], v[92:95]
	v_mfma_f32_16x16x32_bf16 v[84:87], v[156:159], v[212:215], v[84:87]
	v_mfma_f32_16x16x32_bf16 v[76:79], v[164:167], v[212:215], v[76:79]
	v_mfma_f32_16x16x32_bf16 v[112:115], v[168:171], v[184:187], v[112:115]
	v_mfma_f32_16x16x32_bf16 v[104:107], v[176:179], v[184:187], v[104:107]
	v_mfma_f32_16x16x32_bf16 v[96:99], v[168:171], v[192:195], v[96:99]
	v_mfma_f32_16x16x32_bf16 v[88:91], v[176:179], v[192:195], v[88:91]
	v_mfma_f32_16x16x32_bf16 v[80:83], v[168:171], v[200:203], v[80:83]
	v_mfma_f32_16x16x32_bf16 v[72:75], v[176:179], v[200:203], v[72:75]
	v_mfma_f32_16x16x32_bf16 v[68:71], v[168:171], v[208:211], v[68:71]
	v_mfma_f32_16x16x32_bf16 v[64:67], v[176:179], v[208:211], v[64:67]
	v_mfma_f32_16x16x32_bf16 v[112:115], v[172:175], v[188:191], v[112:115]
	v_mfma_f32_16x16x32_bf16 v[104:107], v[180:183], v[188:191], v[104:107]
	v_mfma_f32_16x16x32_bf16 v[96:99], v[172:175], v[196:199], v[96:99]
	v_mfma_f32_16x16x32_bf16 v[88:91], v[180:183], v[196:199], v[88:91]
	v_mfma_f32_16x16x32_bf16 v[80:83], v[172:175], v[204:207], v[80:83]
	v_mfma_f32_16x16x32_bf16 v[72:75], v[180:183], v[204:207], v[72:75]
	v_mfma_f32_16x16x32_bf16 v[68:71], v[172:175], v[212:215], v[68:71]
	v_mfma_f32_16x16x32_bf16 v[64:67], v[180:183], v[212:215], v[64:67]
	s_setprio 0
	s_barrier
; #define PG8_STAGE(bufoff, gbase, voff) do { _Pragma("unroll") for (int _i = 0; _i < 2; ++_i) \
;         __builtin_amdgcn_global_load_lds((const unsigned*)((const char*)(gbase) + (voff)[_i]), (PG8_LAS unsigned*)(lds + (bufoff) + ldsw + _i * 8192), 16, 0, 0); } while (0)
; #define PG8_LDA(dst, b, h) do { _Pragma("unroll") for (int m = 0; m < 4; ++m) _Pragma("unroll") for (int k = 0; k < 2; ++k) dst[m][k] = *(const PG8_LAS bf16x8*)(lds + PG8_SA(b, h) + aoff + m * 2048 + k * 1024); } while (0)
; #define PG8_LDB(dst, b, h) do { _Pragma("unroll") for (int n = 0; n < 2; ++n) _Pragma("unroll") for (int k = 0; k < 2; ++k) dst[n][k] = *(const PG8_LAS bf16x8*)(lds + PG8_SB(b, h) + boff + n * 2048 + k * 1024); } while (0)
; #define PG8_MMA(ai, bj, At, Bt) do { __builtin_amdgcn_s_setprio(1); _Pragma("unroll") for (int m = 0; m < 4; ++m) _Pragma("unroll") for (int n = 0; n < 2; ++n) _Pragma("unroll") for (int k = 0; k < 2; ++k) \
;         acc[ai][bj][m][n] = __builtin_amdgcn_mfma_f32_16x16x32_bf16(Bt[n][k], At[m][k], acc[ai][bj][m][n], 0, 0, 0); __builtin_amdgcn_s_setprio(0); } while (0)
; #define PG8_WAIT_V(n) asm volatile("s_waitcnt vmcnt(" #n ")" ::: "memory")
; #define PG8_WAIT_L(n) asm volatile("s_waitcnt lgkmcnt(" #n ")" ::: "memory")
; template <class Epi, class Sched, bool ALIGN_EPI = false, bool SP2 = false>
; __device__ __forceinline__ void gemm_phase(PG8_LAS unsigned char* lds, const Gemm g, const Sched& S, const Epi& E) {
;     ...
;             const bool last = (t == nt - 2);
;             const char* a1 = cA + (size_t)(t + 1) * kstep;
;             const char* a2 = last ? nA : cA + (size_t)(t + 2) * kstep; const char* b2 = last ? nB : cB + (size_t)(t + 2) * kstep;
;             const char* a3 = a2 + kstep; const char* b3 = b2 + kstep;
;             if (last && has_next) S.a_ready(nxt);
;             if constexpr (SP2) {
;             PG8_LDB(B0, 0, 0); PG8_LDB(B1, 0, 1); PG8_SCHED; PG8_LDA(At, 0, 0); PG8_STAGE(PG8_SA(1, 1), a1 + hstep, voffA);
;             PG8_WAIT_V(8); PG8_WAIT_L(0); PG8_BAR; PG8_MMA(0, 0, At, B0); PG8_MMA(0, 1, At, B1); PG8_BAR; PG8_SCHED;
;     ...
;             PG8_LDA(At, 1, 1); PG8_STAGE(PG8_SB(1, 0), b3, voffB); PG8_STAGE(PG8_SB(1, 1), b3 + hstep, voffB); PG8_STAGE(PG8_SA(1, 0), a3, voffA);
;             PG8_WAIT_V(8); PG8_WAIT_L(0); PG8_BAR; PG8_MMA(1, 0, At, B0); PG8_MMA(1, 1, At, B1); PG8_BAR; PG8_SCHED;
	s_add_i32 s33, s33, s54
	s_mov_b32 m0, s33
	ds_read_b128 v[184:187], v154 offset:49152
	ds_read_b128 v[188:191], v154 offset:50176
	ds_read_b128 v[192:195], v154 offset:51200
	ds_read_b128 v[196:199], v154 offset:52224
	ds_read_b128 v[200:203], v154 offset:53248
	ds_read_b128 v[204:207], v154 offset:54272
	ds_read_b128 v[208:211], v154 offset:55296
	ds_read_b128 v[212:215], v154 offset:56320
	global_load_lds_dwordx4 v130, s[56:57]
	s_add_i32 m0, s33, 0x2000
	s_add_u32 s44, s44, 0x40080
	s_addc_u32 s45, s45, 0
	s_add_i32 s33, s34, s54
	global_load_lds_dwordx4 v134, s[56:57]
	s_mov_b32 m0, s33
	s_nop 0
	global_load_lds_dwordx4 v130, s[44:45]
	s_add_i32 m0, s33, 0x2000
	s_nop 0
	global_load_lds_dwordx4 v134, s[44:45]
	s_mov_b32 m0, s74
	s_nop 0
	global_load_lds_dwordx4 v128, s[58:59]
	s_mov_b32 m0, s75
	s_nop 0
	global_load_lds_dwordx4 v132, s[58:59]
	s_waitcnt vmcnt(8)
	s_waitcnt lgkmcnt(0)
	s_barrier
	s_setprio 1
	s_waitcnt lgkmcnt(0)
	v_mfma_f32_16x16x32_bf16 v[60:63], v[144:147], v[184:187], v[60:63]
	v_mfma_f32_16x16x32_bf16 v[56:59], v[160:163], v[184:187], v[56:59]
	v_mfma_f32_16x16x32_bf16 v[52:55], v[144:147], v[192:195], v[52:55]
	v_mfma_f32_16x16x32_bf16 v[44:47], v[160:163], v[192:195], v[44:47]
	v_mfma_f32_16x16x32_bf16 v[36:39], v[144:147], v[200:203], v[36:39]
	v_mfma_f32_16x16x32_bf16 v[28:31], v[160:163], v[200:203], v[28:31]
	v_mfma_f32_16x16x32_bf16 v[20:23], v[144:147], v[208:211], v[20:23]
	v_mfma_f32_16x16x32_bf16 v[12:15], v[160:163], v[208:211], v[12:15]
	v_mfma_f32_16x16x32_bf16 v[60:63], v[156:159], v[188:191], v[60:63]
	v_mfma_f32_16x16x32_bf16 v[56:59], v[164:167], v[188:191], v[56:59]
	v_mfma_f32_16x16x32_bf16 v[52:55], v[156:159], v[196:199], v[52:55]
	v_mfma_f32_16x16x32_bf16 v[44:47], v[164:167], v[196:199], v[44:47]
	v_mfma_f32_16x16x32_bf16 v[36:39], v[156:159], v[204:207], v[36:39]
	v_mfma_f32_16x16x32_bf16 v[28:31], v[164:167], v[204:207], v[28:31]
	v_mfma_f32_16x16x32_bf16 v[20:23], v[156:159], v[212:215], v[20:23]
	v_mfma_f32_16x16x32_bf16 v[12:15], v[164:167], v[212:215], v[12:15]
	v_mfma_f32_16x16x32_bf16 v[48:51], v[168:171], v[184:187], v[48:51]
	v_mfma_f32_16x16x32_bf16 v[40:43], v[176:179], v[184:187], v[40:43]
	v_mfma_f32_16x16x32_bf16 v[32:35], v[168:171], v[192:195], v[32:35]
	v_mfma_f32_16x16x32_bf16 v[24:27], v[176:179], v[192:195], v[24:27]
	v_mfma_f32_16x16x32_bf16 v[16:19], v[168:171], v[200:203], v[16:19]
	v_mfma_f32_16x16x32_bf16 v[8:11], v[176:179], v[200:203], v[8:11]
	v_mfma_f32_16x16x32_bf16 v[4:7], v[168:171], v[208:211], v[4:7]
	v_mfma_f32_16x16x32_bf16 v[0:3], v[176:179], v[208:211], v[0:3]
	v_mfma_f32_16x16x32_bf16 v[48:51], v[172:175], v[188:191], v[48:51]
	v_mfma_f32_16x16x32_bf16 v[40:43], v[180:183], v[188:191], v[40:43]
	v_mfma_f32_16x16x32_bf16 v[32:35], v[172:175], v[196:199], v[32:35]
	v_mfma_f32_16x16x32_bf16 v[24:27], v[180:183], v[196:199], v[24:27]
	v_mfma_f32_16x16x32_bf16 v[16:19], v[172:175], v[204:207], v[16:19]
	v_mfma_f32_16x16x32_bf16 v[8:11], v[180:183], v[204:207], v[8:11]
	v_mfma_f32_16x16x32_bf16 v[4:7], v[172:175], v[212:215], v[4:7]
	v_mfma_f32_16x16x32_bf16 v[0:3], v[180:183], v[212:215], v[0:3]
	s_setprio 0
	s_barrier
	s_add_i32 s86, s86, 2
	s_add_u32 s42, s42, 0x100
	s_addc_u32 s43, s43, 0
	s_add_u32 s82, s82, 0x100
	s_addc_u32 s83, s83, 0
	s_cmp_gt_u32 s86, 13
.LBB0_381:
	ds_read_b128 v[144:147], v151
	ds_read_b128 v[156:159], v151 offset:1024
	ds_read_b128 v[160:163], v151 offset:2048
	ds_read_b128 v[164:167], v151 offset:3072
	ds_read_b128 v[168:171], v153
	ds_read_b128 v[172:175], v153 offset:1024
	ds_read_b128 v[176:179], v153 offset:2048
	ds_read_b128 v[180:183], v153 offset:3072
	s_add_u32 s33, s42, 0xfffc0080
	s_addc_u32 s34, s43, -1
	s_cmp_eq_u32 s86, 12
	s_cselect_b32 s47, s23, s34
	s_cselect_b32 s46, s80, s33
	s_cselect_b32 s45, s21, s83
	s_cselect_b32 s44, s81, s82
	s_add_i32 m0, s41, 0xc000
	ds_read_b128 v[184:187], v154
	ds_read_b128 v[188:191], v154 offset:1024
	ds_read_b128 v[192:195], v154 offset:2048
	ds_read_b128 v[196:199], v154 offset:3072
	ds_read_b128 v[200:203], v154 offset:4096
	ds_read_b128 v[204:207], v154 offset:5120
	ds_read_b128 v[208:211], v154 offset:6144
	ds_read_b128 v[212:215], v154 offset:7168
	global_load_lds_dwordx4 v136, s[42:43]
	s_add_i32 m0, s41, 0xe000
	s_nop 0
	global_load_lds_dwordx4 v138, s[42:43]
	s_waitcnt vmcnt(8)
	s_waitcnt lgkmcnt(0)
	s_barrier
	s_setprio 1
	s_waitcnt lgkmcnt(0)
	v_mfma_f32_16x16x32_bf16 v[124:127], v[144:147], v[184:187], v[124:127]
	v_mfma_f32_16x16x32_bf16 v[120:123], v[160:163], v[184:187], v[120:123]
	v_mfma_f32_16x16x32_bf16 v[116:119], v[144:147], v[192:195], v[116:119]
	v_mfma_f32_16x16x32_bf16 v[108:111], v[160:163], v[192:195], v[108:111]
	v_mfma_f32_16x16x32_bf16 v[100:103], v[144:147], v[200:203], v[100:103]
	v_mfma_f32_16x16x32_bf16 v[92:95], v[160:163], v[200:203], v[92:95]
	v_mfma_f32_16x16x32_bf16 v[84:87], v[144:147], v[208:211], v[84:87]
	v_mfma_f32_16x16x32_bf16 v[76:79], v[160:163], v[208:211], v[76:79]
	v_mfma_f32_16x16x32_bf16 v[124:127], v[156:159], v[188:191], v[124:127]
	v_mfma_f32_16x16x32_bf16 v[120:123], v[164:167], v[188:191], v[120:123]
	v_mfma_f32_16x16x32_bf16 v[116:119], v[156:159], v[196:199], v[116:119]
	v_mfma_f32_16x16x32_bf16 v[108:111], v[164:167], v[196:199], v[108:111]
	v_mfma_f32_16x16x32_bf16 v[100:103], v[156:159], v[204:207], v[100:103]
	v_mfma_f32_16x16x32_bf16 v[92:95], v[164:167], v[204:207], v[92:95]
	v_mfma_f32_16x16x32_bf16 v[84:87], v[156:159], v[212:215], v[84:87]
	v_mfma_f32_16x16x32_bf16 v[76:79], v[164:167], v[212:215], v[76:79]
	v_mfma_f32_16x16x32_bf16 v[112:115], v[168:171], v[184:187], v[112:115]
	v_mfma_f32_16x16x32_bf16 v[104:107], v[176:179], v[184:187], v[104:107]
	v_mfma_f32_16x16x32_bf16 v[96:99], v[168:171], v[192:195], v[96:99]
	v_mfma_f32_16x16x32_bf16 v[88:91], v[176:179], v[192:195], v[88:91]
	v_mfma_f32_16x16x32_bf16 v[80:83], v[168:171], v[200:203], v[80:83]
	v_mfma_f32_16x16x32_bf16 v[72:75], v[176:179], v[200:203], v[72:75]
	v_mfma_f32_16x16x32_bf16 v[68:71], v[168:171], v[208:211], v[68:71]
	v_mfma_f32_16x16x32_bf16 v[64:67], v[176:179], v[208:211], v[64:67]
	v_mfma_f32_16x16x32_bf16 v[112:115], v[172:175], v[188:191], v[112:115]
	v_mfma_f32_16x16x32_bf16 v[104:107], v[180:183], v[188:191], v[104:107]
	v_mfma_f32_16x16x32_bf16 v[96:99], v[172:175], v[196:199], v[96:99]
	v_mfma_f32_16x16x32_bf16 v[88:91], v[180:183], v[196:199], v[88:91]
	v_mfma_f32_16x16x32_bf16 v[80:83], v[172:175], v[204:207], v[80:83]
	v_mfma_f32_16x16x32_bf16 v[72:75], v[180:183], v[204:207], v[72:75]
	v_mfma_f32_16x16x32_bf16 v[68:71], v[172:175], v[212:215], v[68:71]
	v_mfma_f32_16x16x32_bf16 v[64:67], v[180:183], v[212:215], v[64:67]
	s_setprio 0
	s_barrier
; #define PG8_STAGE(bufoff, gbase, voff) do { _Pragma("unroll") for (int _i = 0; _i < 2; ++_i) \
;         __builtin_amdgcn_global_load_lds((const unsigned*)((const char*)(gbase) + (voff)[_i]), (PG8_LAS unsigned*)(lds + (bufoff) + ldsw + _i * 8192), 16, 0, 0); } while (0)
; #define PG8_LDA(dst, b, h) do { _Pragma("unroll") for (int m = 0; m < 4; ++m) _Pragma("unroll") for (int k = 0; k < 2; ++k) dst[m][k] = *(const PG8_LAS bf16x8*)(lds + PG8_SA(b, h) + aoff + m * 2048 + k * 1024); } while (0)
; #define PG8_LDB(dst, b, h) do { _Pragma("unroll") for (int n = 0; n < 2; ++n) _Pragma("unroll") for (int k = 0; k < 2; ++k) dst[n][k] = *(const PG8_LAS bf16x8*)(lds + PG8_SB(b, h) + boff + n * 2048 + k * 1024); } while (0)
; #define PG8_MMA(ai, bj, At, Bt) do { __builtin_amdgcn_s_setprio(1); _Pragma("unroll") for (int m = 0; m < 4; ++m) _Pragma("unroll") for (int n = 0; n < 2; ++n) _Pragma("unroll") for (int k = 0; k < 2; ++k) \
;         acc[ai][bj][m][n] = __builtin_amdgcn_mfma_f32_16x16x32_bf16(Bt[n][k], At[m][k], acc[ai][bj][m][n], 0, 0, 0); __builtin_amdgcn_s_setprio(0); } while (0)
; #define PG8_WAIT_V(n) asm volatile("s_waitcnt vmcnt(" #n ")" ::: "memory")
; #define PG8_WAIT_L(n) asm volatile("s_waitcnt lgkmcnt(" #n ")" ::: "memory")
; #define PG8_BAR __builtin_amdgcn_s_barrier()
; #define PG8_SCHED __builtin_amdgcn_sched_barrier(0)
; template <class Epi, class Sched, bool ALIGN_EPI = false, bool SP2 = false>
; __device__ __forceinline__ void gemm_phase(PG8_LAS unsigned char* lds, const Gemm g, const Sched& S, const Epi& E) {
;     ...
;             PG8_LDA(At, 0, 1); PG8_STAGE(PG8_SB(0, 0), b2, voffB); PG8_STAGE(PG8_SB(0, 1), b2 + hstep, voffB); PG8_STAGE(PG8_SA(0, 0), a2, voffA);
;             PG8_WAIT_V(8); PG8_WAIT_L(0); PG8_BAR; PG8_MMA(1, 0, At, B0); PG8_MMA(1, 1, At, B1); PG8_BAR; PG8_SCHED;
;             PG8_LDB(B0, 1, 0); PG8_LDB(B1, 1, 1); PG8_SCHED; PG8_LDA(At, 1, 0); PG8_STAGE(PG8_SA(0, 1), a2 + hstep, voffA);
	s_add_i32 s33, s76, s54
	s_add_u32 s56, s44, s10
	s_addc_u32 s57, s45, s11
	s_mov_b32 m0, s33
	ds_read_b128 v[184:187], v154 offset:16384
	ds_read_b128 v[188:191], v154 offset:17408
	ds_read_b128 v[192:195], v154 offset:18432
	ds_read_b128 v[196:199], v154 offset:19456
	ds_read_b128 v[200:203], v154 offset:20480
	ds_read_b128 v[204:207], v154 offset:21504
	ds_read_b128 v[208:211], v154 offset:22528
	ds_read_b128 v[212:215], v154 offset:23552
	global_load_lds_dwordx4 v130, s[44:45]
	s_add_i32 m0, s33, 0x2000
	s_add_u32 s90, s44, 0x40000
	s_addc_u32 s91, s45, 0
	s_add_i32 s33, s77, s54
	global_load_lds_dwordx4 v134, s[44:45]
	s_mov_b32 m0, s33
	s_add_u32 s58, s46, s10
	s_addc_u32 s59, s47, s11
	global_load_lds_dwordx4 v130, s[90:91]
	s_add_i32 m0, s33, 0x2000
	s_nop 0
	global_load_lds_dwordx4 v134, s[90:91]
	s_mov_b32 m0, s41
	s_nop 0
	global_load_lds_dwordx4 v128, s[46:47]
	s_mov_b32 m0, s63
	s_nop 0
	global_load_lds_dwordx4 v132, s[46:47]
	s_waitcnt vmcnt(8)
	s_waitcnt lgkmcnt(0)
	s_barrier
	s_setprio 1
	s_waitcnt lgkmcnt(0)
	v_mfma_f32_16x16x32_bf16 v[60:63], v[144:147], v[184:187], v[60:63]
	v_mfma_f32_16x16x32_bf16 v[56:59], v[160:163], v[184:187], v[56:59]
	v_mfma_f32_16x16x32_bf16 v[52:55], v[144:147], v[192:195], v[52:55]
	v_mfma_f32_16x16x32_bf16 v[44:47], v[160:163], v[192:195], v[44:47]
	v_mfma_f32_16x16x32_bf16 v[36:39], v[144:147], v[200:203], v[36:39]
	v_mfma_f32_16x16x32_bf16 v[28:31], v[160:163], v[200:203], v[28:31]
	v_mfma_f32_16x16x32_bf16 v[20:23], v[144:147], v[208:211], v[20:23]
	v_mfma_f32_16x16x32_bf16 v[12:15], v[160:163], v[208:211], v[12:15]
	v_mfma_f32_16x16x32_bf16 v[60:63], v[156:159], v[188:191], v[60:63]
	v_mfma_f32_16x16x32_bf16 v[56:59], v[164:167], v[188:191], v[56:59]
	v_mfma_f32_16x16x32_bf16 v[52:55], v[156:159], v[196:199], v[52:55]
	v_mfma_f32_16x16x32_bf16 v[44:47], v[164:167], v[196:199], v[44:47]
	v_mfma_f32_16x16x32_bf16 v[36:39], v[156:159], v[204:207], v[36:39]
	v_mfma_f32_16x16x32_bf16 v[28:31], v[164:167], v[204:207], v[28:31]
	v_mfma_f32_16x16x32_bf16 v[20:23], v[156:159], v[212:215], v[20:23]
	v_mfma_f32_16x16x32_bf16 v[12:15], v[164:167], v[212:215], v[12:15]
	v_mfma_f32_16x16x32_bf16 v[48:51], v[168:171], v[184:187], v[48:51]
	v_mfma_f32_16x16x32_bf16 v[40:43], v[176:179], v[184:187], v[40:43]
	v_mfma_f32_16x16x32_bf16 v[32:35], v[168:171], v[192:195], v[32:35]
	v_mfma_f32_16x16x32_bf16 v[24:27], v[176:179], v[192:195], v[24:27]
	v_mfma_f32_16x16x32_bf16 v[16:19], v[168:171], v[200:203], v[16:19]
	v_mfma_f32_16x16x32_bf16 v[8:11], v[176:179], v[200:203], v[8:11]
	v_mfma_f32_16x16x32_bf16 v[4:7], v[168:171], v[208:211], v[4:7]
	v_mfma_f32_16x16x32_bf16 v[0:3], v[176:179], v[208:211], v[0:3]
	v_mfma_f32_16x16x32_bf16 v[48:51], v[172:175], v[188:191], v[48:51]
	v_mfma_f32_16x16x32_bf16 v[40:43], v[180:183], v[188:191], v[40:43]
	v_mfma_f32_16x16x32_bf16 v[32:35], v[172:175], v[196:199], v[32:35]
	v_mfma_f32_16x16x32_bf16 v[24:27], v[180:183], v[196:199], v[24:27]
	v_mfma_f32_16x16x32_bf16 v[16:19], v[172:175], v[204:207], v[16:19]
	v_mfma_f32_16x16x32_bf16 v[8:11], v[180:183], v[204:207], v[8:11]
	v_mfma_f32_16x16x32_bf16 v[4:7], v[172:175], v[212:215], v[4:7]
	v_mfma_f32_16x16x32_bf16 v[0:3], v[180:183], v[212:215], v[0:3]
	s_setprio 0
	s_barrier
	s_add_i32 s33, 0, 0x18000
	v_add_u32_e32 v155, s33, v149
	s_add_i32 s34, 0, 0x1c000
	ds_read_b128 v[144:147], v155
	ds_read_b128 v[156:159], v155 offset:1024
	ds_read_b128 v[160:163], v155 offset:2048
	ds_read_b128 v[164:167], v155 offset:3072
	v_add_u32_e32 v155, s34, v149
	ds_read_b128 v[168:171], v155
	ds_read_b128 v[172:175], v155 offset:1024
	ds_read_b128 v[176:179], v155 offset:2048
	ds_read_b128 v[180:183], v155 offset:3072
	s_add_u32 s46, s46, 0x40000
	s_addc_u32 s47, s47, 0
	s_mov_b32 m0, s70
	ds_read_b128 v[184:187], v154 offset:32768
	ds_read_b128 v[188:191], v154 offset:33792
	ds_read_b128 v[192:195], v154 offset:34816
	ds_read_b128 v[196:199], v154 offset:35840
	ds_read_b128 v[200:203], v154 offset:36864
	ds_read_b128 v[204:207], v154 offset:37888
	ds_read_b128 v[208:211], v154 offset:38912
	ds_read_b128 v[212:215], v154 offset:39936
	global_load_lds_dwordx4 v128, s[46:47]
	s_mov_b32 m0, s71
	s_nop 0
	global_load_lds_dwordx4 v132, s[46:47]
	s_waitcnt vmcnt(8)
	s_waitcnt lgkmcnt(0)
	s_barrier
; #define PG8_STAGE(bufoff, gbase, voff) do { _Pragma("unroll") for (int _i = 0; _i < 2; ++_i) \
;         __builtin_amdgcn_global_load_lds((const unsigned*)((const char*)(gbase) + (voff)[_i]), (PG8_LAS unsigned*)(lds + (bufoff) + ldsw + _i * 8192), 16, 0, 0); } while (0)
; #define PG8_LDA(dst, b, h) do { _Pragma("unroll") for (int m = 0; m < 4; ++m) _Pragma("unroll") for (int k = 0; k < 2; ++k) dst[m][k] = *(const PG8_LAS bf16x8*)(lds + PG8_SA(b, h) + aoff + m * 2048 + k * 1024); } while (0)
; #define PG8_MMA(ai, bj, At, Bt) do { __builtin_amdgcn_s_setprio(1); _Pragma("unroll") for (int m = 0; m < 4; ++m) _Pragma("unroll") for (int n = 0; n < 2; ++n) _Pragma("unroll") for (int k = 0; k < 2; ++k) \
;         acc[ai][bj][m][n] = __builtin_amdgcn_mfma_f32_16x16x32_bf16(Bt[n][k], At[m][k], acc[ai][bj][m][n], 0, 0, 0); __builtin_amdgcn_s_setprio(0); } while (0)
; #define PG8_WAIT_V(n) asm volatile("s_waitcnt vmcnt(" #n ")" ::: "memory")
; #define PG8_WAIT_L(n) asm volatile("s_waitcnt lgkmcnt(" #n ")" ::: "memory")
; #define PG8_BAR __builtin_amdgcn_s_barrier()
; #define PG8_SCHED __builtin_amdgcn_sched_barrier(0)
; template <class Epi, class Sched, bool ALIGN_EPI = false, bool SP2 = false>
; __device__ __forceinline__ void gemm_phase(PG8_LAS unsigned char* lds, const Gemm g, const Sched& S, const Epi& E) {
;     ...
;             PG8_WAIT_V(8); PG8_WAIT_L(0); PG8_BAR; PG8_MMA(0, 0, At, B0); PG8_MMA(0, 1, At, B1); PG8_BAR; PG8_SCHED;
;             PG8_LDA(At, 1, 1); PG8_STAGE(PG8_SB(1, 0), b3, voffB); PG8_STAGE(PG8_SB(1, 1), b3 + hstep, voffB); PG8_STAGE(PG8_SA(1, 0), a3, voffA);
;             PG8_WAIT_V(8); PG8_WAIT_L(0); PG8_BAR; PG8_MMA(1, 0, At, B0); PG8_MMA(1, 1, At, B1); PG8_BAR; PG8_SCHED;
;     ...
;         if constexpr (ALIGN_EPI) { if (wr == 0) PG8_BAR; }
	s_setprio 1
	s_waitcnt lgkmcnt(0)
	v_mfma_f32_16x16x32_bf16 v[124:127], v[144:147], v[184:187], v[124:127]
	v_mfma_f32_16x16x32_bf16 v[120:123], v[160:163], v[184:187], v[120:123]
	v_mfma_f32_16x16x32_bf16 v[116:119], v[144:147], v[192:195], v[116:119]
	v_mfma_f32_16x16x32_bf16 v[108:111], v[160:163], v[192:195], v[108:111]
	v_mfma_f32_16x16x32_bf16 v[100:103], v[144:147], v[200:203], v[100:103]
	v_mfma_f32_16x16x32_bf16 v[92:95], v[160:163], v[200:203], v[92:95]
	v_mfma_f32_16x16x32_bf16 v[84:87], v[144:147], v[208:211], v[84:87]
	v_mfma_f32_16x16x32_bf16 v[76:79], v[160:163], v[208:211], v[76:79]
	v_mfma_f32_16x16x32_bf16 v[124:127], v[156:159], v[188:191], v[124:127]
	v_mfma_f32_16x16x32_bf16 v[120:123], v[164:167], v[188:191], v[120:123]
	v_mfma_f32_16x16x32_bf16 v[116:119], v[156:159], v[196:199], v[116:119]
	v_mfma_f32_16x16x32_bf16 v[108:111], v[164:167], v[196:199], v[108:111]
	v_mfma_f32_16x16x32_bf16 v[100:103], v[156:159], v[204:207], v[100:103]
	v_mfma_f32_16x16x32_bf16 v[92:95], v[164:167], v[204:207], v[92:95]
	v_mfma_f32_16x16x32_bf16 v[84:87], v[156:159], v[212:215], v[84:87]
	v_mfma_f32_16x16x32_bf16 v[76:79], v[164:167], v[212:215], v[76:79]
	v_mfma_f32_16x16x32_bf16 v[112:115], v[168:171], v[184:187], v[112:115]
	v_mfma_f32_16x16x32_bf16 v[104:107], v[176:179], v[184:187], v[104:107]
	v_mfma_f32_16x16x32_bf16 v[96:99], v[168:171], v[192:195], v[96:99]
	v_mfma_f32_16x16x32_bf16 v[88:91], v[176:179], v[192:195], v[88:91]
	v_mfma_f32_16x16x32_bf16 v[80:83], v[168:171], v[200:203], v[80:83]
	v_mfma_f32_16x16x32_bf16 v[72:75], v[176:179], v[200:203], v[72:75]
	v_mfma_f32_16x16x32_bf16 v[68:71], v[168:171], v[208:211], v[68:71]
	v_mfma_f32_16x16x32_bf16 v[64:67], v[176:179], v[208:211], v[64:67]
	v_mfma_f32_16x16x32_bf16 v[112:115], v[172:175], v[188:191], v[112:115]
	v_mfma_f32_16x16x32_bf16 v[104:107], v[180:183], v[188:191], v[104:107]
	v_mfma_f32_16x16x32_bf16 v[96:99], v[172:175], v[196:199], v[96:99]
	v_mfma_f32_16x16x32_bf16 v[88:91], v[180:183], v[196:199], v[88:91]
	v_mfma_f32_16x16x32_bf16 v[80:83], v[172:175], v[204:207], v[80:83]
	v_mfma_f32_16x16x32_bf16 v[72:75], v[180:183], v[204:207], v[72:75]
	v_mfma_f32_16x16x32_bf16 v[68:71], v[172:175], v[212:215], v[68:71]
	v_mfma_f32_16x16x32_bf16 v[64:67], v[180:183], v[212:215], v[64:67]
	s_setprio 0
	s_barrier
	s_add_i32 s33, s33, s54
	s_mov_b32 m0, s33
	ds_read_b128 v[184:187], v154 offset:49152
	ds_read_b128 v[188:191], v154 offset:50176
	ds_read_b128 v[192:195], v154 offset:51200
	ds_read_b128 v[196:199], v154 offset:52224
	ds_read_b128 v[200:203], v154 offset:53248
	ds_read_b128 v[204:207], v154 offset:54272
	ds_read_b128 v[208:211], v154 offset:55296
	ds_read_b128 v[212:215], v154 offset:56320
	global_load_lds_dwordx4 v130, s[56:57]
	s_add_i32 m0, s33, 0x2000
	s_add_u32 s44, s44, 0x40080
	s_addc_u32 s45, s45, 0
	s_add_i32 s33, s34, s54
	global_load_lds_dwordx4 v134, s[56:57]
	s_mov_b32 m0, s33
	s_nop 0
	global_load_lds_dwordx4 v130, s[44:45]
	s_add_i32 m0, s33, 0x2000
	s_nop 0
	global_load_lds_dwordx4 v134, s[44:45]
	s_mov_b32 m0, s74
	s_nop 0
	global_load_lds_dwordx4 v128, s[58:59]
	s_mov_b32 m0, s75
	s_nop 0
	global_load_lds_dwordx4 v132, s[58:59]
	s_waitcnt vmcnt(8)
	s_waitcnt lgkmcnt(0)
	s_barrier
	s_setprio 1
	s_waitcnt lgkmcnt(0)
	v_mfma_f32_16x16x32_bf16 v[60:63], v[144:147], v[184:187], v[60:63]
	v_mfma_f32_16x16x32_bf16 v[56:59], v[160:163], v[184:187], v[56:59]
	v_mfma_f32_16x16x32_bf16 v[52:55], v[144:147], v[192:195], v[52:55]
	v_mfma_f32_16x16x32_bf16 v[44:47], v[160:163], v[192:195], v[44:47]
	v_mfma_f32_16x16x32_bf16 v[36:39], v[144:147], v[200:203], v[36:39]
	v_mfma_f32_16x16x32_bf16 v[28:31], v[160:163], v[200:203], v[28:31]
	v_mfma_f32_16x16x32_bf16 v[20:23], v[144:147], v[208:211], v[20:23]
	v_mfma_f32_16x16x32_bf16 v[12:15], v[160:163], v[208:211], v[12:15]
	v_mfma_f32_16x16x32_bf16 v[60:63], v[156:159], v[188:191], v[60:63]
	v_mfma_f32_16x16x32_bf16 v[56:59], v[164:167], v[188:191], v[56:59]
	v_mfma_f32_16x16x32_bf16 v[52:55], v[156:159], v[196:199], v[52:55]
	v_mfma_f32_16x16x32_bf16 v[44:47], v[164:167], v[196:199], v[44:47]
	v_mfma_f32_16x16x32_bf16 v[36:39], v[156:159], v[204:207], v[36:39]
	v_mfma_f32_16x16x32_bf16 v[28:31], v[164:167], v[204:207], v[28:31]
	v_mfma_f32_16x16x32_bf16 v[20:23], v[156:159], v[212:215], v[20:23]
	v_mfma_f32_16x16x32_bf16 v[12:15], v[164:167], v[212:215], v[12:15]
	v_mfma_f32_16x16x32_bf16 v[48:51], v[168:171], v[184:187], v[48:51]
	v_mfma_f32_16x16x32_bf16 v[40:43], v[176:179], v[184:187], v[40:43]
	v_mfma_f32_16x16x32_bf16 v[32:35], v[168:171], v[192:195], v[32:35]
	v_mfma_f32_16x16x32_bf16 v[24:27], v[176:179], v[192:195], v[24:27]
	v_mfma_f32_16x16x32_bf16 v[16:19], v[168:171], v[200:203], v[16:19]
	v_mfma_f32_16x16x32_bf16 v[8:11], v[176:179], v[200:203], v[8:11]
	v_mfma_f32_16x16x32_bf16 v[4:7], v[168:171], v[208:211], v[4:7]
	v_mfma_f32_16x16x32_bf16 v[0:3], v[176:179], v[208:211], v[0:3]
	v_mfma_f32_16x16x32_bf16 v[48:51], v[172:175], v[188:191], v[48:51]
	v_mfma_f32_16x16x32_bf16 v[40:43], v[180:183], v[188:191], v[40:43]
	v_mfma_f32_16x16x32_bf16 v[32:35], v[172:175], v[196:199], v[32:35]
	v_mfma_f32_16x16x32_bf16 v[24:27], v[180:183], v[196:199], v[24:27]
	v_mfma_f32_16x16x32_bf16 v[16:19], v[172:175], v[204:207], v[16:19]
	v_mfma_f32_16x16x32_bf16 v[8:11], v[180:183], v[204:207], v[8:11]
	v_mfma_f32_16x16x32_bf16 v[4:7], v[172:175], v[212:215], v[4:7]
	v_mfma_f32_16x16x32_bf16 v[0:3], v[180:183], v[212:215], v[0:3]
	s_setprio 0
	s_barrier
	s_add_i32 s86, s86, 2
	s_add_u32 s42, s42, 0x100
	s_addc_u32 s43, s43, 0
	s_add_u32 s82, s82, 0x100
	s_addc_u32 s83, s83, 0
	s_cmp_gt_u32 s86, 13
	s_cbranch_scc0 .LBB0_381
	s_and_b64 vcc, exec, s[12:13]
	s_cbranch_vccz .LBB0_384
	s_barrier

; #define PG8_STAGE(bufoff, gbase, voff) do { _Pragma("unroll") for (int _i = 0; _i < 2; ++_i) \
;         __builtin_amdgcn_global_load_lds((const unsigned*)((const char*)(gbase) + (voff)[_i]), (PG8_LAS unsigned*)(lds + (bufoff) + ldsw + _i * 8192), 16, 0, 0); } while (0)
; #define PG8_LDA(dst, b, h) do { _Pragma("unroll") for (int m = 0; m < 4; ++m) _Pragma("unroll") for (int k = 0; k < 2; ++k) dst[m][k] = *(const PG8_LAS bf16x8*)(lds + PG8_SA(b, h) + aoff + m * 2048 + k * 1024); } while (0)
; #define PG8_LDB(dst, b, h) do { _Pragma("unroll") for (int n = 0; n < 2; ++n) _Pragma("unroll") for (int k = 0; k < 2; ++k) dst[n][k] = *(const PG8_LAS bf16x8*)(lds + PG8_SB(b, h) + boff + n * 2048 + k * 1024); } while (0)
; #define PG8_WAIT_V(n) asm volatile("s_waitcnt vmcnt(" #n ")" ::: "memory")
; #define PG8_WAIT_L(n) asm volatile("s_waitcnt lgkmcnt(" #n ")" ::: "memory")
; #define PG8_BAR __builtin_amdgcn_s_barrier()
; #define PG8_SCHED __builtin_amdgcn_sched_barrier(0)
; template <class Epi, class Sched, bool ALIGN_EPI = false, bool SP2 = false>
; __device__ __forceinline__ void gemm_phase(PG8_LAS unsigned char* lds, const Gemm g, const Sched& S, const Epi& E) {
;     ...
;         const bool has_next = S.next(ui + 1, nxt);
;         const char* nA = has_next ? (const char*)g.A + (size_t)nxt.pm * tstep : cA; const char* nB = has_next ? (const char*)g.Bt + (size_t)nxt.pn * tstep : cB;
;         for (int t = 0; t < nt; t += 2) {
;             const bool last = (t == nt - 2);
;             const char* a1 = cA + (size_t)(t + 1) * kstep;
;             const char* a2 = last ? nA : cA + (size_t)(t + 2) * kstep; const char* b2 = last ? nB : cB + (size_t)(t + 2) * kstep;
;             const char* a3 = a2 + kstep; const char* b3 = b2 + kstep;
;             if (last && has_next) S.a_ready(nxt);
;             if constexpr (SP2) {
;             PG8_LDB(B0, 0, 0); PG8_LDB(B1, 0, 1); PG8_SCHED; PG8_LDA(At, 0, 0); PG8_STAGE(PG8_SA(1, 1), a1 + hstep, voffA);
;             PG8_WAIT_V(8); PG8_WAIT_L(0); PG8_BAR; PG8_MMA(0, 0, At, B0); PG8_MMA(0, 1, At, B1); PG8_BAR; PG8_SCHED;
;             PG8_LDA(At, 0, 1); PG8_STAGE(PG8_SB(0, 0), b2, voffB); PG8_STAGE(PG8_SB(0, 1), b2 + hstep, voffB); PG8_STAGE(PG8_SA(0, 0), a2, voffA);
;             PG8_WAIT_V(8); PG8_WAIT_L(0); PG8_BAR; PG8_MMA(1, 0, At, B0); PG8_MMA(1, 1, At, B1); PG8_BAR; PG8_SCHED;
.LBB0_589:
	s_ashr_i32 s43, s42, 31
	s_lshl_b64 s[44:45], s[42:43], 19
	s_add_u32 s44, s60, s44
	s_addc_u32 s45, s61, s45
	s_and_b64 s[46:47], s[0:1], exec
	s_cselect_b32 s43, s45, s55
	s_cselect_b32 s86, s44, s54
	s_ashr_i32 s41, s40, 31
	s_lshl_b64 s[46:47], s[40:41], 19
	s_add_u32 s46, s62, s46
	s_addc_u32 s47, s63, s47
	s_and_b64 s[58:59], s[0:1], exec
	s_cselect_b32 s41, s47, s57
	s_cselect_b32 s87, s46, s56
	s_add_u32 s54, s54, 0x40080
	s_addc_u32 s55, s55, 0
	s_add_u32 s90, s56, 0x100
	s_addc_u32 s91, s57, 0
	s_mov_b32 s92, -2
	s_waitcnt lgkmcnt(0)
	s_add_u32 s33, s54, 0xfffc0080
	s_addc_u32 s34, s55, -1
	s_cmp_eq_u32 s92, 12
	s_cselect_b32 s59, s43, s34
	s_cselect_b32 s58, s86, s33
	s_cselect_b32 s57, s41, s91
	s_cselect_b32 s56, s87, s90
	s_add_i32 m0, s53, 0xc000
	global_load_lds_dwordx4 v144, s[54:55]
	s_add_i32 m0, s53, 0xe000
	s_nop 0
	global_load_lds_dwordx4 v146, s[54:55]
	s_waitcnt vmcnt(8)
	s_waitcnt lgkmcnt(0)
	s_barrier
	s_setprio 1
	s_waitcnt lgkmcnt(0)
	v_mfma_f32_16x16x32_bf16 v[124:127], v[128:131], v[184:187], 0
	v_mfma_f32_16x16x32_bf16 v[120:123], v[154:157], v[184:187], 0
	v_mfma_f32_16x16x32_bf16 v[116:119], v[128:131], v[192:195], 0
	v_mfma_f32_16x16x32_bf16 v[112:115], v[154:157], v[192:195], 0
	v_mfma_f32_16x16x32_bf16 v[108:111], v[128:131], v[200:203], 0
	v_mfma_f32_16x16x32_bf16 v[104:107], v[154:157], v[200:203], 0
	v_mfma_f32_16x16x32_bf16 v[100:103], v[128:131], v[208:211], 0
	v_mfma_f32_16x16x32_bf16 v[96:99], v[154:157], v[208:211], 0
	v_mfma_f32_16x16x32_bf16 v[124:127], v[132:135], v[188:191], v[124:127]
	v_mfma_f32_16x16x32_bf16 v[120:123], v[158:161], v[188:191], v[120:123]
	v_mfma_f32_16x16x32_bf16 v[116:119], v[132:135], v[196:199], v[116:119]
	v_mfma_f32_16x16x32_bf16 v[112:115], v[158:161], v[196:199], v[112:115]
	v_mfma_f32_16x16x32_bf16 v[108:111], v[132:135], v[204:207], v[108:111]
	v_mfma_f32_16x16x32_bf16 v[104:107], v[158:161], v[204:207], v[104:107]
	v_mfma_f32_16x16x32_bf16 v[100:103], v[132:135], v[212:215], v[100:103]
	v_mfma_f32_16x16x32_bf16 v[96:99], v[158:161], v[212:215], v[96:99]
	v_mfma_f32_16x16x32_bf16 v[68:71], v[168:171], v[184:187], 0
	v_mfma_f32_16x16x32_bf16 v[60:63], v[176:179], v[184:187], 0
	v_mfma_f32_16x16x32_bf16 v[52:55], v[168:171], v[192:195], 0
	v_mfma_f32_16x16x32_bf16 v[48:51], v[176:179], v[192:195], 0
	v_mfma_f32_16x16x32_bf16 v[44:47], v[168:171], v[200:203], 0
	v_mfma_f32_16x16x32_bf16 v[40:43], v[176:179], v[200:203], 0
	v_mfma_f32_16x16x32_bf16 v[36:39], v[168:171], v[208:211], 0
	v_mfma_f32_16x16x32_bf16 v[32:35], v[176:179], v[208:211], 0
	v_mfma_f32_16x16x32_bf16 v[68:71], v[172:175], v[188:191], v[68:71]
	v_mfma_f32_16x16x32_bf16 v[60:63], v[180:183], v[188:191], v[60:63]
	v_mfma_f32_16x16x32_bf16 v[52:55], v[172:175], v[196:199], v[52:55]
	v_mfma_f32_16x16x32_bf16 v[48:51], v[180:183], v[196:199], v[48:51]
	v_mfma_f32_16x16x32_bf16 v[44:47], v[172:175], v[204:207], v[44:47]
	v_mfma_f32_16x16x32_bf16 v[40:43], v[180:183], v[204:207], v[40:43]
	v_mfma_f32_16x16x32_bf16 v[36:39], v[172:175], v[212:215], v[36:39]
	v_mfma_f32_16x16x32_bf16 v[32:35], v[180:183], v[212:215], v[32:35]
	s_setprio 0
	s_barrier
	s_add_i32 s33, s81, s70
	s_add_u32 s64, s56, s10
	s_addc_u32 s65, s57, s11
	s_mov_b32 m0, s33
	ds_read_b128 v[184:187], v167 offset:16384
	ds_read_b128 v[188:191], v167 offset:17408
	ds_read_b128 v[192:195], v167 offset:18432
	ds_read_b128 v[196:199], v167 offset:19456
	ds_read_b128 v[200:203], v167 offset:20480
	ds_read_b128 v[204:207], v167 offset:21504
	ds_read_b128 v[208:211], v167 offset:22528
	ds_read_b128 v[212:215], v167 offset:23552
	global_load_lds_dwordx4 v138, s[56:57]
	s_add_i32 m0, s33, 0x2000
	s_add_u32 s94, s56, 0x40000
	s_addc_u32 s95, s57, 0
	s_add_i32 s33, s82, s70
	global_load_lds_dwordx4 v142, s[56:57]
	s_mov_b32 m0, s33
	s_add_u32 s84, s58, s10
	s_addc_u32 s85, s59, s11
	global_load_lds_dwordx4 v138, s[94:95]
	s_add_i32 m0, s33, 0x2000
	s_nop 0
	global_load_lds_dwordx4 v142, s[94:95]
	s_mov_b32 m0, s53
	s_nop 0
	global_load_lds_dwordx4 v136, s[58:59]
	s_mov_b32 m0, s72
	s_nop 0
	global_load_lds_dwordx4 v140, s[58:59]
	s_waitcnt vmcnt(8)
	s_waitcnt lgkmcnt(0)
	s_barrier
	s_setprio 1
	s_waitcnt lgkmcnt(0)
	v_mfma_f32_16x16x32_bf16 v[92:95], v[128:131], v[184:187], 0
	v_mfma_f32_16x16x32_bf16 v[88:91], v[154:157], v[184:187], 0
	v_mfma_f32_16x16x32_bf16 v[84:87], v[128:131], v[192:195], 0
	v_mfma_f32_16x16x32_bf16 v[80:83], v[154:157], v[192:195], 0
	v_mfma_f32_16x16x32_bf16 v[76:79], v[128:131], v[200:203], 0
	v_mfma_f32_16x16x32_bf16 v[72:75], v[154:157], v[200:203], 0
	v_mfma_f32_16x16x32_bf16 v[64:67], v[128:131], v[208:211], 0
	v_mfma_f32_16x16x32_bf16 v[56:59], v[154:157], v[208:211], 0
	v_mfma_f32_16x16x32_bf16 v[92:95], v[132:135], v[188:191], v[92:95]
	v_mfma_f32_16x16x32_bf16 v[88:91], v[158:161], v[188:191], v[88:91]
	v_mfma_f32_16x16x32_bf16 v[84:87], v[132:135], v[196:199], v[84:87]
	v_mfma_f32_16x16x32_bf16 v[80:83], v[158:161], v[196:199], v[80:83]
	v_mfma_f32_16x16x32_bf16 v[76:79], v[132:135], v[204:207], v[76:79]
	v_mfma_f32_16x16x32_bf16 v[72:75], v[158:161], v[204:207], v[72:75]
	v_mfma_f32_16x16x32_bf16 v[64:67], v[132:135], v[212:215], v[64:67]
	v_mfma_f32_16x16x32_bf16 v[56:59], v[158:161], v[212:215], v[56:59]
	v_mfma_f32_16x16x32_bf16 v[28:31], v[168:171], v[184:187], 0
	v_mfma_f32_16x16x32_bf16 v[24:27], v[176:179], v[184:187], 0
	v_mfma_f32_16x16x32_bf16 v[20:23], v[168:171], v[192:195], 0
	v_mfma_f32_16x16x32_bf16 v[16:19], v[176:179], v[192:195], 0
	v_mfma_f32_16x16x32_bf16 v[12:15], v[168:171], v[200:203], 0
	v_mfma_f32_16x16x32_bf16 v[8:11], v[176:179], v[200:203], 0
	v_mfma_f32_16x16x32_bf16 v[4:7], v[168:171], v[208:211], 0
	v_mfma_f32_16x16x32_bf16 v[0:3], v[176:179], v[208:211], 0
	v_mfma_f32_16x16x32_bf16 v[28:31], v[172:175], v[188:191], v[28:31]
	v_mfma_f32_16x16x32_bf16 v[24:27], v[180:183], v[188:191], v[24:27]
	v_mfma_f32_16x16x32_bf16 v[20:23], v[172:175], v[196:199], v[20:23]
	v_mfma_f32_16x16x32_bf16 v[16:19], v[180:183], v[196:199], v[16:19]
	v_mfma_f32_16x16x32_bf16 v[12:15], v[172:175], v[204:207], v[12:15]
	v_mfma_f32_16x16x32_bf16 v[8:11], v[180:183], v[204:207], v[8:11]
	v_mfma_f32_16x16x32_bf16 v[4:7], v[172:175], v[212:215], v[4:7]
	v_mfma_f32_16x16x32_bf16 v[0:3], v[180:183], v[212:215], v[0:3]
	s_setprio 0
	s_barrier
; #define PG8_STAGE(bufoff, gbase, voff) do { _Pragma("unroll") for (int _i = 0; _i < 2; ++_i) \
;         __builtin_amdgcn_global_load_lds((const unsigned*)((const char*)(gbase) + (voff)[_i]), (PG8_LAS unsigned*)(lds + (bufoff) + ldsw + _i * 8192), 16, 0, 0); } while (0)
; #define PG8_LDA(dst, b, h) do { _Pragma("unroll") for (int m = 0; m < 4; ++m) _Pragma("unroll") for (int k = 0; k < 2; ++k) dst[m][k] = *(const PG8_LAS bf16x8*)(lds + PG8_SA(b, h) + aoff + m * 2048 + k * 1024); } while (0)
; #define PG8_LDB(dst, b, h) do { _Pragma("unroll") for (int n = 0; n < 2; ++n) _Pragma("unroll") for (int k = 0; k < 2; ++k) dst[n][k] = *(const PG8_LAS bf16x8*)(lds + PG8_SB(b, h) + boff + n * 2048 + k * 1024); } while (0)
; #define PG8_MMA(ai, bj, At, Bt) do { __builtin_amdgcn_s_setprio(1); _Pragma("unroll") for (int m = 0; m < 4; ++m) _Pragma("unroll") for (int n = 0; n < 2; ++n) _Pragma("unroll") for (int k = 0; k < 2; ++k) \
;         acc[ai][bj][m][n] = __builtin_amdgcn_mfma_f32_16x16x32_bf16(Bt[n][k], At[m][k], acc[ai][bj][m][n], 0, 0, 0); __builtin_amdgcn_s_setprio(0); } while (0)
; #define PG8_WAIT_V(n) asm volatile("s_waitcnt vmcnt(" #n ")" ::: "memory")
; #define PG8_WAIT_L(n) asm volatile("s_waitcnt lgkmcnt(" #n ")" ::: "memory")
; #define PG8_BAR __builtin_amdgcn_s_barrier()
; #define PG8_SCHED __builtin_amdgcn_sched_barrier(0)
; template <class Epi, class Sched, bool ALIGN_EPI = false, bool SP2 = false>
; __device__ __forceinline__ void gemm_phase(PG8_LAS unsigned char* lds, const Gemm g, const Sched& S, const Epi& E) {
;     ...
;             PG8_LDB(B0, 1, 0); PG8_LDB(B1, 1, 1); PG8_SCHED; PG8_LDA(At, 1, 0); PG8_STAGE(PG8_SA(0, 1), a2 + hstep, voffA);
;             PG8_WAIT_V(8); PG8_WAIT_L(0); PG8_BAR; PG8_MMA(0, 0, At, B0); PG8_MMA(0, 1, At, B1); PG8_BAR; PG8_SCHED;
;             PG8_LDA(At, 1, 1); PG8_STAGE(PG8_SB(1, 0), b3, voffB); PG8_STAGE(PG8_SB(1, 1), b3 + hstep, voffB); PG8_STAGE(PG8_SA(1, 0), a3, voffA);
;             PG8_WAIT_V(8); PG8_WAIT_L(0); PG8_BAR; PG8_MMA(1, 0, At, B0); PG8_MMA(1, 1, At, B1); PG8_BAR; PG8_SCHED;
	s_add_i32 s33, 0, 0x18000
	v_add_u32_e32 v153, s33, v163
	s_add_i32 s34, 0, 0x1c000
	ds_read_b128 v[128:131], v153
	ds_read_b128 v[132:135], v153 offset:1024
	ds_read_b128 v[154:157], v153 offset:2048
	ds_read_b128 v[158:161], v153 offset:3072
	v_add_u32_e32 v153, s34, v163
	ds_read_b128 v[168:171], v153
	ds_read_b128 v[172:175], v153 offset:1024
	ds_read_b128 v[176:179], v153 offset:2048
	ds_read_b128 v[180:183], v153 offset:3072
	s_add_u32 s58, s58, 0x40000
	s_addc_u32 s59, s59, 0
	s_mov_b32 m0, s73
	ds_read_b128 v[184:187], v167 offset:32768
	ds_read_b128 v[188:191], v167 offset:33792
	ds_read_b128 v[192:195], v167 offset:34816
	ds_read_b128 v[196:199], v167 offset:35840
	ds_read_b128 v[200:203], v167 offset:36864
	ds_read_b128 v[204:207], v167 offset:37888
	ds_read_b128 v[208:211], v167 offset:38912
	ds_read_b128 v[212:215], v167 offset:39936
	global_load_lds_dwordx4 v136, s[58:59]
	s_mov_b32 m0, s74
	s_nop 0
	global_load_lds_dwordx4 v140, s[58:59]
	s_waitcnt vmcnt(8)
	s_waitcnt lgkmcnt(0)
	s_barrier
	s_setprio 1
	s_waitcnt lgkmcnt(0)
	v_mfma_f32_16x16x32_bf16 v[124:127], v[128:131], v[184:187], v[124:127]
	v_mfma_f32_16x16x32_bf16 v[120:123], v[154:157], v[184:187], v[120:123]
	v_mfma_f32_16x16x32_bf16 v[116:119], v[128:131], v[192:195], v[116:119]
	v_mfma_f32_16x16x32_bf16 v[112:115], v[154:157], v[192:195], v[112:115]
	v_mfma_f32_16x16x32_bf16 v[108:111], v[128:131], v[200:203], v[108:111]
	v_mfma_f32_16x16x32_bf16 v[104:107], v[154:157], v[200:203], v[104:107]
	v_mfma_f32_16x16x32_bf16 v[100:103], v[128:131], v[208:211], v[100:103]
	v_mfma_f32_16x16x32_bf16 v[96:99], v[154:157], v[208:211], v[96:99]
	v_mfma_f32_16x16x32_bf16 v[124:127], v[132:135], v[188:191], v[124:127]
	v_mfma_f32_16x16x32_bf16 v[120:123], v[158:161], v[188:191], v[120:123]
	v_mfma_f32_16x16x32_bf16 v[116:119], v[132:135], v[196:199], v[116:119]
	v_mfma_f32_16x16x32_bf16 v[112:115], v[158:161], v[196:199], v[112:115]
	v_mfma_f32_16x16x32_bf16 v[108:111], v[132:135], v[204:207], v[108:111]
	v_mfma_f32_16x16x32_bf16 v[104:107], v[158:161], v[204:207], v[104:107]
	v_mfma_f32_16x16x32_bf16 v[100:103], v[132:135], v[212:215], v[100:103]
	v_mfma_f32_16x16x32_bf16 v[96:99], v[158:161], v[212:215], v[96:99]
	v_mfma_f32_16x16x32_bf16 v[68:71], v[168:171], v[184:187], v[68:71]
	v_mfma_f32_16x16x32_bf16 v[60:63], v[176:179], v[184:187], v[60:63]
	v_mfma_f32_16x16x32_bf16 v[52:55], v[168:171], v[192:195], v[52:55]
	v_mfma_f32_16x16x32_bf16 v[48:51], v[176:179], v[192:195], v[48:51]
	v_mfma_f32_16x16x32_bf16 v[44:47], v[168:171], v[200:203], v[44:47]
	v_mfma_f32_16x16x32_bf16 v[40:43], v[176:179], v[200:203], v[40:43]
	v_mfma_f32_16x16x32_bf16 v[36:39], v[168:171], v[208:211], v[36:39]
	v_mfma_f32_16x16x32_bf16 v[32:35], v[176:179], v[208:211], v[32:35]
	v_mfma_f32_16x16x32_bf16 v[68:71], v[172:175], v[188:191], v[68:71]
	v_mfma_f32_16x16x32_bf16 v[60:63], v[180:183], v[188:191], v[60:63]
	v_mfma_f32_16x16x32_bf16 v[52:55], v[172:175], v[196:199], v[52:55]
	v_mfma_f32_16x16x32_bf16 v[48:51], v[180:183], v[196:199], v[48:51]
	v_mfma_f32_16x16x32_bf16 v[44:47], v[172:175], v[204:207], v[44:47]
	v_mfma_f32_16x16x32_bf16 v[40:43], v[180:183], v[204:207], v[40:43]
	v_mfma_f32_16x16x32_bf16 v[36:39], v[172:175], v[212:215], v[36:39]
	v_mfma_f32_16x16x32_bf16 v[32:35], v[180:183], v[212:215], v[32:35]
	s_setprio 0
	s_barrier
	s_add_i32 s33, s33, s70
	s_mov_b32 m0, s33
	ds_read_b128 v[184:187], v167 offset:49152
	ds_read_b128 v[188:191], v167 offset:50176
	ds_read_b128 v[192:195], v167 offset:51200
	ds_read_b128 v[196:199], v167 offset:52224
	ds_read_b128 v[200:203], v167 offset:53248
	ds_read_b128 v[204:207], v167 offset:54272
	ds_read_b128 v[208:211], v167 offset:55296
	ds_read_b128 v[212:215], v167 offset:56320
	global_load_lds_dwordx4 v138, s[64:65]
	s_add_i32 m0, s33, 0x2000
	s_add_u32 s56, s56, 0x40080
	s_addc_u32 s57, s57, 0
	s_add_i32 s33, s34, s70
	global_load_lds_dwordx4 v142, s[64:65]
	s_mov_b32 m0, s33
	s_nop 0
	global_load_lds_dwordx4 v138, s[56:57]
	s_add_i32 m0, s33, 0x2000
	s_nop 0
	global_load_lds_dwordx4 v142, s[56:57]
	s_mov_b32 m0, s79
	s_nop 0
	global_load_lds_dwordx4 v136, s[84:85]
	s_mov_b32 m0, s80
	s_nop 0
	global_load_lds_dwordx4 v140, s[84:85]
	s_waitcnt vmcnt(8)
	s_waitcnt lgkmcnt(0)
	s_barrier
	s_setprio 1
	s_waitcnt lgkmcnt(0)
	v_mfma_f32_16x16x32_bf16 v[92:95], v[128:131], v[184:187], v[92:95]
	v_mfma_f32_16x16x32_bf16 v[88:91], v[154:157], v[184:187], v[88:91]
	v_mfma_f32_16x16x32_bf16 v[84:87], v[128:131], v[192:195], v[84:87]
	v_mfma_f32_16x16x32_bf16 v[80:83], v[154:157], v[192:195], v[80:83]
	v_mfma_f32_16x16x32_bf16 v[76:79], v[128:131], v[200:203], v[76:79]
	v_mfma_f32_16x16x32_bf16 v[72:75], v[154:157], v[200:203], v[72:75]
	v_mfma_f32_16x16x32_bf16 v[64:67], v[128:131], v[208:211], v[64:67]
	v_mfma_f32_16x16x32_bf16 v[56:59], v[154:157], v[208:211], v[56:59]
	v_mfma_f32_16x16x32_bf16 v[92:95], v[132:135], v[188:191], v[92:95]
	v_mfma_f32_16x16x32_bf16 v[88:91], v[158:161], v[188:191], v[88:91]
	v_mfma_f32_16x16x32_bf16 v[84:87], v[132:135], v[196:199], v[84:87]
	v_mfma_f32_16x16x32_bf16 v[80:83], v[158:161], v[196:199], v[80:83]
	v_mfma_f32_16x16x32_bf16 v[76:79], v[132:135], v[204:207], v[76:79]
	v_mfma_f32_16x16x32_bf16 v[72:75], v[158:161], v[204:207], v[72:75]
	v_mfma_f32_16x16x32_bf16 v[64:67], v[132:135], v[212:215], v[64:67]
	v_mfma_f32_16x16x32_bf16 v[56:59], v[158:161], v[212:215], v[56:59]
	v_mfma_f32_16x16x32_bf16 v[28:31], v[168:171], v[184:187], v[28:31]
	v_mfma_f32_16x16x32_bf16 v[24:27], v[176:179], v[184:187], v[24:27]
	v_mfma_f32_16x16x32_bf16 v[20:23], v[168:171], v[192:195], v[20:23]
	v_mfma_f32_16x16x32_bf16 v[16:19], v[176:179], v[192:195], v[16:19]
	v_mfma_f32_16x16x32_bf16 v[12:15], v[168:171], v[200:203], v[12:15]
	v_mfma_f32_16x16x32_bf16 v[8:11], v[176:179], v[200:203], v[8:11]
	v_mfma_f32_16x16x32_bf16 v[4:7], v[168:171], v[208:211], v[4:7]
	v_mfma_f32_16x16x32_bf16 v[0:3], v[176:179], v[208:211], v[0:3]
	v_mfma_f32_16x16x32_bf16 v[28:31], v[172:175], v[188:191], v[28:31]
	v_mfma_f32_16x16x32_bf16 v[24:27], v[180:183], v[188:191], v[24:27]
	v_mfma_f32_16x16x32_bf16 v[20:23], v[172:175], v[196:199], v[20:23]
	v_mfma_f32_16x16x32_bf16 v[16:19], v[180:183], v[196:199], v[16:19]
	v_mfma_f32_16x16x32_bf16 v[12:15], v[172:175], v[204:207], v[12:15]
	v_mfma_f32_16x16x32_bf16 v[8:11], v[180:183], v[204:207], v[8:11]
	v_mfma_f32_16x16x32_bf16 v[4:7], v[172:175], v[212:215], v[4:7]
	v_mfma_f32_16x16x32_bf16 v[0:3], v[180:183], v[212:215], v[0:3]
	s_setprio 0
	s_barrier
	s_add_i32 s92, s92, 2
	s_add_u32 s54, s54, 0x100
	s_addc_u32 s55, s55, 0
	s_add_u32 s90, s90, 0x100
	s_addc_u32 s91, s91, 0
	s_cmp_gt_u32 s92, 13
; #define PG8_STAGE(bufoff, gbase, voff) do { _Pragma("unroll") for (int _i = 0; _i < 2; ++_i) \
;         __builtin_amdgcn_global_load_lds((const unsigned*)((const char*)(gbase) + (voff)[_i]), (PG8_LAS unsigned*)(lds + (bufoff) + ldsw + _i * 8192), 16, 0, 0); } while (0)
; #define PG8_LDA(dst, b, h) do { _Pragma("unroll") for (int m = 0; m < 4; ++m) _Pragma("unroll") for (int k = 0; k < 2; ++k) dst[m][k] = *(const PG8_LAS bf16x8*)(lds + PG8_SA(b, h) + aoff + m * 2048 + k * 1024); } while (0)
; #define PG8_LDB(dst, b, h) do { _Pragma("unroll") for (int n = 0; n < 2; ++n) _Pragma("unroll") for (int k = 0; k < 2; ++k) dst[n][k] = *(const PG8_LAS bf16x8*)(lds + PG8_SB(b, h) + boff + n * 2048 + k * 1024); } while (0)
; #define PG8_MMA(ai, bj, At, Bt) do { __builtin_amdgcn_s_setprio(1); _Pragma("unroll") for (int m = 0; m < 4; ++m) _Pragma("unroll") for (int n = 0; n < 2; ++n) _Pragma("unroll") for (int k = 0; k < 2; ++k) \
;         acc[ai][bj][m][n] = __builtin_amdgcn_mfma_f32_16x16x32_bf16(Bt[n][k], At[m][k], acc[ai][bj][m][n], 0, 0, 0); __builtin_amdgcn_s_setprio(0); } while (0)
; #define PG8_WAIT_V(n) asm volatile("s_waitcnt vmcnt(" #n ")" ::: "memory")
; #define PG8_WAIT_L(n) asm volatile("s_waitcnt lgkmcnt(" #n ")" ::: "memory")
; template <class Epi, class Sched, bool ALIGN_EPI = false, bool SP2 = false>
; __device__ __forceinline__ void gemm_phase(PG8_LAS unsigned char* lds, const Gemm g, const Sched& S, const Epi& E) {
;     ...
;             const bool last = (t == nt - 2);
;             const char* a1 = cA + (size_t)(t + 1) * kstep;
;             const char* a2 = last ? nA : cA + (size_t)(t + 2) * kstep; const char* b2 = last ? nB : cB + (size_t)(t + 2) * kstep;
;             const char* a3 = a2 + kstep; const char* b3 = b2 + kstep;
;             if (last && has_next) S.a_ready(nxt);
;             if constexpr (SP2) {
;             PG8_LDB(B0, 0, 0); PG8_LDB(B1, 0, 1); PG8_SCHED; PG8_LDA(At, 0, 0); PG8_STAGE(PG8_SA(1, 1), a1 + hstep, voffA);
;             PG8_WAIT_V(8); PG8_WAIT_L(0); PG8_BAR; PG8_MMA(0, 0, At, B0); PG8_MMA(0, 1, At, B1); PG8_BAR; PG8_SCHED;
;             PG8_LDA(At, 0, 1); PG8_STAGE(PG8_SB(0, 0), b2, voffB); PG8_STAGE(PG8_SB(0, 1), b2 + hstep, voffB); PG8_STAGE(PG8_SA(0, 0), a2, voffA);
;             PG8_WAIT_V(8); PG8_WAIT_L(0); PG8_BAR; PG8_MMA(1, 0, At, B0); PG8_MMA(1, 1, At, B1); PG8_BAR; PG8_SCHED;
.LBB0_590:
	ds_read_b128 v[128:131], v165
	ds_read_b128 v[132:135], v165 offset:1024
	ds_read_b128 v[154:157], v165 offset:2048
	ds_read_b128 v[158:161], v165 offset:3072
	ds_read_b128 v[168:171], v166
	ds_read_b128 v[172:175], v166 offset:1024
	ds_read_b128 v[176:179], v166 offset:2048
	ds_read_b128 v[180:183], v166 offset:3072
	s_add_u32 s33, s54, 0xfffc0080
	s_addc_u32 s34, s55, -1
	s_cmp_eq_u32 s92, 12
	s_cselect_b32 s59, s43, s34
	s_cselect_b32 s58, s86, s33
	s_cselect_b32 s57, s41, s91
	s_cselect_b32 s56, s87, s90
	s_add_i32 m0, s53, 0xc000
	ds_read_b128 v[184:187], v167
	ds_read_b128 v[188:191], v167 offset:1024
	ds_read_b128 v[192:195], v167 offset:2048
	ds_read_b128 v[196:199], v167 offset:3072
	ds_read_b128 v[200:203], v167 offset:4096
	ds_read_b128 v[204:207], v167 offset:5120
	ds_read_b128 v[208:211], v167 offset:6144
	ds_read_b128 v[212:215], v167 offset:7168
	global_load_lds_dwordx4 v144, s[54:55]
	s_add_i32 m0, s53, 0xe000
	s_nop 0
	global_load_lds_dwordx4 v146, s[54:55]
	s_waitcnt vmcnt(8)
	s_waitcnt lgkmcnt(0)
	s_barrier
	s_setprio 1
	s_waitcnt lgkmcnt(0)
	v_mfma_f32_16x16x32_bf16 v[124:127], v[128:131], v[184:187], v[124:127]
	v_mfma_f32_16x16x32_bf16 v[120:123], v[154:157], v[184:187], v[120:123]
	v_mfma_f32_16x16x32_bf16 v[116:119], v[128:131], v[192:195], v[116:119]
	v_mfma_f32_16x16x32_bf16 v[112:115], v[154:157], v[192:195], v[112:115]
	v_mfma_f32_16x16x32_bf16 v[108:111], v[128:131], v[200:203], v[108:111]
	v_mfma_f32_16x16x32_bf16 v[104:107], v[154:157], v[200:203], v[104:107]
	v_mfma_f32_16x16x32_bf16 v[100:103], v[128:131], v[208:211], v[100:103]
	v_mfma_f32_16x16x32_bf16 v[96:99], v[154:157], v[208:211], v[96:99]
	v_mfma_f32_16x16x32_bf16 v[124:127], v[132:135], v[188:191], v[124:127]
	v_mfma_f32_16x16x32_bf16 v[120:123], v[158:161], v[188:191], v[120:123]
	v_mfma_f32_16x16x32_bf16 v[116:119], v[132:135], v[196:199], v[116:119]
	v_mfma_f32_16x16x32_bf16 v[112:115], v[158:161], v[196:199], v[112:115]
	v_mfma_f32_16x16x32_bf16 v[108:111], v[132:135], v[204:207], v[108:111]
	v_mfma_f32_16x16x32_bf16 v[104:107], v[158:161], v[204:207], v[104:107]
	v_mfma_f32_16x16x32_bf16 v[100:103], v[132:135], v[212:215], v[100:103]
	v_mfma_f32_16x16x32_bf16 v[96:99], v[158:161], v[212:215], v[96:99]
	v_mfma_f32_16x16x32_bf16 v[68:71], v[168:171], v[184:187], v[68:71]
	v_mfma_f32_16x16x32_bf16 v[60:63], v[176:179], v[184:187], v[60:63]
	v_mfma_f32_16x16x32_bf16 v[52:55], v[168:171], v[192:195], v[52:55]
	v_mfma_f32_16x16x32_bf16 v[48:51], v[176:179], v[192:195], v[48:51]
	v_mfma_f32_16x16x32_bf16 v[44:47], v[168:171], v[200:203], v[44:47]
	v_mfma_f32_16x16x32_bf16 v[40:43], v[176:179], v[200:203], v[40:43]
	v_mfma_f32_16x16x32_bf16 v[36:39], v[168:171], v[208:211], v[36:39]
	v_mfma_f32_16x16x32_bf16 v[32:35], v[176:179], v[208:211], v[32:35]
	v_mfma_f32_16x16x32_bf16 v[68:71], v[172:175], v[188:191], v[68:71]
	v_mfma_f32_16x16x32_bf16 v[60:63], v[180:183], v[188:191], v[60:63]
	v_mfma_f32_16x16x32_bf16 v[52:55], v[172:175], v[196:199], v[52:55]
	v_mfma_f32_16x16x32_bf16 v[48:51], v[180:183], v[196:199], v[48:51]
	v_mfma_f32_16x16x32_bf16 v[44:47], v[172:175], v[204:207], v[44:47]
	v_mfma_f32_16x16x32_bf16 v[40:43], v[180:183], v[204:207], v[40:43]
	v_mfma_f32_16x16x32_bf16 v[36:39], v[172:175], v[212:215], v[36:39]
	v_mfma_f32_16x16x32_bf16 v[32:35], v[180:183], v[212:215], v[32:35]
	s_setprio 0
	s_barrier
	s_add_i32 s33, s81, s70
	s_add_u32 s64, s56, s10
	s_addc_u32 s65, s57, s11
	s_mov_b32 m0, s33
	ds_read_b128 v[184:187], v167 offset:16384
	ds_read_b128 v[188:191], v167 offset:17408
	ds_read_b128 v[192:195], v167 offset:18432
	ds_read_b128 v[196:199], v167 offset:19456
	ds_read_b128 v[200:203], v167 offset:20480
	ds_read_b128 v[204:207], v167 offset:21504
	ds_read_b128 v[208:211], v167 offset:22528
	ds_read_b128 v[212:215], v167 offset:23552
	global_load_lds_dwordx4 v138, s[56:57]
	s_add_i32 m0, s33, 0x2000
	s_add_u32 s94, s56, 0x40000
	s_addc_u32 s95, s57, 0
	s_add_i32 s33, s82, s70
	global_load_lds_dwordx4 v142, s[56:57]
	s_mov_b32 m0, s33
	s_add_u32 s84, s58, s10
	s_addc_u32 s85, s59, s11
	global_load_lds_dwordx4 v138, s[94:95]
	s_add_i32 m0, s33, 0x2000
	s_nop 0
	global_load_lds_dwordx4 v142, s[94:95]
	s_mov_b32 m0, s53
	s_nop 0
	global_load_lds_dwordx4 v136, s[58:59]
	s_mov_b32 m0, s72
	s_nop 0
	global_load_lds_dwordx4 v140, s[58:59]
	s_waitcnt vmcnt(8)
	s_waitcnt lgkmcnt(0)
	s_barrier
	s_setprio 1
	s_waitcnt lgkmcnt(0)
	v_mfma_f32_16x16x32_bf16 v[92:95], v[128:131], v[184:187], v[92:95]
	v_mfma_f32_16x16x32_bf16 v[88:91], v[154:157], v[184:187], v[88:91]
	v_mfma_f32_16x16x32_bf16 v[84:87], v[128:131], v[192:195], v[84:87]
	v_mfma_f32_16x16x32_bf16 v[80:83], v[154:157], v[192:195], v[80:83]
	v_mfma_f32_16x16x32_bf16 v[76:79], v[128:131], v[200:203], v[76:79]
	v_mfma_f32_16x16x32_bf16 v[72:75], v[154:157], v[200:203], v[72:75]
	v_mfma_f32_16x16x32_bf16 v[64:67], v[128:131], v[208:211], v[64:67]
	v_mfma_f32_16x16x32_bf16 v[56:59], v[154:157], v[208:211], v[56:59]
	v_mfma_f32_16x16x32_bf16 v[92:95], v[132:135], v[188:191], v[92:95]
	v_mfma_f32_16x16x32_bf16 v[88:91], v[158:161], v[188:191], v[88:91]
	v_mfma_f32_16x16x32_bf16 v[84:87], v[132:135], v[196:199], v[84:87]
	v_mfma_f32_16x16x32_bf16 v[80:83], v[158:161], v[196:199], v[80:83]
	v_mfma_f32_16x16x32_bf16 v[76:79], v[132:135], v[204:207], v[76:79]
	v_mfma_f32_16x16x32_bf16 v[72:75], v[158:161], v[204:207], v[72:75]
	v_mfma_f32_16x16x32_bf16 v[64:67], v[132:135], v[212:215], v[64:67]
	v_mfma_f32_16x16x32_bf16 v[56:59], v[158:161], v[212:215], v[56:59]
	v_mfma_f32_16x16x32_bf16 v[28:31], v[168:171], v[184:187], v[28:31]
	v_mfma_f32_16x16x32_bf16 v[24:27], v[176:179], v[184:187], v[24:27]
	v_mfma_f32_16x16x32_bf16 v[20:23], v[168:171], v[192:195], v[20:23]
	v_mfma_f32_16x16x32_bf16 v[16:19], v[176:179], v[192:195], v[16:19]
	v_mfma_f32_16x16x32_bf16 v[12:15], v[168:171], v[200:203], v[12:15]
	v_mfma_f32_16x16x32_bf16 v[8:11], v[176:179], v[200:203], v[8:11]
	v_mfma_f32_16x16x32_bf16 v[4:7], v[168:171], v[208:211], v[4:7]
	v_mfma_f32_16x16x32_bf16 v[0:3], v[176:179], v[208:211], v[0:3]
	v_mfma_f32_16x16x32_bf16 v[28:31], v[172:175], v[188:191], v[28:31]
	v_mfma_f32_16x16x32_bf16 v[24:27], v[180:183], v[188:191], v[24:27]
	v_mfma_f32_16x16x32_bf16 v[20:23], v[172:175], v[196:199], v[20:23]
	v_mfma_f32_16x16x32_bf16 v[16:19], v[180:183], v[196:199], v[16:19]
	v_mfma_f32_16x16x32_bf16 v[12:15], v[172:175], v[204:207], v[12:15]
	v_mfma_f32_16x16x32_bf16 v[8:11], v[180:183], v[204:207], v[8:11]
	v_mfma_f32_16x16x32_bf16 v[4:7], v[172:175], v[212:215], v[4:7]
	v_mfma_f32_16x16x32_bf16 v[0:3], v[180:183], v[212:215], v[0:3]
	s_setprio 0
	s_barrier
; #define PG8_STAGE(bufoff, gbase, voff) do { _Pragma("unroll") for (int _i = 0; _i < 2; ++_i) \
;         __builtin_amdgcn_global_load_lds((const unsigned*)((const char*)(gbase) + (voff)[_i]), (PG8_LAS unsigned*)(lds + (bufoff) + ldsw + _i * 8192), 16, 0, 0); } while (0)
; #define PG8_LDA(dst, b, h) do { _Pragma("unroll") for (int m = 0; m < 4; ++m) _Pragma("unroll") for (int k = 0; k < 2; ++k) dst[m][k] = *(const PG8_LAS bf16x8*)(lds + PG8_SA(b, h) + aoff + m * 2048 + k * 1024); } while (0)
; #define PG8_LDB(dst, b, h) do { _Pragma("unroll") for (int n = 0; n < 2; ++n) _Pragma("unroll") for (int k = 0; k < 2; ++k) dst[n][k] = *(const PG8_LAS bf16x8*)(lds + PG8_SB(b, h) + boff + n * 2048 + k * 1024); } while (0)
; #define PG8_MMA(ai, bj, At, Bt) do { __builtin_amdgcn_s_setprio(1); _Pragma("unroll") for (int m = 0; m < 4; ++m) _Pragma("unroll") for (int n = 0; n < 2; ++n) _Pragma("unroll") for (int k = 0; k < 2; ++k) \
;         acc[ai][bj][m][n] = __builtin_amdgcn_mfma_f32_16x16x32_bf16(Bt[n][k], At[m][k], acc[ai][bj][m][n], 0, 0, 0); __builtin_amdgcn_s_setprio(0); } while (0)
; #define PG8_WAIT_V(n) asm volatile("s_waitcnt vmcnt(" #n ")" ::: "memory")
; #define PG8_WAIT_L(n) asm volatile("s_waitcnt lgkmcnt(" #n ")" ::: "memory")
; #define PG8_BAR __builtin_amdgcn_s_barrier()
; #define PG8_SCHED __builtin_amdgcn_sched_barrier(0)
; template <class Epi, class Sched, bool ALIGN_EPI = false, bool SP2 = false>
; __device__ __forceinline__ void gemm_phase(PG8_LAS unsigned char* lds, const Gemm g, const Sched& S, const Epi& E) {
;     ...
;             PG8_LDB(B0, 1, 0); PG8_LDB(B1, 1, 1); PG8_SCHED; PG8_LDA(At, 1, 0); PG8_STAGE(PG8_SA(0, 1), a2 + hstep, voffA);
;             PG8_WAIT_V(8); PG8_WAIT_L(0); PG8_BAR; PG8_MMA(0, 0, At, B0); PG8_MMA(0, 1, At, B1); PG8_BAR; PG8_SCHED;
;             PG8_LDA(At, 1, 1); PG8_STAGE(PG8_SB(1, 0), b3, voffB); PG8_STAGE(PG8_SB(1, 1), b3 + hstep, voffB); PG8_STAGE(PG8_SA(1, 0), a3, voffA);
;             PG8_WAIT_V(8); PG8_WAIT_L(0); PG8_BAR; PG8_MMA(1, 0, At, B0); PG8_MMA(1, 1, At, B1); PG8_BAR; PG8_SCHED;
;     ...
;         if constexpr (ALIGN_EPI) { if (wr == 0) PG8_BAR; }
	s_add_i32 s33, 0, 0x18000
	v_add_u32_e32 v153, s33, v163
	s_add_i32 s34, 0, 0x1c000
	ds_read_b128 v[128:131], v153
	ds_read_b128 v[132:135], v153 offset:1024
	ds_read_b128 v[154:157], v153 offset:2048
	ds_read_b128 v[158:161], v153 offset:3072
	v_add_u32_e32 v153, s34, v163
	ds_read_b128 v[168:171], v153
	ds_read_b128 v[172:175], v153 offset:1024
	ds_read_b128 v[176:179], v153 offset:2048
	ds_read_b128 v[180:183], v153 offset:3072
	s_add_u32 s58, s58, 0x40000
	s_addc_u32 s59, s59, 0
	s_mov_b32 m0, s73
	ds_read_b128 v[184:187], v167 offset:32768
	ds_read_b128 v[188:191], v167 offset:33792
	ds_read_b128 v[192:195], v167 offset:34816
	ds_read_b128 v[196:199], v167 offset:35840
	ds_read_b128 v[200:203], v167 offset:36864
	ds_read_b128 v[204:207], v167 offset:37888
	ds_read_b128 v[208:211], v167 offset:38912
	ds_read_b128 v[212:215], v167 offset:39936
	global_load_lds_dwordx4 v136, s[58:59]
	s_mov_b32 m0, s74
	s_nop 0
	global_load_lds_dwordx4 v140, s[58:59]
	s_waitcnt vmcnt(8)
	s_waitcnt lgkmcnt(0)
	s_barrier
	s_setprio 1
	s_waitcnt lgkmcnt(0)
	v_mfma_f32_16x16x32_bf16 v[124:127], v[128:131], v[184:187], v[124:127]
	v_mfma_f32_16x16x32_bf16 v[120:123], v[154:157], v[184:187], v[120:123]
	v_mfma_f32_16x16x32_bf16 v[116:119], v[128:131], v[192:195], v[116:119]
	v_mfma_f32_16x16x32_bf16 v[112:115], v[154:157], v[192:195], v[112:115]
	v_mfma_f32_16x16x32_bf16 v[108:111], v[128:131], v[200:203], v[108:111]
	v_mfma_f32_16x16x32_bf16 v[104:107], v[154:157], v[200:203], v[104:107]
	v_mfma_f32_16x16x32_bf16 v[100:103], v[128:131], v[208:211], v[100:103]
	v_mfma_f32_16x16x32_bf16 v[96:99], v[154:157], v[208:211], v[96:99]
	v_mfma_f32_16x16x32_bf16 v[124:127], v[132:135], v[188:191], v[124:127]
	v_mfma_f32_16x16x32_bf16 v[120:123], v[158:161], v[188:191], v[120:123]
	v_mfma_f32_16x16x32_bf16 v[116:119], v[132:135], v[196:199], v[116:119]
	v_mfma_f32_16x16x32_bf16 v[112:115], v[158:161], v[196:199], v[112:115]
	v_mfma_f32_16x16x32_bf16 v[108:111], v[132:135], v[204:207], v[108:111]
	v_mfma_f32_16x16x32_bf16 v[104:107], v[158:161], v[204:207], v[104:107]
	v_mfma_f32_16x16x32_bf16 v[100:103], v[132:135], v[212:215], v[100:103]
	v_mfma_f32_16x16x32_bf16 v[96:99], v[158:161], v[212:215], v[96:99]
	v_mfma_f32_16x16x32_bf16 v[68:71], v[168:171], v[184:187], v[68:71]
	v_mfma_f32_16x16x32_bf16 v[60:63], v[176:179], v[184:187], v[60:63]
	v_mfma_f32_16x16x32_bf16 v[52:55], v[168:171], v[192:195], v[52:55]
	v_mfma_f32_16x16x32_bf16 v[48:51], v[176:179], v[192:195], v[48:51]
	v_mfma_f32_16x16x32_bf16 v[44:47], v[168:171], v[200:203], v[44:47]
	v_mfma_f32_16x16x32_bf16 v[40:43], v[176:179], v[200:203], v[40:43]
	v_mfma_f32_16x16x32_bf16 v[36:39], v[168:171], v[208:211], v[36:39]
	v_mfma_f32_16x16x32_bf16 v[32:35], v[176:179], v[208:211], v[32:35]
	v_mfma_f32_16x16x32_bf16 v[68:71], v[172:175], v[188:191], v[68:71]
	v_mfma_f32_16x16x32_bf16 v[60:63], v[180:183], v[188:191], v[60:63]
	v_mfma_f32_16x16x32_bf16 v[52:55], v[172:175], v[196:199], v[52:55]
	v_mfma_f32_16x16x32_bf16 v[48:51], v[180:183], v[196:199], v[48:51]
	v_mfma_f32_16x16x32_bf16 v[44:47], v[172:175], v[204:207], v[44:47]
	v_mfma_f32_16x16x32_bf16 v[40:43], v[180:183], v[204:207], v[40:43]
	v_mfma_f32_16x16x32_bf16 v[36:39], v[172:175], v[212:215], v[36:39]
	v_mfma_f32_16x16x32_bf16 v[32:35], v[180:183], v[212:215], v[32:35]
	s_setprio 0
	s_barrier
	s_add_i32 s33, s33, s70
	s_mov_b32 m0, s33
	ds_read_b128 v[184:187], v167 offset:49152
	ds_read_b128 v[188:191], v167 offset:50176
	ds_read_b128 v[192:195], v167 offset:51200
	ds_read_b128 v[196:199], v167 offset:52224
	ds_read_b128 v[200:203], v167 offset:53248
	ds_read_b128 v[204:207], v167 offset:54272
	ds_read_b128 v[208:211], v167 offset:55296
	ds_read_b128 v[212:215], v167 offset:56320
	global_load_lds_dwordx4 v138, s[64:65]
	s_add_i32 m0, s33, 0x2000
	s_add_u32 s56, s56, 0x40080
	s_addc_u32 s57, s57, 0
	s_add_i32 s33, s34, s70
	global_load_lds_dwordx4 v142, s[64:65]
	s_mov_b32 m0, s33
	s_nop 0
	global_load_lds_dwordx4 v138, s[56:57]
	s_add_i32 m0, s33, 0x2000
	s_nop 0
	global_load_lds_dwordx4 v142, s[56:57]
	s_mov_b32 m0, s79
	s_nop 0
	global_load_lds_dwordx4 v136, s[84:85]
	s_mov_b32 m0, s80
	s_nop 0
	global_load_lds_dwordx4 v140, s[84:85]
	s_waitcnt vmcnt(8)
	s_waitcnt lgkmcnt(0)
	s_barrier
	s_setprio 1
	s_waitcnt lgkmcnt(0)
	v_mfma_f32_16x16x32_bf16 v[92:95], v[128:131], v[184:187], v[92:95]
	v_mfma_f32_16x16x32_bf16 v[88:91], v[154:157], v[184:187], v[88:91]
	v_mfma_f32_16x16x32_bf16 v[84:87], v[128:131], v[192:195], v[84:87]
	v_mfma_f32_16x16x32_bf16 v[80:83], v[154:157], v[192:195], v[80:83]
	v_mfma_f32_16x16x32_bf16 v[76:79], v[128:131], v[200:203], v[76:79]
	v_mfma_f32_16x16x32_bf16 v[72:75], v[154:157], v[200:203], v[72:75]
	v_mfma_f32_16x16x32_bf16 v[64:67], v[128:131], v[208:211], v[64:67]
	v_mfma_f32_16x16x32_bf16 v[56:59], v[154:157], v[208:211], v[56:59]
	v_mfma_f32_16x16x32_bf16 v[92:95], v[132:135], v[188:191], v[92:95]
	v_mfma_f32_16x16x32_bf16 v[88:91], v[158:161], v[188:191], v[88:91]
	v_mfma_f32_16x16x32_bf16 v[84:87], v[132:135], v[196:199], v[84:87]
	v_mfma_f32_16x16x32_bf16 v[80:83], v[158:161], v[196:199], v[80:83]
	v_mfma_f32_16x16x32_bf16 v[76:79], v[132:135], v[204:207], v[76:79]
	v_mfma_f32_16x16x32_bf16 v[72:75], v[158:161], v[204:207], v[72:75]
	v_mfma_f32_16x16x32_bf16 v[64:67], v[132:135], v[212:215], v[64:67]
	v_mfma_f32_16x16x32_bf16 v[56:59], v[158:161], v[212:215], v[56:59]
	v_mfma_f32_16x16x32_bf16 v[28:31], v[168:171], v[184:187], v[28:31]
	v_mfma_f32_16x16x32_bf16 v[24:27], v[176:179], v[184:187], v[24:27]
	v_mfma_f32_16x16x32_bf16 v[20:23], v[168:171], v[192:195], v[20:23]
	v_mfma_f32_16x16x32_bf16 v[16:19], v[176:179], v[192:195], v[16:19]
	v_mfma_f32_16x16x32_bf16 v[12:15], v[168:171], v[200:203], v[12:15]
	v_mfma_f32_16x16x32_bf16 v[8:11], v[176:179], v[200:203], v[8:11]
	v_mfma_f32_16x16x32_bf16 v[4:7], v[168:171], v[208:211], v[4:7]
	v_mfma_f32_16x16x32_bf16 v[0:3], v[176:179], v[208:211], v[0:3]
	v_mfma_f32_16x16x32_bf16 v[28:31], v[172:175], v[188:191], v[28:31]
	v_mfma_f32_16x16x32_bf16 v[24:27], v[180:183], v[188:191], v[24:27]
	v_mfma_f32_16x16x32_bf16 v[20:23], v[172:175], v[196:199], v[20:23]
	v_mfma_f32_16x16x32_bf16 v[16:19], v[180:183], v[196:199], v[16:19]
	v_mfma_f32_16x16x32_bf16 v[12:15], v[172:175], v[204:207], v[12:15]
	v_mfma_f32_16x16x32_bf16 v[8:11], v[180:183], v[204:207], v[8:11]
	v_mfma_f32_16x16x32_bf16 v[4:7], v[172:175], v[212:215], v[4:7]
	v_mfma_f32_16x16x32_bf16 v[0:3], v[180:183], v[212:215], v[0:3]
	s_setprio 0
	s_barrier
	s_add_i32 s92, s92, 2
	s_add_u32 s54, s54, 0x100
	s_addc_u32 s55, s55, 0
	s_add_u32 s90, s90, 0x100
	s_addc_u32 s91, s91, 0
	s_cmp_gt_u32 s92, 13
	s_cbranch_scc0 .LBB0_590
	s_and_b64 vcc, exec, s[12:13]
	s_cbranch_vccz .LBB0_593
	s_barrier

; #define PG8_STAGE(bufoff, gbase, voff) do { _Pragma("unroll") for (int _i = 0; _i < 2; ++_i) \
;         __builtin_amdgcn_global_load_lds((const unsigned*)((const char*)(gbase) + (voff)[_i]), (PG8_LAS unsigned*)(lds + (bufoff) + ldsw + _i * 8192), 16, 0, 0); } while (0)
; #define PG8_LDA(dst, b, h) do { _Pragma("unroll") for (int m = 0; m < 4; ++m) _Pragma("unroll") for (int k = 0; k < 2; ++k) dst[m][k] = *(const PG8_LAS bf16x8*)(lds + PG8_SA(b, h) + aoff + m * 2048 + k * 1024); } while (0)
; #define PG8_MMA(ai, bj, At, Bt) do { __builtin_amdgcn_s_setprio(1); _Pragma("unroll") for (int m = 0; m < 4; ++m) _Pragma("unroll") for (int n = 0; n < 2; ++n) _Pragma("unroll") for (int k = 0; k < 2; ++k) \
;         acc[ai][bj][m][n] = __builtin_amdgcn_mfma_f32_16x16x32_bf16(Bt[n][k], At[m][k], acc[ai][bj][m][n], 0, 0, 0); __builtin_amdgcn_s_setprio(0); } while (0)
; #define PG8_WAIT_V(n) asm volatile("s_waitcnt vmcnt(" #n ")" ::: "memory")
; #define PG8_WAIT_L(n) asm volatile("s_waitcnt lgkmcnt(" #n ")" ::: "memory")
; #define PG8_BAR __builtin_amdgcn_s_barrier()
; #define PG8_SCHED __builtin_amdgcn_sched_barrier(0)
; template <class Epi, class Sched, bool ALIGN_EPI = false, bool SP2 = false>
; __device__ __forceinline__ void gemm_phase(PG8_LAS unsigned char* lds, const Gemm g, const Sched& S, const Epi& E) {
;     ...
;             PG8_WAIT_V(8); PG8_WAIT_L(0); PG8_BAR; PG8_MMA(0, 0, At, B0); PG8_MMA(0, 1, At, B1); PG8_BAR; PG8_SCHED;
;             PG8_LDA(At, 0, 1); PG8_STAGE(PG8_SB(0, 0), b2, voffB); PG8_STAGE(PG8_SB(0, 1), b2 + hstep, voffB); PG8_STAGE(PG8_SA(0, 0), a2, voffA);
;             PG8_WAIT_V(8); PG8_WAIT_L(0); PG8_BAR; PG8_MMA(1, 0, At, B0); PG8_MMA(1, 1, At, B1); PG8_BAR; PG8_SCHED;
.LfwP7_0_e:
	s_waitcnt lgkmcnt(0)
	s_barrier
	s_setprio 1
	s_waitcnt lgkmcnt(0)
	v_mfma_f32_16x16x32_bf16 v[124:127], v[154:157], v[186:189], 0
	v_mfma_f32_16x16x32_bf16 v[116:119], v[162:165], v[186:189], 0
	v_mfma_f32_16x16x32_bf16 v[108:111], v[154:157], v[194:197], 0
	v_mfma_f32_16x16x32_bf16 v[100:103], v[162:165], v[194:197], 0
	v_mfma_f32_16x16x32_bf16 v[92:95], v[154:157], v[202:205], 0
	v_mfma_f32_16x16x32_bf16 v[84:87], v[162:165], v[202:205], 0
	v_mfma_f32_16x16x32_bf16 v[76:79], v[154:157], v[210:213], 0
	v_mfma_f32_16x16x32_bf16 v[68:71], v[162:165], v[210:213], 0
	v_mfma_f32_16x16x32_bf16 v[124:127], v[158:161], v[190:193], v[124:127]
	v_mfma_f32_16x16x32_bf16 v[116:119], v[166:169], v[190:193], v[116:119]
	v_mfma_f32_16x16x32_bf16 v[108:111], v[158:161], v[198:201], v[108:111]
	v_mfma_f32_16x16x32_bf16 v[100:103], v[166:169], v[198:201], v[100:103]
	v_mfma_f32_16x16x32_bf16 v[92:95], v[158:161], v[206:209], v[92:95]
	v_mfma_f32_16x16x32_bf16 v[84:87], v[166:169], v[206:209], v[84:87]
	v_mfma_f32_16x16x32_bf16 v[76:79], v[158:161], v[214:217], v[76:79]
	v_mfma_f32_16x16x32_bf16 v[68:71], v[166:169], v[214:217], v[68:71]
	v_mfma_f32_16x16x32_bf16 v[120:123], v[170:173], v[186:189], 0
	v_mfma_f32_16x16x32_bf16 v[112:115], v[178:181], v[186:189], 0
	v_mfma_f32_16x16x32_bf16 v[104:107], v[170:173], v[194:197], 0
	v_mfma_f32_16x16x32_bf16 v[96:99], v[178:181], v[194:197], 0
	v_mfma_f32_16x16x32_bf16 v[88:91], v[170:173], v[202:205], 0
	v_mfma_f32_16x16x32_bf16 v[80:83], v[178:181], v[202:205], 0
	v_mfma_f32_16x16x32_bf16 v[72:75], v[170:173], v[210:213], 0
	v_mfma_f32_16x16x32_bf16 v[64:67], v[178:181], v[210:213], 0
	v_mfma_f32_16x16x32_bf16 v[120:123], v[174:177], v[190:193], v[120:123]
	v_mfma_f32_16x16x32_bf16 v[112:115], v[182:185], v[190:193], v[112:115]
	v_mfma_f32_16x16x32_bf16 v[104:107], v[174:177], v[198:201], v[104:107]
	v_mfma_f32_16x16x32_bf16 v[96:99], v[182:185], v[198:201], v[96:99]
	v_mfma_f32_16x16x32_bf16 v[88:91], v[174:177], v[206:209], v[88:91]
	v_mfma_f32_16x16x32_bf16 v[80:83], v[182:185], v[206:209], v[80:83]
	v_mfma_f32_16x16x32_bf16 v[72:75], v[174:177], v[214:217], v[72:75]
	v_mfma_f32_16x16x32_bf16 v[64:67], v[182:185], v[214:217], v[64:67]
	s_setprio 0
	s_barrier
	s_add_i32 s33, s62, s52
	s_add_u32 s82, s42, s10
	s_addc_u32 s83, s43, s11
	s_mov_b32 m0, s33
	ds_read_b128 v[186:189], v149 offset:16384
	ds_read_b128 v[190:193], v149 offset:17408
	ds_read_b128 v[194:197], v149 offset:18432
	ds_read_b128 v[198:201], v149 offset:19456
	ds_read_b128 v[202:205], v149 offset:20480
	ds_read_b128 v[206:209], v149 offset:21504
	ds_read_b128 v[210:213], v149 offset:22528
	ds_read_b128 v[214:217], v149 offset:23552
	global_load_lds_dwordx4 v130, s[42:43]
	s_add_i32 m0, s33, 0x2000
	s_add_u32 s78, s42, 0x40000
	s_addc_u32 s79, s43, 0
	s_add_i32 s33, s63, s52
	global_load_lds_dwordx4 v134, s[42:43]
	s_mov_b32 m0, s33
	s_add_u32 s84, s44, s10
	s_addc_u32 s85, s45, s11
	global_load_lds_dwordx4 v130, s[78:79]
	s_add_i32 m0, s33, 0x2000
	s_nop 0
	global_load_lds_dwordx4 v134, s[78:79]
	s_mov_b32 m0, s39
	s_nop 0
	global_load_lds_dwordx4 v128, s[44:45]
	s_mov_b32 m0, s55
	s_nop 0
	global_load_lds_dwordx4 v132, s[44:45]
	s_cmp_eq_u32 s77, 0
	s_cbranch_scc1 .LfwP7_1_s
	s_waitcnt vmcnt(16)
	s_branch .LfwP7_1_e

; #define PG8_STAGE(bufoff, gbase, voff) do { _Pragma("unroll") for (int _i = 0; _i < 2; ++_i) \
;         __builtin_amdgcn_global_load_lds((const unsigned*)((const char*)(gbase) + (voff)[_i]), (PG8_LAS unsigned*)(lds + (bufoff) + ldsw + _i * 8192), 16, 0, 0); } while (0)
; #define PG8_LDA(dst, b, h) do { _Pragma("unroll") for (int m = 0; m < 4; ++m) _Pragma("unroll") for (int k = 0; k < 2; ++k) dst[m][k] = *(const PG8_LAS bf16x8*)(lds + PG8_SA(b, h) + aoff + m * 2048 + k * 1024); } while (0)
; #define PG8_LDB(dst, b, h) do { _Pragma("unroll") for (int n = 0; n < 2; ++n) _Pragma("unroll") for (int k = 0; k < 2; ++k) dst[n][k] = *(const PG8_LAS bf16x8*)(lds + PG8_SB(b, h) + boff + n * 2048 + k * 1024); } while (0)
; #define PG8_MMA(ai, bj, At, Bt) do { __builtin_amdgcn_s_setprio(1); _Pragma("unroll") for (int m = 0; m < 4; ++m) _Pragma("unroll") for (int n = 0; n < 2; ++n) _Pragma("unroll") for (int k = 0; k < 2; ++k) \
;         acc[ai][bj][m][n] = __builtin_amdgcn_mfma_f32_16x16x32_bf16(Bt[n][k], At[m][k], acc[ai][bj][m][n], 0, 0, 0); __builtin_amdgcn_s_setprio(0); } while (0)
; #define PG8_WAIT_V(n) asm volatile("s_waitcnt vmcnt(" #n ")" ::: "memory")
; #define PG8_WAIT_L(n) asm volatile("s_waitcnt lgkmcnt(" #n ")" ::: "memory")
; #define PG8_BAR __builtin_amdgcn_s_barrier()
; #define PG8_SCHED __builtin_amdgcn_sched_barrier(0)
; template <class Epi, class Sched, bool ALIGN_EPI = false, bool SP2 = false>
; __device__ __forceinline__ void gemm_phase(PG8_LAS unsigned char* lds, const Gemm g, const Sched& S, const Epi& E) {
;     ...
;             PG8_WAIT_V(8); PG8_WAIT_L(0); PG8_BAR; PG8_MMA(1, 0, At, B0); PG8_MMA(1, 1, At, B1); PG8_BAR; PG8_SCHED;
;             PG8_LDB(B0, 1, 0); PG8_LDB(B1, 1, 1); PG8_SCHED; PG8_LDA(At, 1, 0); PG8_STAGE(PG8_SA(0, 1), a2 + hstep, voffA);
;             PG8_WAIT_V(8); PG8_WAIT_L(0); PG8_BAR; PG8_MMA(0, 0, At, B0); PG8_MMA(0, 1, At, B1); PG8_BAR; PG8_SCHED;
.LfwP7_1_e:
	s_waitcnt lgkmcnt(0)
	s_barrier
	s_setprio 1
	s_waitcnt lgkmcnt(0)
	v_mfma_f32_16x16x32_bf16 v[60:63], v[154:157], v[186:189], 0
	v_mfma_f32_16x16x32_bf16 v[52:55], v[162:165], v[186:189], 0
	v_mfma_f32_16x16x32_bf16 v[44:47], v[154:157], v[194:197], 0
	v_mfma_f32_16x16x32_bf16 v[36:39], v[162:165], v[194:197], 0
	v_mfma_f32_16x16x32_bf16 v[28:31], v[154:157], v[202:205], 0
	v_mfma_f32_16x16x32_bf16 v[20:23], v[162:165], v[202:205], 0
	v_mfma_f32_16x16x32_bf16 v[12:15], v[154:157], v[210:213], 0
	v_mfma_f32_16x16x32_bf16 v[4:7], v[162:165], v[210:213], 0
	v_mfma_f32_16x16x32_bf16 v[60:63], v[158:161], v[190:193], v[60:63]
	v_mfma_f32_16x16x32_bf16 v[52:55], v[166:169], v[190:193], v[52:55]
	v_mfma_f32_16x16x32_bf16 v[44:47], v[158:161], v[198:201], v[44:47]
	v_mfma_f32_16x16x32_bf16 v[36:39], v[166:169], v[198:201], v[36:39]
	v_mfma_f32_16x16x32_bf16 v[28:31], v[158:161], v[206:209], v[28:31]
	v_mfma_f32_16x16x32_bf16 v[20:23], v[166:169], v[206:209], v[20:23]
	v_mfma_f32_16x16x32_bf16 v[12:15], v[158:161], v[214:217], v[12:15]
	v_mfma_f32_16x16x32_bf16 v[4:7], v[166:169], v[214:217], v[4:7]
	v_mfma_f32_16x16x32_bf16 v[56:59], v[170:173], v[186:189], 0
	v_mfma_f32_16x16x32_bf16 v[48:51], v[178:181], v[186:189], 0
	v_mfma_f32_16x16x32_bf16 v[40:43], v[170:173], v[194:197], 0
	v_mfma_f32_16x16x32_bf16 v[32:35], v[178:181], v[194:197], 0
	v_mfma_f32_16x16x32_bf16 v[24:27], v[170:173], v[202:205], 0
	v_mfma_f32_16x16x32_bf16 v[16:19], v[178:181], v[202:205], 0
	v_mfma_f32_16x16x32_bf16 v[8:11], v[170:173], v[210:213], 0
	v_mfma_f32_16x16x32_bf16 v[0:3], v[178:181], v[210:213], 0
	v_mfma_f32_16x16x32_bf16 v[56:59], v[174:177], v[190:193], v[56:59]
	v_mfma_f32_16x16x32_bf16 v[48:51], v[182:185], v[190:193], v[48:51]
	v_mfma_f32_16x16x32_bf16 v[40:43], v[174:177], v[198:201], v[40:43]
	v_mfma_f32_16x16x32_bf16 v[32:35], v[182:185], v[198:201], v[32:35]
	v_mfma_f32_16x16x32_bf16 v[24:27], v[174:177], v[206:209], v[24:27]
	v_mfma_f32_16x16x32_bf16 v[16:19], v[182:185], v[206:209], v[16:19]
	v_mfma_f32_16x16x32_bf16 v[8:11], v[174:177], v[214:217], v[8:11]
	v_mfma_f32_16x16x32_bf16 v[0:3], v[182:185], v[214:217], v[0:3]
	s_setprio 0
	s_barrier
	s_add_i32 s33, 0, 0x18000
	v_add_u32_e32 v153, s33, v145
	s_add_i32 s34, 0, 0x1c000
	ds_read_b128 v[154:157], v153
	ds_read_b128 v[158:161], v153 offset:1024
	ds_read_b128 v[162:165], v153 offset:2048
	ds_read_b128 v[166:169], v153 offset:3072
	v_add_u32_e32 v153, s34, v145
	ds_read_b128 v[170:173], v153
	ds_read_b128 v[174:177], v153 offset:1024
	ds_read_b128 v[178:181], v153 offset:2048
	ds_read_b128 v[182:185], v153 offset:3072
	s_add_u32 s44, s44, 0x40000
	s_addc_u32 s45, s45, 0
	s_mov_b32 m0, s56
	ds_read_b128 v[186:189], v149 offset:32768
	ds_read_b128 v[190:193], v149 offset:33792
	ds_read_b128 v[194:197], v149 offset:34816
	ds_read_b128 v[198:201], v149 offset:35840
	ds_read_b128 v[202:205], v149 offset:36864
	ds_read_b128 v[206:209], v149 offset:37888
	ds_read_b128 v[210:213], v149 offset:38912
	ds_read_b128 v[214:217], v149 offset:39936
	global_load_lds_dwordx4 v128, s[44:45]
	s_mov_b32 m0, s57
	s_nop 0
	global_load_lds_dwordx4 v132, s[44:45]
	s_waitcnt vmcnt(8)
	s_waitcnt lgkmcnt(0)
	s_barrier
	s_setprio 1
	s_waitcnt lgkmcnt(0)
	v_mfma_f32_16x16x32_bf16 v[124:127], v[154:157], v[186:189], v[124:127]
	v_mfma_f32_16x16x32_bf16 v[116:119], v[162:165], v[186:189], v[116:119]
	v_mfma_f32_16x16x32_bf16 v[108:111], v[154:157], v[194:197], v[108:111]
	v_mfma_f32_16x16x32_bf16 v[100:103], v[162:165], v[194:197], v[100:103]
	v_mfma_f32_16x16x32_bf16 v[92:95], v[154:157], v[202:205], v[92:95]
	v_mfma_f32_16x16x32_bf16 v[84:87], v[162:165], v[202:205], v[84:87]
	v_mfma_f32_16x16x32_bf16 v[76:79], v[154:157], v[210:213], v[76:79]
	v_mfma_f32_16x16x32_bf16 v[68:71], v[162:165], v[210:213], v[68:71]
	v_mfma_f32_16x16x32_bf16 v[124:127], v[158:161], v[190:193], v[124:127]
	v_mfma_f32_16x16x32_bf16 v[116:119], v[166:169], v[190:193], v[116:119]
	v_mfma_f32_16x16x32_bf16 v[108:111], v[158:161], v[198:201], v[108:111]
	v_mfma_f32_16x16x32_bf16 v[100:103], v[166:169], v[198:201], v[100:103]
	v_mfma_f32_16x16x32_bf16 v[92:95], v[158:161], v[206:209], v[92:95]
	v_mfma_f32_16x16x32_bf16 v[84:87], v[166:169], v[206:209], v[84:87]
	v_mfma_f32_16x16x32_bf16 v[76:79], v[158:161], v[214:217], v[76:79]
	v_mfma_f32_16x16x32_bf16 v[68:71], v[166:169], v[214:217], v[68:71]
	v_mfma_f32_16x16x32_bf16 v[120:123], v[170:173], v[186:189], v[120:123]
	v_mfma_f32_16x16x32_bf16 v[112:115], v[178:181], v[186:189], v[112:115]
	v_mfma_f32_16x16x32_bf16 v[104:107], v[170:173], v[194:197], v[104:107]
	v_mfma_f32_16x16x32_bf16 v[96:99], v[178:181], v[194:197], v[96:99]
	v_mfma_f32_16x16x32_bf16 v[88:91], v[170:173], v[202:205], v[88:91]
	v_mfma_f32_16x16x32_bf16 v[80:83], v[178:181], v[202:205], v[80:83]
	v_mfma_f32_16x16x32_bf16 v[72:75], v[170:173], v[210:213], v[72:75]
	v_mfma_f32_16x16x32_bf16 v[64:67], v[178:181], v[210:213], v[64:67]
	v_mfma_f32_16x16x32_bf16 v[120:123], v[174:177], v[190:193], v[120:123]
	v_mfma_f32_16x16x32_bf16 v[112:115], v[182:185], v[190:193], v[112:115]
	v_mfma_f32_16x16x32_bf16 v[104:107], v[174:177], v[198:201], v[104:107]
	v_mfma_f32_16x16x32_bf16 v[96:99], v[182:185], v[198:201], v[96:99]
	v_mfma_f32_16x16x32_bf16 v[88:91], v[174:177], v[206:209], v[88:91]
	v_mfma_f32_16x16x32_bf16 v[80:83], v[182:185], v[206:209], v[80:83]
	v_mfma_f32_16x16x32_bf16 v[72:75], v[174:177], v[214:217], v[72:75]
	v_mfma_f32_16x16x32_bf16 v[64:67], v[182:185], v[214:217], v[64:67]
	s_setprio 0
	s_barrier
; #define PG8_STAGE(bufoff, gbase, voff) do { _Pragma("unroll") for (int _i = 0; _i < 2; ++_i) \
;         __builtin_amdgcn_global_load_lds((const unsigned*)((const char*)(gbase) + (voff)[_i]), (PG8_LAS unsigned*)(lds + (bufoff) + ldsw + _i * 8192), 16, 0, 0); } while (0)
; #define PG8_LDA(dst, b, h) do { _Pragma("unroll") for (int m = 0; m < 4; ++m) _Pragma("unroll") for (int k = 0; k < 2; ++k) dst[m][k] = *(const PG8_LAS bf16x8*)(lds + PG8_SA(b, h) + aoff + m * 2048 + k * 1024); } while (0)
; #define PG8_LDB(dst, b, h) do { _Pragma("unroll") for (int n = 0; n < 2; ++n) _Pragma("unroll") for (int k = 0; k < 2; ++k) dst[n][k] = *(const PG8_LAS bf16x8*)(lds + PG8_SB(b, h) + boff + n * 2048 + k * 1024); } while (0)
; #define PG8_MMA(ai, bj, At, Bt) do { __builtin_amdgcn_s_setprio(1); _Pragma("unroll") for (int m = 0; m < 4; ++m) _Pragma("unroll") for (int n = 0; n < 2; ++n) _Pragma("unroll") for (int k = 0; k < 2; ++k) \
;         acc[ai][bj][m][n] = __builtin_amdgcn_mfma_f32_16x16x32_bf16(Bt[n][k], At[m][k], acc[ai][bj][m][n], 0, 0, 0); __builtin_amdgcn_s_setprio(0); } while (0)
; #define PG8_WAIT_V(n) asm volatile("s_waitcnt vmcnt(" #n ")" ::: "memory")
; #define PG8_WAIT_L(n) asm volatile("s_waitcnt lgkmcnt(" #n ")" ::: "memory")
; template <class Epi, class Sched, bool ALIGN_EPI = false, bool SP2 = false>
; __device__ __forceinline__ void gemm_phase(PG8_LAS unsigned char* lds, const Gemm g, const Sched& S, const Epi& E) {
;     ...
;             const bool last = (t == nt - 2);
;             const char* a1 = cA + (size_t)(t + 1) * kstep;
;             const char* a2 = last ? nA : cA + (size_t)(t + 2) * kstep; const char* b2 = last ? nB : cB + (size_t)(t + 2) * kstep;
;             const char* a3 = a2 + kstep; const char* b3 = b2 + kstep;
;             if (last && has_next) S.a_ready(nxt);
;             if constexpr (SP2) {
;             PG8_LDB(B0, 0, 0); PG8_LDB(B1, 0, 1); PG8_SCHED; PG8_LDA(At, 0, 0); PG8_STAGE(PG8_SA(1, 1), a1 + hstep, voffA);
;             PG8_WAIT_V(8); PG8_WAIT_L(0); PG8_BAR; PG8_MMA(0, 0, At, B0); PG8_MMA(0, 1, At, B1); PG8_BAR; PG8_SCHED;
;     ...
;             PG8_LDA(At, 1, 1); PG8_STAGE(PG8_SB(1, 0), b3, voffB); PG8_STAGE(PG8_SB(1, 1), b3 + hstep, voffB); PG8_STAGE(PG8_SA(1, 0), a3, voffA);
;             PG8_WAIT_V(8); PG8_WAIT_L(0); PG8_BAR; PG8_MMA(1, 0, At, B0); PG8_MMA(1, 1, At, B1); PG8_BAR; PG8_SCHED;
	s_add_i32 s33, s33, s52
	s_mov_b32 m0, s33
	ds_read_b128 v[186:189], v149 offset:49152
	ds_read_b128 v[190:193], v149 offset:50176
	ds_read_b128 v[194:197], v149 offset:51200
	ds_read_b128 v[198:201], v149 offset:52224
	ds_read_b128 v[202:205], v149 offset:53248
	ds_read_b128 v[206:209], v149 offset:54272
	ds_read_b128 v[210:213], v149 offset:55296
	ds_read_b128 v[214:217], v149 offset:56320
	global_load_lds_dwordx4 v130, s[82:83]
	s_add_i32 m0, s33, 0x2000
	s_add_u32 s42, s42, 0x40080
	s_addc_u32 s43, s43, 0
	s_add_i32 s33, s34, s52
	global_load_lds_dwordx4 v134, s[82:83]
	s_mov_b32 m0, s33
	s_nop 0
	global_load_lds_dwordx4 v130, s[42:43]
	s_add_i32 m0, s33, 0x2000
	s_nop 0
	global_load_lds_dwordx4 v134, s[42:43]
	s_mov_b32 m0, s60
	s_nop 0
	global_load_lds_dwordx4 v128, s[84:85]
	s_mov_b32 m0, s61
	s_nop 0
	global_load_lds_dwordx4 v132, s[84:85]
	s_waitcnt vmcnt(8)
	s_waitcnt lgkmcnt(0)
	s_barrier
	s_setprio 1
	s_waitcnt lgkmcnt(0)
	v_mfma_f32_16x16x32_bf16 v[60:63], v[154:157], v[186:189], v[60:63]
	v_mfma_f32_16x16x32_bf16 v[52:55], v[162:165], v[186:189], v[52:55]
	v_mfma_f32_16x16x32_bf16 v[44:47], v[154:157], v[194:197], v[44:47]
	v_mfma_f32_16x16x32_bf16 v[36:39], v[162:165], v[194:197], v[36:39]
	v_mfma_f32_16x16x32_bf16 v[28:31], v[154:157], v[202:205], v[28:31]
	v_mfma_f32_16x16x32_bf16 v[20:23], v[162:165], v[202:205], v[20:23]
	v_mfma_f32_16x16x32_bf16 v[12:15], v[154:157], v[210:213], v[12:15]
	v_mfma_f32_16x16x32_bf16 v[4:7], v[162:165], v[210:213], v[4:7]
	v_mfma_f32_16x16x32_bf16 v[60:63], v[158:161], v[190:193], v[60:63]
	v_mfma_f32_16x16x32_bf16 v[52:55], v[166:169], v[190:193], v[52:55]
	v_mfma_f32_16x16x32_bf16 v[44:47], v[158:161], v[198:201], v[44:47]
	v_mfma_f32_16x16x32_bf16 v[36:39], v[166:169], v[198:201], v[36:39]
	v_mfma_f32_16x16x32_bf16 v[28:31], v[158:161], v[206:209], v[28:31]
	v_mfma_f32_16x16x32_bf16 v[20:23], v[166:169], v[206:209], v[20:23]
	v_mfma_f32_16x16x32_bf16 v[12:15], v[158:161], v[214:217], v[12:15]
	v_mfma_f32_16x16x32_bf16 v[4:7], v[166:169], v[214:217], v[4:7]
	v_mfma_f32_16x16x32_bf16 v[56:59], v[170:173], v[186:189], v[56:59]
	v_mfma_f32_16x16x32_bf16 v[48:51], v[178:181], v[186:189], v[48:51]
	v_mfma_f32_16x16x32_bf16 v[40:43], v[170:173], v[194:197], v[40:43]
	v_mfma_f32_16x16x32_bf16 v[32:35], v[178:181], v[194:197], v[32:35]
	v_mfma_f32_16x16x32_bf16 v[24:27], v[170:173], v[202:205], v[24:27]
	v_mfma_f32_16x16x32_bf16 v[16:19], v[178:181], v[202:205], v[16:19]
	v_mfma_f32_16x16x32_bf16 v[8:11], v[170:173], v[210:213], v[8:11]
	v_mfma_f32_16x16x32_bf16 v[0:3], v[178:181], v[210:213], v[0:3]
	v_mfma_f32_16x16x32_bf16 v[56:59], v[174:177], v[190:193], v[56:59]
	v_mfma_f32_16x16x32_bf16 v[48:51], v[182:185], v[190:193], v[48:51]
	v_mfma_f32_16x16x32_bf16 v[40:43], v[174:177], v[198:201], v[40:43]
	v_mfma_f32_16x16x32_bf16 v[32:35], v[182:185], v[198:201], v[32:35]
	v_mfma_f32_16x16x32_bf16 v[24:27], v[174:177], v[206:209], v[24:27]
	v_mfma_f32_16x16x32_bf16 v[16:19], v[182:185], v[206:209], v[16:19]
	v_mfma_f32_16x16x32_bf16 v[8:11], v[174:177], v[214:217], v[8:11]
	v_mfma_f32_16x16x32_bf16 v[0:3], v[182:185], v[214:217], v[0:3]
	s_setprio 0
	s_barrier
	s_add_i32 s76, s76, 2
	s_add_u32 s40, s40, 0x100
	s_addc_u32 s41, s41, 0
	s_add_u32 s74, s74, 0x100
	s_addc_u32 s75, s75, 0
	s_cmp_gt_u32 s76, 13
.LBB0_714:
	ds_read_b128 v[154:157], v147
	ds_read_b128 v[158:161], v147 offset:1024
	ds_read_b128 v[162:165], v147 offset:2048
	ds_read_b128 v[166:169], v147 offset:3072
	ds_read_b128 v[170:173], v148
	ds_read_b128 v[174:177], v148 offset:1024
	ds_read_b128 v[178:181], v148 offset:2048
	ds_read_b128 v[182:185], v148 offset:3072
	s_add_u32 s33, s40, 0xfffc0080
	s_addc_u32 s34, s41, -1
	s_cmp_eq_u32 s76, 12
	s_cselect_b32 s45, s23, s34
	s_cselect_b32 s44, s72, s33
	s_cselect_b32 s43, s21, s75
	s_cselect_b32 s42, s73, s74
	s_add_i32 m0, s39, 0xc000
	ds_read_b128 v[186:189], v149
	ds_read_b128 v[190:193], v149 offset:1024
	ds_read_b128 v[194:197], v149 offset:2048
	ds_read_b128 v[198:201], v149 offset:3072
	ds_read_b128 v[202:205], v149 offset:4096
	ds_read_b128 v[206:209], v149 offset:5120
	ds_read_b128 v[210:213], v149 offset:6144
	ds_read_b128 v[214:217], v149 offset:7168
	global_load_lds_dwordx4 v136, s[40:41]
	s_add_i32 m0, s39, 0xe000
	s_nop 0
	global_load_lds_dwordx4 v138, s[40:41]
	s_waitcnt vmcnt(8)
	s_waitcnt lgkmcnt(0)
	s_barrier
	s_setprio 1
	s_waitcnt lgkmcnt(0)
	v_mfma_f32_16x16x32_bf16 v[124:127], v[154:157], v[186:189], v[124:127]
	v_mfma_f32_16x16x32_bf16 v[116:119], v[162:165], v[186:189], v[116:119]
	v_mfma_f32_16x16x32_bf16 v[108:111], v[154:157], v[194:197], v[108:111]
	v_mfma_f32_16x16x32_bf16 v[100:103], v[162:165], v[194:197], v[100:103]
	v_mfma_f32_16x16x32_bf16 v[92:95], v[154:157], v[202:205], v[92:95]
	v_mfma_f32_16x16x32_bf16 v[84:87], v[162:165], v[202:205], v[84:87]
	v_mfma_f32_16x16x32_bf16 v[76:79], v[154:157], v[210:213], v[76:79]
	v_mfma_f32_16x16x32_bf16 v[68:71], v[162:165], v[210:213], v[68:71]
	v_mfma_f32_16x16x32_bf16 v[124:127], v[158:161], v[190:193], v[124:127]
	v_mfma_f32_16x16x32_bf16 v[116:119], v[166:169], v[190:193], v[116:119]
	v_mfma_f32_16x16x32_bf16 v[108:111], v[158:161], v[198:201], v[108:111]
	v_mfma_f32_16x16x32_bf16 v[100:103], v[166:169], v[198:201], v[100:103]
	v_mfma_f32_16x16x32_bf16 v[92:95], v[158:161], v[206:209], v[92:95]
	v_mfma_f32_16x16x32_bf16 v[84:87], v[166:169], v[206:209], v[84:87]
	v_mfma_f32_16x16x32_bf16 v[76:79], v[158:161], v[214:217], v[76:79]
	v_mfma_f32_16x16x32_bf16 v[68:71], v[166:169], v[214:217], v[68:71]
	v_mfma_f32_16x16x32_bf16 v[120:123], v[170:173], v[186:189], v[120:123]
	v_mfma_f32_16x16x32_bf16 v[112:115], v[178:181], v[186:189], v[112:115]
	v_mfma_f32_16x16x32_bf16 v[104:107], v[170:173], v[194:197], v[104:107]
	v_mfma_f32_16x16x32_bf16 v[96:99], v[178:181], v[194:197], v[96:99]
	v_mfma_f32_16x16x32_bf16 v[88:91], v[170:173], v[202:205], v[88:91]
	v_mfma_f32_16x16x32_bf16 v[80:83], v[178:181], v[202:205], v[80:83]
	v_mfma_f32_16x16x32_bf16 v[72:75], v[170:173], v[210:213], v[72:75]
	v_mfma_f32_16x16x32_bf16 v[64:67], v[178:181], v[210:213], v[64:67]
	v_mfma_f32_16x16x32_bf16 v[120:123], v[174:177], v[190:193], v[120:123]
	v_mfma_f32_16x16x32_bf16 v[112:115], v[182:185], v[190:193], v[112:115]
	v_mfma_f32_16x16x32_bf16 v[104:107], v[174:177], v[198:201], v[104:107]
	v_mfma_f32_16x16x32_bf16 v[96:99], v[182:185], v[198:201], v[96:99]
	v_mfma_f32_16x16x32_bf16 v[88:91], v[174:177], v[206:209], v[88:91]
	v_mfma_f32_16x16x32_bf16 v[80:83], v[182:185], v[206:209], v[80:83]
	v_mfma_f32_16x16x32_bf16 v[72:75], v[174:177], v[214:217], v[72:75]
	v_mfma_f32_16x16x32_bf16 v[64:67], v[182:185], v[214:217], v[64:67]
	s_setprio 0
	s_barrier
; #define PG8_STAGE(bufoff, gbase, voff) do { _Pragma("unroll") for (int _i = 0; _i < 2; ++_i) \
;         __builtin_amdgcn_global_load_lds((const unsigned*)((const char*)(gbase) + (voff)[_i]), (PG8_LAS unsigned*)(lds + (bufoff) + ldsw + _i * 8192), 16, 0, 0); } while (0)
; #define PG8_LDA(dst, b, h) do { _Pragma("unroll") for (int m = 0; m < 4; ++m) _Pragma("unroll") for (int k = 0; k < 2; ++k) dst[m][k] = *(const PG8_LAS bf16x8*)(lds + PG8_SA(b, h) + aoff + m * 2048 + k * 1024); } while (0)
; #define PG8_LDB(dst, b, h) do { _Pragma("unroll") for (int n = 0; n < 2; ++n) _Pragma("unroll") for (int k = 0; k < 2; ++k) dst[n][k] = *(const PG8_LAS bf16x8*)(lds + PG8_SB(b, h) + boff + n * 2048 + k * 1024); } while (0)
; #define PG8_MMA(ai, bj, At, Bt) do { __builtin_amdgcn_s_setprio(1); _Pragma("unroll") for (int m = 0; m < 4; ++m) _Pragma("unroll") for (int n = 0; n < 2; ++n) _Pragma("unroll") for (int k = 0; k < 2; ++k) \
;         acc[ai][bj][m][n] = __builtin_amdgcn_mfma_f32_16x16x32_bf16(Bt[n][k], At[m][k], acc[ai][bj][m][n], 0, 0, 0); __builtin_amdgcn_s_setprio(0); } while (0)
; #define PG8_WAIT_V(n) asm volatile("s_waitcnt vmcnt(" #n ")" ::: "memory")
; #define PG8_WAIT_L(n) asm volatile("s_waitcnt lgkmcnt(" #n ")" ::: "memory")
; #define PG8_BAR __builtin_amdgcn_s_barrier()
; #define PG8_SCHED __builtin_amdgcn_sched_barrier(0)
; template <class Epi, class Sched, bool ALIGN_EPI = false, bool SP2 = false>
; __device__ __forceinline__ void gemm_phase(PG8_LAS unsigned char* lds, const Gemm g, const Sched& S, const Epi& E) {
;     ...
;             PG8_LDA(At, 0, 1); PG8_STAGE(PG8_SB(0, 0), b2, voffB); PG8_STAGE(PG8_SB(0, 1), b2 + hstep, voffB); PG8_STAGE(PG8_SA(0, 0), a2, voffA);
;             PG8_WAIT_V(8); PG8_WAIT_L(0); PG8_BAR; PG8_MMA(1, 0, At, B0); PG8_MMA(1, 1, At, B1); PG8_BAR; PG8_SCHED;
;             PG8_LDB(B0, 1, 0); PG8_LDB(B1, 1, 1); PG8_SCHED; PG8_LDA(At, 1, 0); PG8_STAGE(PG8_SA(0, 1), a2 + hstep, voffA);
	s_add_i32 s33, s62, s52
	s_add_u32 s82, s42, s10
	s_addc_u32 s83, s43, s11
	s_mov_b32 m0, s33
	ds_read_b128 v[186:189], v149 offset:16384
	ds_read_b128 v[190:193], v149 offset:17408
	ds_read_b128 v[194:197], v149 offset:18432
	ds_read_b128 v[198:201], v149 offset:19456
	ds_read_b128 v[202:205], v149 offset:20480
	ds_read_b128 v[206:209], v149 offset:21504
	ds_read_b128 v[210:213], v149 offset:22528
	ds_read_b128 v[214:217], v149 offset:23552
	global_load_lds_dwordx4 v130, s[42:43]
	s_add_i32 m0, s33, 0x2000
	s_add_u32 s78, s42, 0x40000
	s_addc_u32 s79, s43, 0
	s_add_i32 s33, s63, s52
	global_load_lds_dwordx4 v134, s[42:43]
	s_mov_b32 m0, s33
	s_add_u32 s84, s44, s10
	s_addc_u32 s85, s45, s11
	global_load_lds_dwordx4 v130, s[78:79]
	s_add_i32 m0, s33, 0x2000
	s_nop 0
	global_load_lds_dwordx4 v134, s[78:79]
	s_mov_b32 m0, s39
	s_nop 0
	global_load_lds_dwordx4 v128, s[44:45]
	s_mov_b32 m0, s55
	s_nop 0
	global_load_lds_dwordx4 v132, s[44:45]
	s_waitcnt vmcnt(8)
	s_waitcnt lgkmcnt(0)
	s_barrier
	s_setprio 1
	s_waitcnt lgkmcnt(0)
	v_mfma_f32_16x16x32_bf16 v[60:63], v[154:157], v[186:189], v[60:63]
	v_mfma_f32_16x16x32_bf16 v[52:55], v[162:165], v[186:189], v[52:55]
	v_mfma_f32_16x16x32_bf16 v[44:47], v[154:157], v[194:197], v[44:47]
	v_mfma_f32_16x16x32_bf16 v[36:39], v[162:165], v[194:197], v[36:39]
	v_mfma_f32_16x16x32_bf16 v[28:31], v[154:157], v[202:205], v[28:31]
	v_mfma_f32_16x16x32_bf16 v[20:23], v[162:165], v[202:205], v[20:23]
	v_mfma_f32_16x16x32_bf16 v[12:15], v[154:157], v[210:213], v[12:15]
	v_mfma_f32_16x16x32_bf16 v[4:7], v[162:165], v[210:213], v[4:7]
	v_mfma_f32_16x16x32_bf16 v[60:63], v[158:161], v[190:193], v[60:63]
	v_mfma_f32_16x16x32_bf16 v[52:55], v[166:169], v[190:193], v[52:55]
	v_mfma_f32_16x16x32_bf16 v[44:47], v[158:161], v[198:201], v[44:47]
	v_mfma_f32_16x16x32_bf16 v[36:39], v[166:169], v[198:201], v[36:39]
	v_mfma_f32_16x16x32_bf16 v[28:31], v[158:161], v[206:209], v[28:31]
	v_mfma_f32_16x16x32_bf16 v[20:23], v[166:169], v[206:209], v[20:23]
	v_mfma_f32_16x16x32_bf16 v[12:15], v[158:161], v[214:217], v[12:15]
	v_mfma_f32_16x16x32_bf16 v[4:7], v[166:169], v[214:217], v[4:7]
	v_mfma_f32_16x16x32_bf16 v[56:59], v[170:173], v[186:189], v[56:59]
	v_mfma_f32_16x16x32_bf16 v[48:51], v[178:181], v[186:189], v[48:51]
	v_mfma_f32_16x16x32_bf16 v[40:43], v[170:173], v[194:197], v[40:43]
	v_mfma_f32_16x16x32_bf16 v[32:35], v[178:181], v[194:197], v[32:35]
	v_mfma_f32_16x16x32_bf16 v[24:27], v[170:173], v[202:205], v[24:27]
	v_mfma_f32_16x16x32_bf16 v[16:19], v[178:181], v[202:205], v[16:19]
	v_mfma_f32_16x16x32_bf16 v[8:11], v[170:173], v[210:213], v[8:11]
	v_mfma_f32_16x16x32_bf16 v[0:3], v[178:181], v[210:213], v[0:3]
	v_mfma_f32_16x16x32_bf16 v[56:59], v[174:177], v[190:193], v[56:59]
	v_mfma_f32_16x16x32_bf16 v[48:51], v[182:185], v[190:193], v[48:51]
	v_mfma_f32_16x16x32_bf16 v[40:43], v[174:177], v[198:201], v[40:43]
	v_mfma_f32_16x16x32_bf16 v[32:35], v[182:185], v[198:201], v[32:35]
	v_mfma_f32_16x16x32_bf16 v[24:27], v[174:177], v[206:209], v[24:27]
	v_mfma_f32_16x16x32_bf16 v[16:19], v[182:185], v[206:209], v[16:19]
	v_mfma_f32_16x16x32_bf16 v[8:11], v[174:177], v[214:217], v[8:11]
	v_mfma_f32_16x16x32_bf16 v[0:3], v[182:185], v[214:217], v[0:3]
	s_setprio 0
	s_barrier
	s_add_i32 s33, 0, 0x18000
	v_add_u32_e32 v153, s33, v145
	s_add_i32 s34, 0, 0x1c000
	ds_read_b128 v[154:157], v153
	ds_read_b128 v[158:161], v153 offset:1024
	ds_read_b128 v[162:165], v153 offset:2048
	ds_read_b128 v[166:169], v153 offset:3072
	v_add_u32_e32 v153, s34, v145
	ds_read_b128 v[170:173], v153
	ds_read_b128 v[174:177], v153 offset:1024
	ds_read_b128 v[178:181], v153 offset:2048
	ds_read_b128 v[182:185], v153 offset:3072
	s_add_u32 s44, s44, 0x40000
	s_addc_u32 s45, s45, 0
	s_mov_b32 m0, s56
	ds_read_b128 v[186:189], v149 offset:32768
	ds_read_b128 v[190:193], v149 offset:33792
	ds_read_b128 v[194:197], v149 offset:34816
	ds_read_b128 v[198:201], v149 offset:35840
	ds_read_b128 v[202:205], v149 offset:36864
	ds_read_b128 v[206:209], v149 offset:37888
	ds_read_b128 v[210:213], v149 offset:38912
	ds_read_b128 v[214:217], v149 offset:39936
	global_load_lds_dwordx4 v128, s[44:45]
	s_mov_b32 m0, s57
	s_nop 0
	global_load_lds_dwordx4 v132, s[44:45]
	s_waitcnt vmcnt(8)
	s_waitcnt lgkmcnt(0)
	s_barrier
; #define PG8_STAGE(bufoff, gbase, voff) do { _Pragma("unroll") for (int _i = 0; _i < 2; ++_i) \
;         __builtin_amdgcn_global_load_lds((const unsigned*)((const char*)(gbase) + (voff)[_i]), (PG8_LAS unsigned*)(lds + (bufoff) + ldsw + _i * 8192), 16, 0, 0); } while (0)
; #define PG8_LDA(dst, b, h) do { _Pragma("unroll") for (int m = 0; m < 4; ++m) _Pragma("unroll") for (int k = 0; k < 2; ++k) dst[m][k] = *(const PG8_LAS bf16x8*)(lds + PG8_SA(b, h) + aoff + m * 2048 + k * 1024); } while (0)
; #define PG8_MMA(ai, bj, At, Bt) do { __builtin_amdgcn_s_setprio(1); _Pragma("unroll") for (int m = 0; m < 4; ++m) _Pragma("unroll") for (int n = 0; n < 2; ++n) _Pragma("unroll") for (int k = 0; k < 2; ++k) \
;         acc[ai][bj][m][n] = __builtin_amdgcn_mfma_f32_16x16x32_bf16(Bt[n][k], At[m][k], acc[ai][bj][m][n], 0, 0, 0); __builtin_amdgcn_s_setprio(0); } while (0)
; #define PG8_WAIT_V(n) asm volatile("s_waitcnt vmcnt(" #n ")" ::: "memory")
; #define PG8_WAIT_L(n) asm volatile("s_waitcnt lgkmcnt(" #n ")" ::: "memory")
; #define PG8_BAR __builtin_amdgcn_s_barrier()
; #define PG8_SCHED __builtin_amdgcn_sched_barrier(0)
; template <class Epi, class Sched, bool ALIGN_EPI = false, bool SP2 = false>
; __device__ __forceinline__ void gemm_phase(PG8_LAS unsigned char* lds, const Gemm g, const Sched& S, const Epi& E) {
;     ...
;             PG8_WAIT_V(8); PG8_WAIT_L(0); PG8_BAR; PG8_MMA(0, 0, At, B0); PG8_MMA(0, 1, At, B1); PG8_BAR; PG8_SCHED;
;             PG8_LDA(At, 1, 1); PG8_STAGE(PG8_SB(1, 0), b3, voffB); PG8_STAGE(PG8_SB(1, 1), b3 + hstep, voffB); PG8_STAGE(PG8_SA(1, 0), a3, voffA);
;             PG8_WAIT_V(8); PG8_WAIT_L(0); PG8_BAR; PG8_MMA(1, 0, At, B0); PG8_MMA(1, 1, At, B1); PG8_BAR; PG8_SCHED;
;     ...
;         if constexpr (ALIGN_EPI) { if (wr == 0) PG8_BAR; }
	s_setprio 1
	s_waitcnt lgkmcnt(0)
	v_mfma_f32_16x16x32_bf16 v[124:127], v[154:157], v[186:189], v[124:127]
	v_mfma_f32_16x16x32_bf16 v[116:119], v[162:165], v[186:189], v[116:119]
	v_mfma_f32_16x16x32_bf16 v[108:111], v[154:157], v[194:197], v[108:111]
	v_mfma_f32_16x16x32_bf16 v[100:103], v[162:165], v[194:197], v[100:103]
	v_mfma_f32_16x16x32_bf16 v[92:95], v[154:157], v[202:205], v[92:95]
	v_mfma_f32_16x16x32_bf16 v[84:87], v[162:165], v[202:205], v[84:87]
	v_mfma_f32_16x16x32_bf16 v[76:79], v[154:157], v[210:213], v[76:79]
	v_mfma_f32_16x16x32_bf16 v[68:71], v[162:165], v[210:213], v[68:71]
	v_mfma_f32_16x16x32_bf16 v[124:127], v[158:161], v[190:193], v[124:127]
	v_mfma_f32_16x16x32_bf16 v[116:119], v[166:169], v[190:193], v[116:119]
	v_mfma_f32_16x16x32_bf16 v[108:111], v[158:161], v[198:201], v[108:111]
	v_mfma_f32_16x16x32_bf16 v[100:103], v[166:169], v[198:201], v[100:103]
	v_mfma_f32_16x16x32_bf16 v[92:95], v[158:161], v[206:209], v[92:95]
	v_mfma_f32_16x16x32_bf16 v[84:87], v[166:169], v[206:209], v[84:87]
	v_mfma_f32_16x16x32_bf16 v[76:79], v[158:161], v[214:217], v[76:79]
	v_mfma_f32_16x16x32_bf16 v[68:71], v[166:169], v[214:217], v[68:71]
	v_mfma_f32_16x16x32_bf16 v[120:123], v[170:173], v[186:189], v[120:123]
	v_mfma_f32_16x16x32_bf16 v[112:115], v[178:181], v[186:189], v[112:115]
	v_mfma_f32_16x16x32_bf16 v[104:107], v[170:173], v[194:197], v[104:107]
	v_mfma_f32_16x16x32_bf16 v[96:99], v[178:181], v[194:197], v[96:99]
	v_mfma_f32_16x16x32_bf16 v[88:91], v[170:173], v[202:205], v[88:91]
	v_mfma_f32_16x16x32_bf16 v[80:83], v[178:181], v[202:205], v[80:83]
	v_mfma_f32_16x16x32_bf16 v[72:75], v[170:173], v[210:213], v[72:75]
	v_mfma_f32_16x16x32_bf16 v[64:67], v[178:181], v[210:213], v[64:67]
	v_mfma_f32_16x16x32_bf16 v[120:123], v[174:177], v[190:193], v[120:123]
	v_mfma_f32_16x16x32_bf16 v[112:115], v[182:185], v[190:193], v[112:115]
	v_mfma_f32_16x16x32_bf16 v[104:107], v[174:177], v[198:201], v[104:107]
	v_mfma_f32_16x16x32_bf16 v[96:99], v[182:185], v[198:201], v[96:99]
	v_mfma_f32_16x16x32_bf16 v[88:91], v[174:177], v[206:209], v[88:91]
	v_mfma_f32_16x16x32_bf16 v[80:83], v[182:185], v[206:209], v[80:83]
	v_mfma_f32_16x16x32_bf16 v[72:75], v[174:177], v[214:217], v[72:75]
	v_mfma_f32_16x16x32_bf16 v[64:67], v[182:185], v[214:217], v[64:67]
	s_setprio 0
	s_barrier
	s_add_i32 s33, s33, s52
	s_mov_b32 m0, s33
	ds_read_b128 v[186:189], v149 offset:49152
	ds_read_b128 v[190:193], v149 offset:50176
	ds_read_b128 v[194:197], v149 offset:51200
	ds_read_b128 v[198:201], v149 offset:52224
	ds_read_b128 v[202:205], v149 offset:53248
	ds_read_b128 v[206:209], v149 offset:54272
	ds_read_b128 v[210:213], v149 offset:55296
	ds_read_b128 v[214:217], v149 offset:56320
	global_load_lds_dwordx4 v130, s[82:83]
	s_add_i32 m0, s33, 0x2000
	s_add_u32 s42, s42, 0x40080
	s_addc_u32 s43, s43, 0
	s_add_i32 s33, s34, s52
	global_load_lds_dwordx4 v134, s[82:83]
	s_mov_b32 m0, s33
	s_nop 0
	global_load_lds_dwordx4 v130, s[42:43]
	s_add_i32 m0, s33, 0x2000
	s_nop 0
	global_load_lds_dwordx4 v134, s[42:43]
	s_mov_b32 m0, s60
	s_nop 0
	global_load_lds_dwordx4 v128, s[84:85]
	s_mov_b32 m0, s61
	s_nop 0
	global_load_lds_dwordx4 v132, s[84:85]
	s_waitcnt vmcnt(8)
	s_waitcnt lgkmcnt(0)
	s_barrier
	s_setprio 1
	s_waitcnt lgkmcnt(0)
	v_mfma_f32_16x16x32_bf16 v[60:63], v[154:157], v[186:189], v[60:63]
	v_mfma_f32_16x16x32_bf16 v[52:55], v[162:165], v[186:189], v[52:55]
	v_mfma_f32_16x16x32_bf16 v[44:47], v[154:157], v[194:197], v[44:47]
	v_mfma_f32_16x16x32_bf16 v[36:39], v[162:165], v[194:197], v[36:39]
	v_mfma_f32_16x16x32_bf16 v[28:31], v[154:157], v[202:205], v[28:31]
	v_mfma_f32_16x16x32_bf16 v[20:23], v[162:165], v[202:205], v[20:23]
	v_mfma_f32_16x16x32_bf16 v[12:15], v[154:157], v[210:213], v[12:15]
	v_mfma_f32_16x16x32_bf16 v[4:7], v[162:165], v[210:213], v[4:7]
	v_mfma_f32_16x16x32_bf16 v[60:63], v[158:161], v[190:193], v[60:63]
	v_mfma_f32_16x16x32_bf16 v[52:55], v[166:169], v[190:193], v[52:55]
	v_mfma_f32_16x16x32_bf16 v[44:47], v[158:161], v[198:201], v[44:47]
	v_mfma_f32_16x16x32_bf16 v[36:39], v[166:169], v[198:201], v[36:39]
	v_mfma_f32_16x16x32_bf16 v[28:31], v[158:161], v[206:209], v[28:31]
	v_mfma_f32_16x16x32_bf16 v[20:23], v[166:169], v[206:209], v[20:23]
	v_mfma_f32_16x16x32_bf16 v[12:15], v[158:161], v[214:217], v[12:15]
	v_mfma_f32_16x16x32_bf16 v[4:7], v[166:169], v[214:217], v[4:7]
	v_mfma_f32_16x16x32_bf16 v[56:59], v[170:173], v[186:189], v[56:59]
	v_mfma_f32_16x16x32_bf16 v[48:51], v[178:181], v[186:189], v[48:51]
	v_mfma_f32_16x16x32_bf16 v[40:43], v[170:173], v[194:197], v[40:43]
	v_mfma_f32_16x16x32_bf16 v[32:35], v[178:181], v[194:197], v[32:35]
	v_mfma_f32_16x16x32_bf16 v[24:27], v[170:173], v[202:205], v[24:27]
	v_mfma_f32_16x16x32_bf16 v[16:19], v[178:181], v[202:205], v[16:19]
	v_mfma_f32_16x16x32_bf16 v[8:11], v[170:173], v[210:213], v[8:11]
	v_mfma_f32_16x16x32_bf16 v[0:3], v[178:181], v[210:213], v[0:3]
	v_mfma_f32_16x16x32_bf16 v[56:59], v[174:177], v[190:193], v[56:59]
	v_mfma_f32_16x16x32_bf16 v[48:51], v[182:185], v[190:193], v[48:51]
	v_mfma_f32_16x16x32_bf16 v[40:43], v[174:177], v[198:201], v[40:43]
	v_mfma_f32_16x16x32_bf16 v[32:35], v[182:185], v[198:201], v[32:35]
	v_mfma_f32_16x16x32_bf16 v[24:27], v[174:177], v[206:209], v[24:27]
	v_mfma_f32_16x16x32_bf16 v[16:19], v[182:185], v[206:209], v[16:19]
	v_mfma_f32_16x16x32_bf16 v[8:11], v[174:177], v[214:217], v[8:11]
	v_mfma_f32_16x16x32_bf16 v[0:3], v[182:185], v[214:217], v[0:3]
	s_setprio 0
	s_barrier
	s_add_i32 s76, s76, 2
	s_add_u32 s40, s40, 0x100
	s_addc_u32 s41, s41, 0
	s_add_u32 s74, s74, 0x100
	s_addc_u32 s75, s75, 0
	s_cmp_gt_u32 s76, 13
	s_cbranch_scc0 .LBB0_714
	s_and_b64 vcc, exec, s[12:13]
	s_cbranch_vccz .LBB0_717
	s_barrier

; #define PG8_STAGE(bufoff, gbase, voff) do { _Pragma("unroll") for (int _i = 0; _i < 2; ++_i) \
;         __builtin_amdgcn_global_load_lds((const unsigned*)((const char*)(gbase) + (voff)[_i]), (PG8_LAS unsigned*)(lds + (bufoff) + ldsw + _i * 8192), 16, 0, 0); } while (0)
; #define PG8_LDA(dst, b, h) do { _Pragma("unroll") for (int m = 0; m < 4; ++m) _Pragma("unroll") for (int k = 0; k < 2; ++k) dst[m][k] = *(const PG8_LAS bf16x8*)(lds + PG8_SA(b, h) + aoff + m * 2048 + k * 1024); } while (0)
; #define PG8_LDB(dst, b, h) do { _Pragma("unroll") for (int n = 0; n < 2; ++n) _Pragma("unroll") for (int k = 0; k < 2; ++k) dst[n][k] = *(const PG8_LAS bf16x8*)(lds + PG8_SB(b, h) + boff + n * 2048 + k * 1024); } while (0)
; #define PG8_MMA(ai, bj, At, Bt) do { __builtin_amdgcn_s_setprio(1); _Pragma("unroll") for (int m = 0; m < 4; ++m) _Pragma("unroll") for (int n = 0; n < 2; ++n) _Pragma("unroll") for (int k = 0; k < 2; ++k) \
;         acc[ai][bj][m][n] = __builtin_amdgcn_mfma_f32_16x16x32_bf16(Bt[n][k], At[m][k], acc[ai][bj][m][n], 0, 0, 0); __builtin_amdgcn_s_setprio(0); } while (0)
; #define PG8_WAIT_V(n) asm volatile("s_waitcnt vmcnt(" #n ")" ::: "memory")
; #define PG8_WAIT_L(n) asm volatile("s_waitcnt lgkmcnt(" #n ")" ::: "memory")
; template <class Epi, class Sched, bool ALIGN_EPI = false, bool SP2 = false>
; __device__ __forceinline__ void gemm_phase(PG8_LAS unsigned char* lds, const Gemm g, const Sched& S, const Epi& E) {
;     ...
;             const bool last = (t == nt - 2);
;             const char* a1 = cA + (size_t)(t + 1) * kstep;
;             const char* a2 = last ? nA : cA + (size_t)(t + 2) * kstep; const char* b2 = last ? nB : cB + (size_t)(t + 2) * kstep;
;             const char* a3 = a2 + kstep; const char* b3 = b2 + kstep;
;             if (last && has_next) S.a_ready(nxt);
;             if constexpr (SP2) {
;             PG8_LDB(B0, 0, 0); PG8_LDB(B1, 0, 1); PG8_SCHED; PG8_LDA(At, 0, 0); PG8_STAGE(PG8_SA(1, 1), a1 + hstep, voffA);
;             PG8_WAIT_V(8); PG8_WAIT_L(0); PG8_BAR; PG8_MMA(0, 0, At, B0); PG8_MMA(0, 1, At, B1); PG8_BAR; PG8_SCHED;
;             PG8_LDA(At, 0, 1); PG8_STAGE(PG8_SB(0, 0), b2, voffB); PG8_STAGE(PG8_SB(0, 1), b2 + hstep, voffB); PG8_STAGE(PG8_SA(0, 0), a2, voffA);
;             PG8_WAIT_V(8); PG8_WAIT_L(0); PG8_BAR; PG8_MMA(1, 0, At, B0); PG8_MMA(1, 1, At, B1); PG8_BAR; PG8_SCHED;
.LBB0_788:
	s_add_u32 s42, s42, 0xb0080
	s_addc_u32 s43, s43, 0
	s_add_u32 s86, s44, 0x100
	s_addc_u32 s87, s45, 0
	s_mov_b32 s90, -2
	s_waitcnt lgkmcnt(0)
	s_waitcnt vmcnt(0)
	s_add_u32 s33, s42, 0xfff50080
	s_addc_u32 s34, s43, -1
	s_cmp_eq_u32 s90, 40
	s_cselect_b32 s47, s5, s34
	s_cselect_b32 s46, s4, s33
	s_cselect_b32 s45, s41, s87
	s_cselect_b32 s44, s40, s86
	s_add_i32 m0, s58, 0xc000
	global_load_lds_dwordx4 v162, s[42:43]
	s_add_i32 m0, s58, 0xe000
	s_nop 0
	global_load_lds_dwordx4 v164, s[42:43]
	s_waitcnt vmcnt(8)
	s_waitcnt lgkmcnt(0)
	s_barrier
	s_setprio 1
	s_waitcnt lgkmcnt(0)
	v_mfma_f32_16x16x32_bf16 v[124:127], v[128:131], v[178:181], 0
	v_mfma_f32_16x16x32_bf16 v[120:123], v[136:139], v[178:181], 0
	v_mfma_f32_16x16x32_bf16 v[116:119], v[128:131], v[186:189], 0
	v_mfma_f32_16x16x32_bf16 v[112:115], v[136:139], v[186:189], 0
	v_mfma_f32_16x16x32_bf16 v[108:111], v[128:131], v[194:197], 0
	v_mfma_f32_16x16x32_bf16 v[104:107], v[136:139], v[194:197], 0
	v_mfma_f32_16x16x32_bf16 v[100:103], v[128:131], v[210:213], 0
	v_mfma_f32_16x16x32_bf16 v[96:99], v[136:139], v[210:213], 0
	v_mfma_f32_16x16x32_bf16 v[124:127], v[132:135], v[182:185], v[124:127]
	v_mfma_f32_16x16x32_bf16 v[120:123], v[140:143], v[182:185], v[120:123]
	v_mfma_f32_16x16x32_bf16 v[116:119], v[132:135], v[190:193], v[116:119]
	v_mfma_f32_16x16x32_bf16 v[112:115], v[140:143], v[190:193], v[112:115]
	v_mfma_f32_16x16x32_bf16 v[108:111], v[132:135], v[206:209], v[108:111]
	v_mfma_f32_16x16x32_bf16 v[104:107], v[140:143], v[206:209], v[104:107]
	v_mfma_f32_16x16x32_bf16 v[100:103], v[132:135], v[214:217], v[100:103]
	v_mfma_f32_16x16x32_bf16 v[96:99], v[140:143], v[214:217], v[96:99]
	v_mfma_f32_16x16x32_bf16 v[68:71], v[144:147], v[178:181], 0
	v_mfma_f32_16x16x32_bf16 v[64:67], v[170:173], v[178:181], 0
	v_mfma_f32_16x16x32_bf16 v[60:63], v[144:147], v[186:189], 0
	v_mfma_f32_16x16x32_bf16 v[52:55], v[170:173], v[186:189], 0
	v_mfma_f32_16x16x32_bf16 v[44:47], v[144:147], v[194:197], 0
	v_mfma_f32_16x16x32_bf16 v[40:43], v[170:173], v[194:197], 0
	v_mfma_f32_16x16x32_bf16 v[36:39], v[144:147], v[210:213], 0
	v_mfma_f32_16x16x32_bf16 v[32:35], v[170:173], v[210:213], 0
	v_mfma_f32_16x16x32_bf16 v[68:71], v[148:151], v[182:185], v[68:71]
	v_mfma_f32_16x16x32_bf16 v[64:67], v[174:177], v[182:185], v[64:67]
	v_mfma_f32_16x16x32_bf16 v[60:63], v[148:151], v[190:193], v[60:63]
	v_mfma_f32_16x16x32_bf16 v[52:55], v[174:177], v[190:193], v[52:55]
	v_mfma_f32_16x16x32_bf16 v[44:47], v[148:151], v[206:209], v[44:47]
	v_mfma_f32_16x16x32_bf16 v[40:43], v[174:177], v[206:209], v[40:43]
	v_mfma_f32_16x16x32_bf16 v[36:39], v[148:151], v[214:217], v[36:39]
	v_mfma_f32_16x16x32_bf16 v[32:35], v[174:177], v[214:217], v[32:35]
	s_setprio 0
	s_barrier
	s_add_i32 s33, s74, s56
	s_add_u32 s64, s44, s12
	s_addc_u32 s65, s45, s13
	s_mov_b32 m0, s33
	ds_read_b128 v[178:181], v205 offset:16384
	ds_read_b128 v[182:185], v205 offset:17408
	ds_read_b128 v[186:189], v205 offset:18432
	ds_read_b128 v[190:193], v205 offset:19456
	ds_read_b128 v[194:197], v205 offset:20480
	ds_read_b128 v[206:209], v205 offset:21504
	ds_read_b128 v[210:213], v205 offset:22528
	ds_read_b128 v[214:217], v205 offset:23552
	global_load_lds_dwordx4 v156, s[44:45]
	s_add_i32 m0, s33, 0x2000
	s_add_u32 s92, s44, 0xb0000
	s_addc_u32 s93, s45, 0
	s_add_i32 s33, s75, s56
	global_load_lds_dwordx4 v160, s[44:45]
	s_mov_b32 m0, s33
	s_add_u32 s84, s46, s12
	s_addc_u32 s85, s47, s13
	global_load_lds_dwordx4 v156, s[92:93]
	s_add_i32 m0, s33, 0x2000
	s_nop 0
	global_load_lds_dwordx4 v160, s[92:93]
	s_mov_b32 m0, s58
	s_nop 0
	global_load_lds_dwordx4 v154, s[46:47]
	s_mov_b32 m0, s59
	s_nop 0
	global_load_lds_dwordx4 v158, s[46:47]
	s_waitcnt vmcnt(8)
	s_waitcnt lgkmcnt(0)
	s_barrier
	s_setprio 1
	s_waitcnt lgkmcnt(0)
	v_mfma_f32_16x16x32_bf16 v[92:95], v[128:131], v[178:181], 0
	v_mfma_f32_16x16x32_bf16 v[88:91], v[136:139], v[178:181], 0
	v_mfma_f32_16x16x32_bf16 v[84:87], v[128:131], v[186:189], 0
	v_mfma_f32_16x16x32_bf16 v[80:83], v[136:139], v[186:189], 0
	v_mfma_f32_16x16x32_bf16 v[76:79], v[128:131], v[194:197], 0
	v_mfma_f32_16x16x32_bf16 v[72:75], v[136:139], v[194:197], 0
	v_mfma_f32_16x16x32_bf16 v[56:59], v[128:131], v[210:213], 0
	v_mfma_f32_16x16x32_bf16 v[48:51], v[136:139], v[210:213], 0
	v_mfma_f32_16x16x32_bf16 v[92:95], v[132:135], v[182:185], v[92:95]
	v_mfma_f32_16x16x32_bf16 v[88:91], v[140:143], v[182:185], v[88:91]
	v_mfma_f32_16x16x32_bf16 v[84:87], v[132:135], v[190:193], v[84:87]
	v_mfma_f32_16x16x32_bf16 v[80:83], v[140:143], v[190:193], v[80:83]
	v_mfma_f32_16x16x32_bf16 v[76:79], v[132:135], v[206:209], v[76:79]
	v_mfma_f32_16x16x32_bf16 v[72:75], v[140:143], v[206:209], v[72:75]
	v_mfma_f32_16x16x32_bf16 v[56:59], v[132:135], v[214:217], v[56:59]
	v_mfma_f32_16x16x32_bf16 v[48:51], v[140:143], v[214:217], v[48:51]
	v_mfma_f32_16x16x32_bf16 v[28:31], v[144:147], v[178:181], 0
	v_mfma_f32_16x16x32_bf16 v[24:27], v[170:173], v[178:181], 0
	v_mfma_f32_16x16x32_bf16 v[20:23], v[144:147], v[186:189], 0
	v_mfma_f32_16x16x32_bf16 v[16:19], v[170:173], v[186:189], 0
	v_mfma_f32_16x16x32_bf16 v[12:15], v[144:147], v[194:197], 0
	v_mfma_f32_16x16x32_bf16 v[8:11], v[170:173], v[194:197], 0
	v_mfma_f32_16x16x32_bf16 v[4:7], v[144:147], v[210:213], 0
	v_mfma_f32_16x16x32_bf16 v[0:3], v[170:173], v[210:213], 0
	v_mfma_f32_16x16x32_bf16 v[28:31], v[148:151], v[182:185], v[28:31]
	v_mfma_f32_16x16x32_bf16 v[24:27], v[174:177], v[182:185], v[24:27]
	v_mfma_f32_16x16x32_bf16 v[20:23], v[148:151], v[190:193], v[20:23]
	v_mfma_f32_16x16x32_bf16 v[16:19], v[174:177], v[190:193], v[16:19]
	v_mfma_f32_16x16x32_bf16 v[12:15], v[148:151], v[206:209], v[12:15]
	v_mfma_f32_16x16x32_bf16 v[8:11], v[174:177], v[206:209], v[8:11]
	v_mfma_f32_16x16x32_bf16 v[4:7], v[148:151], v[214:217], v[4:7]
	v_mfma_f32_16x16x32_bf16 v[0:3], v[174:177], v[214:217], v[0:3]
	s_setprio 0
	s_barrier
; #define PG8_STAGE(bufoff, gbase, voff) do { _Pragma("unroll") for (int _i = 0; _i < 2; ++_i) \
;         __builtin_amdgcn_global_load_lds((const unsigned*)((const char*)(gbase) + (voff)[_i]), (PG8_LAS unsigned*)(lds + (bufoff) + ldsw + _i * 8192), 16, 0, 0); } while (0)
; #define PG8_LDA(dst, b, h) do { _Pragma("unroll") for (int m = 0; m < 4; ++m) _Pragma("unroll") for (int k = 0; k < 2; ++k) dst[m][k] = *(const PG8_LAS bf16x8*)(lds + PG8_SA(b, h) + aoff + m * 2048 + k * 1024); } while (0)
; #define PG8_LDB(dst, b, h) do { _Pragma("unroll") for (int n = 0; n < 2; ++n) _Pragma("unroll") for (int k = 0; k < 2; ++k) dst[n][k] = *(const PG8_LAS bf16x8*)(lds + PG8_SB(b, h) + boff + n * 2048 + k * 1024); } while (0)
; #define PG8_MMA(ai, bj, At, Bt) do { __builtin_amdgcn_s_setprio(1); _Pragma("unroll") for (int m = 0; m < 4; ++m) _Pragma("unroll") for (int n = 0; n < 2; ++n) _Pragma("unroll") for (int k = 0; k < 2; ++k) \
;         acc[ai][bj][m][n] = __builtin_amdgcn_mfma_f32_16x16x32_bf16(Bt[n][k], At[m][k], acc[ai][bj][m][n], 0, 0, 0); __builtin_amdgcn_s_setprio(0); } while (0)
; #define PG8_WAIT_V(n) asm volatile("s_waitcnt vmcnt(" #n ")" ::: "memory")
; #define PG8_WAIT_L(n) asm volatile("s_waitcnt lgkmcnt(" #n ")" ::: "memory")
; #define PG8_BAR __builtin_amdgcn_s_barrier()
; #define PG8_SCHED __builtin_amdgcn_sched_barrier(0)
; template <class Epi, class Sched, bool ALIGN_EPI = false, bool SP2 = false>
; __device__ __forceinline__ void gemm_phase(PG8_LAS unsigned char* lds, const Gemm g, const Sched& S, const Epi& E) {
;     ...
;             PG8_LDB(B0, 1, 0); PG8_LDB(B1, 1, 1); PG8_SCHED; PG8_LDA(At, 1, 0); PG8_STAGE(PG8_SA(0, 1), a2 + hstep, voffA);
;             PG8_WAIT_V(8); PG8_WAIT_L(0); PG8_BAR; PG8_MMA(0, 0, At, B0); PG8_MMA(0, 1, At, B1); PG8_BAR; PG8_SCHED;
;             PG8_LDA(At, 1, 1); PG8_STAGE(PG8_SB(1, 0), b3, voffB); PG8_STAGE(PG8_SB(1, 1), b3 + hstep, voffB); PG8_STAGE(PG8_SA(1, 0), a3, voffA);
;             PG8_WAIT_V(8); PG8_WAIT_L(0); PG8_BAR; PG8_MMA(1, 0, At, B0); PG8_MMA(1, 1, At, B1); PG8_BAR; PG8_SCHED;
	s_add_i32 s33, 0, 0x18000
	s_add_i32 s34, 0, 0x1c000
	v_add_u32_e32 v140, s33, v201
	v_add_u32_e32 v153, s34, v201
	ds_read_b128 v[128:131], v140
	ds_read_b128 v[132:135], v140 offset:1024
	ds_read_b128 v[136:139], v140 offset:2048
	ds_read_b128 v[140:143], v140 offset:3072
	ds_read_b128 v[144:147], v153
	ds_read_b128 v[148:151], v153 offset:1024
	ds_read_b128 v[170:173], v153 offset:2048
	ds_read_b128 v[174:177], v153 offset:3072
	s_add_u32 s46, s46, 0xb0000
	s_addc_u32 s47, s47, 0
	s_mov_b32 m0, s60
	ds_read_b128 v[178:181], v205 offset:32768
	ds_read_b128 v[182:185], v205 offset:33792
	ds_read_b128 v[186:189], v205 offset:34816
	ds_read_b128 v[190:193], v205 offset:35840
	ds_read_b128 v[194:197], v205 offset:36864
	ds_read_b128 v[206:209], v205 offset:37888
	ds_read_b128 v[210:213], v205 offset:38912
	ds_read_b128 v[214:217], v205 offset:39936
	global_load_lds_dwordx4 v154, s[46:47]
	s_mov_b32 m0, s61
	s_nop 0
	global_load_lds_dwordx4 v158, s[46:47]
	s_waitcnt vmcnt(8)
	s_waitcnt lgkmcnt(0)
	s_barrier
	s_setprio 1
	s_waitcnt lgkmcnt(0)
	v_mfma_f32_16x16x32_bf16 v[124:127], v[128:131], v[178:181], v[124:127]
	v_mfma_f32_16x16x32_bf16 v[120:123], v[136:139], v[178:181], v[120:123]
	v_mfma_f32_16x16x32_bf16 v[116:119], v[128:131], v[186:189], v[116:119]
	v_mfma_f32_16x16x32_bf16 v[112:115], v[136:139], v[186:189], v[112:115]
	v_mfma_f32_16x16x32_bf16 v[108:111], v[128:131], v[194:197], v[108:111]
	v_mfma_f32_16x16x32_bf16 v[104:107], v[136:139], v[194:197], v[104:107]
	v_mfma_f32_16x16x32_bf16 v[100:103], v[128:131], v[210:213], v[100:103]
	v_mfma_f32_16x16x32_bf16 v[96:99], v[136:139], v[210:213], v[96:99]
	v_mfma_f32_16x16x32_bf16 v[124:127], v[132:135], v[182:185], v[124:127]
	v_mfma_f32_16x16x32_bf16 v[120:123], v[140:143], v[182:185], v[120:123]
	v_mfma_f32_16x16x32_bf16 v[116:119], v[132:135], v[190:193], v[116:119]
	v_mfma_f32_16x16x32_bf16 v[112:115], v[140:143], v[190:193], v[112:115]
	v_mfma_f32_16x16x32_bf16 v[108:111], v[132:135], v[206:209], v[108:111]
	v_mfma_f32_16x16x32_bf16 v[104:107], v[140:143], v[206:209], v[104:107]
	v_mfma_f32_16x16x32_bf16 v[100:103], v[132:135], v[214:217], v[100:103]
	v_mfma_f32_16x16x32_bf16 v[96:99], v[140:143], v[214:217], v[96:99]
	v_mfma_f32_16x16x32_bf16 v[68:71], v[144:147], v[178:181], v[68:71]
	v_mfma_f32_16x16x32_bf16 v[64:67], v[170:173], v[178:181], v[64:67]
	v_mfma_f32_16x16x32_bf16 v[60:63], v[144:147], v[186:189], v[60:63]
	v_mfma_f32_16x16x32_bf16 v[52:55], v[170:173], v[186:189], v[52:55]
	v_mfma_f32_16x16x32_bf16 v[44:47], v[144:147], v[194:197], v[44:47]
	v_mfma_f32_16x16x32_bf16 v[40:43], v[170:173], v[194:197], v[40:43]
	v_mfma_f32_16x16x32_bf16 v[36:39], v[144:147], v[210:213], v[36:39]
	v_mfma_f32_16x16x32_bf16 v[32:35], v[170:173], v[210:213], v[32:35]
	v_mfma_f32_16x16x32_bf16 v[68:71], v[148:151], v[182:185], v[68:71]
	v_mfma_f32_16x16x32_bf16 v[64:67], v[174:177], v[182:185], v[64:67]
	v_mfma_f32_16x16x32_bf16 v[60:63], v[148:151], v[190:193], v[60:63]
	v_mfma_f32_16x16x32_bf16 v[52:55], v[174:177], v[190:193], v[52:55]
	v_mfma_f32_16x16x32_bf16 v[44:47], v[148:151], v[206:209], v[44:47]
	v_mfma_f32_16x16x32_bf16 v[40:43], v[174:177], v[206:209], v[40:43]
	v_mfma_f32_16x16x32_bf16 v[36:39], v[148:151], v[214:217], v[36:39]
	v_mfma_f32_16x16x32_bf16 v[32:35], v[174:177], v[214:217], v[32:35]
	s_setprio 0
	s_barrier
	s_add_i32 s33, s33, s56
	s_mov_b32 m0, s33
	ds_read_b128 v[178:181], v205 offset:49152
	ds_read_b128 v[182:185], v205 offset:50176
	ds_read_b128 v[186:189], v205 offset:51200
	ds_read_b128 v[190:193], v205 offset:52224
	ds_read_b128 v[194:197], v205 offset:53248
	ds_read_b128 v[206:209], v205 offset:54272
	ds_read_b128 v[210:213], v205 offset:55296
	ds_read_b128 v[214:217], v205 offset:56320
	global_load_lds_dwordx4 v156, s[64:65]
	s_add_i32 m0, s33, 0x2000
	s_add_u32 s44, s44, 0xb0080
	s_addc_u32 s45, s45, 0
	s_add_i32 s33, s34, s56
	global_load_lds_dwordx4 v160, s[64:65]
	s_mov_b32 m0, s33
	s_nop 0
	global_load_lds_dwordx4 v156, s[44:45]
	s_add_i32 m0, s33, 0x2000
	s_nop 0
	global_load_lds_dwordx4 v160, s[44:45]
	s_mov_b32 m0, s72
	s_nop 0
	global_load_lds_dwordx4 v154, s[84:85]
	s_mov_b32 m0, s73
	s_nop 0
	global_load_lds_dwordx4 v158, s[84:85]
	s_waitcnt vmcnt(8)
	s_waitcnt lgkmcnt(0)
	s_barrier
	s_setprio 1
	s_waitcnt lgkmcnt(0)
	v_mfma_f32_16x16x32_bf16 v[92:95], v[128:131], v[178:181], v[92:95]
	v_mfma_f32_16x16x32_bf16 v[88:91], v[136:139], v[178:181], v[88:91]
	v_mfma_f32_16x16x32_bf16 v[84:87], v[128:131], v[186:189], v[84:87]
	v_mfma_f32_16x16x32_bf16 v[80:83], v[136:139], v[186:189], v[80:83]
	v_mfma_f32_16x16x32_bf16 v[76:79], v[128:131], v[194:197], v[76:79]
	v_mfma_f32_16x16x32_bf16 v[72:75], v[136:139], v[194:197], v[72:75]
	v_mfma_f32_16x16x32_bf16 v[56:59], v[128:131], v[210:213], v[56:59]
	v_mfma_f32_16x16x32_bf16 v[48:51], v[136:139], v[210:213], v[48:51]
	v_mfma_f32_16x16x32_bf16 v[92:95], v[132:135], v[182:185], v[92:95]
	v_mfma_f32_16x16x32_bf16 v[88:91], v[140:143], v[182:185], v[88:91]
	v_mfma_f32_16x16x32_bf16 v[84:87], v[132:135], v[190:193], v[84:87]
	v_mfma_f32_16x16x32_bf16 v[80:83], v[140:143], v[190:193], v[80:83]
	v_mfma_f32_16x16x32_bf16 v[76:79], v[132:135], v[206:209], v[76:79]
	v_mfma_f32_16x16x32_bf16 v[72:75], v[140:143], v[206:209], v[72:75]
	v_mfma_f32_16x16x32_bf16 v[56:59], v[132:135], v[214:217], v[56:59]
	v_mfma_f32_16x16x32_bf16 v[48:51], v[140:143], v[214:217], v[48:51]
	v_mfma_f32_16x16x32_bf16 v[28:31], v[144:147], v[178:181], v[28:31]
	v_mfma_f32_16x16x32_bf16 v[24:27], v[170:173], v[178:181], v[24:27]
	v_mfma_f32_16x16x32_bf16 v[20:23], v[144:147], v[186:189], v[20:23]
	v_mfma_f32_16x16x32_bf16 v[16:19], v[170:173], v[186:189], v[16:19]
	v_mfma_f32_16x16x32_bf16 v[12:15], v[144:147], v[194:197], v[12:15]
	v_mfma_f32_16x16x32_bf16 v[8:11], v[170:173], v[194:197], v[8:11]
	v_mfma_f32_16x16x32_bf16 v[4:7], v[144:147], v[210:213], v[4:7]
	v_mfma_f32_16x16x32_bf16 v[0:3], v[170:173], v[210:213], v[0:3]
	v_mfma_f32_16x16x32_bf16 v[28:31], v[148:151], v[182:185], v[28:31]
	v_mfma_f32_16x16x32_bf16 v[24:27], v[174:177], v[182:185], v[24:27]
	v_mfma_f32_16x16x32_bf16 v[20:23], v[148:151], v[190:193], v[20:23]
	v_mfma_f32_16x16x32_bf16 v[16:19], v[174:177], v[190:193], v[16:19]
	v_mfma_f32_16x16x32_bf16 v[12:15], v[148:151], v[206:209], v[12:15]
	v_mfma_f32_16x16x32_bf16 v[8:11], v[174:177], v[206:209], v[8:11]
	v_mfma_f32_16x16x32_bf16 v[4:7], v[148:151], v[214:217], v[4:7]
	v_mfma_f32_16x16x32_bf16 v[0:3], v[174:177], v[214:217], v[0:3]
	s_setprio 0
	s_barrier
	s_add_i32 s90, s90, 2
	s_add_u32 s42, s42, 0x100
	s_addc_u32 s43, s43, 0
	s_add_u32 s86, s86, 0x100
	s_addc_u32 s87, s87, 0
	s_cmp_gt_u32 s90, 41
; #define PG8_STAGE(bufoff, gbase, voff) do { _Pragma("unroll") for (int _i = 0; _i < 2; ++_i) \
;         __builtin_amdgcn_global_load_lds((const unsigned*)((const char*)(gbase) + (voff)[_i]), (PG8_LAS unsigned*)(lds + (bufoff) + ldsw + _i * 8192), 16, 0, 0); } while (0)
; #define PG8_LDA(dst, b, h) do { _Pragma("unroll") for (int m = 0; m < 4; ++m) _Pragma("unroll") for (int k = 0; k < 2; ++k) dst[m][k] = *(const PG8_LAS bf16x8*)(lds + PG8_SA(b, h) + aoff + m * 2048 + k * 1024); } while (0)
; #define PG8_LDB(dst, b, h) do { _Pragma("unroll") for (int n = 0; n < 2; ++n) _Pragma("unroll") for (int k = 0; k < 2; ++k) dst[n][k] = *(const PG8_LAS bf16x8*)(lds + PG8_SB(b, h) + boff + n * 2048 + k * 1024); } while (0)
; #define PG8_MMA(ai, bj, At, Bt) do { __builtin_amdgcn_s_setprio(1); _Pragma("unroll") for (int m = 0; m < 4; ++m) _Pragma("unroll") for (int n = 0; n < 2; ++n) _Pragma("unroll") for (int k = 0; k < 2; ++k) \
;         acc[ai][bj][m][n] = __builtin_amdgcn_mfma_f32_16x16x32_bf16(Bt[n][k], At[m][k], acc[ai][bj][m][n], 0, 0, 0); __builtin_amdgcn_s_setprio(0); } while (0)
; #define PG8_WAIT_V(n) asm volatile("s_waitcnt vmcnt(" #n ")" ::: "memory")
; #define PG8_WAIT_L(n) asm volatile("s_waitcnt lgkmcnt(" #n ")" ::: "memory")
; template <class Epi, class Sched, bool ALIGN_EPI = false, bool SP2 = false>
; __device__ __forceinline__ void gemm_phase(PG8_LAS unsigned char* lds, const Gemm g, const Sched& S, const Epi& E) {
;     ...
;             const bool last = (t == nt - 2);
;             const char* a1 = cA + (size_t)(t + 1) * kstep;
;             const char* a2 = last ? nA : cA + (size_t)(t + 2) * kstep; const char* b2 = last ? nB : cB + (size_t)(t + 2) * kstep;
;             const char* a3 = a2 + kstep; const char* b3 = b2 + kstep;
;             if (last && has_next) S.a_ready(nxt);
;             if constexpr (SP2) {
;             PG8_LDB(B0, 0, 0); PG8_LDB(B1, 0, 1); PG8_SCHED; PG8_LDA(At, 0, 0); PG8_STAGE(PG8_SA(1, 1), a1 + hstep, voffA);
;             PG8_WAIT_V(8); PG8_WAIT_L(0); PG8_BAR; PG8_MMA(0, 0, At, B0); PG8_MMA(0, 1, At, B1); PG8_BAR; PG8_SCHED;
;             PG8_LDA(At, 0, 1); PG8_STAGE(PG8_SB(0, 0), b2, voffB); PG8_STAGE(PG8_SB(0, 1), b2 + hstep, voffB); PG8_STAGE(PG8_SA(0, 0), a2, voffA);
;             PG8_WAIT_V(8); PG8_WAIT_L(0); PG8_BAR; PG8_MMA(1, 0, At, B0); PG8_MMA(1, 1, At, B1); PG8_BAR; PG8_SCHED;
.LBB0_789:
	ds_read_b128 v[128:131], v203
	ds_read_b128 v[132:135], v203 offset:1024
	ds_read_b128 v[136:139], v203 offset:2048
	ds_read_b128 v[140:143], v203 offset:3072
	ds_read_b128 v[144:147], v204
	ds_read_b128 v[148:151], v204 offset:1024
	ds_read_b128 v[170:173], v204 offset:2048
	ds_read_b128 v[174:177], v204 offset:3072
	s_add_u32 s33, s42, 0xfff50080
	s_addc_u32 s34, s43, -1
	s_cmp_eq_u32 s90, 40
	s_cselect_b32 s47, s5, s34
	s_cselect_b32 s46, s4, s33
	s_cselect_b32 s45, s41, s87
	s_cselect_b32 s44, s40, s86
	s_add_i32 m0, s58, 0xc000
	ds_read_b128 v[178:181], v205
	ds_read_b128 v[182:185], v205 offset:1024
	ds_read_b128 v[186:189], v205 offset:2048
	ds_read_b128 v[190:193], v205 offset:3072
	ds_read_b128 v[194:197], v205 offset:4096
	ds_read_b128 v[206:209], v205 offset:5120
	ds_read_b128 v[210:213], v205 offset:6144
	ds_read_b128 v[214:217], v205 offset:7168
	global_load_lds_dwordx4 v162, s[42:43]
	s_add_i32 m0, s58, 0xe000
	s_nop 0
	global_load_lds_dwordx4 v164, s[42:43]
	s_waitcnt vmcnt(8)
	s_waitcnt lgkmcnt(0)
	s_barrier
	s_setprio 1
	s_waitcnt lgkmcnt(0)
	v_mfma_f32_16x16x32_bf16 v[124:127], v[128:131], v[178:181], v[124:127]
	v_mfma_f32_16x16x32_bf16 v[120:123], v[136:139], v[178:181], v[120:123]
	v_mfma_f32_16x16x32_bf16 v[116:119], v[128:131], v[186:189], v[116:119]
	v_mfma_f32_16x16x32_bf16 v[112:115], v[136:139], v[186:189], v[112:115]
	v_mfma_f32_16x16x32_bf16 v[108:111], v[128:131], v[194:197], v[108:111]
	v_mfma_f32_16x16x32_bf16 v[104:107], v[136:139], v[194:197], v[104:107]
	v_mfma_f32_16x16x32_bf16 v[100:103], v[128:131], v[210:213], v[100:103]
	v_mfma_f32_16x16x32_bf16 v[96:99], v[136:139], v[210:213], v[96:99]
	v_mfma_f32_16x16x32_bf16 v[124:127], v[132:135], v[182:185], v[124:127]
	v_mfma_f32_16x16x32_bf16 v[120:123], v[140:143], v[182:185], v[120:123]
	v_mfma_f32_16x16x32_bf16 v[116:119], v[132:135], v[190:193], v[116:119]
	v_mfma_f32_16x16x32_bf16 v[112:115], v[140:143], v[190:193], v[112:115]
	v_mfma_f32_16x16x32_bf16 v[108:111], v[132:135], v[206:209], v[108:111]
	v_mfma_f32_16x16x32_bf16 v[104:107], v[140:143], v[206:209], v[104:107]
	v_mfma_f32_16x16x32_bf16 v[100:103], v[132:135], v[214:217], v[100:103]
	v_mfma_f32_16x16x32_bf16 v[96:99], v[140:143], v[214:217], v[96:99]
	v_mfma_f32_16x16x32_bf16 v[68:71], v[144:147], v[178:181], v[68:71]
	v_mfma_f32_16x16x32_bf16 v[64:67], v[170:173], v[178:181], v[64:67]
	v_mfma_f32_16x16x32_bf16 v[60:63], v[144:147], v[186:189], v[60:63]
	v_mfma_f32_16x16x32_bf16 v[52:55], v[170:173], v[186:189], v[52:55]
	v_mfma_f32_16x16x32_bf16 v[44:47], v[144:147], v[194:197], v[44:47]
	v_mfma_f32_16x16x32_bf16 v[40:43], v[170:173], v[194:197], v[40:43]
	v_mfma_f32_16x16x32_bf16 v[36:39], v[144:147], v[210:213], v[36:39]
	v_mfma_f32_16x16x32_bf16 v[32:35], v[170:173], v[210:213], v[32:35]
	v_mfma_f32_16x16x32_bf16 v[68:71], v[148:151], v[182:185], v[68:71]
	v_mfma_f32_16x16x32_bf16 v[64:67], v[174:177], v[182:185], v[64:67]
	v_mfma_f32_16x16x32_bf16 v[60:63], v[148:151], v[190:193], v[60:63]
	v_mfma_f32_16x16x32_bf16 v[52:55], v[174:177], v[190:193], v[52:55]
	v_mfma_f32_16x16x32_bf16 v[44:47], v[148:151], v[206:209], v[44:47]
	v_mfma_f32_16x16x32_bf16 v[40:43], v[174:177], v[206:209], v[40:43]
	v_mfma_f32_16x16x32_bf16 v[36:39], v[148:151], v[214:217], v[36:39]
	v_mfma_f32_16x16x32_bf16 v[32:35], v[174:177], v[214:217], v[32:35]
	s_setprio 0
	s_barrier
	s_add_i32 s33, s74, s56
	s_add_u32 s64, s44, s12
	s_addc_u32 s65, s45, s13
	s_mov_b32 m0, s33
	ds_read_b128 v[178:181], v205 offset:16384
	ds_read_b128 v[182:185], v205 offset:17408
	ds_read_b128 v[186:189], v205 offset:18432
	ds_read_b128 v[190:193], v205 offset:19456
	ds_read_b128 v[194:197], v205 offset:20480
	ds_read_b128 v[206:209], v205 offset:21504
	ds_read_b128 v[210:213], v205 offset:22528
	ds_read_b128 v[214:217], v205 offset:23552
	global_load_lds_dwordx4 v156, s[44:45]
	s_add_i32 m0, s33, 0x2000
	s_add_u32 s92, s44, 0xb0000
	s_addc_u32 s93, s45, 0
	s_add_i32 s33, s75, s56
	global_load_lds_dwordx4 v160, s[44:45]
	s_mov_b32 m0, s33
	s_add_u32 s84, s46, s12
	s_addc_u32 s85, s47, s13
	global_load_lds_dwordx4 v156, s[92:93]
	s_add_i32 m0, s33, 0x2000
	s_nop 0
	global_load_lds_dwordx4 v160, s[92:93]
	s_mov_b32 m0, s58
	s_nop 0
	global_load_lds_dwordx4 v154, s[46:47]
	s_mov_b32 m0, s59
	s_nop 0
	global_load_lds_dwordx4 v158, s[46:47]
	s_waitcnt vmcnt(8)
	s_waitcnt lgkmcnt(0)
	s_barrier
	s_setprio 1
	s_waitcnt lgkmcnt(0)
	v_mfma_f32_16x16x32_bf16 v[92:95], v[128:131], v[178:181], v[92:95]
	v_mfma_f32_16x16x32_bf16 v[88:91], v[136:139], v[178:181], v[88:91]
	v_mfma_f32_16x16x32_bf16 v[84:87], v[128:131], v[186:189], v[84:87]
	v_mfma_f32_16x16x32_bf16 v[80:83], v[136:139], v[186:189], v[80:83]
	v_mfma_f32_16x16x32_bf16 v[76:79], v[128:131], v[194:197], v[76:79]
	v_mfma_f32_16x16x32_bf16 v[72:75], v[136:139], v[194:197], v[72:75]
	v_mfma_f32_16x16x32_bf16 v[56:59], v[128:131], v[210:213], v[56:59]
	v_mfma_f32_16x16x32_bf16 v[48:51], v[136:139], v[210:213], v[48:51]
	v_mfma_f32_16x16x32_bf16 v[92:95], v[132:135], v[182:185], v[92:95]
	v_mfma_f32_16x16x32_bf16 v[88:91], v[140:143], v[182:185], v[88:91]
	v_mfma_f32_16x16x32_bf16 v[84:87], v[132:135], v[190:193], v[84:87]
	v_mfma_f32_16x16x32_bf16 v[80:83], v[140:143], v[190:193], v[80:83]
	v_mfma_f32_16x16x32_bf16 v[76:79], v[132:135], v[206:209], v[76:79]
	v_mfma_f32_16x16x32_bf16 v[72:75], v[140:143], v[206:209], v[72:75]
	v_mfma_f32_16x16x32_bf16 v[56:59], v[132:135], v[214:217], v[56:59]
	v_mfma_f32_16x16x32_bf16 v[48:51], v[140:143], v[214:217], v[48:51]
	v_mfma_f32_16x16x32_bf16 v[28:31], v[144:147], v[178:181], v[28:31]
	v_mfma_f32_16x16x32_bf16 v[24:27], v[170:173], v[178:181], v[24:27]
	v_mfma_f32_16x16x32_bf16 v[20:23], v[144:147], v[186:189], v[20:23]
	v_mfma_f32_16x16x32_bf16 v[16:19], v[170:173], v[186:189], v[16:19]
	v_mfma_f32_16x16x32_bf16 v[12:15], v[144:147], v[194:197], v[12:15]
	v_mfma_f32_16x16x32_bf16 v[8:11], v[170:173], v[194:197], v[8:11]
	v_mfma_f32_16x16x32_bf16 v[4:7], v[144:147], v[210:213], v[4:7]
	v_mfma_f32_16x16x32_bf16 v[0:3], v[170:173], v[210:213], v[0:3]
	v_mfma_f32_16x16x32_bf16 v[28:31], v[148:151], v[182:185], v[28:31]
	v_mfma_f32_16x16x32_bf16 v[24:27], v[174:177], v[182:185], v[24:27]
	v_mfma_f32_16x16x32_bf16 v[20:23], v[148:151], v[190:193], v[20:23]
	v_mfma_f32_16x16x32_bf16 v[16:19], v[174:177], v[190:193], v[16:19]
	v_mfma_f32_16x16x32_bf16 v[12:15], v[148:151], v[206:209], v[12:15]
	v_mfma_f32_16x16x32_bf16 v[8:11], v[174:177], v[206:209], v[8:11]
	v_mfma_f32_16x16x32_bf16 v[4:7], v[148:151], v[214:217], v[4:7]
	v_mfma_f32_16x16x32_bf16 v[0:3], v[174:177], v[214:217], v[0:3]
	s_setprio 0
	s_barrier
; #define PG8_STAGE(bufoff, gbase, voff) do { _Pragma("unroll") for (int _i = 0; _i < 2; ++_i) \
;         __builtin_amdgcn_global_load_lds((const unsigned*)((const char*)(gbase) + (voff)[_i]), (PG8_LAS unsigned*)(lds + (bufoff) + ldsw + _i * 8192), 16, 0, 0); } while (0)
; #define PG8_LDA(dst, b, h) do { _Pragma("unroll") for (int m = 0; m < 4; ++m) _Pragma("unroll") for (int k = 0; k < 2; ++k) dst[m][k] = *(const PG8_LAS bf16x8*)(lds + PG8_SA(b, h) + aoff + m * 2048 + k * 1024); } while (0)
; #define PG8_LDB(dst, b, h) do { _Pragma("unroll") for (int n = 0; n < 2; ++n) _Pragma("unroll") for (int k = 0; k < 2; ++k) dst[n][k] = *(const PG8_LAS bf16x8*)(lds + PG8_SB(b, h) + boff + n * 2048 + k * 1024); } while (0)
; #define PG8_MMA(ai, bj, At, Bt) do { __builtin_amdgcn_s_setprio(1); _Pragma("unroll") for (int m = 0; m < 4; ++m) _Pragma("unroll") for (int n = 0; n < 2; ++n) _Pragma("unroll") for (int k = 0; k < 2; ++k) \
;         acc[ai][bj][m][n] = __builtin_amdgcn_mfma_f32_16x16x32_bf16(Bt[n][k], At[m][k], acc[ai][bj][m][n], 0, 0, 0); __builtin_amdgcn_s_setprio(0); } while (0)
; #define PG8_WAIT_V(n) asm volatile("s_waitcnt vmcnt(" #n ")" ::: "memory")
; #define PG8_WAIT_L(n) asm volatile("s_waitcnt lgkmcnt(" #n ")" ::: "memory")
; #define PG8_BAR __builtin_amdgcn_s_barrier()
; #define PG8_SCHED __builtin_amdgcn_sched_barrier(0)
; template <class Epi, class Sched, bool ALIGN_EPI = false, bool SP2 = false>
; __device__ __forceinline__ void gemm_phase(PG8_LAS unsigned char* lds, const Gemm g, const Sched& S, const Epi& E) {
;     ...
;             PG8_LDB(B0, 1, 0); PG8_LDB(B1, 1, 1); PG8_SCHED; PG8_LDA(At, 1, 0); PG8_STAGE(PG8_SA(0, 1), a2 + hstep, voffA);
;             PG8_WAIT_V(8); PG8_WAIT_L(0); PG8_BAR; PG8_MMA(0, 0, At, B0); PG8_MMA(0, 1, At, B1); PG8_BAR; PG8_SCHED;
;             PG8_LDA(At, 1, 1); PG8_STAGE(PG8_SB(1, 0), b3, voffB); PG8_STAGE(PG8_SB(1, 1), b3 + hstep, voffB); PG8_STAGE(PG8_SA(1, 0), a3, voffA);
;             PG8_WAIT_V(8); PG8_WAIT_L(0); PG8_BAR; PG8_MMA(1, 0, At, B0); PG8_MMA(1, 1, At, B1); PG8_BAR; PG8_SCHED;
;     ...
;         if constexpr (ALIGN_EPI) { if (wr == 0) PG8_BAR; }
	s_add_i32 s33, 0, 0x18000
	s_add_i32 s34, 0, 0x1c000
	v_add_u32_e32 v140, s33, v201
	v_add_u32_e32 v153, s34, v201
	ds_read_b128 v[128:131], v140
	ds_read_b128 v[132:135], v140 offset:1024
	ds_read_b128 v[136:139], v140 offset:2048
	ds_read_b128 v[140:143], v140 offset:3072
	ds_read_b128 v[144:147], v153
	ds_read_b128 v[148:151], v153 offset:1024
	ds_read_b128 v[170:173], v153 offset:2048
	ds_read_b128 v[174:177], v153 offset:3072
	s_add_u32 s46, s46, 0xb0000
	s_addc_u32 s47, s47, 0
	s_mov_b32 m0, s60
	ds_read_b128 v[178:181], v205 offset:32768
	ds_read_b128 v[182:185], v205 offset:33792
	ds_read_b128 v[186:189], v205 offset:34816
	ds_read_b128 v[190:193], v205 offset:35840
	ds_read_b128 v[194:197], v205 offset:36864
	ds_read_b128 v[206:209], v205 offset:37888
	ds_read_b128 v[210:213], v205 offset:38912
	ds_read_b128 v[214:217], v205 offset:39936
	global_load_lds_dwordx4 v154, s[46:47]
	s_mov_b32 m0, s61
	s_nop 0
	global_load_lds_dwordx4 v158, s[46:47]
	s_waitcnt vmcnt(8)
	s_waitcnt lgkmcnt(0)
	s_barrier
	s_setprio 1
	s_waitcnt lgkmcnt(0)
	v_mfma_f32_16x16x32_bf16 v[124:127], v[128:131], v[178:181], v[124:127]
	v_mfma_f32_16x16x32_bf16 v[120:123], v[136:139], v[178:181], v[120:123]
	v_mfma_f32_16x16x32_bf16 v[116:119], v[128:131], v[186:189], v[116:119]
	v_mfma_f32_16x16x32_bf16 v[112:115], v[136:139], v[186:189], v[112:115]
	v_mfma_f32_16x16x32_bf16 v[108:111], v[128:131], v[194:197], v[108:111]
	v_mfma_f32_16x16x32_bf16 v[104:107], v[136:139], v[194:197], v[104:107]
	v_mfma_f32_16x16x32_bf16 v[100:103], v[128:131], v[210:213], v[100:103]
	v_mfma_f32_16x16x32_bf16 v[96:99], v[136:139], v[210:213], v[96:99]
	v_mfma_f32_16x16x32_bf16 v[124:127], v[132:135], v[182:185], v[124:127]
	v_mfma_f32_16x16x32_bf16 v[120:123], v[140:143], v[182:185], v[120:123]
	v_mfma_f32_16x16x32_bf16 v[116:119], v[132:135], v[190:193], v[116:119]
	v_mfma_f32_16x16x32_bf16 v[112:115], v[140:143], v[190:193], v[112:115]
	v_mfma_f32_16x16x32_bf16 v[108:111], v[132:135], v[206:209], v[108:111]
	v_mfma_f32_16x16x32_bf16 v[104:107], v[140:143], v[206:209], v[104:107]
	v_mfma_f32_16x16x32_bf16 v[100:103], v[132:135], v[214:217], v[100:103]
	v_mfma_f32_16x16x32_bf16 v[96:99], v[140:143], v[214:217], v[96:99]
	v_mfma_f32_16x16x32_bf16 v[68:71], v[144:147], v[178:181], v[68:71]
	v_mfma_f32_16x16x32_bf16 v[64:67], v[170:173], v[178:181], v[64:67]
	v_mfma_f32_16x16x32_bf16 v[60:63], v[144:147], v[186:189], v[60:63]
	v_mfma_f32_16x16x32_bf16 v[52:55], v[170:173], v[186:189], v[52:55]
	v_mfma_f32_16x16x32_bf16 v[44:47], v[144:147], v[194:197], v[44:47]
	v_mfma_f32_16x16x32_bf16 v[40:43], v[170:173], v[194:197], v[40:43]
	v_mfma_f32_16x16x32_bf16 v[36:39], v[144:147], v[210:213], v[36:39]
	v_mfma_f32_16x16x32_bf16 v[32:35], v[170:173], v[210:213], v[32:35]
	v_mfma_f32_16x16x32_bf16 v[68:71], v[148:151], v[182:185], v[68:71]
	v_mfma_f32_16x16x32_bf16 v[64:67], v[174:177], v[182:185], v[64:67]
	v_mfma_f32_16x16x32_bf16 v[60:63], v[148:151], v[190:193], v[60:63]
	v_mfma_f32_16x16x32_bf16 v[52:55], v[174:177], v[190:193], v[52:55]
	v_mfma_f32_16x16x32_bf16 v[44:47], v[148:151], v[206:209], v[44:47]
	v_mfma_f32_16x16x32_bf16 v[40:43], v[174:177], v[206:209], v[40:43]
	v_mfma_f32_16x16x32_bf16 v[36:39], v[148:151], v[214:217], v[36:39]
	v_mfma_f32_16x16x32_bf16 v[32:35], v[174:177], v[214:217], v[32:35]
	s_setprio 0
	s_barrier
	s_add_i32 s33, s33, s56
	s_mov_b32 m0, s33
	ds_read_b128 v[178:181], v205 offset:49152
	ds_read_b128 v[182:185], v205 offset:50176
	ds_read_b128 v[186:189], v205 offset:51200
	ds_read_b128 v[190:193], v205 offset:52224
	ds_read_b128 v[194:197], v205 offset:53248
	ds_read_b128 v[206:209], v205 offset:54272
	ds_read_b128 v[210:213], v205 offset:55296
	ds_read_b128 v[214:217], v205 offset:56320
	global_load_lds_dwordx4 v156, s[64:65]
	s_add_i32 m0, s33, 0x2000
	s_add_u32 s44, s44, 0xb0080
	s_addc_u32 s45, s45, 0
	s_add_i32 s33, s34, s56
	global_load_lds_dwordx4 v160, s[64:65]
	s_mov_b32 m0, s33
	s_nop 0
	global_load_lds_dwordx4 v156, s[44:45]
	s_add_i32 m0, s33, 0x2000
	s_nop 0
	global_load_lds_dwordx4 v160, s[44:45]
	s_mov_b32 m0, s72
	s_nop 0
	global_load_lds_dwordx4 v154, s[84:85]
	s_mov_b32 m0, s73
	s_nop 0
	global_load_lds_dwordx4 v158, s[84:85]
	s_waitcnt vmcnt(8)
	s_waitcnt lgkmcnt(0)
	s_barrier
	s_setprio 1
	s_waitcnt lgkmcnt(0)
	v_mfma_f32_16x16x32_bf16 v[92:95], v[128:131], v[178:181], v[92:95]
	v_mfma_f32_16x16x32_bf16 v[88:91], v[136:139], v[178:181], v[88:91]
	v_mfma_f32_16x16x32_bf16 v[84:87], v[128:131], v[186:189], v[84:87]
	v_mfma_f32_16x16x32_bf16 v[80:83], v[136:139], v[186:189], v[80:83]
	v_mfma_f32_16x16x32_bf16 v[76:79], v[128:131], v[194:197], v[76:79]
	v_mfma_f32_16x16x32_bf16 v[72:75], v[136:139], v[194:197], v[72:75]
	v_mfma_f32_16x16x32_bf16 v[56:59], v[128:131], v[210:213], v[56:59]
	v_mfma_f32_16x16x32_bf16 v[48:51], v[136:139], v[210:213], v[48:51]
	v_mfma_f32_16x16x32_bf16 v[92:95], v[132:135], v[182:185], v[92:95]
	v_mfma_f32_16x16x32_bf16 v[88:91], v[140:143], v[182:185], v[88:91]
	v_mfma_f32_16x16x32_bf16 v[84:87], v[132:135], v[190:193], v[84:87]
	v_mfma_f32_16x16x32_bf16 v[80:83], v[140:143], v[190:193], v[80:83]
	v_mfma_f32_16x16x32_bf16 v[76:79], v[132:135], v[206:209], v[76:79]
	v_mfma_f32_16x16x32_bf16 v[72:75], v[140:143], v[206:209], v[72:75]
	v_mfma_f32_16x16x32_bf16 v[56:59], v[132:135], v[214:217], v[56:59]
	v_mfma_f32_16x16x32_bf16 v[48:51], v[140:143], v[214:217], v[48:51]
	v_mfma_f32_16x16x32_bf16 v[28:31], v[144:147], v[178:181], v[28:31]
	v_mfma_f32_16x16x32_bf16 v[24:27], v[170:173], v[178:181], v[24:27]
	v_mfma_f32_16x16x32_bf16 v[20:23], v[144:147], v[186:189], v[20:23]
	v_mfma_f32_16x16x32_bf16 v[16:19], v[170:173], v[186:189], v[16:19]
	v_mfma_f32_16x16x32_bf16 v[12:15], v[144:147], v[194:197], v[12:15]
	v_mfma_f32_16x16x32_bf16 v[8:11], v[170:173], v[194:197], v[8:11]
	v_mfma_f32_16x16x32_bf16 v[4:7], v[144:147], v[210:213], v[4:7]
	v_mfma_f32_16x16x32_bf16 v[0:3], v[170:173], v[210:213], v[0:3]
	v_mfma_f32_16x16x32_bf16 v[28:31], v[148:151], v[182:185], v[28:31]
	v_mfma_f32_16x16x32_bf16 v[24:27], v[174:177], v[182:185], v[24:27]
	v_mfma_f32_16x16x32_bf16 v[20:23], v[148:151], v[190:193], v[20:23]
	v_mfma_f32_16x16x32_bf16 v[16:19], v[174:177], v[190:193], v[16:19]
	v_mfma_f32_16x16x32_bf16 v[12:15], v[148:151], v[206:209], v[12:15]
	v_mfma_f32_16x16x32_bf16 v[8:11], v[174:177], v[206:209], v[8:11]
	v_mfma_f32_16x16x32_bf16 v[4:7], v[148:151], v[214:217], v[4:7]
	v_mfma_f32_16x16x32_bf16 v[0:3], v[174:177], v[214:217], v[0:3]
	s_setprio 0
	s_barrier
	s_add_i32 s90, s90, 2
	s_add_u32 s42, s42, 0x100
	s_addc_u32 s43, s43, 0
	s_add_u32 s86, s86, 0x100
	s_addc_u32 s87, s87, 0
	s_cmp_gt_u32 s90, 41
	s_cbranch_scc0 .LBB0_789
	s_and_b64 vcc, exec, s[20:21]
	s_cbranch_vccz .LBB0_792
	s_barrier

; #define PG8_STAGE(bufoff, gbase, voff) do { _Pragma("unroll") for (int _i = 0; _i < 2; ++_i) \
;         __builtin_amdgcn_global_load_lds((const unsigned*)((const char*)(gbase) + (voff)[_i]), (PG8_LAS unsigned*)(lds + (bufoff) + ldsw + _i * 8192), 16, 0, 0); } while (0)
; #define PG8_LDA(dst, b, h) do { _Pragma("unroll") for (int m = 0; m < 4; ++m) _Pragma("unroll") for (int k = 0; k < 2; ++k) dst[m][k] = *(const PG8_LAS bf16x8*)(lds + PG8_SA(b, h) + aoff + m * 2048 + k * 1024); } while (0)
; #define PG8_MMA(ai, bj, At, Bt) do { __builtin_amdgcn_s_setprio(1); _Pragma("unroll") for (int m = 0; m < 4; ++m) _Pragma("unroll") for (int n = 0; n < 2; ++n) _Pragma("unroll") for (int k = 0; k < 2; ++k) \
;         acc[ai][bj][m][n] = __builtin_amdgcn_mfma_f32_16x16x32_bf16(Bt[n][k], At[m][k], acc[ai][bj][m][n], 0, 0, 0); __builtin_amdgcn_s_setprio(0); } while (0)
; #define PG8_WAIT_V(n) asm volatile("s_waitcnt vmcnt(" #n ")" ::: "memory")
; #define PG8_WAIT_L(n) asm volatile("s_waitcnt lgkmcnt(" #n ")" ::: "memory")
; #define PG8_BAR __builtin_amdgcn_s_barrier()
; #define PG8_SCHED __builtin_amdgcn_sched_barrier(0)
; template <class Epi, class Sched, bool ALIGN_EPI = false, bool SP2 = false>
; __device__ __forceinline__ void gemm_phase(PG8_LAS unsigned char* lds, const Gemm g, const Sched& S, const Epi& E) {
;     ...
;             PG8_WAIT_V(8); PG8_WAIT_L(0); PG8_BAR; PG8_MMA(0, 0, At, B0); PG8_MMA(0, 1, At, B1); PG8_BAR; PG8_SCHED;
;             PG8_LDA(At, 0, 1); PG8_STAGE(PG8_SB(0, 0), b2, voffB); PG8_STAGE(PG8_SB(0, 1), b2 + hstep, voffB); PG8_STAGE(PG8_SA(0, 0), a2, voffA);
;             PG8_WAIT_V(8); PG8_WAIT_L(0); PG8_BAR; PG8_MMA(1, 0, At, B0); PG8_MMA(1, 1, At, B1); PG8_BAR; PG8_SCHED;
.LfwP10_0_e:
	s_waitcnt lgkmcnt(0)
	s_barrier
	s_setprio 1
	s_waitcnt lgkmcnt(0)
	v_mfma_f32_16x16x32_bf16 v[124:127], v[144:147], v[186:189], 0
	v_mfma_f32_16x16x32_bf16 v[120:123], v[162:165], v[186:189], 0
	v_mfma_f32_16x16x32_bf16 v[108:111], v[144:147], v[194:197], 0
	v_mfma_f32_16x16x32_bf16 v[104:107], v[162:165], v[194:197], 0
	v_mfma_f32_16x16x32_bf16 v[92:95], v[144:147], v[202:205], 0
	v_mfma_f32_16x16x32_bf16 v[88:91], v[162:165], v[202:205], 0
	v_mfma_f32_16x16x32_bf16 v[76:79], v[144:147], v[210:213], 0
	v_mfma_f32_16x16x32_bf16 v[72:75], v[162:165], v[210:213], 0
	v_mfma_f32_16x16x32_bf16 v[124:127], v[148:151], v[190:193], v[124:127]
	v_mfma_f32_16x16x32_bf16 v[120:123], v[166:169], v[190:193], v[120:123]
	v_mfma_f32_16x16x32_bf16 v[108:111], v[148:151], v[198:201], v[108:111]
	v_mfma_f32_16x16x32_bf16 v[104:107], v[166:169], v[198:201], v[104:107]
	v_mfma_f32_16x16x32_bf16 v[92:95], v[148:151], v[206:209], v[92:95]
	v_mfma_f32_16x16x32_bf16 v[88:91], v[166:169], v[206:209], v[88:91]
	v_mfma_f32_16x16x32_bf16 v[76:79], v[148:151], v[214:217], v[76:79]
	v_mfma_f32_16x16x32_bf16 v[72:75], v[166:169], v[214:217], v[72:75]
	v_mfma_f32_16x16x32_bf16 v[116:119], v[170:173], v[186:189], 0
	v_mfma_f32_16x16x32_bf16 v[112:115], v[178:181], v[186:189], 0
	v_mfma_f32_16x16x32_bf16 v[100:103], v[170:173], v[194:197], 0
	v_mfma_f32_16x16x32_bf16 v[96:99], v[178:181], v[194:197], 0
	v_mfma_f32_16x16x32_bf16 v[84:87], v[170:173], v[202:205], 0
	v_mfma_f32_16x16x32_bf16 v[80:83], v[178:181], v[202:205], 0
	v_mfma_f32_16x16x32_bf16 v[68:71], v[170:173], v[210:213], 0
	v_mfma_f32_16x16x32_bf16 v[64:67], v[178:181], v[210:213], 0
	v_mfma_f32_16x16x32_bf16 v[116:119], v[174:177], v[190:193], v[116:119]
	v_mfma_f32_16x16x32_bf16 v[112:115], v[182:185], v[190:193], v[112:115]
	v_mfma_f32_16x16x32_bf16 v[100:103], v[174:177], v[198:201], v[100:103]
	v_mfma_f32_16x16x32_bf16 v[96:99], v[182:185], v[198:201], v[96:99]
	v_mfma_f32_16x16x32_bf16 v[84:87], v[174:177], v[206:209], v[84:87]
	v_mfma_f32_16x16x32_bf16 v[80:83], v[182:185], v[206:209], v[80:83]
	v_mfma_f32_16x16x32_bf16 v[68:71], v[174:177], v[214:217], v[68:71]
	v_mfma_f32_16x16x32_bf16 v[64:67], v[182:185], v[214:217], v[64:67]
	s_setprio 0
	s_barrier
	s_add_i32 s33, s78, s62
	s_add_u32 s80, s56, s20
	s_addc_u32 s81, s57, s21
	s_mov_b32 m0, s33
	ds_read_b128 v[186:189], v161 offset:16384
	ds_read_b128 v[190:193], v161 offset:17408
	ds_read_b128 v[194:197], v161 offset:18432
	ds_read_b128 v[198:201], v161 offset:19456
	ds_read_b128 v[202:205], v161 offset:20480
	ds_read_b128 v[206:209], v161 offset:21504
	ds_read_b128 v[210:213], v161 offset:22528
	ds_read_b128 v[214:217], v161 offset:23552
	global_load_lds_dwordx4 v130, s[56:57]
	s_add_i32 m0, s33, 0x2000
	s_add_u32 s92, s56, 0x40000
	s_addc_u32 s93, s57, 0
	s_add_i32 s33, s79, s62
	global_load_lds_dwordx4 v134, s[56:57]
	s_mov_b32 m0, s33
	s_add_u32 s82, s58, s20
	s_addc_u32 s83, s59, s21
	global_load_lds_dwordx4 v130, s[92:93]
	s_add_i32 m0, s33, 0x2000
	s_nop 0
	global_load_lds_dwordx4 v134, s[92:93]
	s_mov_b32 m0, s53
	s_nop 0
	global_load_lds_dwordx4 v128, s[58:59]
	s_mov_b32 m0, s63
	s_nop 0
	global_load_lds_dwordx4 v132, s[58:59]
	s_cmp_eq_u32 s32, 0
	s_cbranch_scc1 .LfwP10_1_s
	s_waitcnt vmcnt(32)
	s_branch .LfwP10_1_e

; #define PG8_STAGE(bufoff, gbase, voff) do { _Pragma("unroll") for (int _i = 0; _i < 2; ++_i) \
;         __builtin_amdgcn_global_load_lds((const unsigned*)((const char*)(gbase) + (voff)[_i]), (PG8_LAS unsigned*)(lds + (bufoff) + ldsw + _i * 8192), 16, 0, 0); } while (0)
; #define PG8_LDA(dst, b, h) do { _Pragma("unroll") for (int m = 0; m < 4; ++m) _Pragma("unroll") for (int k = 0; k < 2; ++k) dst[m][k] = *(const PG8_LAS bf16x8*)(lds + PG8_SA(b, h) + aoff + m * 2048 + k * 1024); } while (0)
; #define PG8_LDB(dst, b, h) do { _Pragma("unroll") for (int n = 0; n < 2; ++n) _Pragma("unroll") for (int k = 0; k < 2; ++k) dst[n][k] = *(const PG8_LAS bf16x8*)(lds + PG8_SB(b, h) + boff + n * 2048 + k * 1024); } while (0)
; #define PG8_MMA(ai, bj, At, Bt) do { __builtin_amdgcn_s_setprio(1); _Pragma("unroll") for (int m = 0; m < 4; ++m) _Pragma("unroll") for (int n = 0; n < 2; ++n) _Pragma("unroll") for (int k = 0; k < 2; ++k) \
;         acc[ai][bj][m][n] = __builtin_amdgcn_mfma_f32_16x16x32_bf16(Bt[n][k], At[m][k], acc[ai][bj][m][n], 0, 0, 0); __builtin_amdgcn_s_setprio(0); } while (0)
; #define PG8_WAIT_V(n) asm volatile("s_waitcnt vmcnt(" #n ")" ::: "memory")
; #define PG8_WAIT_L(n) asm volatile("s_waitcnt lgkmcnt(" #n ")" ::: "memory")
; #define PG8_BAR __builtin_amdgcn_s_barrier()
; #define PG8_SCHED __builtin_amdgcn_sched_barrier(0)
; template <class Epi, class Sched, bool ALIGN_EPI = false, bool SP2 = false>
; __device__ __forceinline__ void gemm_phase(PG8_LAS unsigned char* lds, const Gemm g, const Sched& S, const Epi& E) {
;     ...
;             PG8_WAIT_V(8); PG8_WAIT_L(0); PG8_BAR; PG8_MMA(1, 0, At, B0); PG8_MMA(1, 1, At, B1); PG8_BAR; PG8_SCHED;
;             PG8_LDB(B0, 1, 0); PG8_LDB(B1, 1, 1); PG8_SCHED; PG8_LDA(At, 1, 0); PG8_STAGE(PG8_SA(0, 1), a2 + hstep, voffA);
;             PG8_WAIT_V(8); PG8_WAIT_L(0); PG8_BAR; PG8_MMA(0, 0, At, B0); PG8_MMA(0, 1, At, B1); PG8_BAR; PG8_SCHED;
.LfwP10_1_e:
	s_waitcnt lgkmcnt(0)
	s_barrier
	s_setprio 1
	s_waitcnt lgkmcnt(0)
	v_mfma_f32_16x16x32_bf16 v[60:63], v[144:147], v[186:189], 0
	v_mfma_f32_16x16x32_bf16 v[56:59], v[162:165], v[186:189], 0
	v_mfma_f32_16x16x32_bf16 v[48:51], v[144:147], v[194:197], 0
	v_mfma_f32_16x16x32_bf16 v[40:43], v[162:165], v[194:197], 0
	v_mfma_f32_16x16x32_bf16 v[32:35], v[144:147], v[202:205], 0
	v_mfma_f32_16x16x32_bf16 v[24:27], v[162:165], v[202:205], 0
	v_mfma_f32_16x16x32_bf16 v[16:19], v[144:147], v[210:213], 0
	v_mfma_f32_16x16x32_bf16 v[8:11], v[162:165], v[210:213], 0
	v_mfma_f32_16x16x32_bf16 v[60:63], v[148:151], v[190:193], v[60:63]
	v_mfma_f32_16x16x32_bf16 v[56:59], v[166:169], v[190:193], v[56:59]
	v_mfma_f32_16x16x32_bf16 v[48:51], v[148:151], v[198:201], v[48:51]
	v_mfma_f32_16x16x32_bf16 v[40:43], v[166:169], v[198:201], v[40:43]
	v_mfma_f32_16x16x32_bf16 v[32:35], v[148:151], v[206:209], v[32:35]
	v_mfma_f32_16x16x32_bf16 v[24:27], v[166:169], v[206:209], v[24:27]
	v_mfma_f32_16x16x32_bf16 v[16:19], v[148:151], v[214:217], v[16:19]
	v_mfma_f32_16x16x32_bf16 v[8:11], v[166:169], v[214:217], v[8:11]
	v_mfma_f32_16x16x32_bf16 v[52:55], v[170:173], v[186:189], 0
	v_mfma_f32_16x16x32_bf16 v[44:47], v[178:181], v[186:189], 0
	v_mfma_f32_16x16x32_bf16 v[36:39], v[170:173], v[194:197], 0
	v_mfma_f32_16x16x32_bf16 v[28:31], v[178:181], v[194:197], 0
	v_mfma_f32_16x16x32_bf16 v[20:23], v[170:173], v[202:205], 0
	v_mfma_f32_16x16x32_bf16 v[12:15], v[178:181], v[202:205], 0
	v_mfma_f32_16x16x32_bf16 v[4:7], v[170:173], v[210:213], 0
	v_mfma_f32_16x16x32_bf16 v[0:3], v[178:181], v[210:213], 0
	v_mfma_f32_16x16x32_bf16 v[52:55], v[174:177], v[190:193], v[52:55]
	v_mfma_f32_16x16x32_bf16 v[44:47], v[182:185], v[190:193], v[44:47]
	v_mfma_f32_16x16x32_bf16 v[36:39], v[174:177], v[198:201], v[36:39]
	v_mfma_f32_16x16x32_bf16 v[28:31], v[182:185], v[198:201], v[28:31]
	v_mfma_f32_16x16x32_bf16 v[20:23], v[174:177], v[206:209], v[20:23]
	v_mfma_f32_16x16x32_bf16 v[12:15], v[182:185], v[206:209], v[12:15]
	v_mfma_f32_16x16x32_bf16 v[4:7], v[174:177], v[214:217], v[4:7]
	v_mfma_f32_16x16x32_bf16 v[0:3], v[182:185], v[214:217], v[0:3]
	s_setprio 0
	s_barrier
	s_add_i32 s33, 0, 0x18000
	v_add_u32_e32 v153, s33, v157
	s_add_i32 s34, 0, 0x1c000
	ds_read_b128 v[144:147], v153
	ds_read_b128 v[148:151], v153 offset:1024
	ds_read_b128 v[162:165], v153 offset:2048
	ds_read_b128 v[166:169], v153 offset:3072
	v_add_u32_e32 v153, s34, v157
	ds_read_b128 v[170:173], v153
	ds_read_b128 v[174:177], v153 offset:1024
	ds_read_b128 v[178:181], v153 offset:2048
	ds_read_b128 v[182:185], v153 offset:3072
	s_add_u32 s58, s58, 0x40000
	s_addc_u32 s59, s59, 0
	s_mov_b32 m0, s70
	ds_read_b128 v[186:189], v161 offset:32768
	ds_read_b128 v[190:193], v161 offset:33792
	ds_read_b128 v[194:197], v161 offset:34816
	ds_read_b128 v[198:201], v161 offset:35840
	ds_read_b128 v[202:205], v161 offset:36864
	ds_read_b128 v[206:209], v161 offset:37888
	ds_read_b128 v[210:213], v161 offset:38912
	ds_read_b128 v[214:217], v161 offset:39936
	global_load_lds_dwordx4 v128, s[58:59]
	s_mov_b32 m0, s71
	s_nop 0
	global_load_lds_dwordx4 v132, s[58:59]
	s_waitcnt vmcnt(8)
	s_waitcnt lgkmcnt(0)
	s_barrier
	s_setprio 1
	s_waitcnt lgkmcnt(0)
	v_mfma_f32_16x16x32_bf16 v[124:127], v[144:147], v[186:189], v[124:127]
	v_mfma_f32_16x16x32_bf16 v[120:123], v[162:165], v[186:189], v[120:123]
	v_mfma_f32_16x16x32_bf16 v[108:111], v[144:147], v[194:197], v[108:111]
	v_mfma_f32_16x16x32_bf16 v[104:107], v[162:165], v[194:197], v[104:107]
	v_mfma_f32_16x16x32_bf16 v[92:95], v[144:147], v[202:205], v[92:95]
	v_mfma_f32_16x16x32_bf16 v[88:91], v[162:165], v[202:205], v[88:91]
	v_mfma_f32_16x16x32_bf16 v[76:79], v[144:147], v[210:213], v[76:79]
	v_mfma_f32_16x16x32_bf16 v[72:75], v[162:165], v[210:213], v[72:75]
	v_mfma_f32_16x16x32_bf16 v[124:127], v[148:151], v[190:193], v[124:127]
	v_mfma_f32_16x16x32_bf16 v[120:123], v[166:169], v[190:193], v[120:123]
	v_mfma_f32_16x16x32_bf16 v[108:111], v[148:151], v[198:201], v[108:111]
	v_mfma_f32_16x16x32_bf16 v[104:107], v[166:169], v[198:201], v[104:107]
	v_mfma_f32_16x16x32_bf16 v[92:95], v[148:151], v[206:209], v[92:95]
	v_mfma_f32_16x16x32_bf16 v[88:91], v[166:169], v[206:209], v[88:91]
	v_mfma_f32_16x16x32_bf16 v[76:79], v[148:151], v[214:217], v[76:79]
	v_mfma_f32_16x16x32_bf16 v[72:75], v[166:169], v[214:217], v[72:75]
	v_mfma_f32_16x16x32_bf16 v[116:119], v[170:173], v[186:189], v[116:119]
	v_mfma_f32_16x16x32_bf16 v[112:115], v[178:181], v[186:189], v[112:115]
	v_mfma_f32_16x16x32_bf16 v[100:103], v[170:173], v[194:197], v[100:103]
	v_mfma_f32_16x16x32_bf16 v[96:99], v[178:181], v[194:197], v[96:99]
	v_mfma_f32_16x16x32_bf16 v[84:87], v[170:173], v[202:205], v[84:87]
	v_mfma_f32_16x16x32_bf16 v[80:83], v[178:181], v[202:205], v[80:83]
	v_mfma_f32_16x16x32_bf16 v[68:71], v[170:173], v[210:213], v[68:71]
	v_mfma_f32_16x16x32_bf16 v[64:67], v[178:181], v[210:213], v[64:67]
	v_mfma_f32_16x16x32_bf16 v[116:119], v[174:177], v[190:193], v[116:119]
	v_mfma_f32_16x16x32_bf16 v[112:115], v[182:185], v[190:193], v[112:115]
	v_mfma_f32_16x16x32_bf16 v[100:103], v[174:177], v[198:201], v[100:103]
	v_mfma_f32_16x16x32_bf16 v[96:99], v[182:185], v[198:201], v[96:99]
	v_mfma_f32_16x16x32_bf16 v[84:87], v[174:177], v[206:209], v[84:87]
	v_mfma_f32_16x16x32_bf16 v[80:83], v[182:185], v[206:209], v[80:83]
	v_mfma_f32_16x16x32_bf16 v[68:71], v[174:177], v[214:217], v[68:71]
	v_mfma_f32_16x16x32_bf16 v[64:67], v[182:185], v[214:217], v[64:67]
	s_setprio 0
	s_barrier
; #define PG8_STAGE(bufoff, gbase, voff) do { _Pragma("unroll") for (int _i = 0; _i < 2; ++_i) \
;         __builtin_amdgcn_global_load_lds((const unsigned*)((const char*)(gbase) + (voff)[_i]), (PG8_LAS unsigned*)(lds + (bufoff) + ldsw + _i * 8192), 16, 0, 0); } while (0)
; #define PG8_LDA(dst, b, h) do { _Pragma("unroll") for (int m = 0; m < 4; ++m) _Pragma("unroll") for (int k = 0; k < 2; ++k) dst[m][k] = *(const PG8_LAS bf16x8*)(lds + PG8_SA(b, h) + aoff + m * 2048 + k * 1024); } while (0)
; #define PG8_LDB(dst, b, h) do { _Pragma("unroll") for (int n = 0; n < 2; ++n) _Pragma("unroll") for (int k = 0; k < 2; ++k) dst[n][k] = *(const PG8_LAS bf16x8*)(lds + PG8_SB(b, h) + boff + n * 2048 + k * 1024); } while (0)
; #define PG8_MMA(ai, bj, At, Bt) do { __builtin_amdgcn_s_setprio(1); _Pragma("unroll") for (int m = 0; m < 4; ++m) _Pragma("unroll") for (int n = 0; n < 2; ++n) _Pragma("unroll") for (int k = 0; k < 2; ++k) \
;         acc[ai][bj][m][n] = __builtin_amdgcn_mfma_f32_16x16x32_bf16(Bt[n][k], At[m][k], acc[ai][bj][m][n], 0, 0, 0); __builtin_amdgcn_s_setprio(0); } while (0)
; #define PG8_WAIT_V(n) asm volatile("s_waitcnt vmcnt(" #n ")" ::: "memory")
; #define PG8_WAIT_L(n) asm volatile("s_waitcnt lgkmcnt(" #n ")" ::: "memory")
; template <class Epi, class Sched, bool ALIGN_EPI = false, bool SP2 = false>
; __device__ __forceinline__ void gemm_phase(PG8_LAS unsigned char* lds, const Gemm g, const Sched& S, const Epi& E) {
;     ...
;             const bool last = (t == nt - 2);
;             const char* a1 = cA + (size_t)(t + 1) * kstep;
;             const char* a2 = last ? nA : cA + (size_t)(t + 2) * kstep; const char* b2 = last ? nB : cB + (size_t)(t + 2) * kstep;
;             const char* a3 = a2 + kstep; const char* b3 = b2 + kstep;
;             if (last && has_next) S.a_ready(nxt);
;             if constexpr (SP2) {
;             PG8_LDB(B0, 0, 0); PG8_LDB(B1, 0, 1); PG8_SCHED; PG8_LDA(At, 0, 0); PG8_STAGE(PG8_SA(1, 1), a1 + hstep, voffA);
;             PG8_WAIT_V(8); PG8_WAIT_L(0); PG8_BAR; PG8_MMA(0, 0, At, B0); PG8_MMA(0, 1, At, B1); PG8_BAR; PG8_SCHED;
;     ...
;             PG8_LDA(At, 1, 1); PG8_STAGE(PG8_SB(1, 0), b3, voffB); PG8_STAGE(PG8_SB(1, 1), b3 + hstep, voffB); PG8_STAGE(PG8_SA(1, 0), a3, voffA);
;             PG8_WAIT_V(8); PG8_WAIT_L(0); PG8_BAR; PG8_MMA(1, 0, At, B0); PG8_MMA(1, 1, At, B1); PG8_BAR; PG8_SCHED;
	s_add_i32 s33, s33, s62
	s_mov_b32 m0, s33
	ds_read_b128 v[186:189], v161 offset:49152
	ds_read_b128 v[190:193], v161 offset:50176
	ds_read_b128 v[194:197], v161 offset:51200
	ds_read_b128 v[198:201], v161 offset:52224
	ds_read_b128 v[202:205], v161 offset:53248
	ds_read_b128 v[206:209], v161 offset:54272
	ds_read_b128 v[210:213], v161 offset:55296
	ds_read_b128 v[214:217], v161 offset:56320
	global_load_lds_dwordx4 v130, s[80:81]
	s_add_i32 m0, s33, 0x2000
	s_add_u32 s56, s56, 0x40080
	s_addc_u32 s57, s57, 0
	s_add_i32 s33, s34, s62
	global_load_lds_dwordx4 v134, s[80:81]
	s_mov_b32 m0, s33
	s_nop 0
	global_load_lds_dwordx4 v130, s[56:57]
	s_add_i32 m0, s33, 0x2000
	s_nop 0
	global_load_lds_dwordx4 v134, s[56:57]
	s_mov_b32 m0, s75
	s_nop 0
	global_load_lds_dwordx4 v128, s[82:83]
	s_mov_b32 m0, s76
	s_nop 0
	global_load_lds_dwordx4 v132, s[82:83]
	s_waitcnt vmcnt(8)
	s_waitcnt lgkmcnt(0)
	s_barrier
	s_setprio 1
	s_waitcnt lgkmcnt(0)
	v_mfma_f32_16x16x32_bf16 v[60:63], v[144:147], v[186:189], v[60:63]
	v_mfma_f32_16x16x32_bf16 v[56:59], v[162:165], v[186:189], v[56:59]
	v_mfma_f32_16x16x32_bf16 v[48:51], v[144:147], v[194:197], v[48:51]
	v_mfma_f32_16x16x32_bf16 v[40:43], v[162:165], v[194:197], v[40:43]
	v_mfma_f32_16x16x32_bf16 v[32:35], v[144:147], v[202:205], v[32:35]
	v_mfma_f32_16x16x32_bf16 v[24:27], v[162:165], v[202:205], v[24:27]
	v_mfma_f32_16x16x32_bf16 v[16:19], v[144:147], v[210:213], v[16:19]
	v_mfma_f32_16x16x32_bf16 v[8:11], v[162:165], v[210:213], v[8:11]
	v_mfma_f32_16x16x32_bf16 v[60:63], v[148:151], v[190:193], v[60:63]
	v_mfma_f32_16x16x32_bf16 v[56:59], v[166:169], v[190:193], v[56:59]
	v_mfma_f32_16x16x32_bf16 v[48:51], v[148:151], v[198:201], v[48:51]
	v_mfma_f32_16x16x32_bf16 v[40:43], v[166:169], v[198:201], v[40:43]
	v_mfma_f32_16x16x32_bf16 v[32:35], v[148:151], v[206:209], v[32:35]
	v_mfma_f32_16x16x32_bf16 v[24:27], v[166:169], v[206:209], v[24:27]
	v_mfma_f32_16x16x32_bf16 v[16:19], v[148:151], v[214:217], v[16:19]
	v_mfma_f32_16x16x32_bf16 v[8:11], v[166:169], v[214:217], v[8:11]
	v_mfma_f32_16x16x32_bf16 v[52:55], v[170:173], v[186:189], v[52:55]
	v_mfma_f32_16x16x32_bf16 v[44:47], v[178:181], v[186:189], v[44:47]
	v_mfma_f32_16x16x32_bf16 v[36:39], v[170:173], v[194:197], v[36:39]
	v_mfma_f32_16x16x32_bf16 v[28:31], v[178:181], v[194:197], v[28:31]
	v_mfma_f32_16x16x32_bf16 v[20:23], v[170:173], v[202:205], v[20:23]
	v_mfma_f32_16x16x32_bf16 v[12:15], v[178:181], v[202:205], v[12:15]
	v_mfma_f32_16x16x32_bf16 v[4:7], v[170:173], v[210:213], v[4:7]
	v_mfma_f32_16x16x32_bf16 v[0:3], v[178:181], v[210:213], v[0:3]
	v_mfma_f32_16x16x32_bf16 v[52:55], v[174:177], v[190:193], v[52:55]
	v_mfma_f32_16x16x32_bf16 v[44:47], v[182:185], v[190:193], v[44:47]
	v_mfma_f32_16x16x32_bf16 v[36:39], v[174:177], v[198:201], v[36:39]
	v_mfma_f32_16x16x32_bf16 v[28:31], v[182:185], v[198:201], v[28:31]
	v_mfma_f32_16x16x32_bf16 v[20:23], v[174:177], v[206:209], v[20:23]
	v_mfma_f32_16x16x32_bf16 v[12:15], v[182:185], v[206:209], v[12:15]
	v_mfma_f32_16x16x32_bf16 v[4:7], v[174:177], v[214:217], v[4:7]
	v_mfma_f32_16x16x32_bf16 v[0:3], v[182:185], v[214:217], v[0:3]
	s_setprio 0
	s_barrier
	s_add_i32 s91, s91, 2
	s_add_u32 s54, s54, 0x100
	s_addc_u32 s55, s55, 0
	s_add_u32 s87, s87, 0x100
	s_addc_u32 s90, s90, 0
	s_cmp_gt_u32 s91, 13
.LBB0_915:
	ds_read_b128 v[144:147], v159
	ds_read_b128 v[148:151], v159 offset:1024
	ds_read_b128 v[162:165], v159 offset:2048
	ds_read_b128 v[166:169], v159 offset:3072
	ds_read_b128 v[170:173], v160
	ds_read_b128 v[174:177], v160 offset:1024
	ds_read_b128 v[178:181], v160 offset:2048
	ds_read_b128 v[182:185], v160 offset:3072
	s_add_u32 s33, s54, 0xfffc0080
	s_addc_u32 s34, s55, -1
	s_cmp_eq_u32 s91, 12
	s_cselect_b32 s59, s5, s34
	s_cselect_b32 s58, s45, s33
	s_cselect_b32 s57, s43, s90
	s_cselect_b32 s56, s86, s87
	s_add_i32 m0, s53, 0xc000
	ds_read_b128 v[186:189], v161
	ds_read_b128 v[190:193], v161 offset:1024
	ds_read_b128 v[194:197], v161 offset:2048
	ds_read_b128 v[198:201], v161 offset:3072
	ds_read_b128 v[202:205], v161 offset:4096
	ds_read_b128 v[206:209], v161 offset:5120
	ds_read_b128 v[210:213], v161 offset:6144
	ds_read_b128 v[214:217], v161 offset:7168
	global_load_lds_dwordx4 v136, s[54:55]
	s_add_i32 m0, s53, 0xe000
	s_nop 0
	global_load_lds_dwordx4 v138, s[54:55]
	s_waitcnt vmcnt(8)
	s_waitcnt lgkmcnt(0)
	s_barrier
	s_setprio 1
	s_waitcnt lgkmcnt(0)
	v_mfma_f32_16x16x32_bf16 v[124:127], v[144:147], v[186:189], v[124:127]
	v_mfma_f32_16x16x32_bf16 v[120:123], v[162:165], v[186:189], v[120:123]
	v_mfma_f32_16x16x32_bf16 v[108:111], v[144:147], v[194:197], v[108:111]
	v_mfma_f32_16x16x32_bf16 v[104:107], v[162:165], v[194:197], v[104:107]
	v_mfma_f32_16x16x32_bf16 v[92:95], v[144:147], v[202:205], v[92:95]
	v_mfma_f32_16x16x32_bf16 v[88:91], v[162:165], v[202:205], v[88:91]
	v_mfma_f32_16x16x32_bf16 v[76:79], v[144:147], v[210:213], v[76:79]
	v_mfma_f32_16x16x32_bf16 v[72:75], v[162:165], v[210:213], v[72:75]
	v_mfma_f32_16x16x32_bf16 v[124:127], v[148:151], v[190:193], v[124:127]
	v_mfma_f32_16x16x32_bf16 v[120:123], v[166:169], v[190:193], v[120:123]
	v_mfma_f32_16x16x32_bf16 v[108:111], v[148:151], v[198:201], v[108:111]
	v_mfma_f32_16x16x32_bf16 v[104:107], v[166:169], v[198:201], v[104:107]
	v_mfma_f32_16x16x32_bf16 v[92:95], v[148:151], v[206:209], v[92:95]
	v_mfma_f32_16x16x32_bf16 v[88:91], v[166:169], v[206:209], v[88:91]
	v_mfma_f32_16x16x32_bf16 v[76:79], v[148:151], v[214:217], v[76:79]
	v_mfma_f32_16x16x32_bf16 v[72:75], v[166:169], v[214:217], v[72:75]
	v_mfma_f32_16x16x32_bf16 v[116:119], v[170:173], v[186:189], v[116:119]
	v_mfma_f32_16x16x32_bf16 v[112:115], v[178:181], v[186:189], v[112:115]
	v_mfma_f32_16x16x32_bf16 v[100:103], v[170:173], v[194:197], v[100:103]
	v_mfma_f32_16x16x32_bf16 v[96:99], v[178:181], v[194:197], v[96:99]
	v_mfma_f32_16x16x32_bf16 v[84:87], v[170:173], v[202:205], v[84:87]
	v_mfma_f32_16x16x32_bf16 v[80:83], v[178:181], v[202:205], v[80:83]
	v_mfma_f32_16x16x32_bf16 v[68:71], v[170:173], v[210:213], v[68:71]
	v_mfma_f32_16x16x32_bf16 v[64:67], v[178:181], v[210:213], v[64:67]
	v_mfma_f32_16x16x32_bf16 v[116:119], v[174:177], v[190:193], v[116:119]
	v_mfma_f32_16x16x32_bf16 v[112:115], v[182:185], v[190:193], v[112:115]
	v_mfma_f32_16x16x32_bf16 v[100:103], v[174:177], v[198:201], v[100:103]
	v_mfma_f32_16x16x32_bf16 v[96:99], v[182:185], v[198:201], v[96:99]
	v_mfma_f32_16x16x32_bf16 v[84:87], v[174:177], v[206:209], v[84:87]
	v_mfma_f32_16x16x32_bf16 v[80:83], v[182:185], v[206:209], v[80:83]
	v_mfma_f32_16x16x32_bf16 v[68:71], v[174:177], v[214:217], v[68:71]
	v_mfma_f32_16x16x32_bf16 v[64:67], v[182:185], v[214:217], v[64:67]
	s_setprio 0
	s_barrier
; #define PG8_STAGE(bufoff, gbase, voff) do { _Pragma("unroll") for (int _i = 0; _i < 2; ++_i) \
;         __builtin_amdgcn_global_load_lds((const unsigned*)((const char*)(gbase) + (voff)[_i]), (PG8_LAS unsigned*)(lds + (bufoff) + ldsw + _i * 8192), 16, 0, 0); } while (0)
; #define PG8_LDA(dst, b, h) do { _Pragma("unroll") for (int m = 0; m < 4; ++m) _Pragma("unroll") for (int k = 0; k < 2; ++k) dst[m][k] = *(const PG8_LAS bf16x8*)(lds + PG8_SA(b, h) + aoff + m * 2048 + k * 1024); } while (0)
; #define PG8_LDB(dst, b, h) do { _Pragma("unroll") for (int n = 0; n < 2; ++n) _Pragma("unroll") for (int k = 0; k < 2; ++k) dst[n][k] = *(const PG8_LAS bf16x8*)(lds + PG8_SB(b, h) + boff + n * 2048 + k * 1024); } while (0)
; #define PG8_MMA(ai, bj, At, Bt) do { __builtin_amdgcn_s_setprio(1); _Pragma("unroll") for (int m = 0; m < 4; ++m) _Pragma("unroll") for (int n = 0; n < 2; ++n) _Pragma("unroll") for (int k = 0; k < 2; ++k) \
;         acc[ai][bj][m][n] = __builtin_amdgcn_mfma_f32_16x16x32_bf16(Bt[n][k], At[m][k], acc[ai][bj][m][n], 0, 0, 0); __builtin_amdgcn_s_setprio(0); } while (0)
; #define PG8_WAIT_V(n) asm volatile("s_waitcnt vmcnt(" #n ")" ::: "memory")
; #define PG8_WAIT_L(n) asm volatile("s_waitcnt lgkmcnt(" #n ")" ::: "memory")
; #define PG8_BAR __builtin_amdgcn_s_barrier()
; #define PG8_SCHED __builtin_amdgcn_sched_barrier(0)
; template <class Epi, class Sched, bool ALIGN_EPI = false, bool SP2 = false>
; __device__ __forceinline__ void gemm_phase(PG8_LAS unsigned char* lds, const Gemm g, const Sched& S, const Epi& E) {
;     ...
;             PG8_LDA(At, 0, 1); PG8_STAGE(PG8_SB(0, 0), b2, voffB); PG8_STAGE(PG8_SB(0, 1), b2 + hstep, voffB); PG8_STAGE(PG8_SA(0, 0), a2, voffA);
;             PG8_WAIT_V(8); PG8_WAIT_L(0); PG8_BAR; PG8_MMA(1, 0, At, B0); PG8_MMA(1, 1, At, B1); PG8_BAR; PG8_SCHED;
;             PG8_LDB(B0, 1, 0); PG8_LDB(B1, 1, 1); PG8_SCHED; PG8_LDA(At, 1, 0); PG8_STAGE(PG8_SA(0, 1), a2 + hstep, voffA);
	s_add_i32 s33, s78, s62
	s_add_u32 s80, s56, s20
	s_addc_u32 s81, s57, s21
	s_mov_b32 m0, s33
	ds_read_b128 v[186:189], v161 offset:16384
	ds_read_b128 v[190:193], v161 offset:17408
	ds_read_b128 v[194:197], v161 offset:18432
	ds_read_b128 v[198:201], v161 offset:19456
	ds_read_b128 v[202:205], v161 offset:20480
	ds_read_b128 v[206:209], v161 offset:21504
	ds_read_b128 v[210:213], v161 offset:22528
	ds_read_b128 v[214:217], v161 offset:23552
	global_load_lds_dwordx4 v130, s[56:57]
	s_add_i32 m0, s33, 0x2000
	s_add_u32 s92, s56, 0x40000
	s_addc_u32 s93, s57, 0
	s_add_i32 s33, s79, s62
	global_load_lds_dwordx4 v134, s[56:57]
	s_mov_b32 m0, s33
	s_add_u32 s82, s58, s20
	s_addc_u32 s83, s59, s21
	global_load_lds_dwordx4 v130, s[92:93]
	s_add_i32 m0, s33, 0x2000
	s_nop 0
	global_load_lds_dwordx4 v134, s[92:93]
	s_mov_b32 m0, s53
	s_nop 0
	global_load_lds_dwordx4 v128, s[58:59]
	s_mov_b32 m0, s63
	s_nop 0
	global_load_lds_dwordx4 v132, s[58:59]
	s_waitcnt vmcnt(8)
	s_waitcnt lgkmcnt(0)
	s_barrier
	s_setprio 1
	s_waitcnt lgkmcnt(0)
	v_mfma_f32_16x16x32_bf16 v[60:63], v[144:147], v[186:189], v[60:63]
	v_mfma_f32_16x16x32_bf16 v[56:59], v[162:165], v[186:189], v[56:59]
	v_mfma_f32_16x16x32_bf16 v[48:51], v[144:147], v[194:197], v[48:51]
	v_mfma_f32_16x16x32_bf16 v[40:43], v[162:165], v[194:197], v[40:43]
	v_mfma_f32_16x16x32_bf16 v[32:35], v[144:147], v[202:205], v[32:35]
	v_mfma_f32_16x16x32_bf16 v[24:27], v[162:165], v[202:205], v[24:27]
	v_mfma_f32_16x16x32_bf16 v[16:19], v[144:147], v[210:213], v[16:19]
	v_mfma_f32_16x16x32_bf16 v[8:11], v[162:165], v[210:213], v[8:11]
	v_mfma_f32_16x16x32_bf16 v[60:63], v[148:151], v[190:193], v[60:63]
	v_mfma_f32_16x16x32_bf16 v[56:59], v[166:169], v[190:193], v[56:59]
	v_mfma_f32_16x16x32_bf16 v[48:51], v[148:151], v[198:201], v[48:51]
	v_mfma_f32_16x16x32_bf16 v[40:43], v[166:169], v[198:201], v[40:43]
	v_mfma_f32_16x16x32_bf16 v[32:35], v[148:151], v[206:209], v[32:35]
	v_mfma_f32_16x16x32_bf16 v[24:27], v[166:169], v[206:209], v[24:27]
	v_mfma_f32_16x16x32_bf16 v[16:19], v[148:151], v[214:217], v[16:19]
	v_mfma_f32_16x16x32_bf16 v[8:11], v[166:169], v[214:217], v[8:11]
	v_mfma_f32_16x16x32_bf16 v[52:55], v[170:173], v[186:189], v[52:55]
	v_mfma_f32_16x16x32_bf16 v[44:47], v[178:181], v[186:189], v[44:47]
	v_mfma_f32_16x16x32_bf16 v[36:39], v[170:173], v[194:197], v[36:39]
	v_mfma_f32_16x16x32_bf16 v[28:31], v[178:181], v[194:197], v[28:31]
	v_mfma_f32_16x16x32_bf16 v[20:23], v[170:173], v[202:205], v[20:23]
	v_mfma_f32_16x16x32_bf16 v[12:15], v[178:181], v[202:205], v[12:15]
	v_mfma_f32_16x16x32_bf16 v[4:7], v[170:173], v[210:213], v[4:7]
	v_mfma_f32_16x16x32_bf16 v[0:3], v[178:181], v[210:213], v[0:3]
	v_mfma_f32_16x16x32_bf16 v[52:55], v[174:177], v[190:193], v[52:55]
	v_mfma_f32_16x16x32_bf16 v[44:47], v[182:185], v[190:193], v[44:47]
	v_mfma_f32_16x16x32_bf16 v[36:39], v[174:177], v[198:201], v[36:39]
	v_mfma_f32_16x16x32_bf16 v[28:31], v[182:185], v[198:201], v[28:31]
	v_mfma_f32_16x16x32_bf16 v[20:23], v[174:177], v[206:209], v[20:23]
	v_mfma_f32_16x16x32_bf16 v[12:15], v[182:185], v[206:209], v[12:15]
	v_mfma_f32_16x16x32_bf16 v[4:7], v[174:177], v[214:217], v[4:7]
	v_mfma_f32_16x16x32_bf16 v[0:3], v[182:185], v[214:217], v[0:3]
	s_setprio 0
	s_barrier
	s_add_i32 s33, 0, 0x18000
	v_add_u32_e32 v153, s33, v157
	s_add_i32 s34, 0, 0x1c000
	ds_read_b128 v[144:147], v153
	ds_read_b128 v[148:151], v153 offset:1024
	ds_read_b128 v[162:165], v153 offset:2048
	ds_read_b128 v[166:169], v153 offset:3072
	v_add_u32_e32 v153, s34, v157
	ds_read_b128 v[170:173], v153
	ds_read_b128 v[174:177], v153 offset:1024
	ds_read_b128 v[178:181], v153 offset:2048
	ds_read_b128 v[182:185], v153 offset:3072
	s_add_u32 s58, s58, 0x40000
	s_addc_u32 s59, s59, 0
	s_mov_b32 m0, s70
	ds_read_b128 v[186:189], v161 offset:32768
	ds_read_b128 v[190:193], v161 offset:33792
	ds_read_b128 v[194:197], v161 offset:34816
	ds_read_b128 v[198:201], v161 offset:35840
	ds_read_b128 v[202:205], v161 offset:36864
	ds_read_b128 v[206:209], v161 offset:37888
	ds_read_b128 v[210:213], v161 offset:38912
	ds_read_b128 v[214:217], v161 offset:39936
	global_load_lds_dwordx4 v128, s[58:59]
	s_mov_b32 m0, s71
	s_nop 0
	global_load_lds_dwordx4 v132, s[58:59]
	s_waitcnt vmcnt(8)
	s_waitcnt lgkmcnt(0)
	s_barrier
; #define PG8_STAGE(bufoff, gbase, voff) do { _Pragma("unroll") for (int _i = 0; _i < 2; ++_i) \
;         __builtin_amdgcn_global_load_lds((const unsigned*)((const char*)(gbase) + (voff)[_i]), (PG8_LAS unsigned*)(lds + (bufoff) + ldsw + _i * 8192), 16, 0, 0); } while (0)
; #define PG8_LDA(dst, b, h) do { _Pragma("unroll") for (int m = 0; m < 4; ++m) _Pragma("unroll") for (int k = 0; k < 2; ++k) dst[m][k] = *(const PG8_LAS bf16x8*)(lds + PG8_SA(b, h) + aoff + m * 2048 + k * 1024); } while (0)
; #define PG8_MMA(ai, bj, At, Bt) do { __builtin_amdgcn_s_setprio(1); _Pragma("unroll") for (int m = 0; m < 4; ++m) _Pragma("unroll") for (int n = 0; n < 2; ++n) _Pragma("unroll") for (int k = 0; k < 2; ++k) \
;         acc[ai][bj][m][n] = __builtin_amdgcn_mfma_f32_16x16x32_bf16(Bt[n][k], At[m][k], acc[ai][bj][m][n], 0, 0, 0); __builtin_amdgcn_s_setprio(0); } while (0)
; #define PG8_WAIT_V(n) asm volatile("s_waitcnt vmcnt(" #n ")" ::: "memory")
; #define PG8_WAIT_L(n) asm volatile("s_waitcnt lgkmcnt(" #n ")" ::: "memory")
; #define PG8_BAR __builtin_amdgcn_s_barrier()
; #define PG8_SCHED __builtin_amdgcn_sched_barrier(0)
; template <class Epi, class Sched, bool ALIGN_EPI = false, bool SP2 = false>
; __device__ __forceinline__ void gemm_phase(PG8_LAS unsigned char* lds, const Gemm g, const Sched& S, const Epi& E) {
;     ...
;             PG8_WAIT_V(8); PG8_WAIT_L(0); PG8_BAR; PG8_MMA(0, 0, At, B0); PG8_MMA(0, 1, At, B1); PG8_BAR; PG8_SCHED;
;             PG8_LDA(At, 1, 1); PG8_STAGE(PG8_SB(1, 0), b3, voffB); PG8_STAGE(PG8_SB(1, 1), b3 + hstep, voffB); PG8_STAGE(PG8_SA(1, 0), a3, voffA);
;             PG8_WAIT_V(8); PG8_WAIT_L(0); PG8_BAR; PG8_MMA(1, 0, At, B0); PG8_MMA(1, 1, At, B1); PG8_BAR; PG8_SCHED;
;     ...
;         if constexpr (ALIGN_EPI) { if (wr == 0) PG8_BAR; }
	s_setprio 1
	s_waitcnt lgkmcnt(0)
	v_mfma_f32_16x16x32_bf16 v[124:127], v[144:147], v[186:189], v[124:127]
	v_mfma_f32_16x16x32_bf16 v[120:123], v[162:165], v[186:189], v[120:123]
	v_mfma_f32_16x16x32_bf16 v[108:111], v[144:147], v[194:197], v[108:111]
	v_mfma_f32_16x16x32_bf16 v[104:107], v[162:165], v[194:197], v[104:107]
	v_mfma_f32_16x16x32_bf16 v[92:95], v[144:147], v[202:205], v[92:95]
	v_mfma_f32_16x16x32_bf16 v[88:91], v[162:165], v[202:205], v[88:91]
	v_mfma_f32_16x16x32_bf16 v[76:79], v[144:147], v[210:213], v[76:79]
	v_mfma_f32_16x16x32_bf16 v[72:75], v[162:165], v[210:213], v[72:75]
	v_mfma_f32_16x16x32_bf16 v[124:127], v[148:151], v[190:193], v[124:127]
	v_mfma_f32_16x16x32_bf16 v[120:123], v[166:169], v[190:193], v[120:123]
	v_mfma_f32_16x16x32_bf16 v[108:111], v[148:151], v[198:201], v[108:111]
	v_mfma_f32_16x16x32_bf16 v[104:107], v[166:169], v[198:201], v[104:107]
	v_mfma_f32_16x16x32_bf16 v[92:95], v[148:151], v[206:209], v[92:95]
	v_mfma_f32_16x16x32_bf16 v[88:91], v[166:169], v[206:209], v[88:91]
	v_mfma_f32_16x16x32_bf16 v[76:79], v[148:151], v[214:217], v[76:79]
	v_mfma_f32_16x16x32_bf16 v[72:75], v[166:169], v[214:217], v[72:75]
	v_mfma_f32_16x16x32_bf16 v[116:119], v[170:173], v[186:189], v[116:119]
	v_mfma_f32_16x16x32_bf16 v[112:115], v[178:181], v[186:189], v[112:115]
	v_mfma_f32_16x16x32_bf16 v[100:103], v[170:173], v[194:197], v[100:103]
	v_mfma_f32_16x16x32_bf16 v[96:99], v[178:181], v[194:197], v[96:99]
	v_mfma_f32_16x16x32_bf16 v[84:87], v[170:173], v[202:205], v[84:87]
	v_mfma_f32_16x16x32_bf16 v[80:83], v[178:181], v[202:205], v[80:83]
	v_mfma_f32_16x16x32_bf16 v[68:71], v[170:173], v[210:213], v[68:71]
	v_mfma_f32_16x16x32_bf16 v[64:67], v[178:181], v[210:213], v[64:67]
	v_mfma_f32_16x16x32_bf16 v[116:119], v[174:177], v[190:193], v[116:119]
	v_mfma_f32_16x16x32_bf16 v[112:115], v[182:185], v[190:193], v[112:115]
	v_mfma_f32_16x16x32_bf16 v[100:103], v[174:177], v[198:201], v[100:103]
	v_mfma_f32_16x16x32_bf16 v[96:99], v[182:185], v[198:201], v[96:99]
	v_mfma_f32_16x16x32_bf16 v[84:87], v[174:177], v[206:209], v[84:87]
	v_mfma_f32_16x16x32_bf16 v[80:83], v[182:185], v[206:209], v[80:83]
	v_mfma_f32_16x16x32_bf16 v[68:71], v[174:177], v[214:217], v[68:71]
	v_mfma_f32_16x16x32_bf16 v[64:67], v[182:185], v[214:217], v[64:67]
	s_setprio 0
	s_barrier
	s_add_i32 s33, s33, s62
	s_mov_b32 m0, s33
	ds_read_b128 v[186:189], v161 offset:49152
	ds_read_b128 v[190:193], v161 offset:50176
	ds_read_b128 v[194:197], v161 offset:51200
	ds_read_b128 v[198:201], v161 offset:52224
	ds_read_b128 v[202:205], v161 offset:53248
	ds_read_b128 v[206:209], v161 offset:54272
	ds_read_b128 v[210:213], v161 offset:55296
	ds_read_b128 v[214:217], v161 offset:56320
	global_load_lds_dwordx4 v130, s[80:81]
	s_add_i32 m0, s33, 0x2000
	s_add_u32 s56, s56, 0x40080
	s_addc_u32 s57, s57, 0
	s_add_i32 s33, s34, s62
	global_load_lds_dwordx4 v134, s[80:81]
	s_mov_b32 m0, s33
	s_nop 0
	global_load_lds_dwordx4 v130, s[56:57]
	s_add_i32 m0, s33, 0x2000
	s_nop 0
	global_load_lds_dwordx4 v134, s[56:57]
	s_mov_b32 m0, s75
	s_nop 0
	global_load_lds_dwordx4 v128, s[82:83]
	s_mov_b32 m0, s76
	s_nop 0
	global_load_lds_dwordx4 v132, s[82:83]
	s_waitcnt vmcnt(8)
	s_waitcnt lgkmcnt(0)
	s_barrier
	s_setprio 1
	s_waitcnt lgkmcnt(0)
	v_mfma_f32_16x16x32_bf16 v[60:63], v[144:147], v[186:189], v[60:63]
	v_mfma_f32_16x16x32_bf16 v[56:59], v[162:165], v[186:189], v[56:59]
	v_mfma_f32_16x16x32_bf16 v[48:51], v[144:147], v[194:197], v[48:51]
	v_mfma_f32_16x16x32_bf16 v[40:43], v[162:165], v[194:197], v[40:43]
	v_mfma_f32_16x16x32_bf16 v[32:35], v[144:147], v[202:205], v[32:35]
	v_mfma_f32_16x16x32_bf16 v[24:27], v[162:165], v[202:205], v[24:27]
	v_mfma_f32_16x16x32_bf16 v[16:19], v[144:147], v[210:213], v[16:19]
	v_mfma_f32_16x16x32_bf16 v[8:11], v[162:165], v[210:213], v[8:11]
	v_mfma_f32_16x16x32_bf16 v[60:63], v[148:151], v[190:193], v[60:63]
	v_mfma_f32_16x16x32_bf16 v[56:59], v[166:169], v[190:193], v[56:59]
	v_mfma_f32_16x16x32_bf16 v[48:51], v[148:151], v[198:201], v[48:51]
	v_mfma_f32_16x16x32_bf16 v[40:43], v[166:169], v[198:201], v[40:43]
	v_mfma_f32_16x16x32_bf16 v[32:35], v[148:151], v[206:209], v[32:35]
	v_mfma_f32_16x16x32_bf16 v[24:27], v[166:169], v[206:209], v[24:27]
	v_mfma_f32_16x16x32_bf16 v[16:19], v[148:151], v[214:217], v[16:19]
	v_mfma_f32_16x16x32_bf16 v[8:11], v[166:169], v[214:217], v[8:11]
	v_mfma_f32_16x16x32_bf16 v[52:55], v[170:173], v[186:189], v[52:55]
	v_mfma_f32_16x16x32_bf16 v[44:47], v[178:181], v[186:189], v[44:47]
	v_mfma_f32_16x16x32_bf16 v[36:39], v[170:173], v[194:197], v[36:39]
	v_mfma_f32_16x16x32_bf16 v[28:31], v[178:181], v[194:197], v[28:31]
	v_mfma_f32_16x16x32_bf16 v[20:23], v[170:173], v[202:205], v[20:23]
	v_mfma_f32_16x16x32_bf16 v[12:15], v[178:181], v[202:205], v[12:15]
	v_mfma_f32_16x16x32_bf16 v[4:7], v[170:173], v[210:213], v[4:7]
	v_mfma_f32_16x16x32_bf16 v[0:3], v[178:181], v[210:213], v[0:3]
	v_mfma_f32_16x16x32_bf16 v[52:55], v[174:177], v[190:193], v[52:55]
	v_mfma_f32_16x16x32_bf16 v[44:47], v[182:185], v[190:193], v[44:47]
	v_mfma_f32_16x16x32_bf16 v[36:39], v[174:177], v[198:201], v[36:39]
	v_mfma_f32_16x16x32_bf16 v[28:31], v[182:185], v[198:201], v[28:31]
	v_mfma_f32_16x16x32_bf16 v[20:23], v[174:177], v[206:209], v[20:23]
	v_mfma_f32_16x16x32_bf16 v[12:15], v[182:185], v[206:209], v[12:15]
	v_mfma_f32_16x16x32_bf16 v[4:7], v[174:177], v[214:217], v[4:7]
	v_mfma_f32_16x16x32_bf16 v[0:3], v[182:185], v[214:217], v[0:3]
	s_setprio 0
	s_barrier
	s_add_i32 s91, s91, 2
	s_add_u32 s54, s54, 0x100
	s_addc_u32 s55, s55, 0
	s_add_u32 s87, s87, 0x100
	s_addc_u32 s90, s90, 0
	s_cmp_gt_u32 s91, 13
	s_cbranch_scc0 .LBB0_915
	s_and_b64 vcc, exec, s[22:23]
	s_cbranch_vccz .LBB0_918
	s_barrier

; #define PG8_STAGE(bufoff, gbase, voff) do { _Pragma("unroll") for (int _i = 0; _i < 2; ++_i) \
;         __builtin_amdgcn_global_load_lds((const unsigned*)((const char*)(gbase) + (voff)[_i]), (PG8_LAS unsigned*)(lds + (bufoff) + ldsw + _i * 8192), 16, 0, 0); } while (0)
; #define PG8_LDA(dst, b, h) do { _Pragma("unroll") for (int m = 0; m < 4; ++m) _Pragma("unroll") for (int k = 0; k < 2; ++k) dst[m][k] = *(const PG8_LAS bf16x8*)(lds + PG8_SA(b, h) + aoff + m * 2048 + k * 1024); } while (0)
; #define PG8_LDB(dst, b, h) do { _Pragma("unroll") for (int n = 0; n < 2; ++n) _Pragma("unroll") for (int k = 0; k < 2; ++k) dst[n][k] = *(const PG8_LAS bf16x8*)(lds + PG8_SB(b, h) + boff + n * 2048 + k * 1024); } while (0)
; #define PG8_WAIT_V(n) asm volatile("s_waitcnt vmcnt(" #n ")" ::: "memory")
; #define PG8_WAIT_L(n) asm volatile("s_waitcnt lgkmcnt(" #n ")" ::: "memory")
; #define PG8_BAR __builtin_amdgcn_s_barrier()
; #define PG8_SCHED __builtin_amdgcn_sched_barrier(0)
; template <class Epi, class Sched, bool ALIGN_EPI = false, bool SP2 = false>
; __device__ __forceinline__ void gemm_phase(PG8_LAS unsigned char* lds, const Gemm g, const Sched& S, const Epi& E) {
;     ...
;         const bool has_next = S.next(ui + 1, nxt);
;         const char* nA = has_next ? (const char*)g.A + (size_t)nxt.pm * tstep : cA; const char* nB = has_next ? (const char*)g.Bt + (size_t)nxt.pn * tstep : cB;
;         for (int t = 0; t < nt; t += 2) {
;             const bool last = (t == nt - 2);
;             const char* a1 = cA + (size_t)(t + 1) * kstep;
;             const char* a2 = last ? nA : cA + (size_t)(t + 2) * kstep; const char* b2 = last ? nB : cB + (size_t)(t + 2) * kstep;
;             const char* a3 = a2 + kstep; const char* b3 = b2 + kstep;
;             if (last && has_next) S.a_ready(nxt);
;             if constexpr (SP2) {
;             PG8_LDB(B0, 0, 0); PG8_LDB(B1, 0, 1); PG8_SCHED; PG8_LDA(At, 0, 0); PG8_STAGE(PG8_SA(1, 1), a1 + hstep, voffA);
;             PG8_WAIT_V(8); PG8_WAIT_L(0); PG8_BAR; PG8_MMA(0, 0, At, B0); PG8_MMA(0, 1, At, B1); PG8_BAR; PG8_SCHED;
;             PG8_LDA(At, 0, 1); PG8_STAGE(PG8_SB(0, 0), b2, voffB); PG8_STAGE(PG8_SB(0, 1), b2 + hstep, voffB); PG8_STAGE(PG8_SA(0, 0), a2, voffA);
;             PG8_WAIT_V(8); PG8_WAIT_L(0); PG8_BAR; PG8_MMA(1, 0, At, B0); PG8_MMA(1, 1, At, B1); PG8_BAR; PG8_SCHED;
.LBB0_1209:
	s_ashr_i32 s43, s42, 31
	s_lshl_b64 s[44:45], s[42:43], 19
	s_add_u32 s44, s16, s44
	s_addc_u32 s45, s17, s45
	s_and_b64 s[46:47], s[0:1], exec
	s_cselect_b32 s43, s45, s5
	s_cselect_b32 s76, s44, s4
	s_ashr_i32 s41, s40, 31
	s_lshl_b64 s[46:47], s[40:41], 19
	s_add_u32 s46, s56, s46
	s_addc_u32 s47, s57, s47
	s_and_b64 s[54:55], s[0:1], exec
	s_cselect_b32 s41, s47, s53
	s_cselect_b32 s77, s46, s52
	s_add_u32 s4, s4, 0x40080
	s_addc_u32 s5, s5, 0
	s_add_u32 s78, s52, 0x100
	s_addc_u32 s79, s53, 0
	s_mov_b32 s80, -2
	s_waitcnt lgkmcnt(0)
	s_add_u32 s33, s4, 0xfffc0080
	s_addc_u32 s34, s5, -1
	s_cmp_eq_u32 s80, 12
	s_cselect_b32 s55, s43, s34
	s_cselect_b32 s54, s76, s33
	s_cselect_b32 s53, s41, s79
	s_cselect_b32 s52, s77, s78
	s_add_i32 m0, s49, 0xc000
	global_load_lds_dwordx4 v158, s[4:5]
	s_add_i32 m0, s49, 0xe000
	s_nop 0
	global_load_lds_dwordx4 v160, s[4:5]
	s_waitcnt vmcnt(8)
	s_waitcnt lgkmcnt(0)
	s_barrier
	s_setprio 1
	s_waitcnt lgkmcnt(0)
	v_mfma_f32_16x16x32_bf16 v[124:127], v[128:131], v[184:187], 0
	v_mfma_f32_16x16x32_bf16 v[120:123], v[136:139], v[184:187], 0
	v_mfma_f32_16x16x32_bf16 v[116:119], v[128:131], v[192:195], 0
	v_mfma_f32_16x16x32_bf16 v[112:115], v[136:139], v[192:195], 0
	v_mfma_f32_16x16x32_bf16 v[108:111], v[128:131], v[200:203], 0
	v_mfma_f32_16x16x32_bf16 v[104:107], v[136:139], v[200:203], 0
	v_mfma_f32_16x16x32_bf16 v[100:103], v[128:131], v[208:211], 0
	v_mfma_f32_16x16x32_bf16 v[96:99], v[136:139], v[208:211], 0
	v_mfma_f32_16x16x32_bf16 v[124:127], v[132:135], v[188:191], v[124:127]
	v_mfma_f32_16x16x32_bf16 v[120:123], v[140:143], v[188:191], v[120:123]
	v_mfma_f32_16x16x32_bf16 v[116:119], v[132:135], v[196:199], v[116:119]
	v_mfma_f32_16x16x32_bf16 v[112:115], v[140:143], v[196:199], v[112:115]
	v_mfma_f32_16x16x32_bf16 v[108:111], v[132:135], v[204:207], v[108:111]
	v_mfma_f32_16x16x32_bf16 v[104:107], v[140:143], v[204:207], v[104:107]
	v_mfma_f32_16x16x32_bf16 v[100:103], v[132:135], v[212:215], v[100:103]
	v_mfma_f32_16x16x32_bf16 v[96:99], v[140:143], v[212:215], v[96:99]
	v_mfma_f32_16x16x32_bf16 v[60:63], v[144:147], v[184:187], 0
	v_mfma_f32_16x16x32_bf16 v[56:59], v[170:173], v[184:187], 0
	v_mfma_f32_16x16x32_bf16 v[52:55], v[144:147], v[192:195], 0
	v_mfma_f32_16x16x32_bf16 v[48:51], v[170:173], v[192:195], 0
	v_mfma_f32_16x16x32_bf16 v[44:47], v[144:147], v[200:203], 0
	v_mfma_f32_16x16x32_bf16 v[40:43], v[170:173], v[200:203], 0
	v_mfma_f32_16x16x32_bf16 v[36:39], v[144:147], v[208:211], 0
	v_mfma_f32_16x16x32_bf16 v[32:35], v[170:173], v[208:211], 0
	v_mfma_f32_16x16x32_bf16 v[60:63], v[166:169], v[188:191], v[60:63]
	v_mfma_f32_16x16x32_bf16 v[56:59], v[174:177], v[188:191], v[56:59]
	v_mfma_f32_16x16x32_bf16 v[52:55], v[166:169], v[196:199], v[52:55]
	v_mfma_f32_16x16x32_bf16 v[48:51], v[174:177], v[196:199], v[48:51]
	v_mfma_f32_16x16x32_bf16 v[44:47], v[166:169], v[204:207], v[44:47]
	v_mfma_f32_16x16x32_bf16 v[40:43], v[174:177], v[204:207], v[40:43]
	v_mfma_f32_16x16x32_bf16 v[36:39], v[166:169], v[212:215], v[36:39]
	v_mfma_f32_16x16x32_bf16 v[32:35], v[174:177], v[212:215], v[32:35]
	s_setprio 0
	s_barrier
	s_add_i32 s33, s69, s58
	s_add_u32 s86, s52, s20
	s_addc_u32 s87, s53, s21
	s_mov_b32 m0, s33
	ds_read_b128 v[184:187], v183 offset:16384
	ds_read_b128 v[188:191], v183 offset:17408
	ds_read_b128 v[192:195], v183 offset:18432
	ds_read_b128 v[196:199], v183 offset:19456
	ds_read_b128 v[200:203], v183 offset:20480
	ds_read_b128 v[204:207], v183 offset:21504
	ds_read_b128 v[208:211], v183 offset:22528
	ds_read_b128 v[212:215], v183 offset:23552
	global_load_lds_dwordx4 v150, s[52:53]
	s_add_i32 m0, s33, 0x2000
	s_add_u32 s82, s52, 0x40000
	s_addc_u32 s83, s53, 0
	s_add_i32 s33, s70, s58
	global_load_lds_dwordx4 v156, s[52:53]
	s_mov_b32 m0, s33
	s_add_u32 s88, s54, s20
	s_addc_u32 s89, s55, s21
	global_load_lds_dwordx4 v150, s[82:83]
	s_add_i32 m0, s33, 0x2000
	s_nop 0
	global_load_lds_dwordx4 v156, s[82:83]
	s_mov_b32 m0, s49
	s_nop 0
	global_load_lds_dwordx4 v148, s[54:55]
	s_mov_b32 m0, s60
	s_nop 0
	global_load_lds_dwordx4 v154, s[54:55]
	s_waitcnt vmcnt(8)
	s_waitcnt lgkmcnt(0)
	s_barrier
	s_setprio 1
	s_waitcnt lgkmcnt(0)
	v_mfma_f32_16x16x32_bf16 v[92:95], v[128:131], v[184:187], 0
	v_mfma_f32_16x16x32_bf16 v[88:91], v[136:139], v[184:187], 0
	v_mfma_f32_16x16x32_bf16 v[84:87], v[128:131], v[192:195], 0
	v_mfma_f32_16x16x32_bf16 v[80:83], v[136:139], v[192:195], 0
	v_mfma_f32_16x16x32_bf16 v[76:79], v[128:131], v[200:203], 0
	v_mfma_f32_16x16x32_bf16 v[72:75], v[136:139], v[200:203], 0
	v_mfma_f32_16x16x32_bf16 v[68:71], v[128:131], v[208:211], 0
	v_mfma_f32_16x16x32_bf16 v[64:67], v[136:139], v[208:211], 0
	v_mfma_f32_16x16x32_bf16 v[92:95], v[132:135], v[188:191], v[92:95]
	v_mfma_f32_16x16x32_bf16 v[88:91], v[140:143], v[188:191], v[88:91]
	v_mfma_f32_16x16x32_bf16 v[84:87], v[132:135], v[196:199], v[84:87]
	v_mfma_f32_16x16x32_bf16 v[80:83], v[140:143], v[196:199], v[80:83]
	v_mfma_f32_16x16x32_bf16 v[76:79], v[132:135], v[204:207], v[76:79]
	v_mfma_f32_16x16x32_bf16 v[72:75], v[140:143], v[204:207], v[72:75]
	v_mfma_f32_16x16x32_bf16 v[68:71], v[132:135], v[212:215], v[68:71]
	v_mfma_f32_16x16x32_bf16 v[64:67], v[140:143], v[212:215], v[64:67]
	v_mfma_f32_16x16x32_bf16 v[28:31], v[144:147], v[184:187], 0
	v_mfma_f32_16x16x32_bf16 v[24:27], v[170:173], v[184:187], 0
	v_mfma_f32_16x16x32_bf16 v[20:23], v[144:147], v[192:195], 0
	v_mfma_f32_16x16x32_bf16 v[16:19], v[170:173], v[192:195], 0
	v_mfma_f32_16x16x32_bf16 v[12:15], v[144:147], v[200:203], 0
	v_mfma_f32_16x16x32_bf16 v[8:11], v[170:173], v[200:203], 0
	v_mfma_f32_16x16x32_bf16 v[4:7], v[144:147], v[208:211], 0
	v_mfma_f32_16x16x32_bf16 v[0:3], v[170:173], v[208:211], 0
	v_mfma_f32_16x16x32_bf16 v[28:31], v[166:169], v[188:191], v[28:31]
	v_mfma_f32_16x16x32_bf16 v[24:27], v[174:177], v[188:191], v[24:27]
	v_mfma_f32_16x16x32_bf16 v[20:23], v[166:169], v[196:199], v[20:23]
	v_mfma_f32_16x16x32_bf16 v[16:19], v[174:177], v[196:199], v[16:19]
	v_mfma_f32_16x16x32_bf16 v[12:15], v[166:169], v[204:207], v[12:15]
	v_mfma_f32_16x16x32_bf16 v[8:11], v[174:177], v[204:207], v[8:11]
	v_mfma_f32_16x16x32_bf16 v[4:7], v[166:169], v[212:215], v[4:7]
	v_mfma_f32_16x16x32_bf16 v[0:3], v[174:177], v[212:215], v[0:3]
	s_setprio 0
	s_barrier
; #define PG8_STAGE(bufoff, gbase, voff) do { _Pragma("unroll") for (int _i = 0; _i < 2; ++_i) \
;         __builtin_amdgcn_global_load_lds((const unsigned*)((const char*)(gbase) + (voff)[_i]), (PG8_LAS unsigned*)(lds + (bufoff) + ldsw + _i * 8192), 16, 0, 0); } while (0)
; #define PG8_LDA(dst, b, h) do { _Pragma("unroll") for (int m = 0; m < 4; ++m) _Pragma("unroll") for (int k = 0; k < 2; ++k) dst[m][k] = *(const PG8_LAS bf16x8*)(lds + PG8_SA(b, h) + aoff + m * 2048 + k * 1024); } while (0)
; #define PG8_LDB(dst, b, h) do { _Pragma("unroll") for (int n = 0; n < 2; ++n) _Pragma("unroll") for (int k = 0; k < 2; ++k) dst[n][k] = *(const PG8_LAS bf16x8*)(lds + PG8_SB(b, h) + boff + n * 2048 + k * 1024); } while (0)
; #define PG8_MMA(ai, bj, At, Bt) do { __builtin_amdgcn_s_setprio(1); _Pragma("unroll") for (int m = 0; m < 4; ++m) _Pragma("unroll") for (int n = 0; n < 2; ++n) _Pragma("unroll") for (int k = 0; k < 2; ++k) \
;         acc[ai][bj][m][n] = __builtin_amdgcn_mfma_f32_16x16x32_bf16(Bt[n][k], At[m][k], acc[ai][bj][m][n], 0, 0, 0); __builtin_amdgcn_s_setprio(0); } while (0)
; #define PG8_WAIT_V(n) asm volatile("s_waitcnt vmcnt(" #n ")" ::: "memory")
; #define PG8_WAIT_L(n) asm volatile("s_waitcnt lgkmcnt(" #n ")" ::: "memory")
; #define PG8_BAR __builtin_amdgcn_s_barrier()
; #define PG8_SCHED __builtin_amdgcn_sched_barrier(0)
; template <class Epi, class Sched, bool ALIGN_EPI = false, bool SP2 = false>
; __device__ __forceinline__ void gemm_phase(PG8_LAS unsigned char* lds, const Gemm g, const Sched& S, const Epi& E) {
;     ...
;             PG8_LDB(B0, 1, 0); PG8_LDB(B1, 1, 1); PG8_SCHED; PG8_LDA(At, 1, 0); PG8_STAGE(PG8_SA(0, 1), a2 + hstep, voffA);
;             PG8_WAIT_V(8); PG8_WAIT_L(0); PG8_BAR; PG8_MMA(0, 0, At, B0); PG8_MMA(0, 1, At, B1); PG8_BAR; PG8_SCHED;
;             PG8_LDA(At, 1, 1); PG8_STAGE(PG8_SB(1, 0), b3, voffB); PG8_STAGE(PG8_SB(1, 1), b3 + hstep, voffB); PG8_STAGE(PG8_SA(1, 0), a3, voffA);
;             PG8_WAIT_V(8); PG8_WAIT_L(0); PG8_BAR; PG8_MMA(1, 0, At, B0); PG8_MMA(1, 1, At, B1); PG8_BAR; PG8_SCHED;
	s_add_i32 s33, 0, 0x18000
	s_add_i32 s34, 0, 0x1c000
	v_add_u32_e32 v140, s33, v179
	v_add_u32_e32 v153, s34, v179
	ds_read_b128 v[128:131], v140
	ds_read_b128 v[132:135], v140 offset:1024
	ds_read_b128 v[136:139], v140 offset:2048
	ds_read_b128 v[140:143], v140 offset:3072
	ds_read_b128 v[144:147], v153
	ds_read_b128 v[166:169], v153 offset:1024
	ds_read_b128 v[170:173], v153 offset:2048
	ds_read_b128 v[174:177], v153 offset:3072
	s_add_u32 s54, s54, 0x40000
	s_addc_u32 s55, s55, 0
	s_mov_b32 m0, s61
	ds_read_b128 v[184:187], v183 offset:32768
	ds_read_b128 v[188:191], v183 offset:33792
	ds_read_b128 v[192:195], v183 offset:34816
	ds_read_b128 v[196:199], v183 offset:35840
	ds_read_b128 v[200:203], v183 offset:36864
	ds_read_b128 v[204:207], v183 offset:37888
	ds_read_b128 v[208:211], v183 offset:38912
	ds_read_b128 v[212:215], v183 offset:39936
	global_load_lds_dwordx4 v148, s[54:55]
	s_mov_b32 m0, s62
	s_nop 0
	global_load_lds_dwordx4 v154, s[54:55]
	s_waitcnt vmcnt(8)
	s_waitcnt lgkmcnt(0)
	s_barrier
	s_setprio 1
	s_waitcnt lgkmcnt(0)
	v_mfma_f32_16x16x32_bf16 v[124:127], v[128:131], v[184:187], v[124:127]
	v_mfma_f32_16x16x32_bf16 v[120:123], v[136:139], v[184:187], v[120:123]
	v_mfma_f32_16x16x32_bf16 v[116:119], v[128:131], v[192:195], v[116:119]
	v_mfma_f32_16x16x32_bf16 v[112:115], v[136:139], v[192:195], v[112:115]
	v_mfma_f32_16x16x32_bf16 v[108:111], v[128:131], v[200:203], v[108:111]
	v_mfma_f32_16x16x32_bf16 v[104:107], v[136:139], v[200:203], v[104:107]
	v_mfma_f32_16x16x32_bf16 v[100:103], v[128:131], v[208:211], v[100:103]
	v_mfma_f32_16x16x32_bf16 v[96:99], v[136:139], v[208:211], v[96:99]
	v_mfma_f32_16x16x32_bf16 v[124:127], v[132:135], v[188:191], v[124:127]
	v_mfma_f32_16x16x32_bf16 v[120:123], v[140:143], v[188:191], v[120:123]
	v_mfma_f32_16x16x32_bf16 v[116:119], v[132:135], v[196:199], v[116:119]
	v_mfma_f32_16x16x32_bf16 v[112:115], v[140:143], v[196:199], v[112:115]
	v_mfma_f32_16x16x32_bf16 v[108:111], v[132:135], v[204:207], v[108:111]
	v_mfma_f32_16x16x32_bf16 v[104:107], v[140:143], v[204:207], v[104:107]
	v_mfma_f32_16x16x32_bf16 v[100:103], v[132:135], v[212:215], v[100:103]
	v_mfma_f32_16x16x32_bf16 v[96:99], v[140:143], v[212:215], v[96:99]
	v_mfma_f32_16x16x32_bf16 v[60:63], v[144:147], v[184:187], v[60:63]
	v_mfma_f32_16x16x32_bf16 v[56:59], v[170:173], v[184:187], v[56:59]
	v_mfma_f32_16x16x32_bf16 v[52:55], v[144:147], v[192:195], v[52:55]
	v_mfma_f32_16x16x32_bf16 v[48:51], v[170:173], v[192:195], v[48:51]
	v_mfma_f32_16x16x32_bf16 v[44:47], v[144:147], v[200:203], v[44:47]
	v_mfma_f32_16x16x32_bf16 v[40:43], v[170:173], v[200:203], v[40:43]
	v_mfma_f32_16x16x32_bf16 v[36:39], v[144:147], v[208:211], v[36:39]
	v_mfma_f32_16x16x32_bf16 v[32:35], v[170:173], v[208:211], v[32:35]
	v_mfma_f32_16x16x32_bf16 v[60:63], v[166:169], v[188:191], v[60:63]
	v_mfma_f32_16x16x32_bf16 v[56:59], v[174:177], v[188:191], v[56:59]
	v_mfma_f32_16x16x32_bf16 v[52:55], v[166:169], v[196:199], v[52:55]
	v_mfma_f32_16x16x32_bf16 v[48:51], v[174:177], v[196:199], v[48:51]
	v_mfma_f32_16x16x32_bf16 v[44:47], v[166:169], v[204:207], v[44:47]
	v_mfma_f32_16x16x32_bf16 v[40:43], v[174:177], v[204:207], v[40:43]
	v_mfma_f32_16x16x32_bf16 v[36:39], v[166:169], v[212:215], v[36:39]
	v_mfma_f32_16x16x32_bf16 v[32:35], v[174:177], v[212:215], v[32:35]
	s_setprio 0
	s_barrier
	s_add_i32 s33, s33, s58
	s_mov_b32 m0, s33
	ds_read_b128 v[184:187], v183 offset:49152
	ds_read_b128 v[188:191], v183 offset:50176
	ds_read_b128 v[192:195], v183 offset:51200
	ds_read_b128 v[196:199], v183 offset:52224
	ds_read_b128 v[200:203], v183 offset:53248
	ds_read_b128 v[204:207], v183 offset:54272
	ds_read_b128 v[208:211], v183 offset:55296
	ds_read_b128 v[212:215], v183 offset:56320
	global_load_lds_dwordx4 v150, s[86:87]
	s_add_i32 m0, s33, 0x2000
	s_add_u32 s52, s52, 0x40080
	s_addc_u32 s53, s53, 0
	s_add_i32 s33, s34, s58
	global_load_lds_dwordx4 v156, s[86:87]
	s_mov_b32 m0, s33
	s_nop 0
	global_load_lds_dwordx4 v150, s[52:53]
	s_add_i32 m0, s33, 0x2000
	s_nop 0
	global_load_lds_dwordx4 v156, s[52:53]
	s_mov_b32 m0, s67
	s_nop 0
	global_load_lds_dwordx4 v148, s[88:89]
	s_mov_b32 m0, s68
	s_nop 0
	global_load_lds_dwordx4 v154, s[88:89]
	s_waitcnt vmcnt(8)
	s_waitcnt lgkmcnt(0)
	s_barrier
	s_setprio 1
	s_waitcnt lgkmcnt(0)
	v_mfma_f32_16x16x32_bf16 v[92:95], v[128:131], v[184:187], v[92:95]
	v_mfma_f32_16x16x32_bf16 v[88:91], v[136:139], v[184:187], v[88:91]
	v_mfma_f32_16x16x32_bf16 v[84:87], v[128:131], v[192:195], v[84:87]
	v_mfma_f32_16x16x32_bf16 v[80:83], v[136:139], v[192:195], v[80:83]
	v_mfma_f32_16x16x32_bf16 v[76:79], v[128:131], v[200:203], v[76:79]
	v_mfma_f32_16x16x32_bf16 v[72:75], v[136:139], v[200:203], v[72:75]
	v_mfma_f32_16x16x32_bf16 v[68:71], v[128:131], v[208:211], v[68:71]
	v_mfma_f32_16x16x32_bf16 v[64:67], v[136:139], v[208:211], v[64:67]
	v_mfma_f32_16x16x32_bf16 v[92:95], v[132:135], v[188:191], v[92:95]
	v_mfma_f32_16x16x32_bf16 v[88:91], v[140:143], v[188:191], v[88:91]
	v_mfma_f32_16x16x32_bf16 v[84:87], v[132:135], v[196:199], v[84:87]
	v_mfma_f32_16x16x32_bf16 v[80:83], v[140:143], v[196:199], v[80:83]
	v_mfma_f32_16x16x32_bf16 v[76:79], v[132:135], v[204:207], v[76:79]
	v_mfma_f32_16x16x32_bf16 v[72:75], v[140:143], v[204:207], v[72:75]
	v_mfma_f32_16x16x32_bf16 v[68:71], v[132:135], v[212:215], v[68:71]
	v_mfma_f32_16x16x32_bf16 v[64:67], v[140:143], v[212:215], v[64:67]
	v_mfma_f32_16x16x32_bf16 v[28:31], v[144:147], v[184:187], v[28:31]
	v_mfma_f32_16x16x32_bf16 v[24:27], v[170:173], v[184:187], v[24:27]
	v_mfma_f32_16x16x32_bf16 v[20:23], v[144:147], v[192:195], v[20:23]
	v_mfma_f32_16x16x32_bf16 v[16:19], v[170:173], v[192:195], v[16:19]
	v_mfma_f32_16x16x32_bf16 v[12:15], v[144:147], v[200:203], v[12:15]
	v_mfma_f32_16x16x32_bf16 v[8:11], v[170:173], v[200:203], v[8:11]
	v_mfma_f32_16x16x32_bf16 v[4:7], v[144:147], v[208:211], v[4:7]
	v_mfma_f32_16x16x32_bf16 v[0:3], v[170:173], v[208:211], v[0:3]
	v_mfma_f32_16x16x32_bf16 v[28:31], v[166:169], v[188:191], v[28:31]
	v_mfma_f32_16x16x32_bf16 v[24:27], v[174:177], v[188:191], v[24:27]
	v_mfma_f32_16x16x32_bf16 v[20:23], v[166:169], v[196:199], v[20:23]
	v_mfma_f32_16x16x32_bf16 v[16:19], v[174:177], v[196:199], v[16:19]
	v_mfma_f32_16x16x32_bf16 v[12:15], v[166:169], v[204:207], v[12:15]
	v_mfma_f32_16x16x32_bf16 v[8:11], v[174:177], v[204:207], v[8:11]
	v_mfma_f32_16x16x32_bf16 v[4:7], v[166:169], v[212:215], v[4:7]
	v_mfma_f32_16x16x32_bf16 v[0:3], v[174:177], v[212:215], v[0:3]
	s_setprio 0
	s_barrier
	s_add_i32 s80, s80, 2
	s_add_u32 s4, s4, 0x100
	s_addc_u32 s5, s5, 0
	s_add_u32 s78, s78, 0x100
	s_addc_u32 s79, s79, 0
	s_cmp_gt_u32 s80, 13
; #define PG8_STAGE(bufoff, gbase, voff) do { _Pragma("unroll") for (int _i = 0; _i < 2; ++_i) \
;         __builtin_amdgcn_global_load_lds((const unsigned*)((const char*)(gbase) + (voff)[_i]), (PG8_LAS unsigned*)(lds + (bufoff) + ldsw + _i * 8192), 16, 0, 0); } while (0)
; #define PG8_LDA(dst, b, h) do { _Pragma("unroll") for (int m = 0; m < 4; ++m) _Pragma("unroll") for (int k = 0; k < 2; ++k) dst[m][k] = *(const PG8_LAS bf16x8*)(lds + PG8_SA(b, h) + aoff + m * 2048 + k * 1024); } while (0)
; #define PG8_LDB(dst, b, h) do { _Pragma("unroll") for (int n = 0; n < 2; ++n) _Pragma("unroll") for (int k = 0; k < 2; ++k) dst[n][k] = *(const PG8_LAS bf16x8*)(lds + PG8_SB(b, h) + boff + n * 2048 + k * 1024); } while (0)
; #define PG8_MMA(ai, bj, At, Bt) do { __builtin_amdgcn_s_setprio(1); _Pragma("unroll") for (int m = 0; m < 4; ++m) _Pragma("unroll") for (int n = 0; n < 2; ++n) _Pragma("unroll") for (int k = 0; k < 2; ++k) \
;         acc[ai][bj][m][n] = __builtin_amdgcn_mfma_f32_16x16x32_bf16(Bt[n][k], At[m][k], acc[ai][bj][m][n], 0, 0, 0); __builtin_amdgcn_s_setprio(0); } while (0)
; #define PG8_WAIT_V(n) asm volatile("s_waitcnt vmcnt(" #n ")" ::: "memory")
; #define PG8_WAIT_L(n) asm volatile("s_waitcnt lgkmcnt(" #n ")" ::: "memory")
; #define PG8_BAR __builtin_amdgcn_s_barrier()
; #define PG8_SCHED __builtin_amdgcn_sched_barrier(0)
; template <class Epi, class Sched, bool ALIGN_EPI = false, bool SP2 = false>
; __device__ __forceinline__ void gemm_phase(PG8_LAS unsigned char* lds, const Gemm g, const Sched& S, const Epi& E) {
;     ...
;             PG8_LDB(B0, 0, 0); PG8_LDB(B1, 0, 1); PG8_SCHED; PG8_LDA(At, 0, 0); PG8_STAGE(PG8_SA(1, 1), a1 + hstep, voffA);
;             PG8_WAIT_V(8); PG8_WAIT_L(0); PG8_BAR; PG8_MMA(0, 0, At, B0); PG8_MMA(0, 1, At, B1); PG8_BAR; PG8_SCHED;
;             PG8_LDA(At, 0, 1); PG8_STAGE(PG8_SB(0, 0), b2, voffB); PG8_STAGE(PG8_SB(0, 1), b2 + hstep, voffB); PG8_STAGE(PG8_SA(0, 0), a2, voffA);
;             PG8_WAIT_V(8); PG8_WAIT_L(0); PG8_BAR; PG8_MMA(1, 0, At, B0); PG8_MMA(1, 1, At, B1); PG8_BAR; PG8_SCHED;
.LBB0_1210:
	ds_read_b128 v[128:131], v181
	ds_read_b128 v[132:135], v181 offset:1024
	ds_read_b128 v[136:139], v181 offset:2048
	ds_read_b128 v[140:143], v181 offset:3072
	ds_read_b128 v[144:147], v182
	ds_read_b128 v[166:169], v182 offset:1024
	ds_read_b128 v[170:173], v182 offset:2048
	ds_read_b128 v[174:177], v182 offset:3072
	s_add_u32 s33, s4, 0xfffc0080
	s_addc_u32 s34, s5, -1
	s_cmp_eq_u32 s80, 12
	s_cselect_b32 s55, s43, s34
	s_cselect_b32 s54, s76, s33
	s_cselect_b32 s53, s41, s79
	s_cselect_b32 s52, s77, s78
	s_add_i32 m0, s49, 0xc000
	ds_read_b128 v[184:187], v183
	ds_read_b128 v[188:191], v183 offset:1024
	ds_read_b128 v[192:195], v183 offset:2048
	ds_read_b128 v[196:199], v183 offset:3072
	ds_read_b128 v[200:203], v183 offset:4096
	ds_read_b128 v[204:207], v183 offset:5120
	ds_read_b128 v[208:211], v183 offset:6144
	ds_read_b128 v[212:215], v183 offset:7168
	global_load_lds_dwordx4 v158, s[4:5]
	s_add_i32 m0, s49, 0xe000
	s_nop 0
	global_load_lds_dwordx4 v160, s[4:5]
	s_waitcnt vmcnt(8)
	s_waitcnt lgkmcnt(0)
	s_barrier
	s_setprio 1
	s_waitcnt lgkmcnt(0)
	v_mfma_f32_16x16x32_bf16 v[124:127], v[128:131], v[184:187], v[124:127]
	v_mfma_f32_16x16x32_bf16 v[120:123], v[136:139], v[184:187], v[120:123]
	v_mfma_f32_16x16x32_bf16 v[116:119], v[128:131], v[192:195], v[116:119]
	v_mfma_f32_16x16x32_bf16 v[112:115], v[136:139], v[192:195], v[112:115]
	v_mfma_f32_16x16x32_bf16 v[108:111], v[128:131], v[200:203], v[108:111]
	v_mfma_f32_16x16x32_bf16 v[104:107], v[136:139], v[200:203], v[104:107]
	v_mfma_f32_16x16x32_bf16 v[100:103], v[128:131], v[208:211], v[100:103]
	v_mfma_f32_16x16x32_bf16 v[96:99], v[136:139], v[208:211], v[96:99]
	v_mfma_f32_16x16x32_bf16 v[124:127], v[132:135], v[188:191], v[124:127]
	v_mfma_f32_16x16x32_bf16 v[120:123], v[140:143], v[188:191], v[120:123]
	v_mfma_f32_16x16x32_bf16 v[116:119], v[132:135], v[196:199], v[116:119]
	v_mfma_f32_16x16x32_bf16 v[112:115], v[140:143], v[196:199], v[112:115]
	v_mfma_f32_16x16x32_bf16 v[108:111], v[132:135], v[204:207], v[108:111]
	v_mfma_f32_16x16x32_bf16 v[104:107], v[140:143], v[204:207], v[104:107]
	v_mfma_f32_16x16x32_bf16 v[100:103], v[132:135], v[212:215], v[100:103]
	v_mfma_f32_16x16x32_bf16 v[96:99], v[140:143], v[212:215], v[96:99]
	v_mfma_f32_16x16x32_bf16 v[60:63], v[144:147], v[184:187], v[60:63]
	v_mfma_f32_16x16x32_bf16 v[56:59], v[170:173], v[184:187], v[56:59]
	v_mfma_f32_16x16x32_bf16 v[52:55], v[144:147], v[192:195], v[52:55]
	v_mfma_f32_16x16x32_bf16 v[48:51], v[170:173], v[192:195], v[48:51]
	v_mfma_f32_16x16x32_bf16 v[44:47], v[144:147], v[200:203], v[44:47]
	v_mfma_f32_16x16x32_bf16 v[40:43], v[170:173], v[200:203], v[40:43]
	v_mfma_f32_16x16x32_bf16 v[36:39], v[144:147], v[208:211], v[36:39]
	v_mfma_f32_16x16x32_bf16 v[32:35], v[170:173], v[208:211], v[32:35]
	v_mfma_f32_16x16x32_bf16 v[60:63], v[166:169], v[188:191], v[60:63]
	v_mfma_f32_16x16x32_bf16 v[56:59], v[174:177], v[188:191], v[56:59]
	v_mfma_f32_16x16x32_bf16 v[52:55], v[166:169], v[196:199], v[52:55]
	v_mfma_f32_16x16x32_bf16 v[48:51], v[174:177], v[196:199], v[48:51]
	v_mfma_f32_16x16x32_bf16 v[44:47], v[166:169], v[204:207], v[44:47]
	v_mfma_f32_16x16x32_bf16 v[40:43], v[174:177], v[204:207], v[40:43]
	v_mfma_f32_16x16x32_bf16 v[36:39], v[166:169], v[212:215], v[36:39]
	v_mfma_f32_16x16x32_bf16 v[32:35], v[174:177], v[212:215], v[32:35]
	s_setprio 0
	s_barrier
	s_add_i32 s33, s69, s58
	s_add_u32 s86, s52, s20
	s_addc_u32 s87, s53, s21
	s_mov_b32 m0, s33
	ds_read_b128 v[184:187], v183 offset:16384
	ds_read_b128 v[188:191], v183 offset:17408
	ds_read_b128 v[192:195], v183 offset:18432
	ds_read_b128 v[196:199], v183 offset:19456
	ds_read_b128 v[200:203], v183 offset:20480
	ds_read_b128 v[204:207], v183 offset:21504
	ds_read_b128 v[208:211], v183 offset:22528
	ds_read_b128 v[212:215], v183 offset:23552
	global_load_lds_dwordx4 v150, s[52:53]
	s_add_i32 m0, s33, 0x2000
	s_add_u32 s82, s52, 0x40000
	s_addc_u32 s83, s53, 0
	s_add_i32 s33, s70, s58
	global_load_lds_dwordx4 v156, s[52:53]
	s_mov_b32 m0, s33
	s_add_u32 s88, s54, s20
	s_addc_u32 s89, s55, s21
	global_load_lds_dwordx4 v150, s[82:83]
	s_add_i32 m0, s33, 0x2000
	s_nop 0
	global_load_lds_dwordx4 v156, s[82:83]
	s_mov_b32 m0, s49
	s_nop 0
	global_load_lds_dwordx4 v148, s[54:55]
	s_mov_b32 m0, s60
	s_nop 0
	global_load_lds_dwordx4 v154, s[54:55]
	s_waitcnt vmcnt(8)
	s_waitcnt lgkmcnt(0)
	s_barrier
	s_setprio 1
	s_waitcnt lgkmcnt(0)
	v_mfma_f32_16x16x32_bf16 v[92:95], v[128:131], v[184:187], v[92:95]
	v_mfma_f32_16x16x32_bf16 v[88:91], v[136:139], v[184:187], v[88:91]
	v_mfma_f32_16x16x32_bf16 v[84:87], v[128:131], v[192:195], v[84:87]
	v_mfma_f32_16x16x32_bf16 v[80:83], v[136:139], v[192:195], v[80:83]
	v_mfma_f32_16x16x32_bf16 v[76:79], v[128:131], v[200:203], v[76:79]
	v_mfma_f32_16x16x32_bf16 v[72:75], v[136:139], v[200:203], v[72:75]
	v_mfma_f32_16x16x32_bf16 v[68:71], v[128:131], v[208:211], v[68:71]
	v_mfma_f32_16x16x32_bf16 v[64:67], v[136:139], v[208:211], v[64:67]
	v_mfma_f32_16x16x32_bf16 v[92:95], v[132:135], v[188:191], v[92:95]
	v_mfma_f32_16x16x32_bf16 v[88:91], v[140:143], v[188:191], v[88:91]
	v_mfma_f32_16x16x32_bf16 v[84:87], v[132:135], v[196:199], v[84:87]
	v_mfma_f32_16x16x32_bf16 v[80:83], v[140:143], v[196:199], v[80:83]
	v_mfma_f32_16x16x32_bf16 v[76:79], v[132:135], v[204:207], v[76:79]
	v_mfma_f32_16x16x32_bf16 v[72:75], v[140:143], v[204:207], v[72:75]
	v_mfma_f32_16x16x32_bf16 v[68:71], v[132:135], v[212:215], v[68:71]
	v_mfma_f32_16x16x32_bf16 v[64:67], v[140:143], v[212:215], v[64:67]
	v_mfma_f32_16x16x32_bf16 v[28:31], v[144:147], v[184:187], v[28:31]
	v_mfma_f32_16x16x32_bf16 v[24:27], v[170:173], v[184:187], v[24:27]
	v_mfma_f32_16x16x32_bf16 v[20:23], v[144:147], v[192:195], v[20:23]
	v_mfma_f32_16x16x32_bf16 v[16:19], v[170:173], v[192:195], v[16:19]
	v_mfma_f32_16x16x32_bf16 v[12:15], v[144:147], v[200:203], v[12:15]
	v_mfma_f32_16x16x32_bf16 v[8:11], v[170:173], v[200:203], v[8:11]
	v_mfma_f32_16x16x32_bf16 v[4:7], v[144:147], v[208:211], v[4:7]
	v_mfma_f32_16x16x32_bf16 v[0:3], v[170:173], v[208:211], v[0:3]
	v_mfma_f32_16x16x32_bf16 v[28:31], v[166:169], v[188:191], v[28:31]
	v_mfma_f32_16x16x32_bf16 v[24:27], v[174:177], v[188:191], v[24:27]
	v_mfma_f32_16x16x32_bf16 v[20:23], v[166:169], v[196:199], v[20:23]
	v_mfma_f32_16x16x32_bf16 v[16:19], v[174:177], v[196:199], v[16:19]
	v_mfma_f32_16x16x32_bf16 v[12:15], v[166:169], v[204:207], v[12:15]
	v_mfma_f32_16x16x32_bf16 v[8:11], v[174:177], v[204:207], v[8:11]
	v_mfma_f32_16x16x32_bf16 v[4:7], v[166:169], v[212:215], v[4:7]
	v_mfma_f32_16x16x32_bf16 v[0:3], v[174:177], v[212:215], v[0:3]
	s_setprio 0
	s_barrier
; #define PG8_STAGE(bufoff, gbase, voff) do { _Pragma("unroll") for (int _i = 0; _i < 2; ++_i) \
;         __builtin_amdgcn_global_load_lds((const unsigned*)((const char*)(gbase) + (voff)[_i]), (PG8_LAS unsigned*)(lds + (bufoff) + ldsw + _i * 8192), 16, 0, 0); } while (0)
; #define PG8_LDA(dst, b, h) do { _Pragma("unroll") for (int m = 0; m < 4; ++m) _Pragma("unroll") for (int k = 0; k < 2; ++k) dst[m][k] = *(const PG8_LAS bf16x8*)(lds + PG8_SA(b, h) + aoff + m * 2048 + k * 1024); } while (0)
; #define PG8_LDB(dst, b, h) do { _Pragma("unroll") for (int n = 0; n < 2; ++n) _Pragma("unroll") for (int k = 0; k < 2; ++k) dst[n][k] = *(const PG8_LAS bf16x8*)(lds + PG8_SB(b, h) + boff + n * 2048 + k * 1024); } while (0)
; #define PG8_MMA(ai, bj, At, Bt) do { __builtin_amdgcn_s_setprio(1); _Pragma("unroll") for (int m = 0; m < 4; ++m) _Pragma("unroll") for (int n = 0; n < 2; ++n) _Pragma("unroll") for (int k = 0; k < 2; ++k) \
;         acc[ai][bj][m][n] = __builtin_amdgcn_mfma_f32_16x16x32_bf16(Bt[n][k], At[m][k], acc[ai][bj][m][n], 0, 0, 0); __builtin_amdgcn_s_setprio(0); } while (0)
; #define PG8_WAIT_V(n) asm volatile("s_waitcnt vmcnt(" #n ")" ::: "memory")
; #define PG8_WAIT_L(n) asm volatile("s_waitcnt lgkmcnt(" #n ")" ::: "memory")
; #define PG8_BAR __builtin_amdgcn_s_barrier()
; #define PG8_SCHED __builtin_amdgcn_sched_barrier(0)
; template <class Epi, class Sched, bool ALIGN_EPI = false, bool SP2 = false>
; __device__ __forceinline__ void gemm_phase(PG8_LAS unsigned char* lds, const Gemm g, const Sched& S, const Epi& E) {
;     ...
;             PG8_LDB(B0, 1, 0); PG8_LDB(B1, 1, 1); PG8_SCHED; PG8_LDA(At, 1, 0); PG8_STAGE(PG8_SA(0, 1), a2 + hstep, voffA);
;             PG8_WAIT_V(8); PG8_WAIT_L(0); PG8_BAR; PG8_MMA(0, 0, At, B0); PG8_MMA(0, 1, At, B1); PG8_BAR; PG8_SCHED;
;             PG8_LDA(At, 1, 1); PG8_STAGE(PG8_SB(1, 0), b3, voffB); PG8_STAGE(PG8_SB(1, 1), b3 + hstep, voffB); PG8_STAGE(PG8_SA(1, 0), a3, voffA);
;             PG8_WAIT_V(8); PG8_WAIT_L(0); PG8_BAR; PG8_MMA(1, 0, At, B0); PG8_MMA(1, 1, At, B1); PG8_BAR; PG8_SCHED;
;     ...
;         if constexpr (ALIGN_EPI) { if (wr == 0) PG8_BAR; }
	s_add_i32 s33, 0, 0x18000
	s_add_i32 s34, 0, 0x1c000
	v_add_u32_e32 v140, s33, v179
	v_add_u32_e32 v153, s34, v179
	ds_read_b128 v[128:131], v140
	ds_read_b128 v[132:135], v140 offset:1024
	ds_read_b128 v[136:139], v140 offset:2048
	ds_read_b128 v[140:143], v140 offset:3072
	ds_read_b128 v[144:147], v153
	ds_read_b128 v[166:169], v153 offset:1024
	ds_read_b128 v[170:173], v153 offset:2048
	ds_read_b128 v[174:177], v153 offset:3072
	s_add_u32 s54, s54, 0x40000
	s_addc_u32 s55, s55, 0
	s_mov_b32 m0, s61
	ds_read_b128 v[184:187], v183 offset:32768
	ds_read_b128 v[188:191], v183 offset:33792
	ds_read_b128 v[192:195], v183 offset:34816
	ds_read_b128 v[196:199], v183 offset:35840
	ds_read_b128 v[200:203], v183 offset:36864
	ds_read_b128 v[204:207], v183 offset:37888
	ds_read_b128 v[208:211], v183 offset:38912
	ds_read_b128 v[212:215], v183 offset:39936
	global_load_lds_dwordx4 v148, s[54:55]
	s_mov_b32 m0, s62
	s_nop 0
	global_load_lds_dwordx4 v154, s[54:55]
	s_waitcnt vmcnt(8)
	s_waitcnt lgkmcnt(0)
	s_barrier
	s_setprio 1
	s_waitcnt lgkmcnt(0)
	v_mfma_f32_16x16x32_bf16 v[124:127], v[128:131], v[184:187], v[124:127]
	v_mfma_f32_16x16x32_bf16 v[120:123], v[136:139], v[184:187], v[120:123]
	v_mfma_f32_16x16x32_bf16 v[116:119], v[128:131], v[192:195], v[116:119]
	v_mfma_f32_16x16x32_bf16 v[112:115], v[136:139], v[192:195], v[112:115]
	v_mfma_f32_16x16x32_bf16 v[108:111], v[128:131], v[200:203], v[108:111]
	v_mfma_f32_16x16x32_bf16 v[104:107], v[136:139], v[200:203], v[104:107]
	v_mfma_f32_16x16x32_bf16 v[100:103], v[128:131], v[208:211], v[100:103]
	v_mfma_f32_16x16x32_bf16 v[96:99], v[136:139], v[208:211], v[96:99]
	v_mfma_f32_16x16x32_bf16 v[124:127], v[132:135], v[188:191], v[124:127]
	v_mfma_f32_16x16x32_bf16 v[120:123], v[140:143], v[188:191], v[120:123]
	v_mfma_f32_16x16x32_bf16 v[116:119], v[132:135], v[196:199], v[116:119]
	v_mfma_f32_16x16x32_bf16 v[112:115], v[140:143], v[196:199], v[112:115]
	v_mfma_f32_16x16x32_bf16 v[108:111], v[132:135], v[204:207], v[108:111]
	v_mfma_f32_16x16x32_bf16 v[104:107], v[140:143], v[204:207], v[104:107]
	v_mfma_f32_16x16x32_bf16 v[100:103], v[132:135], v[212:215], v[100:103]
	v_mfma_f32_16x16x32_bf16 v[96:99], v[140:143], v[212:215], v[96:99]
	v_mfma_f32_16x16x32_bf16 v[60:63], v[144:147], v[184:187], v[60:63]
	v_mfma_f32_16x16x32_bf16 v[56:59], v[170:173], v[184:187], v[56:59]
	v_mfma_f32_16x16x32_bf16 v[52:55], v[144:147], v[192:195], v[52:55]
	v_mfma_f32_16x16x32_bf16 v[48:51], v[170:173], v[192:195], v[48:51]
	v_mfma_f32_16x16x32_bf16 v[44:47], v[144:147], v[200:203], v[44:47]
	v_mfma_f32_16x16x32_bf16 v[40:43], v[170:173], v[200:203], v[40:43]
	v_mfma_f32_16x16x32_bf16 v[36:39], v[144:147], v[208:211], v[36:39]
	v_mfma_f32_16x16x32_bf16 v[32:35], v[170:173], v[208:211], v[32:35]
	v_mfma_f32_16x16x32_bf16 v[60:63], v[166:169], v[188:191], v[60:63]
	v_mfma_f32_16x16x32_bf16 v[56:59], v[174:177], v[188:191], v[56:59]
	v_mfma_f32_16x16x32_bf16 v[52:55], v[166:169], v[196:199], v[52:55]
	v_mfma_f32_16x16x32_bf16 v[48:51], v[174:177], v[196:199], v[48:51]
	v_mfma_f32_16x16x32_bf16 v[44:47], v[166:169], v[204:207], v[44:47]
	v_mfma_f32_16x16x32_bf16 v[40:43], v[174:177], v[204:207], v[40:43]
	v_mfma_f32_16x16x32_bf16 v[36:39], v[166:169], v[212:215], v[36:39]
	v_mfma_f32_16x16x32_bf16 v[32:35], v[174:177], v[212:215], v[32:35]
	s_setprio 0
	s_barrier
	s_add_i32 s33, s33, s58
	s_mov_b32 m0, s33
	ds_read_b128 v[184:187], v183 offset:49152
	ds_read_b128 v[188:191], v183 offset:50176
	ds_read_b128 v[192:195], v183 offset:51200
	ds_read_b128 v[196:199], v183 offset:52224
	ds_read_b128 v[200:203], v183 offset:53248
	ds_read_b128 v[204:207], v183 offset:54272
	ds_read_b128 v[208:211], v183 offset:55296
	ds_read_b128 v[212:215], v183 offset:56320
	global_load_lds_dwordx4 v150, s[86:87]
	s_add_i32 m0, s33, 0x2000
	s_add_u32 s52, s52, 0x40080
	s_addc_u32 s53, s53, 0
	s_add_i32 s33, s34, s58
	global_load_lds_dwordx4 v156, s[86:87]
	s_mov_b32 m0, s33
	s_nop 0
	global_load_lds_dwordx4 v150, s[52:53]
	s_add_i32 m0, s33, 0x2000
	s_nop 0
	global_load_lds_dwordx4 v156, s[52:53]
	s_mov_b32 m0, s67
	s_nop 0
	global_load_lds_dwordx4 v148, s[88:89]
	s_mov_b32 m0, s68
	s_nop 0
	global_load_lds_dwordx4 v154, s[88:89]
	s_waitcnt vmcnt(8)
	s_waitcnt lgkmcnt(0)
	s_barrier
	s_setprio 1
	s_waitcnt lgkmcnt(0)
	v_mfma_f32_16x16x32_bf16 v[92:95], v[128:131], v[184:187], v[92:95]
	v_mfma_f32_16x16x32_bf16 v[88:91], v[136:139], v[184:187], v[88:91]
	v_mfma_f32_16x16x32_bf16 v[84:87], v[128:131], v[192:195], v[84:87]
	v_mfma_f32_16x16x32_bf16 v[80:83], v[136:139], v[192:195], v[80:83]
	v_mfma_f32_16x16x32_bf16 v[76:79], v[128:131], v[200:203], v[76:79]
	v_mfma_f32_16x16x32_bf16 v[72:75], v[136:139], v[200:203], v[72:75]
	v_mfma_f32_16x16x32_bf16 v[68:71], v[128:131], v[208:211], v[68:71]
	v_mfma_f32_16x16x32_bf16 v[64:67], v[136:139], v[208:211], v[64:67]
	v_mfma_f32_16x16x32_bf16 v[92:95], v[132:135], v[188:191], v[92:95]
	v_mfma_f32_16x16x32_bf16 v[88:91], v[140:143], v[188:191], v[88:91]
	v_mfma_f32_16x16x32_bf16 v[84:87], v[132:135], v[196:199], v[84:87]
	v_mfma_f32_16x16x32_bf16 v[80:83], v[140:143], v[196:199], v[80:83]
	v_mfma_f32_16x16x32_bf16 v[76:79], v[132:135], v[204:207], v[76:79]
	v_mfma_f32_16x16x32_bf16 v[72:75], v[140:143], v[204:207], v[72:75]
	v_mfma_f32_16x16x32_bf16 v[68:71], v[132:135], v[212:215], v[68:71]
	v_mfma_f32_16x16x32_bf16 v[64:67], v[140:143], v[212:215], v[64:67]
	v_mfma_f32_16x16x32_bf16 v[28:31], v[144:147], v[184:187], v[28:31]
	v_mfma_f32_16x16x32_bf16 v[24:27], v[170:173], v[184:187], v[24:27]
	v_mfma_f32_16x16x32_bf16 v[20:23], v[144:147], v[192:195], v[20:23]
	v_mfma_f32_16x16x32_bf16 v[16:19], v[170:173], v[192:195], v[16:19]
	v_mfma_f32_16x16x32_bf16 v[12:15], v[144:147], v[200:203], v[12:15]
	v_mfma_f32_16x16x32_bf16 v[8:11], v[170:173], v[200:203], v[8:11]
	v_mfma_f32_16x16x32_bf16 v[4:7], v[144:147], v[208:211], v[4:7]
	v_mfma_f32_16x16x32_bf16 v[0:3], v[170:173], v[208:211], v[0:3]
	v_mfma_f32_16x16x32_bf16 v[28:31], v[166:169], v[188:191], v[28:31]
	v_mfma_f32_16x16x32_bf16 v[24:27], v[174:177], v[188:191], v[24:27]
	v_mfma_f32_16x16x32_bf16 v[20:23], v[166:169], v[196:199], v[20:23]
	v_mfma_f32_16x16x32_bf16 v[16:19], v[174:177], v[196:199], v[16:19]
	v_mfma_f32_16x16x32_bf16 v[12:15], v[166:169], v[204:207], v[12:15]
	v_mfma_f32_16x16x32_bf16 v[8:11], v[174:177], v[204:207], v[8:11]
	v_mfma_f32_16x16x32_bf16 v[4:7], v[166:169], v[212:215], v[4:7]
	v_mfma_f32_16x16x32_bf16 v[0:3], v[174:177], v[212:215], v[0:3]
	s_setprio 0
	s_barrier
	s_add_i32 s80, s80, 2
	s_add_u32 s4, s4, 0x100
	s_addc_u32 s5, s5, 0
	s_add_u32 s78, s78, 0x100
	s_addc_u32 s79, s79, 0
	s_cmp_gt_u32 s80, 13
	s_cbranch_scc0 .LBB0_1210
	s_and_b64 vcc, exec, s[22:23]
	s_cbranch_vccz .LBB0_1213
	s_barrier

; #define PG8_STAGE(bufoff, gbase, voff) do { _Pragma("unroll") for (int _i = 0; _i < 2; ++_i) \
;         __builtin_amdgcn_global_load_lds((const unsigned*)((const char*)(gbase) + (voff)[_i]), (PG8_LAS unsigned*)(lds + (bufoff) + ldsw + _i * 8192), 16, 0, 0); } while (0)
; #define PG8_LDA(dst, b, h) do { _Pragma("unroll") for (int m = 0; m < 4; ++m) _Pragma("unroll") for (int k = 0; k < 2; ++k) dst[m][k] = *(const PG8_LAS bf16x8*)(lds + PG8_SA(b, h) + aoff + m * 2048 + k * 1024); } while (0)
; #define PG8_LDB(dst, b, h) do { _Pragma("unroll") for (int n = 0; n < 2; ++n) _Pragma("unroll") for (int k = 0; k < 2; ++k) dst[n][k] = *(const PG8_LAS bf16x8*)(lds + PG8_SB(b, h) + boff + n * 2048 + k * 1024); } while (0)
; #define PG8_MMA(ai, bj, At, Bt) do { __builtin_amdgcn_s_setprio(1); _Pragma("unroll") for (int m = 0; m < 4; ++m) _Pragma("unroll") for (int n = 0; n < 2; ++n) _Pragma("unroll") for (int k = 0; k < 2; ++k) \
;         acc[ai][bj][m][n] = __builtin_amdgcn_mfma_f32_16x16x32_bf16(Bt[n][k], At[m][k], acc[ai][bj][m][n], 0, 0, 0); __builtin_amdgcn_s_setprio(0); } while (0)
; #define PG8_WAIT_V(n) asm volatile("s_waitcnt vmcnt(" #n ")" ::: "memory")
; #define PG8_WAIT_L(n) asm volatile("s_waitcnt lgkmcnt(" #n ")" ::: "memory")
; #define PG8_BAR __builtin_amdgcn_s_barrier()
; #define PG8_SCHED __builtin_amdgcn_sched_barrier(0)
; template <class Epi, class Sched, bool ALIGN_EPI = false, bool SP2 = false>
; __device__ __forceinline__ void gemm_phase(PG8_LAS unsigned char* lds, const Gemm g, const Sched& S, const Epi& E) {
;     ...
;             PG8_LDB(B0, 0, 0); PG8_LDB(B1, 0, 1); PG8_SCHED; PG8_LDA(At, 0, 0); PG8_STAGE(PG8_SA(1, 1), a1 + hstep, voffA);
;             PG8_WAIT_V(8); PG8_WAIT_L(0); PG8_BAR; PG8_MMA(0, 0, At, B0); PG8_MMA(0, 1, At, B1); PG8_BAR; PG8_SCHED;
;             PG8_LDA(At, 0, 1); PG8_STAGE(PG8_SB(0, 0), b2, voffB); PG8_STAGE(PG8_SB(0, 1), b2 + hstep, voffB); PG8_STAGE(PG8_SA(0, 0), a2, voffA);
;             PG8_WAIT_V(8); PG8_WAIT_L(0); PG8_BAR; PG8_MMA(1, 0, At, B0); PG8_MMA(1, 1, At, B1); PG8_BAR; PG8_SCHED;
.LfwP15_0_e:
	s_waitcnt lgkmcnt(0)
	s_barrier
	s_setprio 1
	s_waitcnt lgkmcnt(0)
	v_mfma_f32_16x16x32_bf16 v[124:127], v[154:157], v[186:189], 0
	v_mfma_f32_16x16x32_bf16 v[116:119], v[162:165], v[186:189], 0
	v_mfma_f32_16x16x32_bf16 v[108:111], v[154:157], v[194:197], 0
	v_mfma_f32_16x16x32_bf16 v[100:103], v[162:165], v[194:197], 0
	v_mfma_f32_16x16x32_bf16 v[92:95], v[154:157], v[202:205], 0
	v_mfma_f32_16x16x32_bf16 v[84:87], v[162:165], v[202:205], 0
	v_mfma_f32_16x16x32_bf16 v[76:79], v[154:157], v[210:213], 0
	v_mfma_f32_16x16x32_bf16 v[68:71], v[162:165], v[210:213], 0
	v_mfma_f32_16x16x32_bf16 v[124:127], v[158:161], v[190:193], v[124:127]
	v_mfma_f32_16x16x32_bf16 v[116:119], v[166:169], v[190:193], v[116:119]
	v_mfma_f32_16x16x32_bf16 v[108:111], v[158:161], v[198:201], v[108:111]
	v_mfma_f32_16x16x32_bf16 v[100:103], v[166:169], v[198:201], v[100:103]
	v_mfma_f32_16x16x32_bf16 v[92:95], v[158:161], v[206:209], v[92:95]
	v_mfma_f32_16x16x32_bf16 v[84:87], v[166:169], v[206:209], v[84:87]
	v_mfma_f32_16x16x32_bf16 v[76:79], v[158:161], v[214:217], v[76:79]
	v_mfma_f32_16x16x32_bf16 v[68:71], v[166:169], v[214:217], v[68:71]
	v_mfma_f32_16x16x32_bf16 v[120:123], v[170:173], v[186:189], 0
	v_mfma_f32_16x16x32_bf16 v[112:115], v[178:181], v[186:189], 0
	v_mfma_f32_16x16x32_bf16 v[104:107], v[170:173], v[194:197], 0
	v_mfma_f32_16x16x32_bf16 v[96:99], v[178:181], v[194:197], 0
	v_mfma_f32_16x16x32_bf16 v[88:91], v[170:173], v[202:205], 0
	v_mfma_f32_16x16x32_bf16 v[80:83], v[178:181], v[202:205], 0
	v_mfma_f32_16x16x32_bf16 v[72:75], v[170:173], v[210:213], 0
	v_mfma_f32_16x16x32_bf16 v[64:67], v[178:181], v[210:213], 0
	v_mfma_f32_16x16x32_bf16 v[120:123], v[174:177], v[190:193], v[120:123]
	v_mfma_f32_16x16x32_bf16 v[112:115], v[182:185], v[190:193], v[112:115]
	v_mfma_f32_16x16x32_bf16 v[104:107], v[174:177], v[198:201], v[104:107]
	v_mfma_f32_16x16x32_bf16 v[96:99], v[182:185], v[198:201], v[96:99]
	v_mfma_f32_16x16x32_bf16 v[88:91], v[174:177], v[206:209], v[88:91]
	v_mfma_f32_16x16x32_bf16 v[80:83], v[182:185], v[206:209], v[80:83]
	v_mfma_f32_16x16x32_bf16 v[72:75], v[174:177], v[214:217], v[72:75]
	v_mfma_f32_16x16x32_bf16 v[64:67], v[182:185], v[214:217], v[64:67]
	s_setprio 0
	s_barrier
	s_add_i32 s33, s54, s44
	s_add_u32 s82, s38, s10
	s_addc_u32 s83, s39, s11
	s_mov_b32 m0, s33
	ds_read_b128 v[186:189], v149 offset:16384
	ds_read_b128 v[190:193], v149 offset:17408
	ds_read_b128 v[194:197], v149 offset:18432
	ds_read_b128 v[198:201], v149 offset:19456
	ds_read_b128 v[202:205], v149 offset:20480
	ds_read_b128 v[206:209], v149 offset:21504
	ds_read_b128 v[210:213], v149 offset:22528
	ds_read_b128 v[214:217], v149 offset:23552
	global_load_lds_dwordx4 v130, s[38:39]
	s_add_i32 m0, s33, 0x2000
	s_add_u32 s64, s38, 0x40000
	s_addc_u32 s65, s39, 0
	s_add_i32 s33, s55, s44
	global_load_lds_dwordx4 v134, s[38:39]
	s_mov_b32 m0, s33
	s_add_u32 s84, s40, s10
	s_addc_u32 s85, s41, s11
	global_load_lds_dwordx4 v130, s[64:65]
	s_add_i32 m0, s33, 0x2000
	s_nop 0
	global_load_lds_dwordx4 v134, s[64:65]
	s_mov_b32 m0, s25
	s_nop 0
	global_load_lds_dwordx4 v128, s[40:41]
	s_mov_b32 m0, s47
	s_nop 0
	global_load_lds_dwordx4 v132, s[40:41]
	s_cmp_eq_u32 s77, 0
	s_cbranch_scc1 .LfwP15_1_s
	s_waitcnt vmcnt(16)
	s_branch .LfwP15_1_e

; #define PG8_STAGE(bufoff, gbase, voff) do { _Pragma("unroll") for (int _i = 0; _i < 2; ++_i) \
;         __builtin_amdgcn_global_load_lds((const unsigned*)((const char*)(gbase) + (voff)[_i]), (PG8_LAS unsigned*)(lds + (bufoff) + ldsw + _i * 8192), 16, 0, 0); } while (0)
; #define PG8_LDA(dst, b, h) do { _Pragma("unroll") for (int m = 0; m < 4; ++m) _Pragma("unroll") for (int k = 0; k < 2; ++k) dst[m][k] = *(const PG8_LAS bf16x8*)(lds + PG8_SA(b, h) + aoff + m * 2048 + k * 1024); } while (0)
; #define PG8_LDB(dst, b, h) do { _Pragma("unroll") for (int n = 0; n < 2; ++n) _Pragma("unroll") for (int k = 0; k < 2; ++k) dst[n][k] = *(const PG8_LAS bf16x8*)(lds + PG8_SB(b, h) + boff + n * 2048 + k * 1024); } while (0)
; #define PG8_MMA(ai, bj, At, Bt) do { __builtin_amdgcn_s_setprio(1); _Pragma("unroll") for (int m = 0; m < 4; ++m) _Pragma("unroll") for (int n = 0; n < 2; ++n) _Pragma("unroll") for (int k = 0; k < 2; ++k) \
;         acc[ai][bj][m][n] = __builtin_amdgcn_mfma_f32_16x16x32_bf16(Bt[n][k], At[m][k], acc[ai][bj][m][n], 0, 0, 0); __builtin_amdgcn_s_setprio(0); } while (0)
; #define PG8_WAIT_V(n) asm volatile("s_waitcnt vmcnt(" #n ")" ::: "memory")
; #define PG8_WAIT_L(n) asm volatile("s_waitcnt lgkmcnt(" #n ")" ::: "memory")
; #define PG8_BAR __builtin_amdgcn_s_barrier()
; #define PG8_SCHED __builtin_amdgcn_sched_barrier(0)
; template <class Epi, class Sched, bool ALIGN_EPI = false, bool SP2 = false>
; __device__ __forceinline__ void gemm_phase(PG8_LAS unsigned char* lds, const Gemm g, const Sched& S, const Epi& E) {
;     ...
;             PG8_WAIT_V(8); PG8_WAIT_L(0); PG8_BAR; PG8_MMA(1, 0, At, B0); PG8_MMA(1, 1, At, B1); PG8_BAR; PG8_SCHED;
;             PG8_LDB(B0, 1, 0); PG8_LDB(B1, 1, 1); PG8_SCHED; PG8_LDA(At, 1, 0); PG8_STAGE(PG8_SA(0, 1), a2 + hstep, voffA);
;             PG8_WAIT_V(8); PG8_WAIT_L(0); PG8_BAR; PG8_MMA(0, 0, At, B0); PG8_MMA(0, 1, At, B1); PG8_BAR; PG8_SCHED;
.LfwP15_1_e:
	s_waitcnt lgkmcnt(0)
	s_barrier
	s_setprio 1
	s_waitcnt lgkmcnt(0)
	v_mfma_f32_16x16x32_bf16 v[60:63], v[154:157], v[186:189], 0
	v_mfma_f32_16x16x32_bf16 v[52:55], v[162:165], v[186:189], 0
	v_mfma_f32_16x16x32_bf16 v[44:47], v[154:157], v[194:197], 0
	v_mfma_f32_16x16x32_bf16 v[36:39], v[162:165], v[194:197], 0
	v_mfma_f32_16x16x32_bf16 v[28:31], v[154:157], v[202:205], 0
	v_mfma_f32_16x16x32_bf16 v[20:23], v[162:165], v[202:205], 0
	v_mfma_f32_16x16x32_bf16 v[12:15], v[154:157], v[210:213], 0
	v_mfma_f32_16x16x32_bf16 v[4:7], v[162:165], v[210:213], 0
	v_mfma_f32_16x16x32_bf16 v[60:63], v[158:161], v[190:193], v[60:63]
	v_mfma_f32_16x16x32_bf16 v[52:55], v[166:169], v[190:193], v[52:55]
	v_mfma_f32_16x16x32_bf16 v[44:47], v[158:161], v[198:201], v[44:47]
	v_mfma_f32_16x16x32_bf16 v[36:39], v[166:169], v[198:201], v[36:39]
	v_mfma_f32_16x16x32_bf16 v[28:31], v[158:161], v[206:209], v[28:31]
	v_mfma_f32_16x16x32_bf16 v[20:23], v[166:169], v[206:209], v[20:23]
	v_mfma_f32_16x16x32_bf16 v[12:15], v[158:161], v[214:217], v[12:15]
	v_mfma_f32_16x16x32_bf16 v[4:7], v[166:169], v[214:217], v[4:7]
	v_mfma_f32_16x16x32_bf16 v[56:59], v[170:173], v[186:189], 0
	v_mfma_f32_16x16x32_bf16 v[48:51], v[178:181], v[186:189], 0
	v_mfma_f32_16x16x32_bf16 v[40:43], v[170:173], v[194:197], 0
	v_mfma_f32_16x16x32_bf16 v[32:35], v[178:181], v[194:197], 0
	v_mfma_f32_16x16x32_bf16 v[24:27], v[170:173], v[202:205], 0
	v_mfma_f32_16x16x32_bf16 v[16:19], v[178:181], v[202:205], 0
	v_mfma_f32_16x16x32_bf16 v[8:11], v[170:173], v[210:213], 0
	v_mfma_f32_16x16x32_bf16 v[0:3], v[178:181], v[210:213], 0
	v_mfma_f32_16x16x32_bf16 v[56:59], v[174:177], v[190:193], v[56:59]
	v_mfma_f32_16x16x32_bf16 v[48:51], v[182:185], v[190:193], v[48:51]
	v_mfma_f32_16x16x32_bf16 v[40:43], v[174:177], v[198:201], v[40:43]
	v_mfma_f32_16x16x32_bf16 v[32:35], v[182:185], v[198:201], v[32:35]
	v_mfma_f32_16x16x32_bf16 v[24:27], v[174:177], v[206:209], v[24:27]
	v_mfma_f32_16x16x32_bf16 v[16:19], v[182:185], v[206:209], v[16:19]
	v_mfma_f32_16x16x32_bf16 v[8:11], v[174:177], v[214:217], v[8:11]
	v_mfma_f32_16x16x32_bf16 v[0:3], v[182:185], v[214:217], v[0:3]
	s_setprio 0
	s_barrier
	s_add_i32 s33, 0, 0x18000
	v_add_u32_e32 v153, s33, v145
	s_add_i32 s34, 0, 0x1c000
	ds_read_b128 v[154:157], v153
	ds_read_b128 v[158:161], v153 offset:1024
	ds_read_b128 v[162:165], v153 offset:2048
	ds_read_b128 v[166:169], v153 offset:3072
	v_add_u32_e32 v153, s34, v145
	ds_read_b128 v[170:173], v153
	ds_read_b128 v[174:177], v153 offset:1024
	ds_read_b128 v[178:181], v153 offset:2048
	ds_read_b128 v[182:185], v153 offset:3072
	s_add_u32 s40, s40, 0x40000
	s_addc_u32 s41, s41, 0
	s_mov_b32 m0, s48
	ds_read_b128 v[186:189], v149 offset:32768
	ds_read_b128 v[190:193], v149 offset:33792
	ds_read_b128 v[194:197], v149 offset:34816
	ds_read_b128 v[198:201], v149 offset:35840
	ds_read_b128 v[202:205], v149 offset:36864
	ds_read_b128 v[206:209], v149 offset:37888
	ds_read_b128 v[210:213], v149 offset:38912
	ds_read_b128 v[214:217], v149 offset:39936
	global_load_lds_dwordx4 v128, s[40:41]
	s_mov_b32 m0, s49
	s_nop 0
	global_load_lds_dwordx4 v132, s[40:41]
	s_waitcnt vmcnt(8)
	s_waitcnt lgkmcnt(0)
	s_barrier
	s_setprio 1
	s_waitcnt lgkmcnt(0)
	v_mfma_f32_16x16x32_bf16 v[124:127], v[154:157], v[186:189], v[124:127]
	v_mfma_f32_16x16x32_bf16 v[116:119], v[162:165], v[186:189], v[116:119]
	v_mfma_f32_16x16x32_bf16 v[108:111], v[154:157], v[194:197], v[108:111]
	v_mfma_f32_16x16x32_bf16 v[100:103], v[162:165], v[194:197], v[100:103]
	v_mfma_f32_16x16x32_bf16 v[92:95], v[154:157], v[202:205], v[92:95]
	v_mfma_f32_16x16x32_bf16 v[84:87], v[162:165], v[202:205], v[84:87]
	v_mfma_f32_16x16x32_bf16 v[76:79], v[154:157], v[210:213], v[76:79]
	v_mfma_f32_16x16x32_bf16 v[68:71], v[162:165], v[210:213], v[68:71]
	v_mfma_f32_16x16x32_bf16 v[124:127], v[158:161], v[190:193], v[124:127]
	v_mfma_f32_16x16x32_bf16 v[116:119], v[166:169], v[190:193], v[116:119]
	v_mfma_f32_16x16x32_bf16 v[108:111], v[158:161], v[198:201], v[108:111]
	v_mfma_f32_16x16x32_bf16 v[100:103], v[166:169], v[198:201], v[100:103]
	v_mfma_f32_16x16x32_bf16 v[92:95], v[158:161], v[206:209], v[92:95]
	v_mfma_f32_16x16x32_bf16 v[84:87], v[166:169], v[206:209], v[84:87]
	v_mfma_f32_16x16x32_bf16 v[76:79], v[158:161], v[214:217], v[76:79]
	v_mfma_f32_16x16x32_bf16 v[68:71], v[166:169], v[214:217], v[68:71]
	v_mfma_f32_16x16x32_bf16 v[120:123], v[170:173], v[186:189], v[120:123]
	v_mfma_f32_16x16x32_bf16 v[112:115], v[178:181], v[186:189], v[112:115]
	v_mfma_f32_16x16x32_bf16 v[104:107], v[170:173], v[194:197], v[104:107]
	v_mfma_f32_16x16x32_bf16 v[96:99], v[178:181], v[194:197], v[96:99]
	v_mfma_f32_16x16x32_bf16 v[88:91], v[170:173], v[202:205], v[88:91]
	v_mfma_f32_16x16x32_bf16 v[80:83], v[178:181], v[202:205], v[80:83]
	v_mfma_f32_16x16x32_bf16 v[72:75], v[170:173], v[210:213], v[72:75]
	v_mfma_f32_16x16x32_bf16 v[64:67], v[178:181], v[210:213], v[64:67]
	v_mfma_f32_16x16x32_bf16 v[120:123], v[174:177], v[190:193], v[120:123]
	v_mfma_f32_16x16x32_bf16 v[112:115], v[182:185], v[190:193], v[112:115]
	v_mfma_f32_16x16x32_bf16 v[104:107], v[174:177], v[198:201], v[104:107]
	v_mfma_f32_16x16x32_bf16 v[96:99], v[182:185], v[198:201], v[96:99]
	v_mfma_f32_16x16x32_bf16 v[88:91], v[174:177], v[206:209], v[88:91]
	v_mfma_f32_16x16x32_bf16 v[80:83], v[182:185], v[206:209], v[80:83]
	v_mfma_f32_16x16x32_bf16 v[72:75], v[174:177], v[214:217], v[72:75]
	v_mfma_f32_16x16x32_bf16 v[64:67], v[182:185], v[214:217], v[64:67]
	s_setprio 0
	s_barrier
; #define PG8_STAGE(bufoff, gbase, voff) do { _Pragma("unroll") for (int _i = 0; _i < 2; ++_i) \
;         __builtin_amdgcn_global_load_lds((const unsigned*)((const char*)(gbase) + (voff)[_i]), (PG8_LAS unsigned*)(lds + (bufoff) + ldsw + _i * 8192), 16, 0, 0); } while (0)
; #define PG8_LDA(dst, b, h) do { _Pragma("unroll") for (int m = 0; m < 4; ++m) _Pragma("unroll") for (int k = 0; k < 2; ++k) dst[m][k] = *(const PG8_LAS bf16x8*)(lds + PG8_SA(b, h) + aoff + m * 2048 + k * 1024); } while (0)
; #define PG8_LDB(dst, b, h) do { _Pragma("unroll") for (int n = 0; n < 2; ++n) _Pragma("unroll") for (int k = 0; k < 2; ++k) dst[n][k] = *(const PG8_LAS bf16x8*)(lds + PG8_SB(b, h) + boff + n * 2048 + k * 1024); } while (0)
; #define PG8_MMA(ai, bj, At, Bt) do { __builtin_amdgcn_s_setprio(1); _Pragma("unroll") for (int m = 0; m < 4; ++m) _Pragma("unroll") for (int n = 0; n < 2; ++n) _Pragma("unroll") for (int k = 0; k < 2; ++k) \
;         acc[ai][bj][m][n] = __builtin_amdgcn_mfma_f32_16x16x32_bf16(Bt[n][k], At[m][k], acc[ai][bj][m][n], 0, 0, 0); __builtin_amdgcn_s_setprio(0); } while (0)
; #define PG8_WAIT_V(n) asm volatile("s_waitcnt vmcnt(" #n ")" ::: "memory")
; #define PG8_WAIT_L(n) asm volatile("s_waitcnt lgkmcnt(" #n ")" ::: "memory")
; #define PG8_BAR __builtin_amdgcn_s_barrier()
; #define PG8_SCHED __builtin_amdgcn_sched_barrier(0)
; template <class Epi, class Sched, bool ALIGN_EPI = false, bool SP2 = false>
; __device__ __forceinline__ void gemm_phase(PG8_LAS unsigned char* lds, const Gemm g, const Sched& S, const Epi& E) {
;     ...
;             PG8_LDB(B0, 0, 0); PG8_LDB(B1, 0, 1); PG8_SCHED; PG8_LDA(At, 0, 0); PG8_STAGE(PG8_SA(1, 1), a1 + hstep, voffA);
;             PG8_WAIT_V(8); PG8_WAIT_L(0); PG8_BAR; PG8_MMA(0, 0, At, B0); PG8_MMA(0, 1, At, B1); PG8_BAR; PG8_SCHED;
;     ...
;             PG8_LDA(At, 1, 1); PG8_STAGE(PG8_SB(1, 0), b3, voffB); PG8_STAGE(PG8_SB(1, 1), b3 + hstep, voffB); PG8_STAGE(PG8_SA(1, 0), a3, voffA);
;             PG8_WAIT_V(8); PG8_WAIT_L(0); PG8_BAR; PG8_MMA(1, 0, At, B0); PG8_MMA(1, 1, At, B1); PG8_BAR; PG8_SCHED;
	s_add_i32 s33, s33, s44
	s_mov_b32 m0, s33
	ds_read_b128 v[186:189], v149 offset:49152
	ds_read_b128 v[190:193], v149 offset:50176
	ds_read_b128 v[194:197], v149 offset:51200
	ds_read_b128 v[198:201], v149 offset:52224
	ds_read_b128 v[202:205], v149 offset:53248
	ds_read_b128 v[206:209], v149 offset:54272
	ds_read_b128 v[210:213], v149 offset:55296
	ds_read_b128 v[214:217], v149 offset:56320
	global_load_lds_dwordx4 v130, s[82:83]
	s_add_i32 m0, s33, 0x2000
	s_add_u32 s38, s38, 0x40080
	s_addc_u32 s39, s39, 0
	s_add_i32 s33, s34, s44
	global_load_lds_dwordx4 v134, s[82:83]
	s_mov_b32 m0, s33
	s_nop 0
	global_load_lds_dwordx4 v130, s[38:39]
	s_add_i32 m0, s33, 0x2000
	s_nop 0
	global_load_lds_dwordx4 v134, s[38:39]
	s_mov_b32 m0, s52
	s_nop 0
	global_load_lds_dwordx4 v128, s[84:85]
	s_mov_b32 m0, s53
	s_nop 0
	global_load_lds_dwordx4 v132, s[84:85]
	s_waitcnt vmcnt(8)
	s_waitcnt lgkmcnt(0)
	s_barrier
	s_setprio 1
	s_waitcnt lgkmcnt(0)
	v_mfma_f32_16x16x32_bf16 v[60:63], v[154:157], v[186:189], v[60:63]
	v_mfma_f32_16x16x32_bf16 v[52:55], v[162:165], v[186:189], v[52:55]
	v_mfma_f32_16x16x32_bf16 v[44:47], v[154:157], v[194:197], v[44:47]
	v_mfma_f32_16x16x32_bf16 v[36:39], v[162:165], v[194:197], v[36:39]
	v_mfma_f32_16x16x32_bf16 v[28:31], v[154:157], v[202:205], v[28:31]
	v_mfma_f32_16x16x32_bf16 v[20:23], v[162:165], v[202:205], v[20:23]
	v_mfma_f32_16x16x32_bf16 v[12:15], v[154:157], v[210:213], v[12:15]
	v_mfma_f32_16x16x32_bf16 v[4:7], v[162:165], v[210:213], v[4:7]
	v_mfma_f32_16x16x32_bf16 v[60:63], v[158:161], v[190:193], v[60:63]
	v_mfma_f32_16x16x32_bf16 v[52:55], v[166:169], v[190:193], v[52:55]
	v_mfma_f32_16x16x32_bf16 v[44:47], v[158:161], v[198:201], v[44:47]
	v_mfma_f32_16x16x32_bf16 v[36:39], v[166:169], v[198:201], v[36:39]
	v_mfma_f32_16x16x32_bf16 v[28:31], v[158:161], v[206:209], v[28:31]
	v_mfma_f32_16x16x32_bf16 v[20:23], v[166:169], v[206:209], v[20:23]
	v_mfma_f32_16x16x32_bf16 v[12:15], v[158:161], v[214:217], v[12:15]
	v_mfma_f32_16x16x32_bf16 v[4:7], v[166:169], v[214:217], v[4:7]
	v_mfma_f32_16x16x32_bf16 v[56:59], v[170:173], v[186:189], v[56:59]
	v_mfma_f32_16x16x32_bf16 v[48:51], v[178:181], v[186:189], v[48:51]
	v_mfma_f32_16x16x32_bf16 v[40:43], v[170:173], v[194:197], v[40:43]
	v_mfma_f32_16x16x32_bf16 v[32:35], v[178:181], v[194:197], v[32:35]
	v_mfma_f32_16x16x32_bf16 v[24:27], v[170:173], v[202:205], v[24:27]
	v_mfma_f32_16x16x32_bf16 v[16:19], v[178:181], v[202:205], v[16:19]
	v_mfma_f32_16x16x32_bf16 v[8:11], v[170:173], v[210:213], v[8:11]
	v_mfma_f32_16x16x32_bf16 v[0:3], v[178:181], v[210:213], v[0:3]
	v_mfma_f32_16x16x32_bf16 v[56:59], v[174:177], v[190:193], v[56:59]
	v_mfma_f32_16x16x32_bf16 v[48:51], v[182:185], v[190:193], v[48:51]
	v_mfma_f32_16x16x32_bf16 v[40:43], v[174:177], v[198:201], v[40:43]
	v_mfma_f32_16x16x32_bf16 v[32:35], v[182:185], v[198:201], v[32:35]
	v_mfma_f32_16x16x32_bf16 v[24:27], v[174:177], v[206:209], v[24:27]
	v_mfma_f32_16x16x32_bf16 v[16:19], v[182:185], v[206:209], v[16:19]
	v_mfma_f32_16x16x32_bf16 v[8:11], v[174:177], v[214:217], v[8:11]
	v_mfma_f32_16x16x32_bf16 v[0:3], v[182:185], v[214:217], v[0:3]
	s_setprio 0
	s_barrier
	s_add_i32 s62, s62, 2
	s_add_u32 s36, s36, 0x100
	s_addc_u32 s37, s37, 0
	s_add_u32 s60, s60, 0x100
	s_addc_u32 s61, s61, 0
	s_cmp_gt_u32 s62, 13
.LBB0_1342:
	ds_read_b128 v[154:157], v147
	ds_read_b128 v[158:161], v147 offset:1024
	ds_read_b128 v[162:165], v147 offset:2048
	ds_read_b128 v[166:169], v147 offset:3072
	ds_read_b128 v[170:173], v148
	ds_read_b128 v[174:177], v148 offset:1024
	ds_read_b128 v[178:181], v148 offset:2048
	ds_read_b128 v[182:185], v148 offset:3072
	s_add_u32 s33, s36, 0xfffc0080
	s_addc_u32 s34, s37, -1
	s_cmp_eq_u32 s62, 12
	s_cselect_b32 s41, s19, s34
	s_cselect_b32 s40, s58, s33
	s_cselect_b32 s39, s15, s61
	s_cselect_b32 s38, s59, s60
	s_add_i32 m0, s25, 0xc000
	ds_read_b128 v[186:189], v149
	ds_read_b128 v[190:193], v149 offset:1024
	ds_read_b128 v[194:197], v149 offset:2048
	ds_read_b128 v[198:201], v149 offset:3072
	ds_read_b128 v[202:205], v149 offset:4096
	ds_read_b128 v[206:209], v149 offset:5120
	ds_read_b128 v[210:213], v149 offset:6144
	ds_read_b128 v[214:217], v149 offset:7168
	global_load_lds_dwordx4 v136, s[36:37]
	s_add_i32 m0, s25, 0xe000
	s_nop 0
	global_load_lds_dwordx4 v138, s[36:37]
	s_waitcnt vmcnt(8)
	s_waitcnt lgkmcnt(0)
	s_barrier
	s_setprio 1
	s_waitcnt lgkmcnt(0)
	v_mfma_f32_16x16x32_bf16 v[124:127], v[154:157], v[186:189], v[124:127]
	v_mfma_f32_16x16x32_bf16 v[116:119], v[162:165], v[186:189], v[116:119]
	v_mfma_f32_16x16x32_bf16 v[108:111], v[154:157], v[194:197], v[108:111]
	v_mfma_f32_16x16x32_bf16 v[100:103], v[162:165], v[194:197], v[100:103]
	v_mfma_f32_16x16x32_bf16 v[92:95], v[154:157], v[202:205], v[92:95]
	v_mfma_f32_16x16x32_bf16 v[84:87], v[162:165], v[202:205], v[84:87]
	v_mfma_f32_16x16x32_bf16 v[76:79], v[154:157], v[210:213], v[76:79]
	v_mfma_f32_16x16x32_bf16 v[68:71], v[162:165], v[210:213], v[68:71]
	v_mfma_f32_16x16x32_bf16 v[124:127], v[158:161], v[190:193], v[124:127]
	v_mfma_f32_16x16x32_bf16 v[116:119], v[166:169], v[190:193], v[116:119]
	v_mfma_f32_16x16x32_bf16 v[108:111], v[158:161], v[198:201], v[108:111]
	v_mfma_f32_16x16x32_bf16 v[100:103], v[166:169], v[198:201], v[100:103]
	v_mfma_f32_16x16x32_bf16 v[92:95], v[158:161], v[206:209], v[92:95]
	v_mfma_f32_16x16x32_bf16 v[84:87], v[166:169], v[206:209], v[84:87]
	v_mfma_f32_16x16x32_bf16 v[76:79], v[158:161], v[214:217], v[76:79]
	v_mfma_f32_16x16x32_bf16 v[68:71], v[166:169], v[214:217], v[68:71]
	v_mfma_f32_16x16x32_bf16 v[120:123], v[170:173], v[186:189], v[120:123]
	v_mfma_f32_16x16x32_bf16 v[112:115], v[178:181], v[186:189], v[112:115]
	v_mfma_f32_16x16x32_bf16 v[104:107], v[170:173], v[194:197], v[104:107]
	v_mfma_f32_16x16x32_bf16 v[96:99], v[178:181], v[194:197], v[96:99]
	v_mfma_f32_16x16x32_bf16 v[88:91], v[170:173], v[202:205], v[88:91]
	v_mfma_f32_16x16x32_bf16 v[80:83], v[178:181], v[202:205], v[80:83]
	v_mfma_f32_16x16x32_bf16 v[72:75], v[170:173], v[210:213], v[72:75]
	v_mfma_f32_16x16x32_bf16 v[64:67], v[178:181], v[210:213], v[64:67]
	v_mfma_f32_16x16x32_bf16 v[120:123], v[174:177], v[190:193], v[120:123]
	v_mfma_f32_16x16x32_bf16 v[112:115], v[182:185], v[190:193], v[112:115]
	v_mfma_f32_16x16x32_bf16 v[104:107], v[174:177], v[198:201], v[104:107]
	v_mfma_f32_16x16x32_bf16 v[96:99], v[182:185], v[198:201], v[96:99]
	v_mfma_f32_16x16x32_bf16 v[88:91], v[174:177], v[206:209], v[88:91]
	v_mfma_f32_16x16x32_bf16 v[80:83], v[182:185], v[206:209], v[80:83]
	v_mfma_f32_16x16x32_bf16 v[72:75], v[174:177], v[214:217], v[72:75]
	v_mfma_f32_16x16x32_bf16 v[64:67], v[182:185], v[214:217], v[64:67]
	s_setprio 0
	s_barrier
; #define PG8_STAGE(bufoff, gbase, voff) do { _Pragma("unroll") for (int _i = 0; _i < 2; ++_i) \
;         __builtin_amdgcn_global_load_lds((const unsigned*)((const char*)(gbase) + (voff)[_i]), (PG8_LAS unsigned*)(lds + (bufoff) + ldsw + _i * 8192), 16, 0, 0); } while (0)
; #define PG8_LDA(dst, b, h) do { _Pragma("unroll") for (int m = 0; m < 4; ++m) _Pragma("unroll") for (int k = 0; k < 2; ++k) dst[m][k] = *(const PG8_LAS bf16x8*)(lds + PG8_SA(b, h) + aoff + m * 2048 + k * 1024); } while (0)
; #define PG8_LDB(dst, b, h) do { _Pragma("unroll") for (int n = 0; n < 2; ++n) _Pragma("unroll") for (int k = 0; k < 2; ++k) dst[n][k] = *(const PG8_LAS bf16x8*)(lds + PG8_SB(b, h) + boff + n * 2048 + k * 1024); } while (0)
; #define PG8_MMA(ai, bj, At, Bt) do { __builtin_amdgcn_s_setprio(1); _Pragma("unroll") for (int m = 0; m < 4; ++m) _Pragma("unroll") for (int n = 0; n < 2; ++n) _Pragma("unroll") for (int k = 0; k < 2; ++k) \
;         acc[ai][bj][m][n] = __builtin_amdgcn_mfma_f32_16x16x32_bf16(Bt[n][k], At[m][k], acc[ai][bj][m][n], 0, 0, 0); __builtin_amdgcn_s_setprio(0); } while (0)
; #define PG8_WAIT_V(n) asm volatile("s_waitcnt vmcnt(" #n ")" ::: "memory")
; #define PG8_WAIT_L(n) asm volatile("s_waitcnt lgkmcnt(" #n ")" ::: "memory")
; #define PG8_BAR __builtin_amdgcn_s_barrier()
; #define PG8_SCHED __builtin_amdgcn_sched_barrier(0)
; template <class Epi, class Sched, bool ALIGN_EPI = false, bool SP2 = false>
; __device__ __forceinline__ void gemm_phase(PG8_LAS unsigned char* lds, const Gemm g, const Sched& S, const Epi& E) {
;     ...
;             PG8_LDA(At, 0, 1); PG8_STAGE(PG8_SB(0, 0), b2, voffB); PG8_STAGE(PG8_SB(0, 1), b2 + hstep, voffB); PG8_STAGE(PG8_SA(0, 0), a2, voffA);
;             PG8_WAIT_V(8); PG8_WAIT_L(0); PG8_BAR; PG8_MMA(1, 0, At, B0); PG8_MMA(1, 1, At, B1); PG8_BAR; PG8_SCHED;
;             PG8_LDB(B0, 1, 0); PG8_LDB(B1, 1, 1); PG8_SCHED; PG8_LDA(At, 1, 0); PG8_STAGE(PG8_SA(0, 1), a2 + hstep, voffA);
	s_add_i32 s33, s54, s44
	s_add_u32 s82, s38, s10
	s_addc_u32 s83, s39, s11
	s_mov_b32 m0, s33
	ds_read_b128 v[186:189], v149 offset:16384
	ds_read_b128 v[190:193], v149 offset:17408
	ds_read_b128 v[194:197], v149 offset:18432
	ds_read_b128 v[198:201], v149 offset:19456
	ds_read_b128 v[202:205], v149 offset:20480
	ds_read_b128 v[206:209], v149 offset:21504
	ds_read_b128 v[210:213], v149 offset:22528
	ds_read_b128 v[214:217], v149 offset:23552
	global_load_lds_dwordx4 v130, s[38:39]
	s_add_i32 m0, s33, 0x2000
	s_add_u32 s64, s38, 0x40000
	s_addc_u32 s65, s39, 0
	s_add_i32 s33, s55, s44
	global_load_lds_dwordx4 v134, s[38:39]
	s_mov_b32 m0, s33
	s_add_u32 s84, s40, s10
	s_addc_u32 s85, s41, s11
	global_load_lds_dwordx4 v130, s[64:65]
	s_add_i32 m0, s33, 0x2000
	s_nop 0
	global_load_lds_dwordx4 v134, s[64:65]
	s_mov_b32 m0, s25
	s_nop 0
	global_load_lds_dwordx4 v128, s[40:41]
	s_mov_b32 m0, s47
	s_nop 0
	global_load_lds_dwordx4 v132, s[40:41]
	s_waitcnt vmcnt(8)
	s_waitcnt lgkmcnt(0)
	s_barrier
	s_setprio 1
	s_waitcnt lgkmcnt(0)
	v_mfma_f32_16x16x32_bf16 v[60:63], v[154:157], v[186:189], v[60:63]
	v_mfma_f32_16x16x32_bf16 v[52:55], v[162:165], v[186:189], v[52:55]
	v_mfma_f32_16x16x32_bf16 v[44:47], v[154:157], v[194:197], v[44:47]
	v_mfma_f32_16x16x32_bf16 v[36:39], v[162:165], v[194:197], v[36:39]
	v_mfma_f32_16x16x32_bf16 v[28:31], v[154:157], v[202:205], v[28:31]
	v_mfma_f32_16x16x32_bf16 v[20:23], v[162:165], v[202:205], v[20:23]
	v_mfma_f32_16x16x32_bf16 v[12:15], v[154:157], v[210:213], v[12:15]
	v_mfma_f32_16x16x32_bf16 v[4:7], v[162:165], v[210:213], v[4:7]
	v_mfma_f32_16x16x32_bf16 v[60:63], v[158:161], v[190:193], v[60:63]
	v_mfma_f32_16x16x32_bf16 v[52:55], v[166:169], v[190:193], v[52:55]
	v_mfma_f32_16x16x32_bf16 v[44:47], v[158:161], v[198:201], v[44:47]
	v_mfma_f32_16x16x32_bf16 v[36:39], v[166:169], v[198:201], v[36:39]
	v_mfma_f32_16x16x32_bf16 v[28:31], v[158:161], v[206:209], v[28:31]
	v_mfma_f32_16x16x32_bf16 v[20:23], v[166:169], v[206:209], v[20:23]
	v_mfma_f32_16x16x32_bf16 v[12:15], v[158:161], v[214:217], v[12:15]
	v_mfma_f32_16x16x32_bf16 v[4:7], v[166:169], v[214:217], v[4:7]
	v_mfma_f32_16x16x32_bf16 v[56:59], v[170:173], v[186:189], v[56:59]
	v_mfma_f32_16x16x32_bf16 v[48:51], v[178:181], v[186:189], v[48:51]
	v_mfma_f32_16x16x32_bf16 v[40:43], v[170:173], v[194:197], v[40:43]
	v_mfma_f32_16x16x32_bf16 v[32:35], v[178:181], v[194:197], v[32:35]
	v_mfma_f32_16x16x32_bf16 v[24:27], v[170:173], v[202:205], v[24:27]
	v_mfma_f32_16x16x32_bf16 v[16:19], v[178:181], v[202:205], v[16:19]
	v_mfma_f32_16x16x32_bf16 v[8:11], v[170:173], v[210:213], v[8:11]
	v_mfma_f32_16x16x32_bf16 v[0:3], v[178:181], v[210:213], v[0:3]
	v_mfma_f32_16x16x32_bf16 v[56:59], v[174:177], v[190:193], v[56:59]
	v_mfma_f32_16x16x32_bf16 v[48:51], v[182:185], v[190:193], v[48:51]
	v_mfma_f32_16x16x32_bf16 v[40:43], v[174:177], v[198:201], v[40:43]
	v_mfma_f32_16x16x32_bf16 v[32:35], v[182:185], v[198:201], v[32:35]
	v_mfma_f32_16x16x32_bf16 v[24:27], v[174:177], v[206:209], v[24:27]
	v_mfma_f32_16x16x32_bf16 v[16:19], v[182:185], v[206:209], v[16:19]
	v_mfma_f32_16x16x32_bf16 v[8:11], v[174:177], v[214:217], v[8:11]
	v_mfma_f32_16x16x32_bf16 v[0:3], v[182:185], v[214:217], v[0:3]
	s_setprio 0
	s_barrier
	s_add_i32 s33, 0, 0x18000
	v_add_u32_e32 v153, s33, v145
	s_add_i32 s34, 0, 0x1c000
	ds_read_b128 v[154:157], v153
	ds_read_b128 v[158:161], v153 offset:1024
	ds_read_b128 v[162:165], v153 offset:2048
	ds_read_b128 v[166:169], v153 offset:3072
	v_add_u32_e32 v153, s34, v145
	ds_read_b128 v[170:173], v153
	ds_read_b128 v[174:177], v153 offset:1024
	ds_read_b128 v[178:181], v153 offset:2048
	ds_read_b128 v[182:185], v153 offset:3072
	s_add_u32 s40, s40, 0x40000
	s_addc_u32 s41, s41, 0
	s_mov_b32 m0, s48
	ds_read_b128 v[186:189], v149 offset:32768
	ds_read_b128 v[190:193], v149 offset:33792
	ds_read_b128 v[194:197], v149 offset:34816
	ds_read_b128 v[198:201], v149 offset:35840
	ds_read_b128 v[202:205], v149 offset:36864
	ds_read_b128 v[206:209], v149 offset:37888
	ds_read_b128 v[210:213], v149 offset:38912
	ds_read_b128 v[214:217], v149 offset:39936
	global_load_lds_dwordx4 v128, s[40:41]
	s_mov_b32 m0, s49
	s_nop 0
	global_load_lds_dwordx4 v132, s[40:41]
	s_waitcnt vmcnt(8)
	s_waitcnt lgkmcnt(0)
	s_barrier
; #define PG8_STAGE(bufoff, gbase, voff) do { _Pragma("unroll") for (int _i = 0; _i < 2; ++_i) \
;         __builtin_amdgcn_global_load_lds((const unsigned*)((const char*)(gbase) + (voff)[_i]), (PG8_LAS unsigned*)(lds + (bufoff) + ldsw + _i * 8192), 16, 0, 0); } while (0)
; #define PG8_LDA(dst, b, h) do { _Pragma("unroll") for (int m = 0; m < 4; ++m) _Pragma("unroll") for (int k = 0; k < 2; ++k) dst[m][k] = *(const PG8_LAS bf16x8*)(lds + PG8_SA(b, h) + aoff + m * 2048 + k * 1024); } while (0)
; #define PG8_MMA(ai, bj, At, Bt) do { __builtin_amdgcn_s_setprio(1); _Pragma("unroll") for (int m = 0; m < 4; ++m) _Pragma("unroll") for (int n = 0; n < 2; ++n) _Pragma("unroll") for (int k = 0; k < 2; ++k) \
;         acc[ai][bj][m][n] = __builtin_amdgcn_mfma_f32_16x16x32_bf16(Bt[n][k], At[m][k], acc[ai][bj][m][n], 0, 0, 0); __builtin_amdgcn_s_setprio(0); } while (0)
; #define PG8_WAIT_V(n) asm volatile("s_waitcnt vmcnt(" #n ")" ::: "memory")
; #define PG8_WAIT_L(n) asm volatile("s_waitcnt lgkmcnt(" #n ")" ::: "memory")
; #define PG8_BAR __builtin_amdgcn_s_barrier()
; #define PG8_SCHED __builtin_amdgcn_sched_barrier(0)
; template <class Epi, class Sched, bool ALIGN_EPI = false, bool SP2 = false>
; __device__ __forceinline__ void gemm_phase(PG8_LAS unsigned char* lds, const Gemm g, const Sched& S, const Epi& E) {
;     ...
;             PG8_WAIT_V(8); PG8_WAIT_L(0); PG8_BAR; PG8_MMA(0, 0, At, B0); PG8_MMA(0, 1, At, B1); PG8_BAR; PG8_SCHED;
;             PG8_LDA(At, 1, 1); PG8_STAGE(PG8_SB(1, 0), b3, voffB); PG8_STAGE(PG8_SB(1, 1), b3 + hstep, voffB); PG8_STAGE(PG8_SA(1, 0), a3, voffA);
;             PG8_WAIT_V(8); PG8_WAIT_L(0); PG8_BAR; PG8_MMA(1, 0, At, B0); PG8_MMA(1, 1, At, B1); PG8_BAR; PG8_SCHED;
;     ...
;         if constexpr (ALIGN_EPI) { if (wr == 0) PG8_BAR; }
	s_setprio 1
	s_waitcnt lgkmcnt(0)
	v_mfma_f32_16x16x32_bf16 v[124:127], v[154:157], v[186:189], v[124:127]
	v_mfma_f32_16x16x32_bf16 v[116:119], v[162:165], v[186:189], v[116:119]
	v_mfma_f32_16x16x32_bf16 v[108:111], v[154:157], v[194:197], v[108:111]
	v_mfma_f32_16x16x32_bf16 v[100:103], v[162:165], v[194:197], v[100:103]
	v_mfma_f32_16x16x32_bf16 v[92:95], v[154:157], v[202:205], v[92:95]
	v_mfma_f32_16x16x32_bf16 v[84:87], v[162:165], v[202:205], v[84:87]
	v_mfma_f32_16x16x32_bf16 v[76:79], v[154:157], v[210:213], v[76:79]
	v_mfma_f32_16x16x32_bf16 v[68:71], v[162:165], v[210:213], v[68:71]
	v_mfma_f32_16x16x32_bf16 v[124:127], v[158:161], v[190:193], v[124:127]
	v_mfma_f32_16x16x32_bf16 v[116:119], v[166:169], v[190:193], v[116:119]
	v_mfma_f32_16x16x32_bf16 v[108:111], v[158:161], v[198:201], v[108:111]
	v_mfma_f32_16x16x32_bf16 v[100:103], v[166:169], v[198:201], v[100:103]
	v_mfma_f32_16x16x32_bf16 v[92:95], v[158:161], v[206:209], v[92:95]
	v_mfma_f32_16x16x32_bf16 v[84:87], v[166:169], v[206:209], v[84:87]
	v_mfma_f32_16x16x32_bf16 v[76:79], v[158:161], v[214:217], v[76:79]
	v_mfma_f32_16x16x32_bf16 v[68:71], v[166:169], v[214:217], v[68:71]
	v_mfma_f32_16x16x32_bf16 v[120:123], v[170:173], v[186:189], v[120:123]
	v_mfma_f32_16x16x32_bf16 v[112:115], v[178:181], v[186:189], v[112:115]
	v_mfma_f32_16x16x32_bf16 v[104:107], v[170:173], v[194:197], v[104:107]
	v_mfma_f32_16x16x32_bf16 v[96:99], v[178:181], v[194:197], v[96:99]
	v_mfma_f32_16x16x32_bf16 v[88:91], v[170:173], v[202:205], v[88:91]
	v_mfma_f32_16x16x32_bf16 v[80:83], v[178:181], v[202:205], v[80:83]
	v_mfma_f32_16x16x32_bf16 v[72:75], v[170:173], v[210:213], v[72:75]
	v_mfma_f32_16x16x32_bf16 v[64:67], v[178:181], v[210:213], v[64:67]
	v_mfma_f32_16x16x32_bf16 v[120:123], v[174:177], v[190:193], v[120:123]
	v_mfma_f32_16x16x32_bf16 v[112:115], v[182:185], v[190:193], v[112:115]
	v_mfma_f32_16x16x32_bf16 v[104:107], v[174:177], v[198:201], v[104:107]
	v_mfma_f32_16x16x32_bf16 v[96:99], v[182:185], v[198:201], v[96:99]
	v_mfma_f32_16x16x32_bf16 v[88:91], v[174:177], v[206:209], v[88:91]
	v_mfma_f32_16x16x32_bf16 v[80:83], v[182:185], v[206:209], v[80:83]
	v_mfma_f32_16x16x32_bf16 v[72:75], v[174:177], v[214:217], v[72:75]
	v_mfma_f32_16x16x32_bf16 v[64:67], v[182:185], v[214:217], v[64:67]
	s_setprio 0
	s_barrier
	s_add_i32 s33, s33, s44
	s_mov_b32 m0, s33
	ds_read_b128 v[186:189], v149 offset:49152
	ds_read_b128 v[190:193], v149 offset:50176
	ds_read_b128 v[194:197], v149 offset:51200
	ds_read_b128 v[198:201], v149 offset:52224
	ds_read_b128 v[202:205], v149 offset:53248
	ds_read_b128 v[206:209], v149 offset:54272
	ds_read_b128 v[210:213], v149 offset:55296
	ds_read_b128 v[214:217], v149 offset:56320
	global_load_lds_dwordx4 v130, s[82:83]
	s_add_i32 m0, s33, 0x2000
	s_add_u32 s38, s38, 0x40080
	s_addc_u32 s39, s39, 0
	s_add_i32 s33, s34, s44
	global_load_lds_dwordx4 v134, s[82:83]
	s_mov_b32 m0, s33
	s_nop 0
	global_load_lds_dwordx4 v130, s[38:39]
	s_add_i32 m0, s33, 0x2000
	s_nop 0
	global_load_lds_dwordx4 v134, s[38:39]
	s_mov_b32 m0, s52
	s_nop 0
	global_load_lds_dwordx4 v128, s[84:85]
	s_mov_b32 m0, s53
	s_nop 0
	global_load_lds_dwordx4 v132, s[84:85]
	s_waitcnt vmcnt(8)
	s_waitcnt lgkmcnt(0)
	s_barrier
	s_setprio 1
	s_waitcnt lgkmcnt(0)
	v_mfma_f32_16x16x32_bf16 v[60:63], v[154:157], v[186:189], v[60:63]
	v_mfma_f32_16x16x32_bf16 v[52:55], v[162:165], v[186:189], v[52:55]
	v_mfma_f32_16x16x32_bf16 v[44:47], v[154:157], v[194:197], v[44:47]
	v_mfma_f32_16x16x32_bf16 v[36:39], v[162:165], v[194:197], v[36:39]
	v_mfma_f32_16x16x32_bf16 v[28:31], v[154:157], v[202:205], v[28:31]
	v_mfma_f32_16x16x32_bf16 v[20:23], v[162:165], v[202:205], v[20:23]
	v_mfma_f32_16x16x32_bf16 v[12:15], v[154:157], v[210:213], v[12:15]
	v_mfma_f32_16x16x32_bf16 v[4:7], v[162:165], v[210:213], v[4:7]
	v_mfma_f32_16x16x32_bf16 v[60:63], v[158:161], v[190:193], v[60:63]
	v_mfma_f32_16x16x32_bf16 v[52:55], v[166:169], v[190:193], v[52:55]
	v_mfma_f32_16x16x32_bf16 v[44:47], v[158:161], v[198:201], v[44:47]
	v_mfma_f32_16x16x32_bf16 v[36:39], v[166:169], v[198:201], v[36:39]
	v_mfma_f32_16x16x32_bf16 v[28:31], v[158:161], v[206:209], v[28:31]
	v_mfma_f32_16x16x32_bf16 v[20:23], v[166:169], v[206:209], v[20:23]
	v_mfma_f32_16x16x32_bf16 v[12:15], v[158:161], v[214:217], v[12:15]
	v_mfma_f32_16x16x32_bf16 v[4:7], v[166:169], v[214:217], v[4:7]
	v_mfma_f32_16x16x32_bf16 v[56:59], v[170:173], v[186:189], v[56:59]
	v_mfma_f32_16x16x32_bf16 v[48:51], v[178:181], v[186:189], v[48:51]
	v_mfma_f32_16x16x32_bf16 v[40:43], v[170:173], v[194:197], v[40:43]
	v_mfma_f32_16x16x32_bf16 v[32:35], v[178:181], v[194:197], v[32:35]
	v_mfma_f32_16x16x32_bf16 v[24:27], v[170:173], v[202:205], v[24:27]
	v_mfma_f32_16x16x32_bf16 v[16:19], v[178:181], v[202:205], v[16:19]
	v_mfma_f32_16x16x32_bf16 v[8:11], v[170:173], v[210:213], v[8:11]
	v_mfma_f32_16x16x32_bf16 v[0:3], v[178:181], v[210:213], v[0:3]
	v_mfma_f32_16x16x32_bf16 v[56:59], v[174:177], v[190:193], v[56:59]
	v_mfma_f32_16x16x32_bf16 v[48:51], v[182:185], v[190:193], v[48:51]
	v_mfma_f32_16x16x32_bf16 v[40:43], v[174:177], v[198:201], v[40:43]
	v_mfma_f32_16x16x32_bf16 v[32:35], v[182:185], v[198:201], v[32:35]
	v_mfma_f32_16x16x32_bf16 v[24:27], v[174:177], v[206:209], v[24:27]
	v_mfma_f32_16x16x32_bf16 v[16:19], v[182:185], v[206:209], v[16:19]
	v_mfma_f32_16x16x32_bf16 v[8:11], v[174:177], v[214:217], v[8:11]
	v_mfma_f32_16x16x32_bf16 v[0:3], v[182:185], v[214:217], v[0:3]
	s_setprio 0
	s_barrier
	s_add_i32 s62, s62, 2
	s_add_u32 s36, s36, 0x100
	s_addc_u32 s37, s37, 0
	s_add_u32 s60, s60, 0x100
	s_addc_u32 s61, s61, 0
	s_cmp_gt_u32 s62, 13
	s_cbranch_scc0 .LBB0_1342
	s_and_b64 vcc, exec, s[12:13]
	s_cbranch_vccz .LBB0_1345
	s_barrier

; #define PG8_STAGE(bufoff, gbase, voff) do { _Pragma("unroll") for (int _i = 0; _i < 2; ++_i) \
;         __builtin_amdgcn_global_load_lds((const unsigned*)((const char*)(gbase) + (voff)[_i]), (PG8_LAS unsigned*)(lds + (bufoff) + ldsw + _i * 8192), 16, 0, 0); } while (0)
; #define PG8_LDA(dst, b, h) do { _Pragma("unroll") for (int m = 0; m < 4; ++m) _Pragma("unroll") for (int k = 0; k < 2; ++k) dst[m][k] = *(const PG8_LAS bf16x8*)(lds + PG8_SA(b, h) + aoff + m * 2048 + k * 1024); } while (0)
; #define PG8_LDB(dst, b, h) do { _Pragma("unroll") for (int n = 0; n < 2; ++n) _Pragma("unroll") for (int k = 0; k < 2; ++k) dst[n][k] = *(const PG8_LAS bf16x8*)(lds + PG8_SB(b, h) + boff + n * 2048 + k * 1024); } while (0)
; #define PG8_MMA(ai, bj, At, Bt) do { __builtin_amdgcn_s_setprio(1); _Pragma("unroll") for (int m = 0; m < 4; ++m) _Pragma("unroll") for (int n = 0; n < 2; ++n) _Pragma("unroll") for (int k = 0; k < 2; ++k) \
;         acc[ai][bj][m][n] = __builtin_amdgcn_mfma_f32_16x16x32_bf16(Bt[n][k], At[m][k], acc[ai][bj][m][n], 0, 0, 0); __builtin_amdgcn_s_setprio(0); } while (0)
; #define PG8_WAIT_V(n) asm volatile("s_waitcnt vmcnt(" #n ")" ::: "memory")
; #define PG8_BAR __builtin_amdgcn_s_barrier()
; template <class Epi, class Sched, bool ALIGN_EPI = false, bool SP2 = false>
; __device__ __forceinline__ void gemm_phase(PG8_LAS unsigned char* lds, const Gemm g, const Sched& S, const Epi& E) {
;     ...
;         for (int t = 0; t < nt; t += 2) {
;             const bool last = (t == nt - 2);
;             const char* a1 = cA + (size_t)(t + 1) * kstep;
;             const char* a2 = last ? nA : cA + (size_t)(t + 2) * kstep; const char* b2 = last ? nB : cB + (size_t)(t + 2) * kstep;
;             const char* a3 = a2 + kstep; const char* b3 = b2 + kstep;
;             if (last && has_next) S.a_ready(nxt);
;             if constexpr (SP2) {
;             PG8_LDB(B0, 0, 0); PG8_LDB(B1, 0, 1); PG8_SCHED; PG8_LDA(At, 0, 0); PG8_STAGE(PG8_SA(1, 1), a1 + hstep, voffA);
;             PG8_WAIT_V(8); PG8_WAIT_L(0); PG8_BAR; PG8_MMA(0, 0, At, B0); PG8_MMA(0, 1, At, B1); PG8_BAR; PG8_SCHED;
;             PG8_LDA(At, 0, 1); PG8_STAGE(PG8_SB(0, 0), b2, voffB); PG8_STAGE(PG8_SB(0, 1), b2 + hstep, voffB); PG8_STAGE(PG8_SA(0, 0), a2, voffA);
;             PG8_WAIT_V(8); PG8_WAIT_L(0); PG8_BAR; PG8_MMA(1, 0, At, B0); PG8_MMA(1, 1, At, B1); PG8_BAR; PG8_SCHED;
.LBB0_1416:
	s_add_u32 s24, s24, 0xb0080
	s_addc_u32 s25, s25, 0
	s_add_u32 s55, s30, 0x100
	s_addc_u32 s56, s31, 0
	s_mov_b32 s57, -2
	s_waitcnt lgkmcnt(0)
	s_add_u32 s28, s24, 0xfff50080
	s_addc_u32 s29, s25, -1
	s_cmp_eq_u32 s57, 40
	s_cselect_b32 s31, s5, s29
	s_cselect_b32 s30, s4, s28
	s_cselect_b32 s29, s23, s56
	s_cselect_b32 s28, s22, s55
	s_add_i32 m0, s39, 0xc000
	global_load_lds_dwordx4 v144, s[24:25]
	s_add_i32 m0, s39, 0xe000
	s_nop 0
	global_load_lds_dwordx4 v146, s[24:25]
	s_waitcnt vmcnt(8)
	s_waitcnt lgkmcnt(0)
	s_barrier
	s_setprio 1
	s_waitcnt lgkmcnt(0)
	v_mfma_f32_16x16x32_bf16 v[124:127], v[128:131], v[184:187], 0
	v_mfma_f32_16x16x32_bf16 v[120:123], v[152:155], v[184:187], 0
	v_mfma_f32_16x16x32_bf16 v[116:119], v[128:131], v[192:195], 0
	v_mfma_f32_16x16x32_bf16 v[112:115], v[152:155], v[192:195], 0
	v_mfma_f32_16x16x32_bf16 v[108:111], v[128:131], v[200:203], 0
	v_mfma_f32_16x16x32_bf16 v[104:107], v[152:155], v[200:203], 0
	v_mfma_f32_16x16x32_bf16 v[100:103], v[128:131], v[208:211], 0
	v_mfma_f32_16x16x32_bf16 v[96:99], v[152:155], v[208:211], 0
	v_mfma_f32_16x16x32_bf16 v[124:127], v[132:135], v[188:191], v[124:127]
	v_mfma_f32_16x16x32_bf16 v[120:123], v[164:167], v[188:191], v[120:123]
	v_mfma_f32_16x16x32_bf16 v[116:119], v[132:135], v[196:199], v[116:119]
	v_mfma_f32_16x16x32_bf16 v[112:115], v[164:167], v[196:199], v[112:115]
	v_mfma_f32_16x16x32_bf16 v[108:111], v[132:135], v[204:207], v[108:111]
	v_mfma_f32_16x16x32_bf16 v[104:107], v[164:167], v[204:207], v[104:107]
	v_mfma_f32_16x16x32_bf16 v[100:103], v[132:135], v[212:215], v[100:103]
	v_mfma_f32_16x16x32_bf16 v[96:99], v[164:167], v[212:215], v[96:99]
	v_mfma_f32_16x16x32_bf16 v[64:67], v[168:171], v[184:187], 0
	v_mfma_f32_16x16x32_bf16 v[56:59], v[176:179], v[184:187], 0
	v_mfma_f32_16x16x32_bf16 v[52:55], v[168:171], v[192:195], 0
	v_mfma_f32_16x16x32_bf16 v[48:51], v[176:179], v[192:195], 0
	v_mfma_f32_16x16x32_bf16 v[44:47], v[168:171], v[200:203], 0
	v_mfma_f32_16x16x32_bf16 v[40:43], v[176:179], v[200:203], 0
	v_mfma_f32_16x16x32_bf16 v[36:39], v[168:171], v[208:211], 0
	v_mfma_f32_16x16x32_bf16 v[32:35], v[176:179], v[208:211], 0
	v_mfma_f32_16x16x32_bf16 v[64:67], v[172:175], v[188:191], v[64:67]
	v_mfma_f32_16x16x32_bf16 v[56:59], v[180:183], v[188:191], v[56:59]
	v_mfma_f32_16x16x32_bf16 v[52:55], v[172:175], v[196:199], v[52:55]
	v_mfma_f32_16x16x32_bf16 v[48:51], v[180:183], v[196:199], v[48:51]
	v_mfma_f32_16x16x32_bf16 v[44:47], v[172:175], v[204:207], v[44:47]
	v_mfma_f32_16x16x32_bf16 v[40:43], v[180:183], v[204:207], v[40:43]
	v_mfma_f32_16x16x32_bf16 v[36:39], v[172:175], v[212:215], v[36:39]
	v_mfma_f32_16x16x32_bf16 v[32:35], v[180:183], v[212:215], v[32:35]
	s_setprio 0
	s_barrier
	s_add_i32 s58, s49, s37
	s_add_u32 s62, s28, s10
	s_addc_u32 s63, s29, s11
	s_mov_b32 m0, s58
	ds_read_b128 v[184:187], v163 offset:16384
	ds_read_b128 v[188:191], v163 offset:17408
	ds_read_b128 v[192:195], v163 offset:18432
	ds_read_b128 v[196:199], v163 offset:19456
	ds_read_b128 v[200:203], v163 offset:20480
	ds_read_b128 v[204:207], v163 offset:21504
	ds_read_b128 v[208:211], v163 offset:22528
	ds_read_b128 v[212:215], v163 offset:23552
	global_load_lds_dwordx4 v138, s[28:29]
	s_add_i32 m0, s58, 0x2000
	s_add_u32 s58, s28, 0xb0000
	s_addc_u32 s59, s29, 0
	s_add_i32 s60, s50, s37
	global_load_lds_dwordx4 v142, s[28:29]
	s_mov_b32 m0, s60
	s_add_u32 s64, s30, s10
	s_addc_u32 s65, s31, s11
	global_load_lds_dwordx4 v138, s[58:59]
	s_add_i32 m0, s60, 0x2000
	s_nop 0
	global_load_lds_dwordx4 v142, s[58:59]
	s_mov_b32 m0, s39
	s_nop 0
	global_load_lds_dwordx4 v136, s[30:31]
	s_mov_b32 m0, s40
	s_nop 0
	global_load_lds_dwordx4 v140, s[30:31]
	s_waitcnt vmcnt(8)
	s_waitcnt lgkmcnt(0)
	s_barrier
	s_setprio 1
	s_waitcnt lgkmcnt(0)
	v_mfma_f32_16x16x32_bf16 v[92:95], v[128:131], v[184:187], 0
	v_mfma_f32_16x16x32_bf16 v[88:91], v[152:155], v[184:187], 0
	v_mfma_f32_16x16x32_bf16 v[84:87], v[128:131], v[192:195], 0
	v_mfma_f32_16x16x32_bf16 v[80:83], v[152:155], v[192:195], 0
	v_mfma_f32_16x16x32_bf16 v[76:79], v[128:131], v[200:203], 0
	v_mfma_f32_16x16x32_bf16 v[72:75], v[152:155], v[200:203], 0
	v_mfma_f32_16x16x32_bf16 v[68:71], v[128:131], v[208:211], 0
	v_mfma_f32_16x16x32_bf16 v[60:63], v[152:155], v[208:211], 0
	v_mfma_f32_16x16x32_bf16 v[92:95], v[132:135], v[188:191], v[92:95]
	v_mfma_f32_16x16x32_bf16 v[88:91], v[164:167], v[188:191], v[88:91]
	v_mfma_f32_16x16x32_bf16 v[84:87], v[132:135], v[196:199], v[84:87]
	v_mfma_f32_16x16x32_bf16 v[80:83], v[164:167], v[196:199], v[80:83]
	v_mfma_f32_16x16x32_bf16 v[76:79], v[132:135], v[204:207], v[76:79]
	v_mfma_f32_16x16x32_bf16 v[72:75], v[164:167], v[204:207], v[72:75]
	v_mfma_f32_16x16x32_bf16 v[68:71], v[132:135], v[212:215], v[68:71]
	v_mfma_f32_16x16x32_bf16 v[60:63], v[164:167], v[212:215], v[60:63]
	v_mfma_f32_16x16x32_bf16 v[28:31], v[168:171], v[184:187], 0
	v_mfma_f32_16x16x32_bf16 v[24:27], v[176:179], v[184:187], 0
	v_mfma_f32_16x16x32_bf16 v[20:23], v[168:171], v[192:195], 0
	v_mfma_f32_16x16x32_bf16 v[16:19], v[176:179], v[192:195], 0
	v_mfma_f32_16x16x32_bf16 v[12:15], v[168:171], v[200:203], 0
	v_mfma_f32_16x16x32_bf16 v[8:11], v[176:179], v[200:203], 0
	v_mfma_f32_16x16x32_bf16 v[4:7], v[168:171], v[208:211], 0
	v_mfma_f32_16x16x32_bf16 v[0:3], v[176:179], v[208:211], 0
	v_mfma_f32_16x16x32_bf16 v[28:31], v[172:175], v[188:191], v[28:31]
	v_mfma_f32_16x16x32_bf16 v[24:27], v[180:183], v[188:191], v[24:27]
	v_mfma_f32_16x16x32_bf16 v[20:23], v[172:175], v[196:199], v[20:23]
	v_mfma_f32_16x16x32_bf16 v[16:19], v[180:183], v[196:199], v[16:19]
	v_mfma_f32_16x16x32_bf16 v[12:15], v[172:175], v[204:207], v[12:15]
	v_mfma_f32_16x16x32_bf16 v[8:11], v[180:183], v[204:207], v[8:11]
	v_mfma_f32_16x16x32_bf16 v[4:7], v[172:175], v[212:215], v[4:7]
	v_mfma_f32_16x16x32_bf16 v[0:3], v[180:183], v[212:215], v[0:3]
	s_setprio 0
	s_barrier
; #define PG8_STAGE(bufoff, gbase, voff) do { _Pragma("unroll") for (int _i = 0; _i < 2; ++_i) \
;         __builtin_amdgcn_global_load_lds((const unsigned*)((const char*)(gbase) + (voff)[_i]), (PG8_LAS unsigned*)(lds + (bufoff) + ldsw + _i * 8192), 16, 0, 0); } while (0)
; #define PG8_LDA(dst, b, h) do { _Pragma("unroll") for (int m = 0; m < 4; ++m) _Pragma("unroll") for (int k = 0; k < 2; ++k) dst[m][k] = *(const PG8_LAS bf16x8*)(lds + PG8_SA(b, h) + aoff + m * 2048 + k * 1024); } while (0)
; #define PG8_LDB(dst, b, h) do { _Pragma("unroll") for (int n = 0; n < 2; ++n) _Pragma("unroll") for (int k = 0; k < 2; ++k) dst[n][k] = *(const PG8_LAS bf16x8*)(lds + PG8_SB(b, h) + boff + n * 2048 + k * 1024); } while (0)
; #define PG8_MMA(ai, bj, At, Bt) do { __builtin_amdgcn_s_setprio(1); _Pragma("unroll") for (int m = 0; m < 4; ++m) _Pragma("unroll") for (int n = 0; n < 2; ++n) _Pragma("unroll") for (int k = 0; k < 2; ++k) \
;         acc[ai][bj][m][n] = __builtin_amdgcn_mfma_f32_16x16x32_bf16(Bt[n][k], At[m][k], acc[ai][bj][m][n], 0, 0, 0); __builtin_amdgcn_s_setprio(0); } while (0)
; #define PG8_WAIT_V(n) asm volatile("s_waitcnt vmcnt(" #n ")" ::: "memory")
; #define PG8_WAIT_L(n) asm volatile("s_waitcnt lgkmcnt(" #n ")" ::: "memory")
; #define PG8_BAR __builtin_amdgcn_s_barrier()
; #define PG8_SCHED __builtin_amdgcn_sched_barrier(0)
; template <class Epi, class Sched, bool ALIGN_EPI = false, bool SP2 = false>
; __device__ __forceinline__ void gemm_phase(PG8_LAS unsigned char* lds, const Gemm g, const Sched& S, const Epi& E) {
;     ...
;             PG8_LDB(B0, 1, 0); PG8_LDB(B1, 1, 1); PG8_SCHED; PG8_LDA(At, 1, 0); PG8_STAGE(PG8_SA(0, 1), a2 + hstep, voffA);
;             PG8_WAIT_V(8); PG8_WAIT_L(0); PG8_BAR; PG8_MMA(0, 0, At, B0); PG8_MMA(0, 1, At, B1); PG8_BAR; PG8_SCHED;
;             PG8_LDA(At, 1, 1); PG8_STAGE(PG8_SB(1, 0), b3, voffB); PG8_STAGE(PG8_SB(1, 1), b3 + hstep, voffB); PG8_STAGE(PG8_SA(1, 0), a3, voffA);
;             PG8_WAIT_V(8); PG8_WAIT_L(0); PG8_BAR; PG8_MMA(1, 0, At, B0); PG8_MMA(1, 1, At, B1); PG8_BAR; PG8_SCHED;
	s_add_i32 s58, 0, 0x18000
	s_add_i32 s59, 0, 0x1c000
	v_add_u32_e32 v164, s58, v159
	v_add_u32_e32 v180, s59, v159
	ds_read_b128 v[128:131], v164
	ds_read_b128 v[132:135], v164 offset:1024
	ds_read_b128 v[152:155], v164 offset:2048
	ds_read_b128 v[164:167], v164 offset:3072
	ds_read_b128 v[168:171], v180
	ds_read_b128 v[172:175], v180 offset:1024
	ds_read_b128 v[176:179], v180 offset:2048
	ds_read_b128 v[180:183], v180 offset:3072
	s_add_u32 s30, s30, 0xb0000
	s_addc_u32 s31, s31, 0
	s_mov_b32 m0, s41
	ds_read_b128 v[184:187], v163 offset:32768
	ds_read_b128 v[188:191], v163 offset:33792
	ds_read_b128 v[192:195], v163 offset:34816
	ds_read_b128 v[196:199], v163 offset:35840
	ds_read_b128 v[200:203], v163 offset:36864
	ds_read_b128 v[204:207], v163 offset:37888
	ds_read_b128 v[208:211], v163 offset:38912
	ds_read_b128 v[212:215], v163 offset:39936
	global_load_lds_dwordx4 v136, s[30:31]
	s_mov_b32 m0, s42
	s_nop 0
	global_load_lds_dwordx4 v140, s[30:31]
	s_waitcnt vmcnt(8)
	s_waitcnt lgkmcnt(0)
	s_barrier
	s_setprio 1
	s_waitcnt lgkmcnt(0)
	v_mfma_f32_16x16x32_bf16 v[124:127], v[128:131], v[184:187], v[124:127]
	v_mfma_f32_16x16x32_bf16 v[120:123], v[152:155], v[184:187], v[120:123]
	v_mfma_f32_16x16x32_bf16 v[116:119], v[128:131], v[192:195], v[116:119]
	v_mfma_f32_16x16x32_bf16 v[112:115], v[152:155], v[192:195], v[112:115]
	v_mfma_f32_16x16x32_bf16 v[108:111], v[128:131], v[200:203], v[108:111]
	v_mfma_f32_16x16x32_bf16 v[104:107], v[152:155], v[200:203], v[104:107]
	v_mfma_f32_16x16x32_bf16 v[100:103], v[128:131], v[208:211], v[100:103]
	v_mfma_f32_16x16x32_bf16 v[96:99], v[152:155], v[208:211], v[96:99]
	v_mfma_f32_16x16x32_bf16 v[124:127], v[132:135], v[188:191], v[124:127]
	v_mfma_f32_16x16x32_bf16 v[120:123], v[164:167], v[188:191], v[120:123]
	v_mfma_f32_16x16x32_bf16 v[116:119], v[132:135], v[196:199], v[116:119]
	v_mfma_f32_16x16x32_bf16 v[112:115], v[164:167], v[196:199], v[112:115]
	v_mfma_f32_16x16x32_bf16 v[108:111], v[132:135], v[204:207], v[108:111]
	v_mfma_f32_16x16x32_bf16 v[104:107], v[164:167], v[204:207], v[104:107]
	v_mfma_f32_16x16x32_bf16 v[100:103], v[132:135], v[212:215], v[100:103]
	v_mfma_f32_16x16x32_bf16 v[96:99], v[164:167], v[212:215], v[96:99]
	v_mfma_f32_16x16x32_bf16 v[64:67], v[168:171], v[184:187], v[64:67]
	v_mfma_f32_16x16x32_bf16 v[56:59], v[176:179], v[184:187], v[56:59]
	v_mfma_f32_16x16x32_bf16 v[52:55], v[168:171], v[192:195], v[52:55]
	v_mfma_f32_16x16x32_bf16 v[48:51], v[176:179], v[192:195], v[48:51]
	v_mfma_f32_16x16x32_bf16 v[44:47], v[168:171], v[200:203], v[44:47]
	v_mfma_f32_16x16x32_bf16 v[40:43], v[176:179], v[200:203], v[40:43]
	v_mfma_f32_16x16x32_bf16 v[36:39], v[168:171], v[208:211], v[36:39]
	v_mfma_f32_16x16x32_bf16 v[32:35], v[176:179], v[208:211], v[32:35]
	v_mfma_f32_16x16x32_bf16 v[64:67], v[172:175], v[188:191], v[64:67]
	v_mfma_f32_16x16x32_bf16 v[56:59], v[180:183], v[188:191], v[56:59]
	v_mfma_f32_16x16x32_bf16 v[52:55], v[172:175], v[196:199], v[52:55]
	v_mfma_f32_16x16x32_bf16 v[48:51], v[180:183], v[196:199], v[48:51]
	v_mfma_f32_16x16x32_bf16 v[44:47], v[172:175], v[204:207], v[44:47]
	v_mfma_f32_16x16x32_bf16 v[40:43], v[180:183], v[204:207], v[40:43]
	v_mfma_f32_16x16x32_bf16 v[36:39], v[172:175], v[212:215], v[36:39]
	v_mfma_f32_16x16x32_bf16 v[32:35], v[180:183], v[212:215], v[32:35]
	s_setprio 0
	s_barrier
	s_add_i32 s30, s58, s37
	s_mov_b32 m0, s30
	ds_read_b128 v[184:187], v163 offset:49152
	ds_read_b128 v[188:191], v163 offset:50176
	ds_read_b128 v[192:195], v163 offset:51200
	ds_read_b128 v[196:199], v163 offset:52224
	ds_read_b128 v[200:203], v163 offset:53248
	ds_read_b128 v[204:207], v163 offset:54272
	ds_read_b128 v[208:211], v163 offset:55296
	ds_read_b128 v[212:215], v163 offset:56320
	global_load_lds_dwordx4 v138, s[62:63]
	s_add_i32 m0, s30, 0x2000
	s_add_u32 s28, s28, 0xb0080
	s_addc_u32 s29, s29, 0
	s_add_i32 s30, s59, s37
	global_load_lds_dwordx4 v142, s[62:63]
	s_mov_b32 m0, s30
	s_nop 0
	global_load_lds_dwordx4 v138, s[28:29]
	s_add_i32 m0, s30, 0x2000
	s_nop 0
	global_load_lds_dwordx4 v142, s[28:29]
	s_mov_b32 m0, s47
	s_nop 0
	global_load_lds_dwordx4 v136, s[64:65]
	s_mov_b32 m0, s48
	s_nop 0
	global_load_lds_dwordx4 v140, s[64:65]
	s_waitcnt vmcnt(8)
	s_waitcnt lgkmcnt(0)
	s_barrier
	s_setprio 1
	s_waitcnt lgkmcnt(0)
	v_mfma_f32_16x16x32_bf16 v[92:95], v[128:131], v[184:187], v[92:95]
	v_mfma_f32_16x16x32_bf16 v[88:91], v[152:155], v[184:187], v[88:91]
	v_mfma_f32_16x16x32_bf16 v[84:87], v[128:131], v[192:195], v[84:87]
	v_mfma_f32_16x16x32_bf16 v[80:83], v[152:155], v[192:195], v[80:83]
	v_mfma_f32_16x16x32_bf16 v[76:79], v[128:131], v[200:203], v[76:79]
	v_mfma_f32_16x16x32_bf16 v[72:75], v[152:155], v[200:203], v[72:75]
	v_mfma_f32_16x16x32_bf16 v[68:71], v[128:131], v[208:211], v[68:71]
	v_mfma_f32_16x16x32_bf16 v[60:63], v[152:155], v[208:211], v[60:63]
	v_mfma_f32_16x16x32_bf16 v[92:95], v[132:135], v[188:191], v[92:95]
	v_mfma_f32_16x16x32_bf16 v[88:91], v[164:167], v[188:191], v[88:91]
	v_mfma_f32_16x16x32_bf16 v[84:87], v[132:135], v[196:199], v[84:87]
	v_mfma_f32_16x16x32_bf16 v[80:83], v[164:167], v[196:199], v[80:83]
	v_mfma_f32_16x16x32_bf16 v[76:79], v[132:135], v[204:207], v[76:79]
	v_mfma_f32_16x16x32_bf16 v[72:75], v[164:167], v[204:207], v[72:75]
	v_mfma_f32_16x16x32_bf16 v[68:71], v[132:135], v[212:215], v[68:71]
	v_mfma_f32_16x16x32_bf16 v[60:63], v[164:167], v[212:215], v[60:63]
	v_mfma_f32_16x16x32_bf16 v[28:31], v[168:171], v[184:187], v[28:31]
	v_mfma_f32_16x16x32_bf16 v[24:27], v[176:179], v[184:187], v[24:27]
	v_mfma_f32_16x16x32_bf16 v[20:23], v[168:171], v[192:195], v[20:23]
	v_mfma_f32_16x16x32_bf16 v[16:19], v[176:179], v[192:195], v[16:19]
	v_mfma_f32_16x16x32_bf16 v[12:15], v[168:171], v[200:203], v[12:15]
	v_mfma_f32_16x16x32_bf16 v[8:11], v[176:179], v[200:203], v[8:11]
	v_mfma_f32_16x16x32_bf16 v[4:7], v[168:171], v[208:211], v[4:7]
	v_mfma_f32_16x16x32_bf16 v[0:3], v[176:179], v[208:211], v[0:3]
	v_mfma_f32_16x16x32_bf16 v[28:31], v[172:175], v[188:191], v[28:31]
	v_mfma_f32_16x16x32_bf16 v[24:27], v[180:183], v[188:191], v[24:27]
	v_mfma_f32_16x16x32_bf16 v[20:23], v[172:175], v[196:199], v[20:23]
	v_mfma_f32_16x16x32_bf16 v[16:19], v[180:183], v[196:199], v[16:19]
	v_mfma_f32_16x16x32_bf16 v[12:15], v[172:175], v[204:207], v[12:15]
	v_mfma_f32_16x16x32_bf16 v[8:11], v[180:183], v[204:207], v[8:11]
	v_mfma_f32_16x16x32_bf16 v[4:7], v[172:175], v[212:215], v[4:7]
	v_mfma_f32_16x16x32_bf16 v[0:3], v[180:183], v[212:215], v[0:3]
	s_setprio 0
	s_barrier
	s_add_i32 s57, s57, 2
	s_add_u32 s24, s24, 0x100
	s_addc_u32 s25, s25, 0
	s_add_u32 s55, s55, 0x100
	s_addc_u32 s56, s56, 0
	s_cmp_gt_u32 s57, 41
; #define PG8_STAGE(bufoff, gbase, voff) do { _Pragma("unroll") for (int _i = 0; _i < 2; ++_i) \
;         __builtin_amdgcn_global_load_lds((const unsigned*)((const char*)(gbase) + (voff)[_i]), (PG8_LAS unsigned*)(lds + (bufoff) + ldsw + _i * 8192), 16, 0, 0); } while (0)
; #define PG8_LDA(dst, b, h) do { _Pragma("unroll") for (int m = 0; m < 4; ++m) _Pragma("unroll") for (int k = 0; k < 2; ++k) dst[m][k] = *(const PG8_LAS bf16x8*)(lds + PG8_SA(b, h) + aoff + m * 2048 + k * 1024); } while (0)
; #define PG8_LDB(dst, b, h) do { _Pragma("unroll") for (int n = 0; n < 2; ++n) _Pragma("unroll") for (int k = 0; k < 2; ++k) dst[n][k] = *(const PG8_LAS bf16x8*)(lds + PG8_SB(b, h) + boff + n * 2048 + k * 1024); } while (0)
; #define PG8_MMA(ai, bj, At, Bt) do { __builtin_amdgcn_s_setprio(1); _Pragma("unroll") for (int m = 0; m < 4; ++m) _Pragma("unroll") for (int n = 0; n < 2; ++n) _Pragma("unroll") for (int k = 0; k < 2; ++k) \
;         acc[ai][bj][m][n] = __builtin_amdgcn_mfma_f32_16x16x32_bf16(Bt[n][k], At[m][k], acc[ai][bj][m][n], 0, 0, 0); __builtin_amdgcn_s_setprio(0); } while (0)
; #define PG8_WAIT_V(n) asm volatile("s_waitcnt vmcnt(" #n ")" ::: "memory")
; #define PG8_WAIT_L(n) asm volatile("s_waitcnt lgkmcnt(" #n ")" ::: "memory")
; #define PG8_BAR __builtin_amdgcn_s_barrier()
; #define PG8_SCHED __builtin_amdgcn_sched_barrier(0)
; template <class Epi, class Sched, bool ALIGN_EPI = false, bool SP2 = false>
; __device__ __forceinline__ void gemm_phase(PG8_LAS unsigned char* lds, const Gemm g, const Sched& S, const Epi& E) {
;     ...
;             PG8_LDB(B0, 0, 0); PG8_LDB(B1, 0, 1); PG8_SCHED; PG8_LDA(At, 0, 0); PG8_STAGE(PG8_SA(1, 1), a1 + hstep, voffA);
;             PG8_WAIT_V(8); PG8_WAIT_L(0); PG8_BAR; PG8_MMA(0, 0, At, B0); PG8_MMA(0, 1, At, B1); PG8_BAR; PG8_SCHED;
;             PG8_LDA(At, 0, 1); PG8_STAGE(PG8_SB(0, 0), b2, voffB); PG8_STAGE(PG8_SB(0, 1), b2 + hstep, voffB); PG8_STAGE(PG8_SA(0, 0), a2, voffA);
;             PG8_WAIT_V(8); PG8_WAIT_L(0); PG8_BAR; PG8_MMA(1, 0, At, B0); PG8_MMA(1, 1, At, B1); PG8_BAR; PG8_SCHED;
.LBB0_1417:
	ds_read_b128 v[128:131], v161
	ds_read_b128 v[132:135], v161 offset:1024
	ds_read_b128 v[152:155], v161 offset:2048
	ds_read_b128 v[164:167], v161 offset:3072
	ds_read_b128 v[168:171], v162
	ds_read_b128 v[172:175], v162 offset:1024
	ds_read_b128 v[176:179], v162 offset:2048
	ds_read_b128 v[180:183], v162 offset:3072
	s_add_u32 s28, s24, 0xfff50080
	s_addc_u32 s29, s25, -1
	s_cmp_eq_u32 s57, 40
	s_cselect_b32 s31, s5, s29
	s_cselect_b32 s30, s4, s28
	s_cselect_b32 s29, s23, s56
	s_cselect_b32 s28, s22, s55
	s_add_i32 m0, s39, 0xc000
	ds_read_b128 v[184:187], v163
	ds_read_b128 v[188:191], v163 offset:1024
	ds_read_b128 v[192:195], v163 offset:2048
	ds_read_b128 v[196:199], v163 offset:3072
	ds_read_b128 v[200:203], v163 offset:4096
	ds_read_b128 v[204:207], v163 offset:5120
	ds_read_b128 v[208:211], v163 offset:6144
	ds_read_b128 v[212:215], v163 offset:7168
	global_load_lds_dwordx4 v144, s[24:25]
	s_add_i32 m0, s39, 0xe000
	s_nop 0
	global_load_lds_dwordx4 v146, s[24:25]
	s_waitcnt vmcnt(8)
	s_waitcnt lgkmcnt(0)
	s_barrier
	s_setprio 1
	s_waitcnt lgkmcnt(0)
	v_mfma_f32_16x16x32_bf16 v[124:127], v[128:131], v[184:187], v[124:127]
	v_mfma_f32_16x16x32_bf16 v[120:123], v[152:155], v[184:187], v[120:123]
	v_mfma_f32_16x16x32_bf16 v[116:119], v[128:131], v[192:195], v[116:119]
	v_mfma_f32_16x16x32_bf16 v[112:115], v[152:155], v[192:195], v[112:115]
	v_mfma_f32_16x16x32_bf16 v[108:111], v[128:131], v[200:203], v[108:111]
	v_mfma_f32_16x16x32_bf16 v[104:107], v[152:155], v[200:203], v[104:107]
	v_mfma_f32_16x16x32_bf16 v[100:103], v[128:131], v[208:211], v[100:103]
	v_mfma_f32_16x16x32_bf16 v[96:99], v[152:155], v[208:211], v[96:99]
	v_mfma_f32_16x16x32_bf16 v[124:127], v[132:135], v[188:191], v[124:127]
	v_mfma_f32_16x16x32_bf16 v[120:123], v[164:167], v[188:191], v[120:123]
	v_mfma_f32_16x16x32_bf16 v[116:119], v[132:135], v[196:199], v[116:119]
	v_mfma_f32_16x16x32_bf16 v[112:115], v[164:167], v[196:199], v[112:115]
	v_mfma_f32_16x16x32_bf16 v[108:111], v[132:135], v[204:207], v[108:111]
	v_mfma_f32_16x16x32_bf16 v[104:107], v[164:167], v[204:207], v[104:107]
	v_mfma_f32_16x16x32_bf16 v[100:103], v[132:135], v[212:215], v[100:103]
	v_mfma_f32_16x16x32_bf16 v[96:99], v[164:167], v[212:215], v[96:99]
	v_mfma_f32_16x16x32_bf16 v[64:67], v[168:171], v[184:187], v[64:67]
	v_mfma_f32_16x16x32_bf16 v[56:59], v[176:179], v[184:187], v[56:59]
	v_mfma_f32_16x16x32_bf16 v[52:55], v[168:171], v[192:195], v[52:55]
	v_mfma_f32_16x16x32_bf16 v[48:51], v[176:179], v[192:195], v[48:51]
	v_mfma_f32_16x16x32_bf16 v[44:47], v[168:171], v[200:203], v[44:47]
	v_mfma_f32_16x16x32_bf16 v[40:43], v[176:179], v[200:203], v[40:43]
	v_mfma_f32_16x16x32_bf16 v[36:39], v[168:171], v[208:211], v[36:39]
	v_mfma_f32_16x16x32_bf16 v[32:35], v[176:179], v[208:211], v[32:35]
	v_mfma_f32_16x16x32_bf16 v[64:67], v[172:175], v[188:191], v[64:67]
	v_mfma_f32_16x16x32_bf16 v[56:59], v[180:183], v[188:191], v[56:59]
	v_mfma_f32_16x16x32_bf16 v[52:55], v[172:175], v[196:199], v[52:55]
	v_mfma_f32_16x16x32_bf16 v[48:51], v[180:183], v[196:199], v[48:51]
	v_mfma_f32_16x16x32_bf16 v[44:47], v[172:175], v[204:207], v[44:47]
	v_mfma_f32_16x16x32_bf16 v[40:43], v[180:183], v[204:207], v[40:43]
	v_mfma_f32_16x16x32_bf16 v[36:39], v[172:175], v[212:215], v[36:39]
	v_mfma_f32_16x16x32_bf16 v[32:35], v[180:183], v[212:215], v[32:35]
	s_setprio 0
	s_barrier
	s_add_i32 s58, s49, s37
	s_add_u32 s62, s28, s10
	s_addc_u32 s63, s29, s11
	s_mov_b32 m0, s58
	ds_read_b128 v[184:187], v163 offset:16384
	ds_read_b128 v[188:191], v163 offset:17408
	ds_read_b128 v[192:195], v163 offset:18432
	ds_read_b128 v[196:199], v163 offset:19456
	ds_read_b128 v[200:203], v163 offset:20480
	ds_read_b128 v[204:207], v163 offset:21504
	ds_read_b128 v[208:211], v163 offset:22528
	ds_read_b128 v[212:215], v163 offset:23552
	global_load_lds_dwordx4 v138, s[28:29]
	s_add_i32 m0, s58, 0x2000
	s_add_u32 s58, s28, 0xb0000
	s_addc_u32 s59, s29, 0
	s_add_i32 s60, s50, s37
	global_load_lds_dwordx4 v142, s[28:29]
	s_mov_b32 m0, s60
	s_add_u32 s64, s30, s10
	s_addc_u32 s65, s31, s11
	global_load_lds_dwordx4 v138, s[58:59]
	s_add_i32 m0, s60, 0x2000
	s_nop 0
	global_load_lds_dwordx4 v142, s[58:59]
	s_mov_b32 m0, s39
	s_nop 0
	global_load_lds_dwordx4 v136, s[30:31]
	s_mov_b32 m0, s40
	s_nop 0
	global_load_lds_dwordx4 v140, s[30:31]
	s_waitcnt vmcnt(8)
	s_waitcnt lgkmcnt(0)
	s_barrier
	s_setprio 1
	s_waitcnt lgkmcnt(0)
	v_mfma_f32_16x16x32_bf16 v[92:95], v[128:131], v[184:187], v[92:95]
	v_mfma_f32_16x16x32_bf16 v[88:91], v[152:155], v[184:187], v[88:91]
	v_mfma_f32_16x16x32_bf16 v[84:87], v[128:131], v[192:195], v[84:87]
	v_mfma_f32_16x16x32_bf16 v[80:83], v[152:155], v[192:195], v[80:83]
	v_mfma_f32_16x16x32_bf16 v[76:79], v[128:131], v[200:203], v[76:79]
	v_mfma_f32_16x16x32_bf16 v[72:75], v[152:155], v[200:203], v[72:75]
	v_mfma_f32_16x16x32_bf16 v[68:71], v[128:131], v[208:211], v[68:71]
	v_mfma_f32_16x16x32_bf16 v[60:63], v[152:155], v[208:211], v[60:63]
	v_mfma_f32_16x16x32_bf16 v[92:95], v[132:135], v[188:191], v[92:95]
	v_mfma_f32_16x16x32_bf16 v[88:91], v[164:167], v[188:191], v[88:91]
	v_mfma_f32_16x16x32_bf16 v[84:87], v[132:135], v[196:199], v[84:87]
	v_mfma_f32_16x16x32_bf16 v[80:83], v[164:167], v[196:199], v[80:83]
	v_mfma_f32_16x16x32_bf16 v[76:79], v[132:135], v[204:207], v[76:79]
	v_mfma_f32_16x16x32_bf16 v[72:75], v[164:167], v[204:207], v[72:75]
	v_mfma_f32_16x16x32_bf16 v[68:71], v[132:135], v[212:215], v[68:71]
	v_mfma_f32_16x16x32_bf16 v[60:63], v[164:167], v[212:215], v[60:63]
	v_mfma_f32_16x16x32_bf16 v[28:31], v[168:171], v[184:187], v[28:31]
	v_mfma_f32_16x16x32_bf16 v[24:27], v[176:179], v[184:187], v[24:27]
	v_mfma_f32_16x16x32_bf16 v[20:23], v[168:171], v[192:195], v[20:23]
	v_mfma_f32_16x16x32_bf16 v[16:19], v[176:179], v[192:195], v[16:19]
	v_mfma_f32_16x16x32_bf16 v[12:15], v[168:171], v[200:203], v[12:15]
	v_mfma_f32_16x16x32_bf16 v[8:11], v[176:179], v[200:203], v[8:11]
	v_mfma_f32_16x16x32_bf16 v[4:7], v[168:171], v[208:211], v[4:7]
	v_mfma_f32_16x16x32_bf16 v[0:3], v[176:179], v[208:211], v[0:3]
	v_mfma_f32_16x16x32_bf16 v[28:31], v[172:175], v[188:191], v[28:31]
	v_mfma_f32_16x16x32_bf16 v[24:27], v[180:183], v[188:191], v[24:27]
	v_mfma_f32_16x16x32_bf16 v[20:23], v[172:175], v[196:199], v[20:23]
	v_mfma_f32_16x16x32_bf16 v[16:19], v[180:183], v[196:199], v[16:19]
	v_mfma_f32_16x16x32_bf16 v[12:15], v[172:175], v[204:207], v[12:15]
	v_mfma_f32_16x16x32_bf16 v[8:11], v[180:183], v[204:207], v[8:11]
	v_mfma_f32_16x16x32_bf16 v[4:7], v[172:175], v[212:215], v[4:7]
	v_mfma_f32_16x16x32_bf16 v[0:3], v[180:183], v[212:215], v[0:3]
	s_setprio 0
	s_barrier
; #define PG8_STAGE(bufoff, gbase, voff) do { _Pragma("unroll") for (int _i = 0; _i < 2; ++_i) \
;         __builtin_amdgcn_global_load_lds((const unsigned*)((const char*)(gbase) + (voff)[_i]), (PG8_LAS unsigned*)(lds + (bufoff) + ldsw + _i * 8192), 16, 0, 0); } while (0)
; #define PG8_LDA(dst, b, h) do { _Pragma("unroll") for (int m = 0; m < 4; ++m) _Pragma("unroll") for (int k = 0; k < 2; ++k) dst[m][k] = *(const PG8_LAS bf16x8*)(lds + PG8_SA(b, h) + aoff + m * 2048 + k * 1024); } while (0)
; #define PG8_LDB(dst, b, h) do { _Pragma("unroll") for (int n = 0; n < 2; ++n) _Pragma("unroll") for (int k = 0; k < 2; ++k) dst[n][k] = *(const PG8_LAS bf16x8*)(lds + PG8_SB(b, h) + boff + n * 2048 + k * 1024); } while (0)
; #define PG8_MMA(ai, bj, At, Bt) do { __builtin_amdgcn_s_setprio(1); _Pragma("unroll") for (int m = 0; m < 4; ++m) _Pragma("unroll") for (int n = 0; n < 2; ++n) _Pragma("unroll") for (int k = 0; k < 2; ++k) \
;         acc[ai][bj][m][n] = __builtin_amdgcn_mfma_f32_16x16x32_bf16(Bt[n][k], At[m][k], acc[ai][bj][m][n], 0, 0, 0); __builtin_amdgcn_s_setprio(0); } while (0)
; #define PG8_WAIT_V(n) asm volatile("s_waitcnt vmcnt(" #n ")" ::: "memory")
; #define PG8_WAIT_L(n) asm volatile("s_waitcnt lgkmcnt(" #n ")" ::: "memory")
; #define PG8_BAR __builtin_amdgcn_s_barrier()
; #define PG8_SCHED __builtin_amdgcn_sched_barrier(0)
; template <class Epi, class Sched, bool ALIGN_EPI = false, bool SP2 = false>
; __device__ __forceinline__ void gemm_phase(PG8_LAS unsigned char* lds, const Gemm g, const Sched& S, const Epi& E) {
;     ...
;             PG8_LDB(B0, 1, 0); PG8_LDB(B1, 1, 1); PG8_SCHED; PG8_LDA(At, 1, 0); PG8_STAGE(PG8_SA(0, 1), a2 + hstep, voffA);
;             PG8_WAIT_V(8); PG8_WAIT_L(0); PG8_BAR; PG8_MMA(0, 0, At, B0); PG8_MMA(0, 1, At, B1); PG8_BAR; PG8_SCHED;
;             PG8_LDA(At, 1, 1); PG8_STAGE(PG8_SB(1, 0), b3, voffB); PG8_STAGE(PG8_SB(1, 1), b3 + hstep, voffB); PG8_STAGE(PG8_SA(1, 0), a3, voffA);
;             PG8_WAIT_V(8); PG8_WAIT_L(0); PG8_BAR; PG8_MMA(1, 0, At, B0); PG8_MMA(1, 1, At, B1); PG8_BAR; PG8_SCHED;
;     ...
;         if constexpr (ALIGN_EPI) { if (wr == 0) PG8_BAR; }
	s_add_i32 s58, 0, 0x18000
	s_add_i32 s59, 0, 0x1c000
	v_add_u32_e32 v164, s58, v159
	v_add_u32_e32 v180, s59, v159
	ds_read_b128 v[128:131], v164
	ds_read_b128 v[132:135], v164 offset:1024
	ds_read_b128 v[152:155], v164 offset:2048
	ds_read_b128 v[164:167], v164 offset:3072
	ds_read_b128 v[168:171], v180
	ds_read_b128 v[172:175], v180 offset:1024
	ds_read_b128 v[176:179], v180 offset:2048
	ds_read_b128 v[180:183], v180 offset:3072
	s_add_u32 s30, s30, 0xb0000
	s_addc_u32 s31, s31, 0
	s_mov_b32 m0, s41
	ds_read_b128 v[184:187], v163 offset:32768
	ds_read_b128 v[188:191], v163 offset:33792
	ds_read_b128 v[192:195], v163 offset:34816
	ds_read_b128 v[196:199], v163 offset:35840
	ds_read_b128 v[200:203], v163 offset:36864
	ds_read_b128 v[204:207], v163 offset:37888
	ds_read_b128 v[208:211], v163 offset:38912
	ds_read_b128 v[212:215], v163 offset:39936
	global_load_lds_dwordx4 v136, s[30:31]
	s_mov_b32 m0, s42
	s_nop 0
	global_load_lds_dwordx4 v140, s[30:31]
	s_waitcnt vmcnt(8)
	s_waitcnt lgkmcnt(0)
	s_barrier
	s_setprio 1
	s_waitcnt lgkmcnt(0)
	v_mfma_f32_16x16x32_bf16 v[124:127], v[128:131], v[184:187], v[124:127]
	v_mfma_f32_16x16x32_bf16 v[120:123], v[152:155], v[184:187], v[120:123]
	v_mfma_f32_16x16x32_bf16 v[116:119], v[128:131], v[192:195], v[116:119]
	v_mfma_f32_16x16x32_bf16 v[112:115], v[152:155], v[192:195], v[112:115]
	v_mfma_f32_16x16x32_bf16 v[108:111], v[128:131], v[200:203], v[108:111]
	v_mfma_f32_16x16x32_bf16 v[104:107], v[152:155], v[200:203], v[104:107]
	v_mfma_f32_16x16x32_bf16 v[100:103], v[128:131], v[208:211], v[100:103]
	v_mfma_f32_16x16x32_bf16 v[96:99], v[152:155], v[208:211], v[96:99]
	v_mfma_f32_16x16x32_bf16 v[124:127], v[132:135], v[188:191], v[124:127]
	v_mfma_f32_16x16x32_bf16 v[120:123], v[164:167], v[188:191], v[120:123]
	v_mfma_f32_16x16x32_bf16 v[116:119], v[132:135], v[196:199], v[116:119]
	v_mfma_f32_16x16x32_bf16 v[112:115], v[164:167], v[196:199], v[112:115]
	v_mfma_f32_16x16x32_bf16 v[108:111], v[132:135], v[204:207], v[108:111]
	v_mfma_f32_16x16x32_bf16 v[104:107], v[164:167], v[204:207], v[104:107]
	v_mfma_f32_16x16x32_bf16 v[100:103], v[132:135], v[212:215], v[100:103]
	v_mfma_f32_16x16x32_bf16 v[96:99], v[164:167], v[212:215], v[96:99]
	v_mfma_f32_16x16x32_bf16 v[64:67], v[168:171], v[184:187], v[64:67]
	v_mfma_f32_16x16x32_bf16 v[56:59], v[176:179], v[184:187], v[56:59]
	v_mfma_f32_16x16x32_bf16 v[52:55], v[168:171], v[192:195], v[52:55]
	v_mfma_f32_16x16x32_bf16 v[48:51], v[176:179], v[192:195], v[48:51]
	v_mfma_f32_16x16x32_bf16 v[44:47], v[168:171], v[200:203], v[44:47]
	v_mfma_f32_16x16x32_bf16 v[40:43], v[176:179], v[200:203], v[40:43]
	v_mfma_f32_16x16x32_bf16 v[36:39], v[168:171], v[208:211], v[36:39]
	v_mfma_f32_16x16x32_bf16 v[32:35], v[176:179], v[208:211], v[32:35]
	v_mfma_f32_16x16x32_bf16 v[64:67], v[172:175], v[188:191], v[64:67]
	v_mfma_f32_16x16x32_bf16 v[56:59], v[180:183], v[188:191], v[56:59]
	v_mfma_f32_16x16x32_bf16 v[52:55], v[172:175], v[196:199], v[52:55]
	v_mfma_f32_16x16x32_bf16 v[48:51], v[180:183], v[196:199], v[48:51]
	v_mfma_f32_16x16x32_bf16 v[44:47], v[172:175], v[204:207], v[44:47]
	v_mfma_f32_16x16x32_bf16 v[40:43], v[180:183], v[204:207], v[40:43]
	v_mfma_f32_16x16x32_bf16 v[36:39], v[172:175], v[212:215], v[36:39]
	v_mfma_f32_16x16x32_bf16 v[32:35], v[180:183], v[212:215], v[32:35]
	s_setprio 0
	s_barrier
	s_add_i32 s30, s58, s37
	s_mov_b32 m0, s30
	ds_read_b128 v[184:187], v163 offset:49152
	ds_read_b128 v[188:191], v163 offset:50176
	ds_read_b128 v[192:195], v163 offset:51200
	ds_read_b128 v[196:199], v163 offset:52224
	ds_read_b128 v[200:203], v163 offset:53248
	ds_read_b128 v[204:207], v163 offset:54272
	ds_read_b128 v[208:211], v163 offset:55296
	ds_read_b128 v[212:215], v163 offset:56320
	global_load_lds_dwordx4 v138, s[62:63]
	s_add_i32 m0, s30, 0x2000
	s_add_u32 s28, s28, 0xb0080
	s_addc_u32 s29, s29, 0
	s_add_i32 s30, s59, s37
	global_load_lds_dwordx4 v142, s[62:63]
	s_mov_b32 m0, s30
	s_nop 0
	global_load_lds_dwordx4 v138, s[28:29]
	s_add_i32 m0, s30, 0x2000
	s_nop 0
	global_load_lds_dwordx4 v142, s[28:29]
	s_mov_b32 m0, s47
	s_nop 0
	global_load_lds_dwordx4 v136, s[64:65]
	s_mov_b32 m0, s48
	s_nop 0
	global_load_lds_dwordx4 v140, s[64:65]
	s_waitcnt vmcnt(8)
	s_waitcnt lgkmcnt(0)
	s_barrier
	s_setprio 1
	s_waitcnt lgkmcnt(0)
	v_mfma_f32_16x16x32_bf16 v[92:95], v[128:131], v[184:187], v[92:95]
	v_mfma_f32_16x16x32_bf16 v[88:91], v[152:155], v[184:187], v[88:91]
	v_mfma_f32_16x16x32_bf16 v[84:87], v[128:131], v[192:195], v[84:87]
	v_mfma_f32_16x16x32_bf16 v[80:83], v[152:155], v[192:195], v[80:83]
	v_mfma_f32_16x16x32_bf16 v[76:79], v[128:131], v[200:203], v[76:79]
	v_mfma_f32_16x16x32_bf16 v[72:75], v[152:155], v[200:203], v[72:75]
	v_mfma_f32_16x16x32_bf16 v[68:71], v[128:131], v[208:211], v[68:71]
	v_mfma_f32_16x16x32_bf16 v[60:63], v[152:155], v[208:211], v[60:63]
	v_mfma_f32_16x16x32_bf16 v[92:95], v[132:135], v[188:191], v[92:95]
	v_mfma_f32_16x16x32_bf16 v[88:91], v[164:167], v[188:191], v[88:91]
	v_mfma_f32_16x16x32_bf16 v[84:87], v[132:135], v[196:199], v[84:87]
	v_mfma_f32_16x16x32_bf16 v[80:83], v[164:167], v[196:199], v[80:83]
	v_mfma_f32_16x16x32_bf16 v[76:79], v[132:135], v[204:207], v[76:79]
	v_mfma_f32_16x16x32_bf16 v[72:75], v[164:167], v[204:207], v[72:75]
	v_mfma_f32_16x16x32_bf16 v[68:71], v[132:135], v[212:215], v[68:71]
	v_mfma_f32_16x16x32_bf16 v[60:63], v[164:167], v[212:215], v[60:63]
	v_mfma_f32_16x16x32_bf16 v[28:31], v[168:171], v[184:187], v[28:31]
	v_mfma_f32_16x16x32_bf16 v[24:27], v[176:179], v[184:187], v[24:27]
	v_mfma_f32_16x16x32_bf16 v[20:23], v[168:171], v[192:195], v[20:23]
	v_mfma_f32_16x16x32_bf16 v[16:19], v[176:179], v[192:195], v[16:19]
	v_mfma_f32_16x16x32_bf16 v[12:15], v[168:171], v[200:203], v[12:15]
	v_mfma_f32_16x16x32_bf16 v[8:11], v[176:179], v[200:203], v[8:11]
	v_mfma_f32_16x16x32_bf16 v[4:7], v[168:171], v[208:211], v[4:7]
	v_mfma_f32_16x16x32_bf16 v[0:3], v[176:179], v[208:211], v[0:3]
	v_mfma_f32_16x16x32_bf16 v[28:31], v[172:175], v[188:191], v[28:31]
	v_mfma_f32_16x16x32_bf16 v[24:27], v[180:183], v[188:191], v[24:27]
	v_mfma_f32_16x16x32_bf16 v[20:23], v[172:175], v[196:199], v[20:23]
	v_mfma_f32_16x16x32_bf16 v[16:19], v[180:183], v[196:199], v[16:19]
	v_mfma_f32_16x16x32_bf16 v[12:15], v[172:175], v[204:207], v[12:15]
	v_mfma_f32_16x16x32_bf16 v[8:11], v[180:183], v[204:207], v[8:11]
	v_mfma_f32_16x16x32_bf16 v[4:7], v[172:175], v[212:215], v[4:7]
	v_mfma_f32_16x16x32_bf16 v[0:3], v[180:183], v[212:215], v[0:3]
	s_setprio 0
	s_barrier
	s_add_i32 s57, s57, 2
	s_add_u32 s24, s24, 0x100
	s_addc_u32 s25, s25, 0
	s_add_u32 s55, s55, 0x100
	s_addc_u32 s56, s56, 0
	s_cmp_gt_u32 s57, 41
	s_cbranch_scc0 .LBB0_1417
	s_and_b64 vcc, exec, s[12:13]
	s_cbranch_vccz .LBB0_1420
	s_barrier
